# v83 stack with the 8 s_setprio toggles per K-loop iteration removed (priority made no difference; 8 fewer instructions per iteration)
# baseline (speedup 1.0000x reference)
; #define PG8_STAGE(bufoff, gbase, voff) do { _Pragma("unroll") for (int _i = 0; _i < 2; ++_i) \
;         __builtin_amdgcn_global_load_lds((const unsigned*)((const char*)(gbase) + (voff)[_i]), (PG8_LAS unsigned*)(lds + (bufoff) + ldsw + _i * 8192), 16, 0, 0); } while (0)
; #define PG8_LDA(dst, b, h) do { _Pragma("unroll") for (int m = 0; m < 4; ++m) _Pragma("unroll") for (int k = 0; k < 2; ++k) dst[m][k] = *(const PG8_LAS bf16x8*)(lds + PG8_SA(b, h) + aoff + m * 2048 + k * 1024); } while (0)
; #define PG8_LDB(dst, b, h) do { _Pragma("unroll") for (int n = 0; n < 2; ++n) _Pragma("unroll") for (int k = 0; k < 2; ++k) dst[n][k] = *(const PG8_LAS bf16x8*)(lds + PG8_SB(b, h) + boff + n * 2048 + k * 1024); } while (0)
; #define PG8_MMA(ai, bj, At, Bt) do { __builtin_amdgcn_s_setprio(1); _Pragma("unroll") for (int m = 0; m < 4; ++m) _Pragma("unroll") for (int n = 0; n < 2; ++n) _Pragma("unroll") for (int k = 0; k < 2; ++k) \
;         acc[ai][bj][m][n] = __builtin_amdgcn_mfma_f32_16x16x32_bf16(Bt[n][k], At[m][k], acc[ai][bj][m][n], 0, 0, 0); __builtin_amdgcn_s_setprio(0); } while (0)
; #define PG8_WAIT_V(n) asm volatile("s_waitcnt vmcnt(" #n ")" ::: "memory")
; #define PG8_BAR __builtin_amdgcn_s_barrier()
; template <class Epi, class Sched, bool ALIGN_EPI = false, bool SP2 = false>
; __device__ __forceinline__ void gemm_phase(PG8_LAS unsigned char* lds, const Gemm g, const Sched& S, const Epi& E) {
;     ...
;         for (int t = 0; t < nt; t += 2) {
;             const bool last = (t == nt - 2);
;             const char* a1 = cA + (size_t)(t + 1) * kstep;
;             const char* a2 = last ? nA : cA + (size_t)(t + 2) * kstep; const char* b2 = last ? nB : cB + (size_t)(t + 2) * kstep;
;             const char* a3 = a2 + kstep; const char* b3 = b2 + kstep;
;             if (last && has_next) S.a_ready(nxt);
;             if constexpr (SP2) {
;             PG8_LDB(B0, 0, 0); PG8_LDB(B1, 0, 1); PG8_SCHED; PG8_LDA(At, 0, 0); PG8_STAGE(PG8_SA(1, 1), a1 + hstep, voffA);
;             PG8_WAIT_V(8); PG8_WAIT_L(0); PG8_BAR; PG8_MMA(0, 0, At, B0); PG8_MMA(0, 1, At, B1); PG8_BAR; PG8_SCHED;
;             PG8_LDA(At, 0, 1); PG8_STAGE(PG8_SB(0, 0), b2, voffB); PG8_STAGE(PG8_SB(0, 1), b2 + hstep, voffB); PG8_STAGE(PG8_SA(0, 0), a2, voffA);
;             PG8_WAIT_V(8); PG8_WAIT_L(0); PG8_BAR; PG8_MMA(1, 0, At, B0); PG8_MMA(1, 1, At, B1); PG8_BAR; PG8_SCHED;
.LBB0_304:
	v_add_u32_e32 v166, s54, v169
	ds_read_b128 v[162:165], v166
	ds_read_b128 v[182:185], v166 offset:1024
	ds_read_b128 v[186:189], v166 offset:2048
	ds_read_b128 v[190:193], v166 offset:3072
	ds_read_b128 v[194:197], v166 offset:16384
	ds_read_b128 v[198:201], v166 offset:17408
	ds_read_b128 v[202:205], v166 offset:18432
	ds_read_b128 v[206:209], v166 offset:19456
	s_cmp_eq_u32 s53, s10
	v_lshl_add_u64 v[172:173], v[160:161], 0, s[22:23]
	s_cselect_b64 vcc, -1, 0
	s_add_i32 s10, s10, 2
	v_cndmask_b32_e32 v173, v173, v153, vcc
	v_cndmask_b32_e32 v172, v172, v152, vcc
	v_cndmask_b32_e32 v245, v159, v155, vcc
	v_cndmask_b32_e32 v244, v158, v154, vcc
	s_mov_b32 m0, s56
	v_lshl_add_u64 v[246:247], v[160:161], 0, v[148:149]
	ds_read_b128 v[210:213], v179
	ds_read_b128 v[216:219], v179 offset:1024
	ds_read_b128 v[220:223], v179 offset:2048
	ds_read_b128 v[224:227], v179 offset:3072
	ds_read_b128 v[228:231], v179 offset:4096
	ds_read_b128 v[232:235], v179 offset:5120
	ds_read_b128 v[236:239], v179 offset:6144
	ds_read_b128 v[240:243], v179 offset:7168
	global_load_lds_dwordx4 v[246:247], off
	s_mov_b32 m0, s57
	v_lshl_add_u64 v[246:247], v[160:161], 0, v[146:147]
	global_load_lds_dwordx4 v[246:247], off
	s_waitcnt vmcnt(8) lgkmcnt(0)
	s_barrier
	v_mfma_f32_16x16x32_bf16 v[124:127], v[162:165], v[210:213], v[124:127]
	v_mfma_f32_16x16x32_bf16 v[116:119], v[186:189], v[210:213], v[116:119]
	v_mfma_f32_16x16x32_bf16 v[108:111], v[162:165], v[220:223], v[108:111]
	v_mfma_f32_16x16x32_bf16 v[100:103], v[186:189], v[220:223], v[100:103]
	v_mfma_f32_16x16x32_bf16 v[92:95], v[162:165], v[228:231], v[92:95]
	v_mfma_f32_16x16x32_bf16 v[84:87], v[186:189], v[228:231], v[84:87]
	v_mfma_f32_16x16x32_bf16 v[76:79], v[162:165], v[236:239], v[76:79]
	v_mfma_f32_16x16x32_bf16 v[68:71], v[186:189], v[236:239], v[68:71]
	v_mfma_f32_16x16x32_bf16 v[124:127], v[182:185], v[216:219], v[124:127]
	v_mfma_f32_16x16x32_bf16 v[116:119], v[190:193], v[216:219], v[116:119]
	v_mfma_f32_16x16x32_bf16 v[108:111], v[182:185], v[224:227], v[108:111]
	v_mfma_f32_16x16x32_bf16 v[100:103], v[190:193], v[224:227], v[100:103]
	v_mfma_f32_16x16x32_bf16 v[92:95], v[182:185], v[232:235], v[92:95]
	v_mfma_f32_16x16x32_bf16 v[84:87], v[190:193], v[232:235], v[84:87]
	v_mfma_f32_16x16x32_bf16 v[76:79], v[182:185], v[240:243], v[76:79]
	v_mfma_f32_16x16x32_bf16 v[68:71], v[190:193], v[240:243], v[68:71]
	v_mfma_f32_16x16x32_bf16 v[120:123], v[194:197], v[210:213], v[120:123]
	v_mfma_f32_16x16x32_bf16 v[112:115], v[202:205], v[210:213], v[112:115]
	v_mfma_f32_16x16x32_bf16 v[104:107], v[194:197], v[220:223], v[104:107]
	v_mfma_f32_16x16x32_bf16 v[96:99], v[202:205], v[220:223], v[96:99]
	v_mfma_f32_16x16x32_bf16 v[88:91], v[194:197], v[228:231], v[88:91]
	v_mfma_f32_16x16x32_bf16 v[80:83], v[202:205], v[228:231], v[80:83]
	v_mfma_f32_16x16x32_bf16 v[72:75], v[194:197], v[236:239], v[72:75]
	v_mfma_f32_16x16x32_bf16 v[64:67], v[202:205], v[236:239], v[64:67]
	v_mfma_f32_16x16x32_bf16 v[120:123], v[198:201], v[216:219], v[120:123]
	v_mfma_f32_16x16x32_bf16 v[112:115], v[206:209], v[216:219], v[112:115]
	v_mfma_f32_16x16x32_bf16 v[104:107], v[198:201], v[224:227], v[104:107]
	v_mfma_f32_16x16x32_bf16 v[96:99], v[206:209], v[224:227], v[96:99]
	v_mfma_f32_16x16x32_bf16 v[88:91], v[198:201], v[232:235], v[88:91]
	v_mfma_f32_16x16x32_bf16 v[80:83], v[206:209], v[232:235], v[80:83]
	v_mfma_f32_16x16x32_bf16 v[72:75], v[198:201], v[240:243], v[72:75]
	v_mfma_f32_16x16x32_bf16 v[64:67], v[206:209], v[240:243], v[64:67]
	s_barrier
	s_mov_b32 m0, s60
	v_lshl_add_u64 v[246:247], v[244:245], 0, v[138:139]
	ds_read_b128 v[210:213], v179 offset:16384
	ds_read_b128 v[216:219], v179 offset:17408
	ds_read_b128 v[220:223], v179 offset:18432
	ds_read_b128 v[224:227], v179 offset:19456
	ds_read_b128 v[228:231], v179 offset:20480
	ds_read_b128 v[232:235], v179 offset:21504
	ds_read_b128 v[236:239], v179 offset:22528
	ds_read_b128 v[240:243], v179 offset:23552
	global_load_lds_dwordx4 v[246:247], off
	v_lshl_add_u64 v[248:249], v[244:245], 0, v[134:135]
	s_mov_b32 m0, s61
	v_lshl_add_u64 v[244:245], v[244:245], 0, s[14:15]
	global_load_lds_dwordx4 v[248:249], off
	v_lshl_add_u64 v[250:251], v[244:245], 0, v[138:139]
	s_mov_b32 m0, s62
	v_lshl_add_u64 v[244:245], v[244:245], 0, v[134:135]
	global_load_lds_dwordx4 v[250:251], off
	s_add_i32 m0, s62, 0x2000
	v_lshl_add_u64 v[252:253], v[172:173], 0, v[140:141]
	global_load_lds_dwordx4 v[244:245], off
	s_mov_b32 m0, s46
	v_lshl_add_u64 v[214:215], v[172:173], 0, v[136:137]
	global_load_lds_dwordx4 v[252:253], off
	s_mov_b32 m0, s47
	s_nop 0
	global_load_lds_dwordx4 v[214:215], off
	s_waitcnt vmcnt(8) lgkmcnt(0)
	s_barrier
; #define PG8_STAGE(bufoff, gbase, voff) do { _Pragma("unroll") for (int _i = 0; _i < 2; ++_i) \
;         __builtin_amdgcn_global_load_lds((const unsigned*)((const char*)(gbase) + (voff)[_i]), (PG8_LAS unsigned*)(lds + (bufoff) + ldsw + _i * 8192), 16, 0, 0); } while (0)
; #define PG8_LDA(dst, b, h) do { _Pragma("unroll") for (int m = 0; m < 4; ++m) _Pragma("unroll") for (int k = 0; k < 2; ++k) dst[m][k] = *(const PG8_LAS bf16x8*)(lds + PG8_SA(b, h) + aoff + m * 2048 + k * 1024); } while (0)
; #define PG8_LDB(dst, b, h) do { _Pragma("unroll") for (int n = 0; n < 2; ++n) _Pragma("unroll") for (int k = 0; k < 2; ++k) dst[n][k] = *(const PG8_LAS bf16x8*)(lds + PG8_SB(b, h) + boff + n * 2048 + k * 1024); } while (0)
; #define PG8_MMA(ai, bj, At, Bt) do { __builtin_amdgcn_s_setprio(1); _Pragma("unroll") for (int m = 0; m < 4; ++m) _Pragma("unroll") for (int n = 0; n < 2; ++n) _Pragma("unroll") for (int k = 0; k < 2; ++k) \
;         acc[ai][bj][m][n] = __builtin_amdgcn_mfma_f32_16x16x32_bf16(Bt[n][k], At[m][k], acc[ai][bj][m][n], 0, 0, 0); __builtin_amdgcn_s_setprio(0); } while (0)
; #define PG8_WAIT_V(n) asm volatile("s_waitcnt vmcnt(" #n ")" ::: "memory")
; #define PG8_WAIT_L(n) asm volatile("s_waitcnt lgkmcnt(" #n ")" ::: "memory")
; #define PG8_BAR __builtin_amdgcn_s_barrier()
; #define PG8_SCHED __builtin_amdgcn_sched_barrier(0)
; template <class Epi, class Sched, bool ALIGN_EPI = false, bool SP2 = false>
; __device__ __forceinline__ void gemm_phase(PG8_LAS unsigned char* lds, const Gemm g, const Sched& S, const Epi& E) {
;     ...
;             PG8_WAIT_V(8); PG8_WAIT_L(0); PG8_BAR; PG8_MMA(1, 0, At, B0); PG8_MMA(1, 1, At, B1); PG8_BAR; PG8_SCHED;
;             PG8_LDB(B0, 1, 0); PG8_LDB(B1, 1, 1); PG8_SCHED; PG8_LDA(At, 1, 0); PG8_STAGE(PG8_SA(0, 1), a2 + hstep, voffA);
;             PG8_WAIT_V(8); PG8_WAIT_L(0); PG8_BAR; PG8_MMA(0, 0, At, B0); PG8_MMA(0, 1, At, B1); PG8_BAR; PG8_SCHED;
	v_mfma_f32_16x16x32_bf16 v[60:63], v[162:165], v[210:213], v[60:63]
	v_mfma_f32_16x16x32_bf16 v[52:55], v[186:189], v[210:213], v[52:55]
	v_mfma_f32_16x16x32_bf16 v[44:47], v[162:165], v[220:223], v[44:47]
	v_mfma_f32_16x16x32_bf16 v[36:39], v[186:189], v[220:223], v[36:39]
	v_mfma_f32_16x16x32_bf16 v[28:31], v[162:165], v[228:231], v[28:31]
	v_mfma_f32_16x16x32_bf16 v[20:23], v[186:189], v[228:231], v[20:23]
	v_mfma_f32_16x16x32_bf16 v[12:15], v[162:165], v[236:239], v[12:15]
	v_mfma_f32_16x16x32_bf16 v[4:7], v[186:189], v[236:239], v[4:7]
	v_mfma_f32_16x16x32_bf16 v[60:63], v[182:185], v[216:219], v[60:63]
	v_mfma_f32_16x16x32_bf16 v[52:55], v[190:193], v[216:219], v[52:55]
	v_mfma_f32_16x16x32_bf16 v[44:47], v[182:185], v[224:227], v[44:47]
	v_mfma_f32_16x16x32_bf16 v[36:39], v[190:193], v[224:227], v[36:39]
	v_mfma_f32_16x16x32_bf16 v[28:31], v[182:185], v[232:235], v[28:31]
	v_mfma_f32_16x16x32_bf16 v[20:23], v[190:193], v[232:235], v[20:23]
	v_mfma_f32_16x16x32_bf16 v[12:15], v[182:185], v[240:243], v[12:15]
	v_mfma_f32_16x16x32_bf16 v[4:7], v[190:193], v[240:243], v[4:7]
	v_mfma_f32_16x16x32_bf16 v[56:59], v[194:197], v[210:213], v[56:59]
	v_mfma_f32_16x16x32_bf16 v[48:51], v[202:205], v[210:213], v[48:51]
	v_mfma_f32_16x16x32_bf16 v[40:43], v[194:197], v[220:223], v[40:43]
	v_mfma_f32_16x16x32_bf16 v[32:35], v[202:205], v[220:223], v[32:35]
	v_mfma_f32_16x16x32_bf16 v[24:27], v[194:197], v[228:231], v[24:27]
	v_mfma_f32_16x16x32_bf16 v[16:19], v[202:205], v[228:231], v[16:19]
	v_mfma_f32_16x16x32_bf16 v[8:11], v[194:197], v[236:239], v[8:11]
	v_mfma_f32_16x16x32_bf16 v[0:3], v[202:205], v[236:239], v[0:3]
	v_mfma_f32_16x16x32_bf16 v[56:59], v[198:201], v[216:219], v[56:59]
	v_mfma_f32_16x16x32_bf16 v[48:51], v[206:209], v[216:219], v[48:51]
	v_mfma_f32_16x16x32_bf16 v[40:43], v[198:201], v[224:227], v[40:43]
	v_mfma_f32_16x16x32_bf16 v[32:35], v[206:209], v[224:227], v[32:35]
	v_mfma_f32_16x16x32_bf16 v[24:27], v[198:201], v[232:235], v[24:27]
	v_mfma_f32_16x16x32_bf16 v[16:19], v[206:209], v[232:235], v[16:19]
	v_mfma_f32_16x16x32_bf16 v[8:11], v[198:201], v[240:243], v[8:11]
	v_mfma_f32_16x16x32_bf16 v[0:3], v[206:209], v[240:243], v[0:3]
	s_barrier
	s_add_i32 s11, 0, 0x18000
	s_add_i32 s13, 0, 0x1c000
	ds_read_b128 v[162:165], v166 offset:32768
	ds_read_b128 v[182:185], v166 offset:33792
	ds_read_b128 v[186:189], v166 offset:34816
	ds_read_b128 v[190:193], v166 offset:35840
	ds_read_b128 v[194:197], v166 offset:49152
	ds_read_b128 v[198:201], v166 offset:50176
	ds_read_b128 v[202:205], v166 offset:51200
	ds_read_b128 v[206:209], v166 offset:52224
	v_lshl_add_u64 v[172:173], v[172:173], 0, s[14:15]
	s_mov_b32 m0, s48
	v_lshl_add_u64 v[170:171], v[172:173], 0, v[140:141]
	ds_read_b128 v[210:213], v179 offset:32768
	ds_read_b128 v[216:219], v179 offset:33792
	ds_read_b128 v[220:223], v179 offset:34816
	ds_read_b128 v[224:227], v179 offset:35840
	ds_read_b128 v[228:231], v179 offset:36864
	ds_read_b128 v[232:235], v179 offset:37888
	ds_read_b128 v[236:239], v179 offset:38912
	ds_read_b128 v[240:243], v179 offset:39936
	global_load_lds_dwordx4 v[170:171], off
	s_mov_b32 m0, s49
	v_lshl_add_u64 v[170:171], v[172:173], 0, v[136:137]
	global_load_lds_dwordx4 v[170:171], off
	s_waitcnt vmcnt(8) lgkmcnt(0)
	s_barrier
	v_mfma_f32_16x16x32_bf16 v[124:127], v[162:165], v[210:213], v[124:127]
	v_mfma_f32_16x16x32_bf16 v[116:119], v[186:189], v[210:213], v[116:119]
	v_mfma_f32_16x16x32_bf16 v[108:111], v[162:165], v[220:223], v[108:111]
	v_mfma_f32_16x16x32_bf16 v[100:103], v[186:189], v[220:223], v[100:103]
	v_mfma_f32_16x16x32_bf16 v[92:95], v[162:165], v[228:231], v[92:95]
	v_mfma_f32_16x16x32_bf16 v[84:87], v[186:189], v[228:231], v[84:87]
	v_mfma_f32_16x16x32_bf16 v[76:79], v[162:165], v[236:239], v[76:79]
	v_mfma_f32_16x16x32_bf16 v[68:71], v[186:189], v[236:239], v[68:71]
	v_mfma_f32_16x16x32_bf16 v[124:127], v[182:185], v[216:219], v[124:127]
	v_mfma_f32_16x16x32_bf16 v[116:119], v[190:193], v[216:219], v[116:119]
	v_mfma_f32_16x16x32_bf16 v[108:111], v[182:185], v[224:227], v[108:111]
	v_mfma_f32_16x16x32_bf16 v[100:103], v[190:193], v[224:227], v[100:103]
	v_mfma_f32_16x16x32_bf16 v[92:95], v[182:185], v[232:235], v[92:95]
	v_mfma_f32_16x16x32_bf16 v[84:87], v[190:193], v[232:235], v[84:87]
	v_mfma_f32_16x16x32_bf16 v[76:79], v[182:185], v[240:243], v[76:79]
	v_mfma_f32_16x16x32_bf16 v[68:71], v[190:193], v[240:243], v[68:71]
	v_mfma_f32_16x16x32_bf16 v[120:123], v[194:197], v[210:213], v[120:123]
	v_mfma_f32_16x16x32_bf16 v[112:115], v[202:205], v[210:213], v[112:115]
	v_mfma_f32_16x16x32_bf16 v[104:107], v[194:197], v[220:223], v[104:107]
	v_mfma_f32_16x16x32_bf16 v[96:99], v[202:205], v[220:223], v[96:99]
	v_mfma_f32_16x16x32_bf16 v[88:91], v[194:197], v[228:231], v[88:91]
	v_mfma_f32_16x16x32_bf16 v[80:83], v[202:205], v[228:231], v[80:83]
	v_mfma_f32_16x16x32_bf16 v[72:75], v[194:197], v[236:239], v[72:75]
	v_mfma_f32_16x16x32_bf16 v[64:67], v[202:205], v[236:239], v[64:67]
	v_mfma_f32_16x16x32_bf16 v[120:123], v[198:201], v[216:219], v[120:123]
	v_mfma_f32_16x16x32_bf16 v[112:115], v[206:209], v[216:219], v[112:115]
	v_mfma_f32_16x16x32_bf16 v[104:107], v[198:201], v[224:227], v[104:107]
	v_mfma_f32_16x16x32_bf16 v[96:99], v[206:209], v[224:227], v[96:99]
	v_mfma_f32_16x16x32_bf16 v[88:91], v[198:201], v[232:235], v[88:91]
	v_mfma_f32_16x16x32_bf16 v[80:83], v[206:209], v[232:235], v[80:83]
	v_mfma_f32_16x16x32_bf16 v[72:75], v[198:201], v[240:243], v[72:75]
	v_mfma_f32_16x16x32_bf16 v[64:67], v[206:209], v[240:243], v[64:67]
	s_barrier
; #define PG8_STAGE(bufoff, gbase, voff) do { _Pragma("unroll") for (int _i = 0; _i < 2; ++_i) \
;         __builtin_amdgcn_global_load_lds((const unsigned*)((const char*)(gbase) + (voff)[_i]), (PG8_LAS unsigned*)(lds + (bufoff) + ldsw + _i * 8192), 16, 0, 0); } while (0)
; #define PG8_LDA(dst, b, h) do { _Pragma("unroll") for (int m = 0; m < 4; ++m) _Pragma("unroll") for (int k = 0; k < 2; ++k) dst[m][k] = *(const PG8_LAS bf16x8*)(lds + PG8_SA(b, h) + aoff + m * 2048 + k * 1024); } while (0)
; #define PG8_MMA(ai, bj, At, Bt) do { __builtin_amdgcn_s_setprio(1); _Pragma("unroll") for (int m = 0; m < 4; ++m) _Pragma("unroll") for (int n = 0; n < 2; ++n) _Pragma("unroll") for (int k = 0; k < 2; ++k) \
;         acc[ai][bj][m][n] = __builtin_amdgcn_mfma_f32_16x16x32_bf16(Bt[n][k], At[m][k], acc[ai][bj][m][n], 0, 0, 0); __builtin_amdgcn_s_setprio(0); } while (0)
; #define PG8_WAIT_V(n) asm volatile("s_waitcnt vmcnt(" #n ")" ::: "memory")
; #define PG8_WAIT_L(n) asm volatile("s_waitcnt lgkmcnt(" #n ")" ::: "memory")
; #define PG8_BAR __builtin_amdgcn_s_barrier()
; #define PG8_SCHED __builtin_amdgcn_sched_barrier(0)
; template <class Epi, class Sched, bool ALIGN_EPI = false, bool SP2 = false>
; __device__ __forceinline__ void gemm_phase(PG8_LAS unsigned char* lds, const Gemm g, const Sched& S, const Epi& E) {
;     ...
;         for (int t = 0; t < nt; t += 2) {
;     ...
;             PG8_LDA(At, 1, 1); PG8_STAGE(PG8_SB(1, 0), b3, voffB); PG8_STAGE(PG8_SB(1, 1), b3 + hstep, voffB); PG8_STAGE(PG8_SA(1, 0), a3, voffA);
;             PG8_WAIT_V(8); PG8_WAIT_L(0); PG8_BAR; PG8_MMA(1, 0, At, B0); PG8_MMA(1, 1, At, B1); PG8_BAR; PG8_SCHED;
	s_add_i32 s11, s11, s29
	s_add_i32 m0, s11, 0xffffff80
	ds_read_b128 v[210:213], v179 offset:49152
	ds_read_b128 v[216:219], v179 offset:50176
	ds_read_b128 v[220:223], v179 offset:51200
	ds_read_b128 v[224:227], v179 offset:52224
	global_load_lds_dwordx4 v[246:247], off offset:128
	s_add_i32 m0, s11, 0x1f80
	s_add_i32 s11, s13, s29
	global_load_lds_dwordx4 v[248:249], off offset:128
	s_add_i32 m0, s11, 0xffffff80
	ds_read_b128 v[240:243], v179 offset:56320
	global_load_lds_dwordx4 v[250:251], off offset:128
	s_add_i32 m0, s11, 0x1f80
	ds_read_b128 v[236:239], v179 offset:55296
	global_load_lds_dwordx4 v[244:245], off offset:128
	s_add_i32 m0, s50, 0xffffff80
	ds_read_b128 v[232:235], v179 offset:54272
	global_load_lds_dwordx4 v[252:253], off offset:128
	s_add_i32 m0, s51, 0xffffff80
	ds_read_b128 v[228:231], v179 offset:53248
	global_load_lds_dwordx4 v[214:215], off offset:128
	s_waitcnt vmcnt(8) lgkmcnt(0)
	s_barrier
	v_mfma_f32_16x16x32_bf16 v[60:63], v[162:165], v[210:213], v[60:63]
	v_mfma_f32_16x16x32_bf16 v[52:55], v[186:189], v[210:213], v[52:55]
	v_mfma_f32_16x16x32_bf16 v[44:47], v[162:165], v[220:223], v[44:47]
	v_mfma_f32_16x16x32_bf16 v[36:39], v[186:189], v[220:223], v[36:39]
	v_mfma_f32_16x16x32_bf16 v[28:31], v[162:165], v[228:231], v[28:31]
	v_mfma_f32_16x16x32_bf16 v[20:23], v[186:189], v[228:231], v[20:23]
	v_mfma_f32_16x16x32_bf16 v[12:15], v[162:165], v[236:239], v[12:15]
	v_mfma_f32_16x16x32_bf16 v[4:7], v[186:189], v[236:239], v[4:7]
	v_mfma_f32_16x16x32_bf16 v[60:63], v[182:185], v[216:219], v[60:63]
	v_mfma_f32_16x16x32_bf16 v[52:55], v[190:193], v[216:219], v[52:55]
	v_mfma_f32_16x16x32_bf16 v[44:47], v[182:185], v[224:227], v[44:47]
	v_mfma_f32_16x16x32_bf16 v[36:39], v[190:193], v[224:227], v[36:39]
	v_mfma_f32_16x16x32_bf16 v[28:31], v[182:185], v[232:235], v[28:31]
	v_mfma_f32_16x16x32_bf16 v[20:23], v[190:193], v[232:235], v[20:23]
	v_mfma_f32_16x16x32_bf16 v[12:15], v[182:185], v[240:243], v[12:15]
	v_mfma_f32_16x16x32_bf16 v[4:7], v[190:193], v[240:243], v[4:7]
	v_mfma_f32_16x16x32_bf16 v[56:59], v[194:197], v[210:213], v[56:59]
	v_mfma_f32_16x16x32_bf16 v[48:51], v[202:205], v[210:213], v[48:51]
	v_mfma_f32_16x16x32_bf16 v[40:43], v[194:197], v[220:223], v[40:43]
	v_mfma_f32_16x16x32_bf16 v[32:35], v[202:205], v[220:223], v[32:35]
	v_mfma_f32_16x16x32_bf16 v[24:27], v[194:197], v[228:231], v[24:27]
	v_mfma_f32_16x16x32_bf16 v[16:19], v[202:205], v[228:231], v[16:19]
	v_mfma_f32_16x16x32_bf16 v[8:11], v[194:197], v[236:239], v[8:11]
	v_mfma_f32_16x16x32_bf16 v[0:3], v[202:205], v[236:239], v[0:3]
	v_mfma_f32_16x16x32_bf16 v[56:59], v[198:201], v[216:219], v[56:59]
	v_mfma_f32_16x16x32_bf16 v[48:51], v[206:209], v[216:219], v[48:51]
	v_mfma_f32_16x16x32_bf16 v[40:43], v[198:201], v[224:227], v[40:43]
	v_mfma_f32_16x16x32_bf16 v[32:35], v[206:209], v[224:227], v[32:35]
	v_mfma_f32_16x16x32_bf16 v[24:27], v[198:201], v[232:235], v[24:27]
	v_mfma_f32_16x16x32_bf16 v[16:19], v[206:209], v[232:235], v[16:19]
	v_mfma_f32_16x16x32_bf16 v[8:11], v[198:201], v[240:243], v[8:11]
	v_mfma_f32_16x16x32_bf16 v[0:3], v[206:209], v[240:243], v[0:3]
	s_barrier
	v_lshl_add_u64 v[158:159], v[158:159], 0, s[26:27]
	s_cmp_ge_i32 s10, s52
	v_lshl_add_u64 v[160:161], v[160:161], 0, s[26:27]
	s_cbranch_scc0 .LBB0_304

; #define PG8_STAGE(bufoff, gbase, voff) do { _Pragma("unroll") for (int _i = 0; _i < 2; ++_i) \
;         __builtin_amdgcn_global_load_lds((const unsigned*)((const char*)(gbase) + (voff)[_i]), (PG8_LAS unsigned*)(lds + (bufoff) + ldsw + _i * 8192), 16, 0, 0); } while (0)
; #define PG8_LDA(dst, b, h) do { _Pragma("unroll") for (int m = 0; m < 4; ++m) _Pragma("unroll") for (int k = 0; k < 2; ++k) dst[m][k] = *(const PG8_LAS bf16x8*)(lds + PG8_SA(b, h) + aoff + m * 2048 + k * 1024); } while (0)
; #define PG8_LDB(dst, b, h) do { _Pragma("unroll") for (int n = 0; n < 2; ++n) _Pragma("unroll") for (int k = 0; k < 2; ++k) dst[n][k] = *(const PG8_LAS bf16x8*)(lds + PG8_SB(b, h) + boff + n * 2048 + k * 1024); } while (0)
; #define PG8_MMA(ai, bj, At, Bt) do { __builtin_amdgcn_s_setprio(1); _Pragma("unroll") for (int m = 0; m < 4; ++m) _Pragma("unroll") for (int n = 0; n < 2; ++n) _Pragma("unroll") for (int k = 0; k < 2; ++k) \
;         acc[ai][bj][m][n] = __builtin_amdgcn_mfma_f32_16x16x32_bf16(Bt[n][k], At[m][k], acc[ai][bj][m][n], 0, 0, 0); __builtin_amdgcn_s_setprio(0); } while (0)
; #define PG8_WAIT_V(n) asm volatile("s_waitcnt vmcnt(" #n ")" ::: "memory")
; #define PG8_BAR __builtin_amdgcn_s_barrier()
; template <class Epi, class Sched, bool ALIGN_EPI = false, bool SP2 = false>
; __device__ __forceinline__ void gemm_phase(PG8_LAS unsigned char* lds, const Gemm g, const Sched& S, const Epi& E) {
;     ...
;         for (int t = 0; t < nt; t += 2) {
;             const bool last = (t == nt - 2);
;             const char* a1 = cA + (size_t)(t + 1) * kstep;
;             const char* a2 = last ? nA : cA + (size_t)(t + 2) * kstep; const char* b2 = last ? nB : cB + (size_t)(t + 2) * kstep;
;             const char* a3 = a2 + kstep; const char* b3 = b2 + kstep;
;             if (last && has_next) S.a_ready(nxt);
;             if constexpr (SP2) {
;             PG8_LDB(B0, 0, 0); PG8_LDB(B1, 0, 1); PG8_SCHED; PG8_LDA(At, 0, 0); PG8_STAGE(PG8_SA(1, 1), a1 + hstep, voffA);
;             PG8_WAIT_V(8); PG8_WAIT_L(0); PG8_BAR; PG8_MMA(0, 0, At, B0); PG8_MMA(0, 1, At, B1); PG8_BAR; PG8_SCHED;
;             PG8_LDA(At, 0, 1); PG8_STAGE(PG8_SB(0, 0), b2, voffB); PG8_STAGE(PG8_SB(0, 1), b2 + hstep, voffB); PG8_STAGE(PG8_SA(0, 0), a2, voffA);
;             PG8_WAIT_V(8); PG8_WAIT_L(0); PG8_BAR; PG8_MMA(1, 0, At, B0); PG8_MMA(1, 1, At, B1); PG8_BAR; PG8_SCHED;
.LBB0_371:
	v_add_u32_e32 v255, s54, v201
	ds_read_b128 v[136:139], v255
	ds_read_b128 v[140:143], v255 offset:1024
	ds_read_b128 v[144:147], v255 offset:2048
	ds_read_b128 v[148:151], v255 offset:3072
	ds_read_b128 v[152:155], v255 offset:16384
	ds_read_b128 v[182:185], v255 offset:17408
	ds_read_b128 v[186:189], v255 offset:18432
	ds_read_b128 v[190:193], v255 offset:19456
	s_cmp_eq_u32 s48, s12
	v_lshl_add_u64 v[194:195], v[134:135], 0, s[22:23]
	s_cselect_b64 vcc, -1, 0
	s_add_i32 s12, s12, 2
	v_cndmask_b32_e32 v199, v195, v179, vcc
	v_cndmask_b32_e32 v198, v194, v178, vcc
	v_cndmask_b32_e32 v215, v133, v181, vcc
	v_cndmask_b32_e32 v214, v132, v180, vcc
	s_mov_b32 m0, s56
	v_lshl_add_u64 v[236:237], v[134:135], 0, v[174:175]
	ds_read_b128 v[194:197], v203
	ds_read_b128 v[206:209], v203 offset:1024
	ds_read_b128 v[210:213], v203 offset:2048
	ds_read_b128 v[216:219], v203 offset:3072
	ds_read_b128 v[220:223], v203 offset:4096
	ds_read_b128 v[224:227], v203 offset:5120
	ds_read_b128 v[228:231], v203 offset:6144
	ds_read_b128 v[232:235], v203 offset:7168
	global_load_lds_dwordx4 v[236:237], off
	s_mov_b32 m0, s57
	v_lshl_add_u64 v[236:237], v[134:135], 0, v[172:173]
	global_load_lds_dwordx4 v[236:237], off
	s_waitcnt vmcnt(8) lgkmcnt(0)
	s_barrier
	v_mfma_f32_16x16x32_bf16 v[124:127], v[136:139], v[194:197], v[124:127]
	v_mfma_f32_16x16x32_bf16 v[128:131], v[144:147], v[194:197], v[128:131]
	v_mfma_f32_16x16x32_bf16 v[112:115], v[136:139], v[210:213], v[112:115]
	v_mfma_f32_16x16x32_bf16 v[108:111], v[144:147], v[210:213], v[108:111]
	v_mfma_f32_16x16x32_bf16 v[96:99], v[136:139], v[220:223], v[96:99]
	v_mfma_f32_16x16x32_bf16 v[92:95], v[144:147], v[220:223], v[92:95]
	v_mfma_f32_16x16x32_bf16 v[80:83], v[136:139], v[228:231], v[80:83]
	v_mfma_f32_16x16x32_bf16 v[76:79], v[144:147], v[228:231], v[76:79]
	v_mfma_f32_16x16x32_bf16 v[124:127], v[140:143], v[206:209], v[124:127]
	v_mfma_f32_16x16x32_bf16 v[128:131], v[148:151], v[206:209], v[128:131]
	v_mfma_f32_16x16x32_bf16 v[112:115], v[140:143], v[216:219], v[112:115]
	v_mfma_f32_16x16x32_bf16 v[108:111], v[148:151], v[216:219], v[108:111]
	v_mfma_f32_16x16x32_bf16 v[96:99], v[140:143], v[224:227], v[96:99]
	v_mfma_f32_16x16x32_bf16 v[92:95], v[148:151], v[224:227], v[92:95]
	v_mfma_f32_16x16x32_bf16 v[80:83], v[140:143], v[232:235], v[80:83]
	v_mfma_f32_16x16x32_bf16 v[76:79], v[148:151], v[232:235], v[76:79]
	v_mfma_f32_16x16x32_bf16 v[120:123], v[152:155], v[194:197], v[120:123]
	v_mfma_f32_16x16x32_bf16 v[116:119], v[186:189], v[194:197], v[116:119]
	v_mfma_f32_16x16x32_bf16 v[104:107], v[152:155], v[210:213], v[104:107]
	v_mfma_f32_16x16x32_bf16 v[100:103], v[186:189], v[210:213], v[100:103]
	v_mfma_f32_16x16x32_bf16 v[88:91], v[152:155], v[220:223], v[88:91]
	v_mfma_f32_16x16x32_bf16 v[84:87], v[186:189], v[220:223], v[84:87]
	v_mfma_f32_16x16x32_bf16 v[72:75], v[152:155], v[228:231], v[72:75]
	v_mfma_f32_16x16x32_bf16 v[68:71], v[186:189], v[228:231], v[68:71]
	v_mfma_f32_16x16x32_bf16 v[120:123], v[182:185], v[206:209], v[120:123]
	v_mfma_f32_16x16x32_bf16 v[116:119], v[190:193], v[206:209], v[116:119]
	v_mfma_f32_16x16x32_bf16 v[104:107], v[182:185], v[216:219], v[104:107]
	v_mfma_f32_16x16x32_bf16 v[100:103], v[190:193], v[216:219], v[100:103]
	v_mfma_f32_16x16x32_bf16 v[88:91], v[182:185], v[224:227], v[88:91]
	v_mfma_f32_16x16x32_bf16 v[84:87], v[190:193], v[224:227], v[84:87]
	v_mfma_f32_16x16x32_bf16 v[72:75], v[182:185], v[232:235], v[72:75]
	v_mfma_f32_16x16x32_bf16 v[68:71], v[190:193], v[232:235], v[68:71]
	s_barrier
	s_mov_b32 m0, s58
	v_lshl_add_u64 v[236:237], v[214:215], 0, v[166:167]
	ds_read_b128 v[194:197], v203 offset:16384
	ds_read_b128 v[206:209], v203 offset:17408
	ds_read_b128 v[210:213], v203 offset:18432
	ds_read_b128 v[216:219], v203 offset:19456
	ds_read_b128 v[220:223], v203 offset:20480
	ds_read_b128 v[224:227], v203 offset:21504
	ds_read_b128 v[228:231], v203 offset:22528
	ds_read_b128 v[232:235], v203 offset:23552
	global_load_lds_dwordx4 v[236:237], off
	v_lshl_add_u64 v[238:239], v[214:215], 0, v[170:171]
	s_mov_b32 m0, s59
	v_lshl_add_u64 v[214:215], v[214:215], 0, s[14:15]
	s_add_i32 s13, s55, s30
	global_load_lds_dwordx4 v[238:239], off
	v_lshl_add_u64 v[240:241], v[214:215], 0, v[166:167]
	s_mov_b32 m0, s13
	v_lshl_add_u64 v[214:215], v[214:215], 0, v[170:171]
	global_load_lds_dwordx4 v[240:241], off
	s_add_i32 m0, s13, 0x2000
	v_lshl_add_u64 v[242:243], v[198:199], 0, v[164:165]
	global_load_lds_dwordx4 v[214:215], off
	s_mov_b32 m0, s31
	v_lshl_add_u64 v[244:245], v[198:199], 0, v[168:169]
	global_load_lds_dwordx4 v[242:243], off
	s_mov_b32 m0, s34
	s_nop 0
	global_load_lds_dwordx4 v[244:245], off
	s_waitcnt vmcnt(8) lgkmcnt(0)
	s_barrier
; #define PG8_STAGE(bufoff, gbase, voff) do { _Pragma("unroll") for (int _i = 0; _i < 2; ++_i) \
;         __builtin_amdgcn_global_load_lds((const unsigned*)((const char*)(gbase) + (voff)[_i]), (PG8_LAS unsigned*)(lds + (bufoff) + ldsw + _i * 8192), 16, 0, 0); } while (0)
; #define PG8_LDA(dst, b, h) do { _Pragma("unroll") for (int m = 0; m < 4; ++m) _Pragma("unroll") for (int k = 0; k < 2; ++k) dst[m][k] = *(const PG8_LAS bf16x8*)(lds + PG8_SA(b, h) + aoff + m * 2048 + k * 1024); } while (0)
; #define PG8_LDB(dst, b, h) do { _Pragma("unroll") for (int n = 0; n < 2; ++n) _Pragma("unroll") for (int k = 0; k < 2; ++k) dst[n][k] = *(const PG8_LAS bf16x8*)(lds + PG8_SB(b, h) + boff + n * 2048 + k * 1024); } while (0)
; #define PG8_MMA(ai, bj, At, Bt) do { __builtin_amdgcn_s_setprio(1); _Pragma("unroll") for (int m = 0; m < 4; ++m) _Pragma("unroll") for (int n = 0; n < 2; ++n) _Pragma("unroll") for (int k = 0; k < 2; ++k) \
;         acc[ai][bj][m][n] = __builtin_amdgcn_mfma_f32_16x16x32_bf16(Bt[n][k], At[m][k], acc[ai][bj][m][n], 0, 0, 0); __builtin_amdgcn_s_setprio(0); } while (0)
; #define PG8_WAIT_V(n) asm volatile("s_waitcnt vmcnt(" #n ")" ::: "memory")
; #define PG8_WAIT_L(n) asm volatile("s_waitcnt lgkmcnt(" #n ")" ::: "memory")
; #define PG8_BAR __builtin_amdgcn_s_barrier()
; #define PG8_SCHED __builtin_amdgcn_sched_barrier(0)
; template <class Epi, class Sched, bool ALIGN_EPI = false, bool SP2 = false>
; __device__ __forceinline__ void gemm_phase(PG8_LAS unsigned char* lds, const Gemm g, const Sched& S, const Epi& E) {
;     ...
;             PG8_WAIT_V(8); PG8_WAIT_L(0); PG8_BAR; PG8_MMA(1, 0, At, B0); PG8_MMA(1, 1, At, B1); PG8_BAR; PG8_SCHED;
;             PG8_LDB(B0, 1, 0); PG8_LDB(B1, 1, 1); PG8_SCHED; PG8_LDA(At, 1, 0); PG8_STAGE(PG8_SA(0, 1), a2 + hstep, voffA);
;             PG8_WAIT_V(8); PG8_WAIT_L(0); PG8_BAR; PG8_MMA(0, 0, At, B0); PG8_MMA(0, 1, At, B1); PG8_BAR; PG8_SCHED;
	v_mfma_f32_16x16x32_bf16 v[64:67], v[136:139], v[194:197], v[64:67]
	v_mfma_f32_16x16x32_bf16 v[60:63], v[144:147], v[194:197], v[60:63]
	v_mfma_f32_16x16x32_bf16 v[48:51], v[136:139], v[210:213], v[48:51]
	v_mfma_f32_16x16x32_bf16 v[44:47], v[144:147], v[210:213], v[44:47]
	v_mfma_f32_16x16x32_bf16 v[32:35], v[136:139], v[220:223], v[32:35]
	v_mfma_f32_16x16x32_bf16 v[28:31], v[144:147], v[220:223], v[28:31]
	v_mfma_f32_16x16x32_bf16 v[16:19], v[136:139], v[228:231], v[16:19]
	v_mfma_f32_16x16x32_bf16 v[12:15], v[144:147], v[228:231], v[12:15]
	v_mfma_f32_16x16x32_bf16 v[64:67], v[140:143], v[206:209], v[64:67]
	v_mfma_f32_16x16x32_bf16 v[60:63], v[148:151], v[206:209], v[60:63]
	v_mfma_f32_16x16x32_bf16 v[48:51], v[140:143], v[216:219], v[48:51]
	v_mfma_f32_16x16x32_bf16 v[44:47], v[148:151], v[216:219], v[44:47]
	v_mfma_f32_16x16x32_bf16 v[32:35], v[140:143], v[224:227], v[32:35]
	v_mfma_f32_16x16x32_bf16 v[28:31], v[148:151], v[224:227], v[28:31]
	v_mfma_f32_16x16x32_bf16 v[16:19], v[140:143], v[232:235], v[16:19]
	v_mfma_f32_16x16x32_bf16 v[12:15], v[148:151], v[232:235], v[12:15]
	v_mfma_f32_16x16x32_bf16 v[56:59], v[152:155], v[194:197], v[56:59]
	v_mfma_f32_16x16x32_bf16 v[52:55], v[186:189], v[194:197], v[52:55]
	v_mfma_f32_16x16x32_bf16 v[40:43], v[152:155], v[210:213], v[40:43]
	v_mfma_f32_16x16x32_bf16 v[36:39], v[186:189], v[210:213], v[36:39]
	v_mfma_f32_16x16x32_bf16 v[24:27], v[152:155], v[220:223], v[24:27]
	v_mfma_f32_16x16x32_bf16 v[20:23], v[186:189], v[220:223], v[20:23]
	v_mfma_f32_16x16x32_bf16 v[8:11], v[152:155], v[228:231], v[8:11]
	v_mfma_f32_16x16x32_bf16 v[4:7], v[186:189], v[228:231], v[4:7]
	v_mfma_f32_16x16x32_bf16 v[56:59], v[182:185], v[206:209], v[56:59]
	v_mfma_f32_16x16x32_bf16 v[52:55], v[190:193], v[206:209], v[52:55]
	v_mfma_f32_16x16x32_bf16 v[40:43], v[182:185], v[216:219], v[40:43]
	v_mfma_f32_16x16x32_bf16 v[36:39], v[190:193], v[216:219], v[36:39]
	v_mfma_f32_16x16x32_bf16 v[24:27], v[182:185], v[224:227], v[24:27]
	v_mfma_f32_16x16x32_bf16 v[20:23], v[190:193], v[224:227], v[20:23]
	v_mfma_f32_16x16x32_bf16 v[8:11], v[182:185], v[232:235], v[8:11]
	v_mfma_f32_16x16x32_bf16 v[4:7], v[190:193], v[232:235], v[4:7]
	s_barrier
	s_add_i32 s13, 0, 0x18000
	s_add_i32 s29, 0, 0x1c000
	ds_read_b128 v[136:139], v255 offset:32768
	ds_read_b128 v[140:143], v255 offset:33792
	ds_read_b128 v[144:147], v255 offset:34816
	ds_read_b128 v[148:151], v255 offset:35840
	ds_read_b128 v[152:155], v255 offset:49152
	ds_read_b128 v[182:185], v255 offset:50176
	ds_read_b128 v[186:189], v255 offset:51200
	ds_read_b128 v[190:193], v255 offset:52224
	v_lshl_add_u64 v[198:199], v[198:199], 0, s[14:15]
	s_mov_b32 m0, s35
	v_lshl_add_u64 v[246:247], v[198:199], 0, v[164:165]
	ds_read_b128 v[194:197], v203 offset:32768
	ds_read_b128 v[206:209], v203 offset:33792
	ds_read_b128 v[210:213], v203 offset:34816
	ds_read_b128 v[216:219], v203 offset:35840
	ds_read_b128 v[220:223], v203 offset:36864
	ds_read_b128 v[224:227], v203 offset:37888
	ds_read_b128 v[228:231], v203 offset:38912
	ds_read_b128 v[232:235], v203 offset:39936
	global_load_lds_dwordx4 v[246:247], off
	s_mov_b32 m0, s36
	v_lshl_add_u64 v[198:199], v[198:199], 0, v[168:169]
	global_load_lds_dwordx4 v[198:199], off
	s_waitcnt vmcnt(8) lgkmcnt(0)
	s_barrier
	v_mfma_f32_16x16x32_bf16 v[124:127], v[136:139], v[194:197], v[124:127]
	v_mfma_f32_16x16x32_bf16 v[128:131], v[144:147], v[194:197], v[128:131]
	v_mfma_f32_16x16x32_bf16 v[112:115], v[136:139], v[210:213], v[112:115]
	v_mfma_f32_16x16x32_bf16 v[108:111], v[144:147], v[210:213], v[108:111]
	v_mfma_f32_16x16x32_bf16 v[96:99], v[136:139], v[220:223], v[96:99]
	v_mfma_f32_16x16x32_bf16 v[92:95], v[144:147], v[220:223], v[92:95]
	v_mfma_f32_16x16x32_bf16 v[80:83], v[136:139], v[228:231], v[80:83]
	v_mfma_f32_16x16x32_bf16 v[76:79], v[144:147], v[228:231], v[76:79]
	v_mfma_f32_16x16x32_bf16 v[124:127], v[140:143], v[206:209], v[124:127]
	v_mfma_f32_16x16x32_bf16 v[128:131], v[148:151], v[206:209], v[128:131]
	v_mfma_f32_16x16x32_bf16 v[112:115], v[140:143], v[216:219], v[112:115]
	v_mfma_f32_16x16x32_bf16 v[108:111], v[148:151], v[216:219], v[108:111]
	v_mfma_f32_16x16x32_bf16 v[96:99], v[140:143], v[224:227], v[96:99]
	v_mfma_f32_16x16x32_bf16 v[92:95], v[148:151], v[224:227], v[92:95]
	v_mfma_f32_16x16x32_bf16 v[80:83], v[140:143], v[232:235], v[80:83]
	v_mfma_f32_16x16x32_bf16 v[76:79], v[148:151], v[232:235], v[76:79]
	v_mfma_f32_16x16x32_bf16 v[120:123], v[152:155], v[194:197], v[120:123]
	v_mfma_f32_16x16x32_bf16 v[116:119], v[186:189], v[194:197], v[116:119]
	v_mfma_f32_16x16x32_bf16 v[104:107], v[152:155], v[210:213], v[104:107]
	v_mfma_f32_16x16x32_bf16 v[100:103], v[186:189], v[210:213], v[100:103]
	v_mfma_f32_16x16x32_bf16 v[88:91], v[152:155], v[220:223], v[88:91]
	v_mfma_f32_16x16x32_bf16 v[84:87], v[186:189], v[220:223], v[84:87]
	v_mfma_f32_16x16x32_bf16 v[72:75], v[152:155], v[228:231], v[72:75]
	v_mfma_f32_16x16x32_bf16 v[68:71], v[186:189], v[228:231], v[68:71]
	v_mfma_f32_16x16x32_bf16 v[120:123], v[182:185], v[206:209], v[120:123]
	v_mfma_f32_16x16x32_bf16 v[116:119], v[190:193], v[206:209], v[116:119]
	v_mfma_f32_16x16x32_bf16 v[104:107], v[182:185], v[216:219], v[104:107]
	v_mfma_f32_16x16x32_bf16 v[100:103], v[190:193], v[216:219], v[100:103]
	v_mfma_f32_16x16x32_bf16 v[88:91], v[182:185], v[224:227], v[88:91]
	v_mfma_f32_16x16x32_bf16 v[84:87], v[190:193], v[224:227], v[84:87]
	v_mfma_f32_16x16x32_bf16 v[72:75], v[182:185], v[232:235], v[72:75]
	v_mfma_f32_16x16x32_bf16 v[68:71], v[190:193], v[232:235], v[68:71]
	s_barrier
; #define PG8_STAGE(bufoff, gbase, voff) do { _Pragma("unroll") for (int _i = 0; _i < 2; ++_i) \
;         __builtin_amdgcn_global_load_lds((const unsigned*)((const char*)(gbase) + (voff)[_i]), (PG8_LAS unsigned*)(lds + (bufoff) + ldsw + _i * 8192), 16, 0, 0); } while (0)
; #define PG8_LDA(dst, b, h) do { _Pragma("unroll") for (int m = 0; m < 4; ++m) _Pragma("unroll") for (int k = 0; k < 2; ++k) dst[m][k] = *(const PG8_LAS bf16x8*)(lds + PG8_SA(b, h) + aoff + m * 2048 + k * 1024); } while (0)
; #define PG8_MMA(ai, bj, At, Bt) do { __builtin_amdgcn_s_setprio(1); _Pragma("unroll") for (int m = 0; m < 4; ++m) _Pragma("unroll") for (int n = 0; n < 2; ++n) _Pragma("unroll") for (int k = 0; k < 2; ++k) \
;         acc[ai][bj][m][n] = __builtin_amdgcn_mfma_f32_16x16x32_bf16(Bt[n][k], At[m][k], acc[ai][bj][m][n], 0, 0, 0); __builtin_amdgcn_s_setprio(0); } while (0)
; #define PG8_WAIT_V(n) asm volatile("s_waitcnt vmcnt(" #n ")" ::: "memory")
; #define PG8_WAIT_L(n) asm volatile("s_waitcnt lgkmcnt(" #n ")" ::: "memory")
; #define PG8_BAR __builtin_amdgcn_s_barrier()
; #define PG8_SCHED __builtin_amdgcn_sched_barrier(0)
; template <class Epi, class Sched, bool ALIGN_EPI = false, bool SP2 = false>
; __device__ __forceinline__ void gemm_phase(PG8_LAS unsigned char* lds, const Gemm g, const Sched& S, const Epi& E) {
;     ...
;         for (int t = 0; t < nt; t += 2) {
;     ...
;             PG8_LDA(At, 1, 1); PG8_STAGE(PG8_SB(1, 0), b3, voffB); PG8_STAGE(PG8_SB(1, 1), b3 + hstep, voffB); PG8_STAGE(PG8_SA(1, 0), a3, voffA);
;             PG8_WAIT_V(8); PG8_WAIT_L(0); PG8_BAR; PG8_MMA(1, 0, At, B0); PG8_MMA(1, 1, At, B1); PG8_BAR; PG8_SCHED;
	s_add_i32 s13, s13, s30
	s_add_i32 m0, s13, 0xffffff80
	ds_read_b128 v[194:197], v203 offset:49152
	ds_read_b128 v[206:209], v203 offset:50176
	ds_read_b128 v[210:213], v203 offset:51200
	ds_read_b128 v[216:219], v203 offset:52224
	global_load_lds_dwordx4 v[236:237], off offset:128
	s_add_i32 m0, s13, 0x1f80
	s_add_i32 s13, s29, s30
	global_load_lds_dwordx4 v[238:239], off offset:128
	s_add_i32 m0, s13, 0xffffff80
	ds_read_b128 v[232:235], v203 offset:56320
	global_load_lds_dwordx4 v[240:241], off offset:128
	s_add_i32 m0, s13, 0x1f80
	ds_read_b128 v[228:231], v203 offset:55296
	global_load_lds_dwordx4 v[214:215], off offset:128
	s_add_i32 m0, s37, 0xffffff80
	ds_read_b128 v[224:227], v203 offset:54272
	global_load_lds_dwordx4 v[242:243], off offset:128
	s_add_i32 m0, s41, 0xffffff80
	ds_read_b128 v[220:223], v203 offset:53248
	global_load_lds_dwordx4 v[244:245], off offset:128
	s_waitcnt vmcnt(8) lgkmcnt(0)
	s_barrier
	v_mfma_f32_16x16x32_bf16 v[64:67], v[136:139], v[194:197], v[64:67]
	v_mfma_f32_16x16x32_bf16 v[60:63], v[144:147], v[194:197], v[60:63]
	v_mfma_f32_16x16x32_bf16 v[48:51], v[136:139], v[210:213], v[48:51]
	v_mfma_f32_16x16x32_bf16 v[44:47], v[144:147], v[210:213], v[44:47]
	v_mfma_f32_16x16x32_bf16 v[32:35], v[136:139], v[220:223], v[32:35]
	v_mfma_f32_16x16x32_bf16 v[28:31], v[144:147], v[220:223], v[28:31]
	v_mfma_f32_16x16x32_bf16 v[16:19], v[136:139], v[228:231], v[16:19]
	v_mfma_f32_16x16x32_bf16 v[12:15], v[144:147], v[228:231], v[12:15]
	v_mfma_f32_16x16x32_bf16 v[64:67], v[140:143], v[206:209], v[64:67]
	v_mfma_f32_16x16x32_bf16 v[60:63], v[148:151], v[206:209], v[60:63]
	v_mfma_f32_16x16x32_bf16 v[48:51], v[140:143], v[216:219], v[48:51]
	v_mfma_f32_16x16x32_bf16 v[44:47], v[148:151], v[216:219], v[44:47]
	v_mfma_f32_16x16x32_bf16 v[32:35], v[140:143], v[224:227], v[32:35]
	v_mfma_f32_16x16x32_bf16 v[28:31], v[148:151], v[224:227], v[28:31]
	v_mfma_f32_16x16x32_bf16 v[16:19], v[140:143], v[232:235], v[16:19]
	v_mfma_f32_16x16x32_bf16 v[12:15], v[148:151], v[232:235], v[12:15]
	v_mfma_f32_16x16x32_bf16 v[56:59], v[152:155], v[194:197], v[56:59]
	v_mfma_f32_16x16x32_bf16 v[52:55], v[186:189], v[194:197], v[52:55]
	v_mfma_f32_16x16x32_bf16 v[40:43], v[152:155], v[210:213], v[40:43]
	v_mfma_f32_16x16x32_bf16 v[36:39], v[186:189], v[210:213], v[36:39]
	v_mfma_f32_16x16x32_bf16 v[24:27], v[152:155], v[220:223], v[24:27]
	v_mfma_f32_16x16x32_bf16 v[20:23], v[186:189], v[220:223], v[20:23]
	v_mfma_f32_16x16x32_bf16 v[8:11], v[152:155], v[228:231], v[8:11]
	v_mfma_f32_16x16x32_bf16 v[4:7], v[186:189], v[228:231], v[4:7]
	v_mfma_f32_16x16x32_bf16 v[56:59], v[182:185], v[206:209], v[56:59]
	v_mfma_f32_16x16x32_bf16 v[52:55], v[190:193], v[206:209], v[52:55]
	v_mfma_f32_16x16x32_bf16 v[40:43], v[182:185], v[216:219], v[40:43]
	v_mfma_f32_16x16x32_bf16 v[36:39], v[190:193], v[216:219], v[36:39]
	v_mfma_f32_16x16x32_bf16 v[24:27], v[182:185], v[224:227], v[24:27]
	v_mfma_f32_16x16x32_bf16 v[20:23], v[190:193], v[224:227], v[20:23]
	v_mfma_f32_16x16x32_bf16 v[8:11], v[182:185], v[232:235], v[8:11]
	v_mfma_f32_16x16x32_bf16 v[4:7], v[190:193], v[232:235], v[4:7]
	s_barrier
	v_lshl_add_u64 v[132:133], v[132:133], 0, s[26:27]
	s_cmp_ge_i32 s12, s47
	v_lshl_add_u64 v[134:135], v[134:135], 0, s[26:27]
	s_cbranch_scc0 .LBB0_371

; #define PG8_STAGE(bufoff, gbase, voff) do { _Pragma("unroll") for (int _i = 0; _i < 2; ++_i) \
;         __builtin_amdgcn_global_load_lds((const unsigned*)((const char*)(gbase) + (voff)[_i]), (PG8_LAS unsigned*)(lds + (bufoff) + ldsw + _i * 8192), 16, 0, 0); } while (0)
; #define PG8_LDA(dst, b, h) do { _Pragma("unroll") for (int m = 0; m < 4; ++m) _Pragma("unroll") for (int k = 0; k < 2; ++k) dst[m][k] = *(const PG8_LAS bf16x8*)(lds + PG8_SA(b, h) + aoff + m * 2048 + k * 1024); } while (0)
; #define PG8_LDB(dst, b, h) do { _Pragma("unroll") for (int n = 0; n < 2; ++n) _Pragma("unroll") for (int k = 0; k < 2; ++k) dst[n][k] = *(const PG8_LAS bf16x8*)(lds + PG8_SB(b, h) + boff + n * 2048 + k * 1024); } while (0)
; #define PG8_MMA(ai, bj, At, Bt) do { __builtin_amdgcn_s_setprio(1); _Pragma("unroll") for (int m = 0; m < 4; ++m) _Pragma("unroll") for (int n = 0; n < 2; ++n) _Pragma("unroll") for (int k = 0; k < 2; ++k) \
;         acc[ai][bj][m][n] = __builtin_amdgcn_mfma_f32_16x16x32_bf16(Bt[n][k], At[m][k], acc[ai][bj][m][n], 0, 0, 0); __builtin_amdgcn_s_setprio(0); } while (0)
; #define PG8_WAIT_V(n) asm volatile("s_waitcnt vmcnt(" #n ")" ::: "memory")
; #define PG8_BAR __builtin_amdgcn_s_barrier()
; template <class Epi, class Sched, bool ALIGN_EPI = false, bool SP2 = false>
; __device__ __forceinline__ void gemm_phase(PG8_LAS unsigned char* lds, const Gemm g, const Sched& S, const Epi& E) {
;     ...
;         for (int t = 0; t < nt; t += 2) {
;             const bool last = (t == nt - 2);
;             const char* a1 = cA + (size_t)(t + 1) * kstep;
;             const char* a2 = last ? nA : cA + (size_t)(t + 2) * kstep; const char* b2 = last ? nB : cB + (size_t)(t + 2) * kstep;
;             const char* a3 = a2 + kstep; const char* b3 = b2 + kstep;
;             if (last && has_next) S.a_ready(nxt);
;             if constexpr (SP2) {
;             PG8_LDB(B0, 0, 0); PG8_LDB(B1, 0, 1); PG8_SCHED; PG8_LDA(At, 0, 0); PG8_STAGE(PG8_SA(1, 1), a1 + hstep, voffA);
;             PG8_WAIT_V(8); PG8_WAIT_L(0); PG8_BAR; PG8_MMA(0, 0, At, B0); PG8_MMA(0, 1, At, B1); PG8_BAR; PG8_SCHED;
;             PG8_LDA(At, 0, 1); PG8_STAGE(PG8_SB(0, 0), b2, voffB); PG8_STAGE(PG8_SB(0, 1), b2 + hstep, voffB); PG8_STAGE(PG8_SA(0, 0), a2, voffA);
;             PG8_WAIT_V(8); PG8_WAIT_L(0); PG8_BAR; PG8_MMA(1, 0, At, B0); PG8_MMA(1, 1, At, B1); PG8_BAR; PG8_SCHED;
.LBB0_454:
	v_add_u32_e32 v165, s69, v171
	ds_read_b128 v[132:135], v165
	ds_read_b128 v[136:139], v165 offset:1024
	ds_read_b128 v[176:179], v165 offset:2048
	ds_read_b128 v[180:183], v165 offset:3072
	ds_read_b128 v[184:187], v165 offset:16384
	ds_read_b128 v[188:191], v165 offset:17408
	ds_read_b128 v[192:195], v165 offset:18432
	ds_read_b128 v[196:199], v165 offset:19456
	s_cmp_eq_u32 s62, s12
	v_lshl_add_u64 v[200:201], v[130:131], 0, s[24:25]
	s_cselect_b64 vcc, -1, 0
	s_add_i32 s12, s12, 2
	v_cndmask_b32_e32 v209, v201, v173, vcc
	v_cndmask_b32_e32 v208, v200, v172, vcc
	v_cndmask_b32_e32 v213, v129, v175, vcc
	v_cndmask_b32_e32 v212, v128, v174, vcc
	v_lshl_add_u64 v[214:215], v[130:131], 0, v[160:161]
	s_add_i32 m0, s41, 0xc000
	ds_read_b128 v[200:203], v216
	ds_read_b128 v[204:207], v216 offset:1024
	ds_read_b128 v[218:221], v216 offset:2048
	ds_read_b128 v[222:225], v216 offset:3072
	ds_read_b128 v[226:229], v216 offset:4096
	ds_read_b128 v[230:233], v216 offset:5120
	ds_read_b128 v[234:237], v216 offset:6144
	ds_read_b128 v[238:241], v216 offset:7168
	global_load_lds_dwordx4 v[214:215], off
	s_add_i32 m0, s41, 0xe000
	v_lshl_add_u64 v[214:215], v[130:131], 0, v[158:159]
	global_load_lds_dwordx4 v[214:215], off
	s_waitcnt vmcnt(8) lgkmcnt(0)
	s_barrier
	v_mfma_f32_16x16x32_bf16 v[124:127], v[132:135], v[200:203], v[124:127]
	v_mfma_f32_16x16x32_bf16 v[120:123], v[176:179], v[200:203], v[120:123]
	v_mfma_f32_16x16x32_bf16 v[108:111], v[132:135], v[218:221], v[108:111]
	v_mfma_f32_16x16x32_bf16 v[104:107], v[176:179], v[218:221], v[104:107]
	v_mfma_f32_16x16x32_bf16 v[92:95], v[132:135], v[226:229], v[92:95]
	v_mfma_f32_16x16x32_bf16 v[88:91], v[176:179], v[226:229], v[88:91]
	v_mfma_f32_16x16x32_bf16 v[76:79], v[132:135], v[234:237], v[76:79]
	v_mfma_f32_16x16x32_bf16 v[72:75], v[176:179], v[234:237], v[72:75]
	v_mfma_f32_16x16x32_bf16 v[124:127], v[136:139], v[204:207], v[124:127]
	v_mfma_f32_16x16x32_bf16 v[120:123], v[180:183], v[204:207], v[120:123]
	v_mfma_f32_16x16x32_bf16 v[108:111], v[136:139], v[222:225], v[108:111]
	v_mfma_f32_16x16x32_bf16 v[104:107], v[180:183], v[222:225], v[104:107]
	v_mfma_f32_16x16x32_bf16 v[92:95], v[136:139], v[230:233], v[92:95]
	v_mfma_f32_16x16x32_bf16 v[88:91], v[180:183], v[230:233], v[88:91]
	v_mfma_f32_16x16x32_bf16 v[76:79], v[136:139], v[238:241], v[76:79]
	v_mfma_f32_16x16x32_bf16 v[72:75], v[180:183], v[238:241], v[72:75]
	s_cmp_gt_u32 s75, 3
	s_cbranch_scc1 .Lie_skipk0
	v_mfma_f32_16x16x32_bf16 v[116:119], v[184:187], v[200:203], v[116:119]
	v_mfma_f32_16x16x32_bf16 v[112:115], v[192:195], v[200:203], v[112:115]
	v_mfma_f32_16x16x32_bf16 v[100:103], v[184:187], v[218:221], v[100:103]
	v_mfma_f32_16x16x32_bf16 v[96:99], v[192:195], v[218:221], v[96:99]
	v_mfma_f32_16x16x32_bf16 v[84:87], v[184:187], v[226:229], v[84:87]
	v_mfma_f32_16x16x32_bf16 v[80:83], v[192:195], v[226:229], v[80:83]
	v_mfma_f32_16x16x32_bf16 v[68:71], v[184:187], v[234:237], v[68:71]
	v_mfma_f32_16x16x32_bf16 v[64:67], v[192:195], v[234:237], v[64:67]
	v_mfma_f32_16x16x32_bf16 v[116:119], v[188:191], v[204:207], v[116:119]
	v_mfma_f32_16x16x32_bf16 v[112:115], v[196:199], v[204:207], v[112:115]
	v_mfma_f32_16x16x32_bf16 v[100:103], v[188:191], v[222:225], v[100:103]
	v_mfma_f32_16x16x32_bf16 v[96:99], v[196:199], v[222:225], v[96:99]
	v_mfma_f32_16x16x32_bf16 v[84:87], v[188:191], v[230:233], v[84:87]
	v_mfma_f32_16x16x32_bf16 v[80:83], v[196:199], v[230:233], v[80:83]
	v_mfma_f32_16x16x32_bf16 v[68:71], v[188:191], v[238:241], v[68:71]
	v_mfma_f32_16x16x32_bf16 v[64:67], v[196:199], v[238:241], v[64:67]
.Lie_skipk0:
	s_barrier
	s_add_i32 s13, s69, s37
	v_lshl_add_u64 v[214:215], v[212:213], 0, v[146:147]
	s_mov_b32 m0, s13
	ds_read_b128 v[200:203], v216 offset:16384
	ds_read_b128 v[204:207], v216 offset:17408
	ds_read_b128 v[218:221], v216 offset:18432
	ds_read_b128 v[222:225], v216 offset:19456
	ds_read_b128 v[226:229], v216 offset:20480
	ds_read_b128 v[230:233], v216 offset:21504
	ds_read_b128 v[234:237], v216 offset:22528
	ds_read_b128 v[238:241], v216 offset:23552
	global_load_lds_dwordx4 v[214:215], off
	v_lshl_add_u64 v[242:243], v[212:213], 0, v[150:151]
	s_add_i32 m0, s13, 0x2000
	v_lshl_add_u64 v[212:213], v[212:213], 0, s[16:17]
	s_add_i32 s13, s70, s37
	global_load_lds_dwordx4 v[242:243], off
	v_lshl_add_u64 v[244:245], v[212:213], 0, v[146:147]
	s_mov_b32 m0, s13
	v_lshl_add_u64 v[212:213], v[212:213], 0, v[150:151]
	global_load_lds_dwordx4 v[244:245], off
	s_add_i32 m0, s13, 0x2000
	v_lshl_add_u64 v[246:247], v[208:209], 0, v[144:145]
	global_load_lds_dwordx4 v[212:213], off
	s_mov_b32 m0, s41
	v_lshl_add_u64 v[248:249], v[208:209], 0, v[148:149]
	global_load_lds_dwordx4 v[246:247], off
	s_mov_b32 m0, s50
	s_nop 0
	global_load_lds_dwordx4 v[248:249], off
	s_waitcnt vmcnt(8) lgkmcnt(0)
	s_barrier
	v_mfma_f32_16x16x32_bf16 v[60:63], v[132:135], v[200:203], v[60:63]
	v_mfma_f32_16x16x32_bf16 v[56:59], v[176:179], v[200:203], v[56:59]
	v_mfma_f32_16x16x32_bf16 v[44:47], v[132:135], v[218:221], v[44:47]
	v_mfma_f32_16x16x32_bf16 v[40:43], v[176:179], v[218:221], v[40:43]
	v_mfma_f32_16x16x32_bf16 v[28:31], v[132:135], v[226:229], v[28:31]
	v_mfma_f32_16x16x32_bf16 v[24:27], v[176:179], v[226:229], v[24:27]
	v_mfma_f32_16x16x32_bf16 v[12:15], v[132:135], v[234:237], v[12:15]
	v_mfma_f32_16x16x32_bf16 v[8:11], v[176:179], v[234:237], v[8:11]
	v_mfma_f32_16x16x32_bf16 v[60:63], v[136:139], v[204:207], v[60:63]
	v_mfma_f32_16x16x32_bf16 v[56:59], v[180:183], v[204:207], v[56:59]
	v_mfma_f32_16x16x32_bf16 v[44:47], v[136:139], v[222:225], v[44:47]
	v_mfma_f32_16x16x32_bf16 v[40:43], v[180:183], v[222:225], v[40:43]
	v_mfma_f32_16x16x32_bf16 v[28:31], v[136:139], v[230:233], v[28:31]
	v_mfma_f32_16x16x32_bf16 v[24:27], v[180:183], v[230:233], v[24:27]
	v_mfma_f32_16x16x32_bf16 v[12:15], v[136:139], v[238:241], v[12:15]
	v_mfma_f32_16x16x32_bf16 v[8:11], v[180:183], v[238:241], v[8:11]
	s_cmp_gt_u32 s75, 3
	s_cbranch_scc1 .Lie_skipk1
; #define PG8_STAGE(bufoff, gbase, voff) do { _Pragma("unroll") for (int _i = 0; _i < 2; ++_i) \
;         __builtin_amdgcn_global_load_lds((const unsigned*)((const char*)(gbase) + (voff)[_i]), (PG8_LAS unsigned*)(lds + (bufoff) + ldsw + _i * 8192), 16, 0, 0); } while (0)
; #define PG8_LDA(dst, b, h) do { _Pragma("unroll") for (int m = 0; m < 4; ++m) _Pragma("unroll") for (int k = 0; k < 2; ++k) dst[m][k] = *(const PG8_LAS bf16x8*)(lds + PG8_SA(b, h) + aoff + m * 2048 + k * 1024); } while (0)
; #define PG8_LDB(dst, b, h) do { _Pragma("unroll") for (int n = 0; n < 2; ++n) _Pragma("unroll") for (int k = 0; k < 2; ++k) dst[n][k] = *(const PG8_LAS bf16x8*)(lds + PG8_SB(b, h) + boff + n * 2048 + k * 1024); } while (0)
; #define PG8_MMA(ai, bj, At, Bt) do { __builtin_amdgcn_s_setprio(1); _Pragma("unroll") for (int m = 0; m < 4; ++m) _Pragma("unroll") for (int n = 0; n < 2; ++n) _Pragma("unroll") for (int k = 0; k < 2; ++k) \
;         acc[ai][bj][m][n] = __builtin_amdgcn_mfma_f32_16x16x32_bf16(Bt[n][k], At[m][k], acc[ai][bj][m][n], 0, 0, 0); __builtin_amdgcn_s_setprio(0); } while (0)
; #define PG8_WAIT_V(n) asm volatile("s_waitcnt vmcnt(" #n ")" ::: "memory")
; #define PG8_WAIT_L(n) asm volatile("s_waitcnt lgkmcnt(" #n ")" ::: "memory")
; #define PG8_BAR __builtin_amdgcn_s_barrier()
; #define PG8_SCHED __builtin_amdgcn_sched_barrier(0)
; template <class Epi, class Sched, bool ALIGN_EPI = false, bool SP2 = false>
; __device__ __forceinline__ void gemm_phase(PG8_LAS unsigned char* lds, const Gemm g, const Sched& S, const Epi& E) {
;     ...
;             PG8_WAIT_V(8); PG8_WAIT_L(0); PG8_BAR; PG8_MMA(1, 0, At, B0); PG8_MMA(1, 1, At, B1); PG8_BAR; PG8_SCHED;
;             PG8_LDB(B0, 1, 0); PG8_LDB(B1, 1, 1); PG8_SCHED; PG8_LDA(At, 1, 0); PG8_STAGE(PG8_SA(0, 1), a2 + hstep, voffA);
;             PG8_WAIT_V(8); PG8_WAIT_L(0); PG8_BAR; PG8_MMA(0, 0, At, B0); PG8_MMA(0, 1, At, B1); PG8_BAR; PG8_SCHED;
	v_mfma_f32_16x16x32_bf16 v[52:55], v[184:187], v[200:203], v[52:55]
	v_mfma_f32_16x16x32_bf16 v[48:51], v[192:195], v[200:203], v[48:51]
	v_mfma_f32_16x16x32_bf16 v[36:39], v[184:187], v[218:221], v[36:39]
	v_mfma_f32_16x16x32_bf16 v[32:35], v[192:195], v[218:221], v[32:35]
	v_mfma_f32_16x16x32_bf16 v[20:23], v[184:187], v[226:229], v[20:23]
	v_mfma_f32_16x16x32_bf16 v[16:19], v[192:195], v[226:229], v[16:19]
	v_mfma_f32_16x16x32_bf16 v[4:7], v[184:187], v[234:237], v[4:7]
	v_mfma_f32_16x16x32_bf16 v[0:3], v[192:195], v[234:237], v[0:3]
	v_mfma_f32_16x16x32_bf16 v[52:55], v[188:191], v[204:207], v[52:55]
	v_mfma_f32_16x16x32_bf16 v[48:51], v[196:199], v[204:207], v[48:51]
	v_mfma_f32_16x16x32_bf16 v[36:39], v[188:191], v[222:225], v[36:39]
	v_mfma_f32_16x16x32_bf16 v[32:35], v[196:199], v[222:225], v[32:35]
	v_mfma_f32_16x16x32_bf16 v[20:23], v[188:191], v[230:233], v[20:23]
	v_mfma_f32_16x16x32_bf16 v[16:19], v[196:199], v[230:233], v[16:19]
	v_mfma_f32_16x16x32_bf16 v[4:7], v[188:191], v[238:241], v[4:7]
	v_mfma_f32_16x16x32_bf16 v[0:3], v[196:199], v[238:241], v[0:3]
.Lie_skipk1:
	s_barrier
	s_add_i32 s13, 0, 0x18000
	s_add_i32 s15, 0, 0x1c000
	ds_read_b128 v[132:135], v165 offset:32768
	ds_read_b128 v[136:139], v165 offset:33792
	ds_read_b128 v[176:179], v165 offset:34816
	ds_read_b128 v[180:183], v165 offset:35840
	ds_read_b128 v[184:187], v165 offset:49152
	ds_read_b128 v[188:191], v165 offset:50176
	ds_read_b128 v[192:195], v165 offset:51200
	ds_read_b128 v[196:199], v165 offset:52224
	v_lshl_add_u64 v[208:209], v[208:209], 0, s[16:17]
	s_mov_b32 m0, s52
	v_lshl_add_u64 v[250:251], v[208:209], 0, v[144:145]
	ds_read_b128 v[200:203], v216 offset:32768
	ds_read_b128 v[204:207], v216 offset:33792
	ds_read_b128 v[218:221], v216 offset:34816
	ds_read_b128 v[222:225], v216 offset:35840
	ds_read_b128 v[226:229], v216 offset:36864
	ds_read_b128 v[230:233], v216 offset:37888
	ds_read_b128 v[234:237], v216 offset:38912
	ds_read_b128 v[238:241], v216 offset:39936
	global_load_lds_dwordx4 v[250:251], off
	s_mov_b32 m0, s53
	v_lshl_add_u64 v[208:209], v[208:209], 0, v[148:149]
	global_load_lds_dwordx4 v[208:209], off
	s_waitcnt vmcnt(8) lgkmcnt(0)
	s_barrier
	v_mfma_f32_16x16x32_bf16 v[124:127], v[132:135], v[200:203], v[124:127]
	v_mfma_f32_16x16x32_bf16 v[120:123], v[176:179], v[200:203], v[120:123]
	v_mfma_f32_16x16x32_bf16 v[108:111], v[132:135], v[218:221], v[108:111]
	v_mfma_f32_16x16x32_bf16 v[104:107], v[176:179], v[218:221], v[104:107]
	v_mfma_f32_16x16x32_bf16 v[92:95], v[132:135], v[226:229], v[92:95]
	v_mfma_f32_16x16x32_bf16 v[88:91], v[176:179], v[226:229], v[88:91]
	v_mfma_f32_16x16x32_bf16 v[76:79], v[132:135], v[234:237], v[76:79]
	v_mfma_f32_16x16x32_bf16 v[72:75], v[176:179], v[234:237], v[72:75]
	v_mfma_f32_16x16x32_bf16 v[124:127], v[136:139], v[204:207], v[124:127]
	v_mfma_f32_16x16x32_bf16 v[120:123], v[180:183], v[204:207], v[120:123]
	v_mfma_f32_16x16x32_bf16 v[108:111], v[136:139], v[222:225], v[108:111]
	v_mfma_f32_16x16x32_bf16 v[104:107], v[180:183], v[222:225], v[104:107]
	v_mfma_f32_16x16x32_bf16 v[92:95], v[136:139], v[230:233], v[92:95]
	v_mfma_f32_16x16x32_bf16 v[88:91], v[180:183], v[230:233], v[88:91]
	v_mfma_f32_16x16x32_bf16 v[76:79], v[136:139], v[238:241], v[76:79]
	v_mfma_f32_16x16x32_bf16 v[72:75], v[180:183], v[238:241], v[72:75]
	s_cmp_gt_u32 s75, 3
	s_cbranch_scc1 .Lie_skipk2
	v_mfma_f32_16x16x32_bf16 v[116:119], v[184:187], v[200:203], v[116:119]
	v_mfma_f32_16x16x32_bf16 v[112:115], v[192:195], v[200:203], v[112:115]
	v_mfma_f32_16x16x32_bf16 v[100:103], v[184:187], v[218:221], v[100:103]
	v_mfma_f32_16x16x32_bf16 v[96:99], v[192:195], v[218:221], v[96:99]
	v_mfma_f32_16x16x32_bf16 v[84:87], v[184:187], v[226:229], v[84:87]
	v_mfma_f32_16x16x32_bf16 v[80:83], v[192:195], v[226:229], v[80:83]
	v_mfma_f32_16x16x32_bf16 v[68:71], v[184:187], v[234:237], v[68:71]
	v_mfma_f32_16x16x32_bf16 v[64:67], v[192:195], v[234:237], v[64:67]
	v_mfma_f32_16x16x32_bf16 v[116:119], v[188:191], v[204:207], v[116:119]
	v_mfma_f32_16x16x32_bf16 v[112:115], v[196:199], v[204:207], v[112:115]
	v_mfma_f32_16x16x32_bf16 v[100:103], v[188:191], v[222:225], v[100:103]
	v_mfma_f32_16x16x32_bf16 v[96:99], v[196:199], v[222:225], v[96:99]
	v_mfma_f32_16x16x32_bf16 v[84:87], v[188:191], v[230:233], v[84:87]
	v_mfma_f32_16x16x32_bf16 v[80:83], v[196:199], v[230:233], v[80:83]
	v_mfma_f32_16x16x32_bf16 v[68:71], v[188:191], v[238:241], v[68:71]
	v_mfma_f32_16x16x32_bf16 v[64:67], v[196:199], v[238:241], v[64:67]
; #define PG8_STAGE(bufoff, gbase, voff) do { _Pragma("unroll") for (int _i = 0; _i < 2; ++_i) \
;         __builtin_amdgcn_global_load_lds((const unsigned*)((const char*)(gbase) + (voff)[_i]), (PG8_LAS unsigned*)(lds + (bufoff) + ldsw + _i * 8192), 16, 0, 0); } while (0)
; #define PG8_LDA(dst, b, h) do { _Pragma("unroll") for (int m = 0; m < 4; ++m) _Pragma("unroll") for (int k = 0; k < 2; ++k) dst[m][k] = *(const PG8_LAS bf16x8*)(lds + PG8_SA(b, h) + aoff + m * 2048 + k * 1024); } while (0)
; #define PG8_MMA(ai, bj, At, Bt) do { __builtin_amdgcn_s_setprio(1); _Pragma("unroll") for (int m = 0; m < 4; ++m) _Pragma("unroll") for (int n = 0; n < 2; ++n) _Pragma("unroll") for (int k = 0; k < 2; ++k) \
;         acc[ai][bj][m][n] = __builtin_amdgcn_mfma_f32_16x16x32_bf16(Bt[n][k], At[m][k], acc[ai][bj][m][n], 0, 0, 0); __builtin_amdgcn_s_setprio(0); } while (0)
; #define PG8_WAIT_V(n) asm volatile("s_waitcnt vmcnt(" #n ")" ::: "memory")
; #define PG8_WAIT_L(n) asm volatile("s_waitcnt lgkmcnt(" #n ")" ::: "memory")
; #define PG8_BAR __builtin_amdgcn_s_barrier()
; #define PG8_SCHED __builtin_amdgcn_sched_barrier(0)
; template <class Epi, class Sched, bool ALIGN_EPI = false, bool SP2 = false>
; __device__ __forceinline__ void gemm_phase(PG8_LAS unsigned char* lds, const Gemm g, const Sched& S, const Epi& E) {
;     ...
;         for (int t = 0; t < nt; t += 2) {
;     ...
;             PG8_LDA(At, 1, 1); PG8_STAGE(PG8_SB(1, 0), b3, voffB); PG8_STAGE(PG8_SB(1, 1), b3 + hstep, voffB); PG8_STAGE(PG8_SA(1, 0), a3, voffA);
;             PG8_WAIT_V(8); PG8_WAIT_L(0); PG8_BAR; PG8_MMA(1, 0, At, B0); PG8_MMA(1, 1, At, B1); PG8_BAR; PG8_SCHED;
.Lie_skipk2:
	s_barrier
	s_add_i32 s13, s13, s37
	s_add_i32 m0, s13, 0xffffff80
	ds_read_b128 v[200:203], v216 offset:49152
	ds_read_b128 v[204:207], v216 offset:50176
	ds_read_b128 v[218:221], v216 offset:51200
	ds_read_b128 v[222:225], v216 offset:52224
	global_load_lds_dwordx4 v[214:215], off offset:128
	s_add_i32 m0, s13, 0x1f80
	s_add_i32 s13, s15, s37
	global_load_lds_dwordx4 v[242:243], off offset:128
	s_add_i32 m0, s13, 0xffffff80
	ds_read_b128 v[238:241], v216 offset:56320
	global_load_lds_dwordx4 v[244:245], off offset:128
	s_add_i32 m0, s13, 0x1f80
	ds_read_b128 v[234:237], v216 offset:55296
	global_load_lds_dwordx4 v[212:213], off offset:128
	s_add_i32 m0, s56, 0xffffff80
	ds_read_b128 v[230:233], v216 offset:54272
	global_load_lds_dwordx4 v[246:247], off offset:128
	s_add_i32 m0, s57, 0xffffff80
	ds_read_b128 v[226:229], v216 offset:53248
	global_load_lds_dwordx4 v[248:249], off offset:128
	s_waitcnt vmcnt(8) lgkmcnt(0)
	s_barrier
	v_mfma_f32_16x16x32_bf16 v[60:63], v[132:135], v[200:203], v[60:63]
	v_mfma_f32_16x16x32_bf16 v[56:59], v[176:179], v[200:203], v[56:59]
	v_mfma_f32_16x16x32_bf16 v[44:47], v[132:135], v[218:221], v[44:47]
	v_mfma_f32_16x16x32_bf16 v[40:43], v[176:179], v[218:221], v[40:43]
	v_mfma_f32_16x16x32_bf16 v[28:31], v[132:135], v[226:229], v[28:31]
	v_mfma_f32_16x16x32_bf16 v[24:27], v[176:179], v[226:229], v[24:27]
	v_mfma_f32_16x16x32_bf16 v[12:15], v[132:135], v[234:237], v[12:15]
	v_mfma_f32_16x16x32_bf16 v[8:11], v[176:179], v[234:237], v[8:11]
	v_mfma_f32_16x16x32_bf16 v[60:63], v[136:139], v[204:207], v[60:63]
	v_mfma_f32_16x16x32_bf16 v[56:59], v[180:183], v[204:207], v[56:59]
	v_mfma_f32_16x16x32_bf16 v[44:47], v[136:139], v[222:225], v[44:47]
	v_mfma_f32_16x16x32_bf16 v[40:43], v[180:183], v[222:225], v[40:43]
	v_mfma_f32_16x16x32_bf16 v[28:31], v[136:139], v[230:233], v[28:31]
	v_mfma_f32_16x16x32_bf16 v[24:27], v[180:183], v[230:233], v[24:27]
	v_mfma_f32_16x16x32_bf16 v[12:15], v[136:139], v[238:241], v[12:15]
	v_mfma_f32_16x16x32_bf16 v[8:11], v[180:183], v[238:241], v[8:11]
	s_cmp_gt_u32 s75, 3
	s_cbranch_scc1 .Lie_skipk3
	v_mfma_f32_16x16x32_bf16 v[52:55], v[184:187], v[200:203], v[52:55]
	v_mfma_f32_16x16x32_bf16 v[48:51], v[192:195], v[200:203], v[48:51]
	v_mfma_f32_16x16x32_bf16 v[36:39], v[184:187], v[218:221], v[36:39]
	v_mfma_f32_16x16x32_bf16 v[32:35], v[192:195], v[218:221], v[32:35]
	v_mfma_f32_16x16x32_bf16 v[20:23], v[184:187], v[226:229], v[20:23]
	v_mfma_f32_16x16x32_bf16 v[16:19], v[192:195], v[226:229], v[16:19]
	v_mfma_f32_16x16x32_bf16 v[4:7], v[184:187], v[234:237], v[4:7]
	v_mfma_f32_16x16x32_bf16 v[0:3], v[192:195], v[234:237], v[0:3]
	v_mfma_f32_16x16x32_bf16 v[52:55], v[188:191], v[204:207], v[52:55]
	v_mfma_f32_16x16x32_bf16 v[48:51], v[196:199], v[204:207], v[48:51]
	v_mfma_f32_16x16x32_bf16 v[36:39], v[188:191], v[222:225], v[36:39]
	v_mfma_f32_16x16x32_bf16 v[32:35], v[196:199], v[222:225], v[32:35]
	v_mfma_f32_16x16x32_bf16 v[20:23], v[188:191], v[230:233], v[20:23]
	v_mfma_f32_16x16x32_bf16 v[16:19], v[196:199], v[230:233], v[16:19]
	v_mfma_f32_16x16x32_bf16 v[4:7], v[188:191], v[238:241], v[4:7]
	v_mfma_f32_16x16x32_bf16 v[0:3], v[196:199], v[238:241], v[0:3]
.Lie_skipk3:
	s_barrier
	v_lshl_add_u64 v[128:129], v[128:129], 0, s[34:35]
	s_cmp_ge_i32 s12, s58
	v_lshl_add_u64 v[130:131], v[130:131], 0, s[34:35]
	s_cbranch_scc0 .LBB0_454

; #define PG8_STAGE(bufoff, gbase, voff) do { _Pragma("unroll") for (int _i = 0; _i < 2; ++_i) \
;         __builtin_amdgcn_global_load_lds((const unsigned*)((const char*)(gbase) + (voff)[_i]), (PG8_LAS unsigned*)(lds + (bufoff) + ldsw + _i * 8192), 16, 0, 0); } while (0)
; #define PG8_LDA(dst, b, h) do { _Pragma("unroll") for (int m = 0; m < 4; ++m) _Pragma("unroll") for (int k = 0; k < 2; ++k) dst[m][k] = *(const PG8_LAS bf16x8*)(lds + PG8_SA(b, h) + aoff + m * 2048 + k * 1024); } while (0)
; #define PG8_LDB(dst, b, h) do { _Pragma("unroll") for (int n = 0; n < 2; ++n) _Pragma("unroll") for (int k = 0; k < 2; ++k) dst[n][k] = *(const PG8_LAS bf16x8*)(lds + PG8_SB(b, h) + boff + n * 2048 + k * 1024); } while (0)
; #define PG8_MMA(ai, bj, At, Bt) do { __builtin_amdgcn_s_setprio(1); _Pragma("unroll") for (int m = 0; m < 4; ++m) _Pragma("unroll") for (int n = 0; n < 2; ++n) _Pragma("unroll") for (int k = 0; k < 2; ++k) \
;         acc[ai][bj][m][n] = __builtin_amdgcn_mfma_f32_16x16x32_bf16(Bt[n][k], At[m][k], acc[ai][bj][m][n], 0, 0, 0); __builtin_amdgcn_s_setprio(0); } while (0)
; #define PG8_WAIT_V(n) asm volatile("s_waitcnt vmcnt(" #n ")" ::: "memory")
; #define PG8_BAR __builtin_amdgcn_s_barrier()
; template <class Epi, class Sched, bool ALIGN_EPI = false, bool SP2 = false>
; __device__ __forceinline__ void gemm_phase(PG8_LAS unsigned char* lds, const Gemm g, const Sched& S, const Epi& E) {
;     ...
;         for (int t = 0; t < nt; t += 2) {
;             const bool last = (t == nt - 2);
;             const char* a1 = cA + (size_t)(t + 1) * kstep;
;             const char* a2 = last ? nA : cA + (size_t)(t + 2) * kstep; const char* b2 = last ? nB : cB + (size_t)(t + 2) * kstep;
;             const char* a3 = a2 + kstep; const char* b3 = b2 + kstep;
;             if (last && has_next) S.a_ready(nxt);
;             if constexpr (SP2) {
;             PG8_LDB(B0, 0, 0); PG8_LDB(B1, 0, 1); PG8_SCHED; PG8_LDA(At, 0, 0); PG8_STAGE(PG8_SA(1, 1), a1 + hstep, voffA);
;             PG8_WAIT_V(8); PG8_WAIT_L(0); PG8_BAR; PG8_MMA(0, 0, At, B0); PG8_MMA(0, 1, At, B1); PG8_BAR; PG8_SCHED;
;             PG8_LDA(At, 0, 1); PG8_STAGE(PG8_SB(0, 0), b2, voffB); PG8_STAGE(PG8_SB(0, 1), b2 + hstep, voffB); PG8_STAGE(PG8_SA(0, 0), a2, voffA);
;             PG8_WAIT_V(8); PG8_WAIT_L(0); PG8_BAR; PG8_MMA(1, 0, At, B0); PG8_MMA(1, 1, At, B1); PG8_BAR; PG8_SCHED;
.LBB0_635:
	v_add_u32_e32 v255, s64, v209
	ds_read_b128 v[92:95], v255
	ds_read_b128 v[128:131], v255 offset:1024
	ds_read_b128 v[132:135], v255 offset:2048
	ds_read_b128 v[144:147], v255 offset:3072
	ds_read_b128 v[148:151], v255 offset:16384
	ds_read_b128 v[152:155], v255 offset:17408
	ds_read_b128 v[190:193], v255 offset:18432
	ds_read_b128 v[194:197], v255 offset:19456
	s_cmp_eq_u32 s58, s10
	v_lshl_add_u64 v[198:199], v[90:91], 0, s[24:25]
	s_cselect_b64 vcc, -1, 0
	s_add_i32 s10, s10, 2
	v_cndmask_b32_e32 v207, v199, v187, vcc
	v_cndmask_b32_e32 v206, v198, v186, vcc
	v_cndmask_b32_e32 v215, v89, v189, vcc
	v_cndmask_b32_e32 v214, v88, v188, vcc
	v_lshl_add_u64 v[238:239], v[90:91], 0, v[180:181]
	s_add_i32 m0, s41, 0xc000
	ds_read_b128 v[198:201], v216
	ds_read_b128 v[202:205], v216 offset:1024
	ds_read_b128 v[210:213], v216 offset:2048
	ds_read_b128 v[218:221], v216 offset:3072
	ds_read_b128 v[222:225], v216 offset:4096
	ds_read_b128 v[226:229], v216 offset:5120
	ds_read_b128 v[230:233], v216 offset:6144
	ds_read_b128 v[234:237], v216 offset:7168
	global_load_lds_dwordx4 v[238:239], off
	s_add_i32 m0, s41, 0xe000
	v_lshl_add_u64 v[238:239], v[90:91], 0, v[178:179]
	global_load_lds_dwordx4 v[238:239], off
	s_waitcnt vmcnt(8) lgkmcnt(0)
	s_barrier
	v_mfma_f32_16x16x32_bf16 v[140:143], v[92:95], v[198:201], v[140:143]
	v_mfma_f32_16x16x32_bf16 v[136:139], v[132:135], v[198:201], v[136:139]
	v_mfma_f32_16x16x32_bf16 v[116:119], v[92:95], v[210:213], v[116:119]
	v_mfma_f32_16x16x32_bf16 v[112:115], v[132:135], v[210:213], v[112:115]
	v_mfma_f32_16x16x32_bf16 v[100:103], v[92:95], v[222:225], v[100:103]
	v_mfma_f32_16x16x32_bf16 v[96:99], v[132:135], v[222:225], v[96:99]
	v_mfma_f32_16x16x32_bf16 v[76:79], v[92:95], v[230:233], v[76:79]
	v_mfma_f32_16x16x32_bf16 v[72:75], v[132:135], v[230:233], v[72:75]
	v_mfma_f32_16x16x32_bf16 v[140:143], v[128:131], v[202:205], v[140:143]
	v_mfma_f32_16x16x32_bf16 v[136:139], v[144:147], v[202:205], v[136:139]
	v_mfma_f32_16x16x32_bf16 v[116:119], v[128:131], v[218:221], v[116:119]
	v_mfma_f32_16x16x32_bf16 v[112:115], v[144:147], v[218:221], v[112:115]
	v_mfma_f32_16x16x32_bf16 v[100:103], v[128:131], v[226:229], v[100:103]
	v_mfma_f32_16x16x32_bf16 v[96:99], v[144:147], v[226:229], v[96:99]
	v_mfma_f32_16x16x32_bf16 v[76:79], v[128:131], v[234:237], v[76:79]
	v_mfma_f32_16x16x32_bf16 v[72:75], v[144:147], v[234:237], v[72:75]
	v_mfma_f32_16x16x32_bf16 v[124:127], v[148:151], v[198:201], v[124:127]
	v_mfma_f32_16x16x32_bf16 v[120:123], v[190:193], v[198:201], v[120:123]
	v_mfma_f32_16x16x32_bf16 v[108:111], v[148:151], v[210:213], v[108:111]
	v_mfma_f32_16x16x32_bf16 v[104:107], v[190:193], v[210:213], v[104:107]
	v_mfma_f32_16x16x32_bf16 v[84:87], v[148:151], v[222:225], v[84:87]
	v_mfma_f32_16x16x32_bf16 v[80:83], v[190:193], v[222:225], v[80:83]
	v_mfma_f32_16x16x32_bf16 v[68:71], v[148:151], v[230:233], v[68:71]
	v_mfma_f32_16x16x32_bf16 v[64:67], v[190:193], v[230:233], v[64:67]
	v_mfma_f32_16x16x32_bf16 v[124:127], v[152:155], v[202:205], v[124:127]
	v_mfma_f32_16x16x32_bf16 v[120:123], v[194:197], v[202:205], v[120:123]
	v_mfma_f32_16x16x32_bf16 v[108:111], v[152:155], v[218:221], v[108:111]
	v_mfma_f32_16x16x32_bf16 v[104:107], v[194:197], v[218:221], v[104:107]
	v_mfma_f32_16x16x32_bf16 v[84:87], v[152:155], v[226:229], v[84:87]
	v_mfma_f32_16x16x32_bf16 v[80:83], v[194:197], v[226:229], v[80:83]
	v_mfma_f32_16x16x32_bf16 v[68:71], v[152:155], v[234:237], v[68:71]
	v_mfma_f32_16x16x32_bf16 v[64:67], v[194:197], v[234:237], v[64:67]
	s_barrier
	s_add_i32 s11, s64, s35
	v_lshl_add_u64 v[238:239], v[214:215], 0, v[168:169]
	s_mov_b32 m0, s11
	ds_read_b128 v[198:201], v216 offset:16384
	ds_read_b128 v[202:205], v216 offset:17408
	ds_read_b128 v[210:213], v216 offset:18432
	ds_read_b128 v[218:221], v216 offset:19456
	ds_read_b128 v[222:225], v216 offset:20480
	ds_read_b128 v[226:229], v216 offset:21504
	ds_read_b128 v[230:233], v216 offset:22528
	ds_read_b128 v[234:237], v216 offset:23552
	global_load_lds_dwordx4 v[238:239], off
	v_lshl_add_u64 v[240:241], v[214:215], 0, v[172:173]
	s_add_i32 m0, s11, 0x2000
	v_lshl_add_u64 v[214:215], v[214:215], 0, s[18:19]
	s_add_i32 s11, s65, s35
	global_load_lds_dwordx4 v[240:241], off
	v_lshl_add_u64 v[242:243], v[214:215], 0, v[168:169]
	s_mov_b32 m0, s11
	v_lshl_add_u64 v[214:215], v[214:215], 0, v[172:173]
	global_load_lds_dwordx4 v[242:243], off
	s_add_i32 m0, s11, 0x2000
	v_lshl_add_u64 v[244:245], v[206:207], 0, v[166:167]
	global_load_lds_dwordx4 v[214:215], off
	s_mov_b32 m0, s41
	v_lshl_add_u64 v[246:247], v[206:207], 0, v[170:171]
	global_load_lds_dwordx4 v[244:245], off
	s_mov_b32 m0, s50
	s_nop 0
	global_load_lds_dwordx4 v[246:247], off
	s_waitcnt vmcnt(8) lgkmcnt(0)
	s_barrier
; #define PG8_STAGE(bufoff, gbase, voff) do { _Pragma("unroll") for (int _i = 0; _i < 2; ++_i) \
;         __builtin_amdgcn_global_load_lds((const unsigned*)((const char*)(gbase) + (voff)[_i]), (PG8_LAS unsigned*)(lds + (bufoff) + ldsw + _i * 8192), 16, 0, 0); } while (0)
; #define PG8_LDA(dst, b, h) do { _Pragma("unroll") for (int m = 0; m < 4; ++m) _Pragma("unroll") for (int k = 0; k < 2; ++k) dst[m][k] = *(const PG8_LAS bf16x8*)(lds + PG8_SA(b, h) + aoff + m * 2048 + k * 1024); } while (0)
; #define PG8_LDB(dst, b, h) do { _Pragma("unroll") for (int n = 0; n < 2; ++n) _Pragma("unroll") for (int k = 0; k < 2; ++k) dst[n][k] = *(const PG8_LAS bf16x8*)(lds + PG8_SB(b, h) + boff + n * 2048 + k * 1024); } while (0)
; #define PG8_MMA(ai, bj, At, Bt) do { __builtin_amdgcn_s_setprio(1); _Pragma("unroll") for (int m = 0; m < 4; ++m) _Pragma("unroll") for (int n = 0; n < 2; ++n) _Pragma("unroll") for (int k = 0; k < 2; ++k) \
;         acc[ai][bj][m][n] = __builtin_amdgcn_mfma_f32_16x16x32_bf16(Bt[n][k], At[m][k], acc[ai][bj][m][n], 0, 0, 0); __builtin_amdgcn_s_setprio(0); } while (0)
; #define PG8_WAIT_V(n) asm volatile("s_waitcnt vmcnt(" #n ")" ::: "memory")
; #define PG8_WAIT_L(n) asm volatile("s_waitcnt lgkmcnt(" #n ")" ::: "memory")
; #define PG8_BAR __builtin_amdgcn_s_barrier()
; #define PG8_SCHED __builtin_amdgcn_sched_barrier(0)
; template <class Epi, class Sched, bool ALIGN_EPI = false, bool SP2 = false>
; __device__ __forceinline__ void gemm_phase(PG8_LAS unsigned char* lds, const Gemm g, const Sched& S, const Epi& E) {
;     ...
;             PG8_WAIT_V(8); PG8_WAIT_L(0); PG8_BAR; PG8_MMA(1, 0, At, B0); PG8_MMA(1, 1, At, B1); PG8_BAR; PG8_SCHED;
;             PG8_LDB(B0, 1, 0); PG8_LDB(B1, 1, 1); PG8_SCHED; PG8_LDA(At, 1, 0); PG8_STAGE(PG8_SA(0, 1), a2 + hstep, voffA);
;             PG8_WAIT_V(8); PG8_WAIT_L(0); PG8_BAR; PG8_MMA(0, 0, At, B0); PG8_MMA(0, 1, At, B1); PG8_BAR; PG8_SCHED;
	v_mfma_f32_16x16x32_bf16 v[60:63], v[92:95], v[198:201], v[60:63]
	v_mfma_f32_16x16x32_bf16 v[56:59], v[132:135], v[198:201], v[56:59]
	v_mfma_f32_16x16x32_bf16 v[44:47], v[92:95], v[210:213], v[44:47]
	v_mfma_f32_16x16x32_bf16 v[40:43], v[132:135], v[210:213], v[40:43]
	v_mfma_f32_16x16x32_bf16 v[28:31], v[92:95], v[222:225], v[28:31]
	v_mfma_f32_16x16x32_bf16 v[24:27], v[132:135], v[222:225], v[24:27]
	v_mfma_f32_16x16x32_bf16 v[12:15], v[92:95], v[230:233], v[12:15]
	v_mfma_f32_16x16x32_bf16 v[8:11], v[132:135], v[230:233], v[8:11]
	v_mfma_f32_16x16x32_bf16 v[60:63], v[128:131], v[202:205], v[60:63]
	v_mfma_f32_16x16x32_bf16 v[56:59], v[144:147], v[202:205], v[56:59]
	v_mfma_f32_16x16x32_bf16 v[44:47], v[128:131], v[218:221], v[44:47]
	v_mfma_f32_16x16x32_bf16 v[40:43], v[144:147], v[218:221], v[40:43]
	v_mfma_f32_16x16x32_bf16 v[28:31], v[128:131], v[226:229], v[28:31]
	v_mfma_f32_16x16x32_bf16 v[24:27], v[144:147], v[226:229], v[24:27]
	v_mfma_f32_16x16x32_bf16 v[12:15], v[128:131], v[234:237], v[12:15]
	v_mfma_f32_16x16x32_bf16 v[8:11], v[144:147], v[234:237], v[8:11]
	v_mfma_f32_16x16x32_bf16 v[52:55], v[148:151], v[198:201], v[52:55]
	v_mfma_f32_16x16x32_bf16 v[48:51], v[190:193], v[198:201], v[48:51]
	v_mfma_f32_16x16x32_bf16 v[36:39], v[148:151], v[210:213], v[36:39]
	v_mfma_f32_16x16x32_bf16 v[32:35], v[190:193], v[210:213], v[32:35]
	v_mfma_f32_16x16x32_bf16 v[20:23], v[148:151], v[222:225], v[20:23]
	v_mfma_f32_16x16x32_bf16 v[16:19], v[190:193], v[222:225], v[16:19]
	v_mfma_f32_16x16x32_bf16 v[4:7], v[148:151], v[230:233], v[4:7]
	v_mfma_f32_16x16x32_bf16 v[0:3], v[190:193], v[230:233], v[0:3]
	v_mfma_f32_16x16x32_bf16 v[52:55], v[152:155], v[202:205], v[52:55]
	v_mfma_f32_16x16x32_bf16 v[48:51], v[194:197], v[202:205], v[48:51]
	v_mfma_f32_16x16x32_bf16 v[36:39], v[152:155], v[218:221], v[36:39]
	v_mfma_f32_16x16x32_bf16 v[32:35], v[194:197], v[218:221], v[32:35]
	v_mfma_f32_16x16x32_bf16 v[20:23], v[152:155], v[226:229], v[20:23]
	v_mfma_f32_16x16x32_bf16 v[16:19], v[194:197], v[226:229], v[16:19]
	v_mfma_f32_16x16x32_bf16 v[4:7], v[152:155], v[234:237], v[4:7]
	v_mfma_f32_16x16x32_bf16 v[0:3], v[194:197], v[234:237], v[0:3]
	s_barrier
	s_add_i32 s11, 0, 0x18000
	s_add_i32 s14, 0, 0x1c000
	ds_read_b128 v[92:95], v255 offset:32768
	ds_read_b128 v[128:131], v255 offset:33792
	ds_read_b128 v[132:135], v255 offset:34816
	ds_read_b128 v[144:147], v255 offset:35840
	ds_read_b128 v[148:151], v255 offset:49152
	ds_read_b128 v[152:155], v255 offset:50176
	ds_read_b128 v[190:193], v255 offset:51200
	ds_read_b128 v[194:197], v255 offset:52224
	v_lshl_add_u64 v[206:207], v[206:207], 0, s[18:19]
	s_mov_b32 m0, s51
	v_lshl_add_u64 v[248:249], v[206:207], 0, v[166:167]
	ds_read_b128 v[198:201], v216 offset:32768
	ds_read_b128 v[202:205], v216 offset:33792
	ds_read_b128 v[210:213], v216 offset:34816
	ds_read_b128 v[218:221], v216 offset:35840
	ds_read_b128 v[222:225], v216 offset:36864
	ds_read_b128 v[226:229], v216 offset:37888
	ds_read_b128 v[230:233], v216 offset:38912
	ds_read_b128 v[234:237], v216 offset:39936
	global_load_lds_dwordx4 v[248:249], off
	s_mov_b32 m0, s52
	v_lshl_add_u64 v[206:207], v[206:207], 0, v[170:171]
	global_load_lds_dwordx4 v[206:207], off
	s_waitcnt vmcnt(8) lgkmcnt(0)
	s_barrier
	v_mfma_f32_16x16x32_bf16 v[140:143], v[92:95], v[198:201], v[140:143]
	v_mfma_f32_16x16x32_bf16 v[136:139], v[132:135], v[198:201], v[136:139]
	v_mfma_f32_16x16x32_bf16 v[116:119], v[92:95], v[210:213], v[116:119]
	v_mfma_f32_16x16x32_bf16 v[112:115], v[132:135], v[210:213], v[112:115]
	v_mfma_f32_16x16x32_bf16 v[100:103], v[92:95], v[222:225], v[100:103]
	v_mfma_f32_16x16x32_bf16 v[96:99], v[132:135], v[222:225], v[96:99]
	v_mfma_f32_16x16x32_bf16 v[76:79], v[92:95], v[230:233], v[76:79]
	v_mfma_f32_16x16x32_bf16 v[72:75], v[132:135], v[230:233], v[72:75]
	v_mfma_f32_16x16x32_bf16 v[140:143], v[128:131], v[202:205], v[140:143]
	v_mfma_f32_16x16x32_bf16 v[136:139], v[144:147], v[202:205], v[136:139]
	v_mfma_f32_16x16x32_bf16 v[116:119], v[128:131], v[218:221], v[116:119]
	v_mfma_f32_16x16x32_bf16 v[112:115], v[144:147], v[218:221], v[112:115]
	v_mfma_f32_16x16x32_bf16 v[100:103], v[128:131], v[226:229], v[100:103]
	v_mfma_f32_16x16x32_bf16 v[96:99], v[144:147], v[226:229], v[96:99]
	v_mfma_f32_16x16x32_bf16 v[76:79], v[128:131], v[234:237], v[76:79]
	v_mfma_f32_16x16x32_bf16 v[72:75], v[144:147], v[234:237], v[72:75]
	v_mfma_f32_16x16x32_bf16 v[124:127], v[148:151], v[198:201], v[124:127]
	v_mfma_f32_16x16x32_bf16 v[120:123], v[190:193], v[198:201], v[120:123]
	v_mfma_f32_16x16x32_bf16 v[108:111], v[148:151], v[210:213], v[108:111]
	v_mfma_f32_16x16x32_bf16 v[104:107], v[190:193], v[210:213], v[104:107]
	v_mfma_f32_16x16x32_bf16 v[84:87], v[148:151], v[222:225], v[84:87]
	v_mfma_f32_16x16x32_bf16 v[80:83], v[190:193], v[222:225], v[80:83]
	v_mfma_f32_16x16x32_bf16 v[68:71], v[148:151], v[230:233], v[68:71]
	v_mfma_f32_16x16x32_bf16 v[64:67], v[190:193], v[230:233], v[64:67]
	v_mfma_f32_16x16x32_bf16 v[124:127], v[152:155], v[202:205], v[124:127]
	v_mfma_f32_16x16x32_bf16 v[120:123], v[194:197], v[202:205], v[120:123]
	v_mfma_f32_16x16x32_bf16 v[108:111], v[152:155], v[218:221], v[108:111]
	v_mfma_f32_16x16x32_bf16 v[104:107], v[194:197], v[218:221], v[104:107]
	v_mfma_f32_16x16x32_bf16 v[84:87], v[152:155], v[226:229], v[84:87]
	v_mfma_f32_16x16x32_bf16 v[80:83], v[194:197], v[226:229], v[80:83]
	v_mfma_f32_16x16x32_bf16 v[68:71], v[152:155], v[234:237], v[68:71]
	v_mfma_f32_16x16x32_bf16 v[64:67], v[194:197], v[234:237], v[64:67]
	s_barrier
; #define PG8_STAGE(bufoff, gbase, voff) do { _Pragma("unroll") for (int _i = 0; _i < 2; ++_i) \
;         __builtin_amdgcn_global_load_lds((const unsigned*)((const char*)(gbase) + (voff)[_i]), (PG8_LAS unsigned*)(lds + (bufoff) + ldsw + _i * 8192), 16, 0, 0); } while (0)
; #define PG8_LDA(dst, b, h) do { _Pragma("unroll") for (int m = 0; m < 4; ++m) _Pragma("unroll") for (int k = 0; k < 2; ++k) dst[m][k] = *(const PG8_LAS bf16x8*)(lds + PG8_SA(b, h) + aoff + m * 2048 + k * 1024); } while (0)
; #define PG8_MMA(ai, bj, At, Bt) do { __builtin_amdgcn_s_setprio(1); _Pragma("unroll") for (int m = 0; m < 4; ++m) _Pragma("unroll") for (int n = 0; n < 2; ++n) _Pragma("unroll") for (int k = 0; k < 2; ++k) \
;         acc[ai][bj][m][n] = __builtin_amdgcn_mfma_f32_16x16x32_bf16(Bt[n][k], At[m][k], acc[ai][bj][m][n], 0, 0, 0); __builtin_amdgcn_s_setprio(0); } while (0)
; #define PG8_WAIT_V(n) asm volatile("s_waitcnt vmcnt(" #n ")" ::: "memory")
; #define PG8_WAIT_L(n) asm volatile("s_waitcnt lgkmcnt(" #n ")" ::: "memory")
; #define PG8_BAR __builtin_amdgcn_s_barrier()
; #define PG8_SCHED __builtin_amdgcn_sched_barrier(0)
; template <class Epi, class Sched, bool ALIGN_EPI = false, bool SP2 = false>
; __device__ __forceinline__ void gemm_phase(PG8_LAS unsigned char* lds, const Gemm g, const Sched& S, const Epi& E) {
;     ...
;         for (int t = 0; t < nt; t += 2) {
;     ...
;             PG8_LDA(At, 1, 1); PG8_STAGE(PG8_SB(1, 0), b3, voffB); PG8_STAGE(PG8_SB(1, 1), b3 + hstep, voffB); PG8_STAGE(PG8_SA(1, 0), a3, voffA);
;             PG8_WAIT_V(8); PG8_WAIT_L(0); PG8_BAR; PG8_MMA(1, 0, At, B0); PG8_MMA(1, 1, At, B1); PG8_BAR; PG8_SCHED;
	s_add_i32 s11, s11, s35
	s_add_i32 m0, s11, 0xffffff80
	ds_read_b128 v[198:201], v216 offset:49152
	ds_read_b128 v[202:205], v216 offset:50176
	ds_read_b128 v[210:213], v216 offset:51200
	ds_read_b128 v[218:221], v216 offset:52224
	global_load_lds_dwordx4 v[238:239], off offset:128
	s_add_i32 m0, s11, 0x1f80
	s_add_i32 s11, s14, s35
	global_load_lds_dwordx4 v[240:241], off offset:128
	s_add_i32 m0, s11, 0xffffff80
	ds_read_b128 v[234:237], v216 offset:56320
	global_load_lds_dwordx4 v[242:243], off offset:128
	s_add_i32 m0, s11, 0x1f80
	ds_read_b128 v[230:233], v216 offset:55296
	global_load_lds_dwordx4 v[214:215], off offset:128
	s_add_i32 m0, s54, 0xffffff80
	ds_read_b128 v[226:229], v216 offset:54272
	global_load_lds_dwordx4 v[244:245], off offset:128
	s_add_i32 m0, s55, 0xffffff80
	ds_read_b128 v[222:225], v216 offset:53248
	global_load_lds_dwordx4 v[246:247], off offset:128
	s_waitcnt vmcnt(8) lgkmcnt(0)
	s_barrier
	v_mfma_f32_16x16x32_bf16 v[60:63], v[92:95], v[198:201], v[60:63]
	v_mfma_f32_16x16x32_bf16 v[56:59], v[132:135], v[198:201], v[56:59]
	v_mfma_f32_16x16x32_bf16 v[44:47], v[92:95], v[210:213], v[44:47]
	v_mfma_f32_16x16x32_bf16 v[40:43], v[132:135], v[210:213], v[40:43]
	v_mfma_f32_16x16x32_bf16 v[28:31], v[92:95], v[222:225], v[28:31]
	v_mfma_f32_16x16x32_bf16 v[24:27], v[132:135], v[222:225], v[24:27]
	v_mfma_f32_16x16x32_bf16 v[12:15], v[92:95], v[230:233], v[12:15]
	v_mfma_f32_16x16x32_bf16 v[8:11], v[132:135], v[230:233], v[8:11]
	v_mfma_f32_16x16x32_bf16 v[60:63], v[128:131], v[202:205], v[60:63]
	v_mfma_f32_16x16x32_bf16 v[56:59], v[144:147], v[202:205], v[56:59]
	v_mfma_f32_16x16x32_bf16 v[44:47], v[128:131], v[218:221], v[44:47]
	v_mfma_f32_16x16x32_bf16 v[40:43], v[144:147], v[218:221], v[40:43]
	v_mfma_f32_16x16x32_bf16 v[28:31], v[128:131], v[226:229], v[28:31]
	v_mfma_f32_16x16x32_bf16 v[24:27], v[144:147], v[226:229], v[24:27]
	v_mfma_f32_16x16x32_bf16 v[12:15], v[128:131], v[234:237], v[12:15]
	v_mfma_f32_16x16x32_bf16 v[8:11], v[144:147], v[234:237], v[8:11]
	v_mfma_f32_16x16x32_bf16 v[52:55], v[148:151], v[198:201], v[52:55]
	v_mfma_f32_16x16x32_bf16 v[48:51], v[190:193], v[198:201], v[48:51]
	v_mfma_f32_16x16x32_bf16 v[36:39], v[148:151], v[210:213], v[36:39]
	v_mfma_f32_16x16x32_bf16 v[32:35], v[190:193], v[210:213], v[32:35]
	v_mfma_f32_16x16x32_bf16 v[20:23], v[148:151], v[222:225], v[20:23]
	v_mfma_f32_16x16x32_bf16 v[16:19], v[190:193], v[222:225], v[16:19]
	v_mfma_f32_16x16x32_bf16 v[4:7], v[148:151], v[230:233], v[4:7]
	v_mfma_f32_16x16x32_bf16 v[0:3], v[190:193], v[230:233], v[0:3]
	v_mfma_f32_16x16x32_bf16 v[52:55], v[152:155], v[202:205], v[52:55]
	v_mfma_f32_16x16x32_bf16 v[48:51], v[194:197], v[202:205], v[48:51]
	v_mfma_f32_16x16x32_bf16 v[36:39], v[152:155], v[218:221], v[36:39]
	v_mfma_f32_16x16x32_bf16 v[32:35], v[194:197], v[218:221], v[32:35]
	v_mfma_f32_16x16x32_bf16 v[20:23], v[152:155], v[226:229], v[20:23]
	v_mfma_f32_16x16x32_bf16 v[16:19], v[194:197], v[226:229], v[16:19]
	v_mfma_f32_16x16x32_bf16 v[4:7], v[152:155], v[234:237], v[4:7]
	v_mfma_f32_16x16x32_bf16 v[0:3], v[194:197], v[234:237], v[0:3]
	s_barrier
	v_lshl_add_u64 v[88:89], v[88:89], 0, s[30:31]
	s_cmp_ge_i32 s10, s57
	v_lshl_add_u64 v[90:91], v[90:91], 0, s[30:31]
	s_cbranch_scc0 .LBB0_635

; #define PG8_STAGE(bufoff, gbase, voff) do { _Pragma("unroll") for (int _i = 0; _i < 2; ++_i) \
;         __builtin_amdgcn_global_load_lds((const unsigned*)((const char*)(gbase) + (voff)[_i]), (PG8_LAS unsigned*)(lds + (bufoff) + ldsw + _i * 8192), 16, 0, 0); } while (0)
; #define PG8_LDA(dst, b, h) do { _Pragma("unroll") for (int m = 0; m < 4; ++m) _Pragma("unroll") for (int k = 0; k < 2; ++k) dst[m][k] = *(const PG8_LAS bf16x8*)(lds + PG8_SA(b, h) + aoff + m * 2048 + k * 1024); } while (0)
; #define PG8_LDB(dst, b, h) do { _Pragma("unroll") for (int n = 0; n < 2; ++n) _Pragma("unroll") for (int k = 0; k < 2; ++k) dst[n][k] = *(const PG8_LAS bf16x8*)(lds + PG8_SB(b, h) + boff + n * 2048 + k * 1024); } while (0)
; #define PG8_MMA(ai, bj, At, Bt) do { __builtin_amdgcn_s_setprio(1); _Pragma("unroll") for (int m = 0; m < 4; ++m) _Pragma("unroll") for (int n = 0; n < 2; ++n) _Pragma("unroll") for (int k = 0; k < 2; ++k) \
;         acc[ai][bj][m][n] = __builtin_amdgcn_mfma_f32_16x16x32_bf16(Bt[n][k], At[m][k], acc[ai][bj][m][n], 0, 0, 0); __builtin_amdgcn_s_setprio(0); } while (0)
; #define PG8_WAIT_V(n) asm volatile("s_waitcnt vmcnt(" #n ")" ::: "memory")
; #define PG8_BAR __builtin_amdgcn_s_barrier()
; template <class Epi, class Sched, bool ALIGN_EPI = false, bool SP2 = false>
; __device__ __forceinline__ void gemm_phase(PG8_LAS unsigned char* lds, const Gemm g, const Sched& S, const Epi& E) {
;     ...
;         for (int t = 0; t < nt; t += 2) {
;             const bool last = (t == nt - 2);
;             const char* a1 = cA + (size_t)(t + 1) * kstep;
;             const char* a2 = last ? nA : cA + (size_t)(t + 2) * kstep; const char* b2 = last ? nB : cB + (size_t)(t + 2) * kstep;
;             const char* a3 = a2 + kstep; const char* b3 = b2 + kstep;
;             if (last && has_next) S.a_ready(nxt);
;             if constexpr (SP2) {
;             PG8_LDB(B0, 0, 0); PG8_LDB(B1, 0, 1); PG8_SCHED; PG8_LDA(At, 0, 0); PG8_STAGE(PG8_SA(1, 1), a1 + hstep, voffA);
;             PG8_WAIT_V(8); PG8_WAIT_L(0); PG8_BAR; PG8_MMA(0, 0, At, B0); PG8_MMA(0, 1, At, B1); PG8_BAR; PG8_SCHED;
;             PG8_LDA(At, 0, 1); PG8_STAGE(PG8_SB(0, 0), b2, voffB); PG8_STAGE(PG8_SB(0, 1), b2 + hstep, voffB); PG8_STAGE(PG8_SA(0, 0), a2, voffA);
;             PG8_WAIT_V(8); PG8_WAIT_L(0); PG8_BAR; PG8_MMA(1, 0, At, B0); PG8_MMA(1, 1, At, B1); PG8_BAR; PG8_SCHED;
.LBB0_722:
	v_add_u32_e32 v255, s59, v183
	ds_read_b128 v[116:119], v255
	ds_read_b128 v[136:139], v255 offset:1024
	ds_read_b128 v[140:143], v255 offset:2048
	ds_read_b128 v[144:147], v255 offset:3072
	ds_read_b128 v[148:151], v255 offset:16384
	ds_read_b128 v[188:191], v255 offset:17408
	ds_read_b128 v[192:195], v255 offset:18432
	ds_read_b128 v[198:201], v255 offset:19456
	s_cmp_eq_u32 s53, s8
	v_lshl_add_u64 v[204:205], v[114:115], 0, s[18:19]
	s_cselect_b64 vcc, -1, 0
	s_add_i32 s8, s8, 2
	v_cndmask_b32_e32 v213, v205, v185, vcc
	v_cndmask_b32_e32 v212, v204, v184, vcc
	v_cndmask_b32_e32 v215, v113, v187, vcc
	v_cndmask_b32_e32 v214, v112, v186, vcc
	v_lshl_add_u64 v[240:241], v[114:115], 0, v[178:179]
	s_add_i32 m0, s34, 0xc000
	ds_read_b128 v[204:207], v202
	ds_read_b128 v[208:211], v202 offset:1024
	ds_read_b128 v[216:219], v202 offset:2048
	ds_read_b128 v[220:223], v202 offset:3072
	ds_read_b128 v[224:227], v202 offset:4096
	ds_read_b128 v[228:231], v202 offset:5120
	ds_read_b128 v[232:235], v202 offset:6144
	ds_read_b128 v[236:239], v202 offset:7168
	global_load_lds_dwordx4 v[240:241], off
	s_add_i32 m0, s34, 0xe000
	v_lshl_add_u64 v[240:241], v[114:115], 0, v[176:177]
	global_load_lds_dwordx4 v[240:241], off
	s_waitcnt vmcnt(8) lgkmcnt(0)
	s_barrier
	v_mfma_f32_16x16x32_bf16 v[132:135], v[116:119], v[204:207], v[132:135]
	v_mfma_f32_16x16x32_bf16 v[128:131], v[140:143], v[204:207], v[128:131]
	v_mfma_f32_16x16x32_bf16 v[108:111], v[116:119], v[216:219], v[108:111]
	v_mfma_f32_16x16x32_bf16 v[104:107], v[140:143], v[216:219], v[104:107]
	v_mfma_f32_16x16x32_bf16 v[92:95], v[116:119], v[224:227], v[92:95]
	v_mfma_f32_16x16x32_bf16 v[88:91], v[140:143], v[224:227], v[88:91]
	v_mfma_f32_16x16x32_bf16 v[76:79], v[116:119], v[232:235], v[76:79]
	v_mfma_f32_16x16x32_bf16 v[72:75], v[140:143], v[232:235], v[72:75]
	v_mfma_f32_16x16x32_bf16 v[132:135], v[136:139], v[208:211], v[132:135]
	v_mfma_f32_16x16x32_bf16 v[128:131], v[144:147], v[208:211], v[128:131]
	v_mfma_f32_16x16x32_bf16 v[108:111], v[136:139], v[220:223], v[108:111]
	v_mfma_f32_16x16x32_bf16 v[104:107], v[144:147], v[220:223], v[104:107]
	v_mfma_f32_16x16x32_bf16 v[92:95], v[136:139], v[228:231], v[92:95]
	v_mfma_f32_16x16x32_bf16 v[88:91], v[144:147], v[228:231], v[88:91]
	v_mfma_f32_16x16x32_bf16 v[76:79], v[136:139], v[236:239], v[76:79]
	v_mfma_f32_16x16x32_bf16 v[72:75], v[144:147], v[236:239], v[72:75]
	v_mfma_f32_16x16x32_bf16 v[124:127], v[148:151], v[204:207], v[124:127]
	v_mfma_f32_16x16x32_bf16 v[120:123], v[192:195], v[204:207], v[120:123]
	v_mfma_f32_16x16x32_bf16 v[100:103], v[148:151], v[216:219], v[100:103]
	v_mfma_f32_16x16x32_bf16 v[96:99], v[192:195], v[216:219], v[96:99]
	v_mfma_f32_16x16x32_bf16 v[84:87], v[148:151], v[224:227], v[84:87]
	v_mfma_f32_16x16x32_bf16 v[80:83], v[192:195], v[224:227], v[80:83]
	v_mfma_f32_16x16x32_bf16 v[68:71], v[148:151], v[232:235], v[68:71]
	v_mfma_f32_16x16x32_bf16 v[64:67], v[192:195], v[232:235], v[64:67]
	v_mfma_f32_16x16x32_bf16 v[124:127], v[188:191], v[208:211], v[124:127]
	v_mfma_f32_16x16x32_bf16 v[120:123], v[198:201], v[208:211], v[120:123]
	v_mfma_f32_16x16x32_bf16 v[100:103], v[188:191], v[220:223], v[100:103]
	v_mfma_f32_16x16x32_bf16 v[96:99], v[198:201], v[220:223], v[96:99]
	v_mfma_f32_16x16x32_bf16 v[84:87], v[188:191], v[228:231], v[84:87]
	v_mfma_f32_16x16x32_bf16 v[80:83], v[198:201], v[228:231], v[80:83]
	v_mfma_f32_16x16x32_bf16 v[68:71], v[188:191], v[236:239], v[68:71]
	v_mfma_f32_16x16x32_bf16 v[64:67], v[198:201], v[236:239], v[64:67]
	s_barrier
	s_add_i32 s9, s59, s29
	v_lshl_add_u64 v[240:241], v[214:215], 0, v[164:165]
	s_mov_b32 m0, s9
	ds_read_b128 v[204:207], v202 offset:16384
	ds_read_b128 v[208:211], v202 offset:17408
	ds_read_b128 v[216:219], v202 offset:18432
	ds_read_b128 v[220:223], v202 offset:19456
	ds_read_b128 v[224:227], v202 offset:20480
	ds_read_b128 v[228:231], v202 offset:21504
	ds_read_b128 v[232:235], v202 offset:22528
	ds_read_b128 v[236:239], v202 offset:23552
	global_load_lds_dwordx4 v[240:241], off
	v_lshl_add_u64 v[242:243], v[214:215], 0, v[168:169]
	s_add_i32 m0, s9, 0x2000
	v_lshl_add_u64 v[214:215], v[214:215], 0, s[12:13]
	s_add_i32 s9, s60, s29
	global_load_lds_dwordx4 v[242:243], off
	v_lshl_add_u64 v[244:245], v[214:215], 0, v[164:165]
	s_mov_b32 m0, s9
	v_lshl_add_u64 v[214:215], v[214:215], 0, v[168:169]
	global_load_lds_dwordx4 v[244:245], off
	s_add_i32 m0, s9, 0x2000
	v_lshl_add_u64 v[246:247], v[212:213], 0, v[162:163]
	global_load_lds_dwordx4 v[214:215], off
	s_mov_b32 m0, s34
	v_lshl_add_u64 v[248:249], v[212:213], 0, v[166:167]
	global_load_lds_dwordx4 v[246:247], off
	s_mov_b32 m0, s36
	s_nop 0
	global_load_lds_dwordx4 v[248:249], off
	s_waitcnt vmcnt(8) lgkmcnt(0)
	s_barrier
; #define PG8_STAGE(bufoff, gbase, voff) do { _Pragma("unroll") for (int _i = 0; _i < 2; ++_i) \
;         __builtin_amdgcn_global_load_lds((const unsigned*)((const char*)(gbase) + (voff)[_i]), (PG8_LAS unsigned*)(lds + (bufoff) + ldsw + _i * 8192), 16, 0, 0); } while (0)
; #define PG8_LDA(dst, b, h) do { _Pragma("unroll") for (int m = 0; m < 4; ++m) _Pragma("unroll") for (int k = 0; k < 2; ++k) dst[m][k] = *(const PG8_LAS bf16x8*)(lds + PG8_SA(b, h) + aoff + m * 2048 + k * 1024); } while (0)
; #define PG8_LDB(dst, b, h) do { _Pragma("unroll") for (int n = 0; n < 2; ++n) _Pragma("unroll") for (int k = 0; k < 2; ++k) dst[n][k] = *(const PG8_LAS bf16x8*)(lds + PG8_SB(b, h) + boff + n * 2048 + k * 1024); } while (0)
; #define PG8_MMA(ai, bj, At, Bt) do { __builtin_amdgcn_s_setprio(1); _Pragma("unroll") for (int m = 0; m < 4; ++m) _Pragma("unroll") for (int n = 0; n < 2; ++n) _Pragma("unroll") for (int k = 0; k < 2; ++k) \
;         acc[ai][bj][m][n] = __builtin_amdgcn_mfma_f32_16x16x32_bf16(Bt[n][k], At[m][k], acc[ai][bj][m][n], 0, 0, 0); __builtin_amdgcn_s_setprio(0); } while (0)
; #define PG8_WAIT_V(n) asm volatile("s_waitcnt vmcnt(" #n ")" ::: "memory")
; #define PG8_WAIT_L(n) asm volatile("s_waitcnt lgkmcnt(" #n ")" ::: "memory")
; #define PG8_BAR __builtin_amdgcn_s_barrier()
; #define PG8_SCHED __builtin_amdgcn_sched_barrier(0)
; template <class Epi, class Sched, bool ALIGN_EPI = false, bool SP2 = false>
; __device__ __forceinline__ void gemm_phase(PG8_LAS unsigned char* lds, const Gemm g, const Sched& S, const Epi& E) {
;     ...
;             PG8_WAIT_V(8); PG8_WAIT_L(0); PG8_BAR; PG8_MMA(1, 0, At, B0); PG8_MMA(1, 1, At, B1); PG8_BAR; PG8_SCHED;
;             PG8_LDB(B0, 1, 0); PG8_LDB(B1, 1, 1); PG8_SCHED; PG8_LDA(At, 1, 0); PG8_STAGE(PG8_SA(0, 1), a2 + hstep, voffA);
	v_mfma_f32_16x16x32_bf16 v[60:63], v[116:119], v[204:207], v[60:63]
	v_mfma_f32_16x16x32_bf16 v[56:59], v[140:143], v[204:207], v[56:59]
	v_mfma_f32_16x16x32_bf16 v[44:47], v[116:119], v[216:219], v[44:47]
	v_mfma_f32_16x16x32_bf16 v[40:43], v[140:143], v[216:219], v[40:43]
	v_mfma_f32_16x16x32_bf16 v[28:31], v[116:119], v[224:227], v[28:31]
	v_mfma_f32_16x16x32_bf16 v[24:27], v[140:143], v[224:227], v[24:27]
	v_mfma_f32_16x16x32_bf16 v[12:15], v[116:119], v[232:235], v[12:15]
	v_mfma_f32_16x16x32_bf16 v[8:11], v[140:143], v[232:235], v[8:11]
	v_mfma_f32_16x16x32_bf16 v[60:63], v[136:139], v[208:211], v[60:63]
	v_mfma_f32_16x16x32_bf16 v[56:59], v[144:147], v[208:211], v[56:59]
	v_mfma_f32_16x16x32_bf16 v[44:47], v[136:139], v[220:223], v[44:47]
	v_mfma_f32_16x16x32_bf16 v[40:43], v[144:147], v[220:223], v[40:43]
	v_mfma_f32_16x16x32_bf16 v[28:31], v[136:139], v[228:231], v[28:31]
	v_mfma_f32_16x16x32_bf16 v[24:27], v[144:147], v[228:231], v[24:27]
	v_mfma_f32_16x16x32_bf16 v[12:15], v[136:139], v[236:239], v[12:15]
	v_mfma_f32_16x16x32_bf16 v[8:11], v[144:147], v[236:239], v[8:11]
	v_mfma_f32_16x16x32_bf16 v[52:55], v[148:151], v[204:207], v[52:55]
	v_mfma_f32_16x16x32_bf16 v[48:51], v[192:195], v[204:207], v[48:51]
	v_mfma_f32_16x16x32_bf16 v[36:39], v[148:151], v[216:219], v[36:39]
	v_mfma_f32_16x16x32_bf16 v[32:35], v[192:195], v[216:219], v[32:35]
	v_mfma_f32_16x16x32_bf16 v[20:23], v[148:151], v[224:227], v[20:23]
	v_mfma_f32_16x16x32_bf16 v[16:19], v[192:195], v[224:227], v[16:19]
	v_mfma_f32_16x16x32_bf16 v[4:7], v[148:151], v[232:235], v[4:7]
	v_mfma_f32_16x16x32_bf16 v[0:3], v[192:195], v[232:235], v[0:3]
	v_mfma_f32_16x16x32_bf16 v[52:55], v[188:191], v[208:211], v[52:55]
	v_mfma_f32_16x16x32_bf16 v[48:51], v[198:201], v[208:211], v[48:51]
	v_mfma_f32_16x16x32_bf16 v[36:39], v[188:191], v[220:223], v[36:39]
	v_mfma_f32_16x16x32_bf16 v[32:35], v[198:201], v[220:223], v[32:35]
	v_mfma_f32_16x16x32_bf16 v[20:23], v[188:191], v[228:231], v[20:23]
	v_mfma_f32_16x16x32_bf16 v[16:19], v[198:201], v[228:231], v[16:19]
	v_mfma_f32_16x16x32_bf16 v[4:7], v[188:191], v[236:239], v[4:7]
	v_mfma_f32_16x16x32_bf16 v[0:3], v[198:201], v[236:239], v[0:3]
	s_barrier
	s_add_i32 s9, 0, 0x18000
	s_add_i32 s10, 0, 0x1c000
	ds_read_b128 v[116:119], v255 offset:32768
	ds_read_b128 v[136:139], v255 offset:33792
	ds_read_b128 v[140:143], v255 offset:34816
	ds_read_b128 v[144:147], v255 offset:35840
	ds_read_b128 v[148:151], v255 offset:49152
	ds_read_b128 v[188:191], v255 offset:50176
	ds_read_b128 v[192:195], v255 offset:51200
	ds_read_b128 v[198:201], v255 offset:52224
	v_lshl_add_u64 v[212:213], v[212:213], 0, s[12:13]
	s_mov_b32 m0, s37
	v_lshl_add_u64 v[250:251], v[212:213], 0, v[162:163]
	ds_read_b128 v[204:207], v202 offset:32768
	ds_read_b128 v[208:211], v202 offset:33792
	ds_read_b128 v[216:219], v202 offset:34816
	ds_read_b128 v[220:223], v202 offset:35840
	ds_read_b128 v[224:227], v202 offset:36864
	ds_read_b128 v[228:231], v202 offset:37888
	ds_read_b128 v[232:235], v202 offset:38912
	ds_read_b128 v[236:239], v202 offset:39936
	global_load_lds_dwordx4 v[250:251], off
	s_mov_b32 m0, s41
	v_lshl_add_u64 v[212:213], v[212:213], 0, v[166:167]
	global_load_lds_dwordx4 v[212:213], off
	s_waitcnt vmcnt(8) lgkmcnt(0)
	s_barrier
; #define PG8_STAGE(bufoff, gbase, voff) do { _Pragma("unroll") for (int _i = 0; _i < 2; ++_i) \
;         __builtin_amdgcn_global_load_lds((const unsigned*)((const char*)(gbase) + (voff)[_i]), (PG8_LAS unsigned*)(lds + (bufoff) + ldsw + _i * 8192), 16, 0, 0); } while (0)
; #define PG8_LDA(dst, b, h) do { _Pragma("unroll") for (int m = 0; m < 4; ++m) _Pragma("unroll") for (int k = 0; k < 2; ++k) dst[m][k] = *(const PG8_LAS bf16x8*)(lds + PG8_SA(b, h) + aoff + m * 2048 + k * 1024); } while (0)
; #define PG8_MMA(ai, bj, At, Bt) do { __builtin_amdgcn_s_setprio(1); _Pragma("unroll") for (int m = 0; m < 4; ++m) _Pragma("unroll") for (int n = 0; n < 2; ++n) _Pragma("unroll") for (int k = 0; k < 2; ++k) \
;         acc[ai][bj][m][n] = __builtin_amdgcn_mfma_f32_16x16x32_bf16(Bt[n][k], At[m][k], acc[ai][bj][m][n], 0, 0, 0); __builtin_amdgcn_s_setprio(0); } while (0)
; #define PG8_WAIT_V(n) asm volatile("s_waitcnt vmcnt(" #n ")" ::: "memory")
; #define PG8_WAIT_L(n) asm volatile("s_waitcnt lgkmcnt(" #n ")" ::: "memory")
; #define PG8_BAR __builtin_amdgcn_s_barrier()
; #define PG8_SCHED __builtin_amdgcn_sched_barrier(0)
; template <class Epi, class Sched, bool ALIGN_EPI = false, bool SP2 = false>
; __device__ __forceinline__ void gemm_phase(PG8_LAS unsigned char* lds, const Gemm g, const Sched& S, const Epi& E) {
;     ...
;         for (int t = 0; t < nt; t += 2) {
;     ...
;             PG8_WAIT_V(8); PG8_WAIT_L(0); PG8_BAR; PG8_MMA(0, 0, At, B0); PG8_MMA(0, 1, At, B1); PG8_BAR; PG8_SCHED;
;             PG8_LDA(At, 1, 1); PG8_STAGE(PG8_SB(1, 0), b3, voffB); PG8_STAGE(PG8_SB(1, 1), b3 + hstep, voffB); PG8_STAGE(PG8_SA(1, 0), a3, voffA);
;             PG8_WAIT_V(8); PG8_WAIT_L(0); PG8_BAR; PG8_MMA(1, 0, At, B0); PG8_MMA(1, 1, At, B1); PG8_BAR; PG8_SCHED;
	v_mfma_f32_16x16x32_bf16 v[132:135], v[116:119], v[204:207], v[132:135]
	v_mfma_f32_16x16x32_bf16 v[128:131], v[140:143], v[204:207], v[128:131]
	v_mfma_f32_16x16x32_bf16 v[108:111], v[116:119], v[216:219], v[108:111]
	v_mfma_f32_16x16x32_bf16 v[104:107], v[140:143], v[216:219], v[104:107]
	v_mfma_f32_16x16x32_bf16 v[92:95], v[116:119], v[224:227], v[92:95]
	v_mfma_f32_16x16x32_bf16 v[88:91], v[140:143], v[224:227], v[88:91]
	v_mfma_f32_16x16x32_bf16 v[76:79], v[116:119], v[232:235], v[76:79]
	v_mfma_f32_16x16x32_bf16 v[72:75], v[140:143], v[232:235], v[72:75]
	v_mfma_f32_16x16x32_bf16 v[132:135], v[136:139], v[208:211], v[132:135]
	v_mfma_f32_16x16x32_bf16 v[128:131], v[144:147], v[208:211], v[128:131]
	v_mfma_f32_16x16x32_bf16 v[108:111], v[136:139], v[220:223], v[108:111]
	v_mfma_f32_16x16x32_bf16 v[104:107], v[144:147], v[220:223], v[104:107]
	v_mfma_f32_16x16x32_bf16 v[92:95], v[136:139], v[228:231], v[92:95]
	v_mfma_f32_16x16x32_bf16 v[88:91], v[144:147], v[228:231], v[88:91]
	v_mfma_f32_16x16x32_bf16 v[76:79], v[136:139], v[236:239], v[76:79]
	v_mfma_f32_16x16x32_bf16 v[72:75], v[144:147], v[236:239], v[72:75]
	v_mfma_f32_16x16x32_bf16 v[124:127], v[148:151], v[204:207], v[124:127]
	v_mfma_f32_16x16x32_bf16 v[120:123], v[192:195], v[204:207], v[120:123]
	v_mfma_f32_16x16x32_bf16 v[100:103], v[148:151], v[216:219], v[100:103]
	v_mfma_f32_16x16x32_bf16 v[96:99], v[192:195], v[216:219], v[96:99]
	v_mfma_f32_16x16x32_bf16 v[84:87], v[148:151], v[224:227], v[84:87]
	v_mfma_f32_16x16x32_bf16 v[80:83], v[192:195], v[224:227], v[80:83]
	v_mfma_f32_16x16x32_bf16 v[68:71], v[148:151], v[232:235], v[68:71]
	v_mfma_f32_16x16x32_bf16 v[64:67], v[192:195], v[232:235], v[64:67]
	v_mfma_f32_16x16x32_bf16 v[124:127], v[188:191], v[208:211], v[124:127]
	v_mfma_f32_16x16x32_bf16 v[120:123], v[198:201], v[208:211], v[120:123]
	v_mfma_f32_16x16x32_bf16 v[100:103], v[188:191], v[220:223], v[100:103]
	v_mfma_f32_16x16x32_bf16 v[96:99], v[198:201], v[220:223], v[96:99]
	v_mfma_f32_16x16x32_bf16 v[84:87], v[188:191], v[228:231], v[84:87]
	v_mfma_f32_16x16x32_bf16 v[80:83], v[198:201], v[228:231], v[80:83]
	v_mfma_f32_16x16x32_bf16 v[68:71], v[188:191], v[236:239], v[68:71]
	v_mfma_f32_16x16x32_bf16 v[64:67], v[198:201], v[236:239], v[64:67]
	s_barrier
	s_add_i32 s9, s9, s29
	s_add_i32 m0, s9, 0xffffff80
	ds_read_b128 v[204:207], v202 offset:49152
	ds_read_b128 v[208:211], v202 offset:50176
	ds_read_b128 v[216:219], v202 offset:51200
	ds_read_b128 v[220:223], v202 offset:52224
	global_load_lds_dwordx4 v[240:241], off offset:128
	s_add_i32 m0, s9, 0x1f80
	s_add_i32 s9, s10, s29
	global_load_lds_dwordx4 v[242:243], off offset:128
	s_add_i32 m0, s9, 0xffffff80
	ds_read_b128 v[236:239], v202 offset:56320
	global_load_lds_dwordx4 v[244:245], off offset:128
	s_add_i32 m0, s9, 0x1f80
	ds_read_b128 v[232:235], v202 offset:55296
	global_load_lds_dwordx4 v[214:215], off offset:128
	s_add_i32 m0, s49, 0xffffff80
	ds_read_b128 v[228:231], v202 offset:54272
	global_load_lds_dwordx4 v[246:247], off offset:128
	s_add_i32 m0, s50, 0xffffff80
	ds_read_b128 v[224:227], v202 offset:53248
	global_load_lds_dwordx4 v[248:249], off offset:128
	s_waitcnt vmcnt(8) lgkmcnt(0)
	s_barrier
	v_mfma_f32_16x16x32_bf16 v[60:63], v[116:119], v[204:207], v[60:63]
	v_mfma_f32_16x16x32_bf16 v[56:59], v[140:143], v[204:207], v[56:59]
	v_mfma_f32_16x16x32_bf16 v[44:47], v[116:119], v[216:219], v[44:47]
	v_mfma_f32_16x16x32_bf16 v[40:43], v[140:143], v[216:219], v[40:43]
	v_mfma_f32_16x16x32_bf16 v[28:31], v[116:119], v[224:227], v[28:31]
	v_mfma_f32_16x16x32_bf16 v[24:27], v[140:143], v[224:227], v[24:27]
	v_mfma_f32_16x16x32_bf16 v[12:15], v[116:119], v[232:235], v[12:15]
	v_mfma_f32_16x16x32_bf16 v[8:11], v[140:143], v[232:235], v[8:11]
	v_mfma_f32_16x16x32_bf16 v[60:63], v[136:139], v[208:211], v[60:63]
	v_mfma_f32_16x16x32_bf16 v[56:59], v[144:147], v[208:211], v[56:59]
	v_mfma_f32_16x16x32_bf16 v[44:47], v[136:139], v[220:223], v[44:47]
	v_mfma_f32_16x16x32_bf16 v[40:43], v[144:147], v[220:223], v[40:43]
	v_mfma_f32_16x16x32_bf16 v[28:31], v[136:139], v[228:231], v[28:31]
	v_mfma_f32_16x16x32_bf16 v[24:27], v[144:147], v[228:231], v[24:27]
	v_mfma_f32_16x16x32_bf16 v[12:15], v[136:139], v[236:239], v[12:15]
	v_mfma_f32_16x16x32_bf16 v[8:11], v[144:147], v[236:239], v[8:11]
	v_mfma_f32_16x16x32_bf16 v[52:55], v[148:151], v[204:207], v[52:55]
	v_mfma_f32_16x16x32_bf16 v[48:51], v[192:195], v[204:207], v[48:51]
	v_mfma_f32_16x16x32_bf16 v[36:39], v[148:151], v[216:219], v[36:39]
	v_mfma_f32_16x16x32_bf16 v[32:35], v[192:195], v[216:219], v[32:35]
	v_mfma_f32_16x16x32_bf16 v[20:23], v[148:151], v[224:227], v[20:23]
	v_mfma_f32_16x16x32_bf16 v[16:19], v[192:195], v[224:227], v[16:19]
	v_mfma_f32_16x16x32_bf16 v[4:7], v[148:151], v[232:235], v[4:7]
	v_mfma_f32_16x16x32_bf16 v[0:3], v[192:195], v[232:235], v[0:3]
	v_mfma_f32_16x16x32_bf16 v[52:55], v[188:191], v[208:211], v[52:55]
	v_mfma_f32_16x16x32_bf16 v[48:51], v[198:201], v[208:211], v[48:51]
	v_mfma_f32_16x16x32_bf16 v[36:39], v[188:191], v[220:223], v[36:39]
	v_mfma_f32_16x16x32_bf16 v[32:35], v[198:201], v[220:223], v[32:35]
	v_mfma_f32_16x16x32_bf16 v[20:23], v[188:191], v[228:231], v[20:23]
	v_mfma_f32_16x16x32_bf16 v[16:19], v[198:201], v[228:231], v[16:19]
	v_mfma_f32_16x16x32_bf16 v[4:7], v[188:191], v[236:239], v[4:7]
	v_mfma_f32_16x16x32_bf16 v[0:3], v[198:201], v[236:239], v[0:3]
	s_barrier
	v_lshl_add_u64 v[112:113], v[112:113], 0, s[26:27]
	s_cmp_ge_i32 s8, s51
	v_lshl_add_u64 v[114:115], v[114:115], 0, s[26:27]
	s_cbranch_scc0 .LBB0_722

; #define PG8_STAGE(bufoff, gbase, voff) do { _Pragma("unroll") for (int _i = 0; _i < 2; ++_i) \
;         __builtin_amdgcn_global_load_lds((const unsigned*)((const char*)(gbase) + (voff)[_i]), (PG8_LAS unsigned*)(lds + (bufoff) + ldsw + _i * 8192), 16, 0, 0); } while (0)
; #define PG8_LDA(dst, b, h) do { _Pragma("unroll") for (int m = 0; m < 4; ++m) _Pragma("unroll") for (int k = 0; k < 2; ++k) dst[m][k] = *(const PG8_LAS bf16x8*)(lds + PG8_SA(b, h) + aoff + m * 2048 + k * 1024); } while (0)
; #define PG8_LDB(dst, b, h) do { _Pragma("unroll") for (int n = 0; n < 2; ++n) _Pragma("unroll") for (int k = 0; k < 2; ++k) dst[n][k] = *(const PG8_LAS bf16x8*)(lds + PG8_SB(b, h) + boff + n * 2048 + k * 1024); } while (0)
; #define PG8_MMA(ai, bj, At, Bt) do { __builtin_amdgcn_s_setprio(1); _Pragma("unroll") for (int m = 0; m < 4; ++m) _Pragma("unroll") for (int n = 0; n < 2; ++n) _Pragma("unroll") for (int k = 0; k < 2; ++k) \
;         acc[ai][bj][m][n] = __builtin_amdgcn_mfma_f32_16x16x32_bf16(Bt[n][k], At[m][k], acc[ai][bj][m][n], 0, 0, 0); __builtin_amdgcn_s_setprio(0); } while (0)
; #define PG8_WAIT_V(n) asm volatile("s_waitcnt vmcnt(" #n ")" ::: "memory")
; #define PG8_BAR __builtin_amdgcn_s_barrier()
; template <class Epi, class Sched, bool ALIGN_EPI = false, bool SP2 = false>
; __device__ __forceinline__ void gemm_phase(PG8_LAS unsigned char* lds, const Gemm g, const Sched& S, const Epi& E) {
;     ...
;         for (int t = 0; t < nt; t += 2) {
;             const bool last = (t == nt - 2);
;             const char* a1 = cA + (size_t)(t + 1) * kstep;
;             const char* a2 = last ? nA : cA + (size_t)(t + 2) * kstep; const char* b2 = last ? nB : cB + (size_t)(t + 2) * kstep;
;             const char* a3 = a2 + kstep; const char* b3 = b2 + kstep;
;             if (last && has_next) S.a_ready(nxt);
;             if constexpr (SP2) {
;             PG8_LDB(B0, 0, 0); PG8_LDB(B1, 0, 1); PG8_SCHED; PG8_LDA(At, 0, 0); PG8_STAGE(PG8_SA(1, 1), a1 + hstep, voffA);
;             PG8_WAIT_V(8); PG8_WAIT_L(0); PG8_BAR; PG8_MMA(0, 0, At, B0); PG8_MMA(0, 1, At, B1); PG8_BAR; PG8_SCHED;
;             PG8_LDA(At, 0, 1); PG8_STAGE(PG8_SB(0, 0), b2, voffB); PG8_STAGE(PG8_SB(0, 1), b2 + hstep, voffB); PG8_STAGE(PG8_SA(0, 0), a2, voffA);
;             PG8_WAIT_V(8); PG8_WAIT_L(0); PG8_BAR; PG8_MMA(1, 0, At, B0); PG8_MMA(1, 1, At, B1); PG8_BAR; PG8_SCHED;
.LBB0_940:
	v_add_u32_e32 v255, s55, v199
	ds_read_b128 v[132:135], v201
	ds_read_b128 v[136:139], v201 offset:1024
	ds_read_b128 v[140:143], v201 offset:2048
	ds_read_b128 v[144:147], v201 offset:3072
	ds_read_b128 v[148:151], v255
	ds_read_b128 v[180:183], v255 offset:1024
	ds_read_b128 v[184:187], v255 offset:2048
	ds_read_b128 v[188:191], v255 offset:3072
	s_cmp_eq_u32 s48, s12
	v_lshl_add_u64 v[192:193], v[130:131], 0, s[22:23]
	s_cselect_b64 vcc, -1, 0
	s_add_i32 s12, s12, 2
	v_cndmask_b32_e32 v197, v193, v177, vcc
	v_cndmask_b32_e32 v196, v192, v176, vcc
	v_cndmask_b32_e32 v213, v129, v179, vcc
	v_cndmask_b32_e32 v212, v128, v178, vcc
	s_mov_b32 m0, s56
	v_lshl_add_u64 v[214:215], v[130:131], 0, v[172:173]
	ds_read_b128 v[192:195], v202
	ds_read_b128 v[204:207], v202 offset:1024
	ds_read_b128 v[208:211], v202 offset:2048
	ds_read_b128 v[216:219], v202 offset:3072
	ds_read_b128 v[220:223], v202 offset:4096
	ds_read_b128 v[224:227], v202 offset:5120
	ds_read_b128 v[228:231], v202 offset:6144
	ds_read_b128 v[232:235], v202 offset:7168
	global_load_lds_dwordx4 v[214:215], off
	s_mov_b32 m0, s57
	v_lshl_add_u64 v[214:215], v[130:131], 0, v[170:171]
	global_load_lds_dwordx4 v[214:215], off
	s_waitcnt vmcnt(8) lgkmcnt(0)
	s_barrier
	v_mfma_f32_16x16x32_bf16 v[120:123], v[132:135], v[192:195], v[120:123]
	v_mfma_f32_16x16x32_bf16 v[124:127], v[140:143], v[192:195], v[124:127]
	v_mfma_f32_16x16x32_bf16 v[108:111], v[132:135], v[208:211], v[108:111]
	v_mfma_f32_16x16x32_bf16 v[104:107], v[140:143], v[208:211], v[104:107]
	v_mfma_f32_16x16x32_bf16 v[92:95], v[132:135], v[220:223], v[92:95]
	v_mfma_f32_16x16x32_bf16 v[88:91], v[140:143], v[220:223], v[88:91]
	v_mfma_f32_16x16x32_bf16 v[76:79], v[132:135], v[228:231], v[76:79]
	v_mfma_f32_16x16x32_bf16 v[72:75], v[140:143], v[228:231], v[72:75]
	v_mfma_f32_16x16x32_bf16 v[120:123], v[136:139], v[204:207], v[120:123]
	v_mfma_f32_16x16x32_bf16 v[124:127], v[144:147], v[204:207], v[124:127]
	v_mfma_f32_16x16x32_bf16 v[108:111], v[136:139], v[216:219], v[108:111]
	v_mfma_f32_16x16x32_bf16 v[104:107], v[144:147], v[216:219], v[104:107]
	v_mfma_f32_16x16x32_bf16 v[92:95], v[136:139], v[224:227], v[92:95]
	v_mfma_f32_16x16x32_bf16 v[88:91], v[144:147], v[224:227], v[88:91]
	v_mfma_f32_16x16x32_bf16 v[76:79], v[136:139], v[232:235], v[76:79]
	v_mfma_f32_16x16x32_bf16 v[72:75], v[144:147], v[232:235], v[72:75]
	v_mfma_f32_16x16x32_bf16 v[116:119], v[148:151], v[192:195], v[116:119]
	v_mfma_f32_16x16x32_bf16 v[112:115], v[184:187], v[192:195], v[112:115]
	v_mfma_f32_16x16x32_bf16 v[100:103], v[148:151], v[208:211], v[100:103]
	v_mfma_f32_16x16x32_bf16 v[96:99], v[184:187], v[208:211], v[96:99]
	v_mfma_f32_16x16x32_bf16 v[84:87], v[148:151], v[220:223], v[84:87]
	v_mfma_f32_16x16x32_bf16 v[80:83], v[184:187], v[220:223], v[80:83]
	v_mfma_f32_16x16x32_bf16 v[68:71], v[148:151], v[228:231], v[68:71]
	v_mfma_f32_16x16x32_bf16 v[64:67], v[184:187], v[228:231], v[64:67]
	v_mfma_f32_16x16x32_bf16 v[116:119], v[180:183], v[204:207], v[116:119]
	v_mfma_f32_16x16x32_bf16 v[112:115], v[188:191], v[204:207], v[112:115]
	v_mfma_f32_16x16x32_bf16 v[100:103], v[180:183], v[216:219], v[100:103]
	v_mfma_f32_16x16x32_bf16 v[96:99], v[188:191], v[216:219], v[96:99]
	v_mfma_f32_16x16x32_bf16 v[84:87], v[180:183], v[224:227], v[84:87]
	v_mfma_f32_16x16x32_bf16 v[80:83], v[188:191], v[224:227], v[80:83]
	v_mfma_f32_16x16x32_bf16 v[68:71], v[180:183], v[232:235], v[68:71]
	v_mfma_f32_16x16x32_bf16 v[64:67], v[188:191], v[232:235], v[64:67]
	s_barrier
	s_mov_b32 m0, s58
	v_lshl_add_u64 v[214:215], v[212:213], 0, v[164:165]
	ds_read_b128 v[192:195], v202 offset:16384
	ds_read_b128 v[204:207], v202 offset:17408
	ds_read_b128 v[208:211], v202 offset:18432
	ds_read_b128 v[216:219], v202 offset:19456
	ds_read_b128 v[220:223], v202 offset:20480
	ds_read_b128 v[224:227], v202 offset:21504
	ds_read_b128 v[228:231], v202 offset:22528
	ds_read_b128 v[232:235], v202 offset:23552
	global_load_lds_dwordx4 v[214:215], off
	v_lshl_add_u64 v[236:237], v[212:213], 0, v[168:169]
	s_mov_b32 m0, s59
	v_lshl_add_u64 v[212:213], v[212:213], 0, s[14:15]
	s_add_i32 s13, s55, s30
	global_load_lds_dwordx4 v[236:237], off
	v_lshl_add_u64 v[238:239], v[212:213], 0, v[164:165]
	s_mov_b32 m0, s13
	v_lshl_add_u64 v[212:213], v[212:213], 0, v[168:169]
	global_load_lds_dwordx4 v[238:239], off
	s_add_i32 m0, s13, 0x2000
	v_lshl_add_u64 v[240:241], v[196:197], 0, v[162:163]
	global_load_lds_dwordx4 v[212:213], off
	s_mov_b32 m0, s31
	v_lshl_add_u64 v[242:243], v[196:197], 0, v[166:167]
	global_load_lds_dwordx4 v[240:241], off
	s_mov_b32 m0, s34
	s_nop 0
	global_load_lds_dwordx4 v[242:243], off
	s_waitcnt vmcnt(8) lgkmcnt(0)
	s_barrier
; #define PG8_STAGE(bufoff, gbase, voff) do { _Pragma("unroll") for (int _i = 0; _i < 2; ++_i) \
;         __builtin_amdgcn_global_load_lds((const unsigned*)((const char*)(gbase) + (voff)[_i]), (PG8_LAS unsigned*)(lds + (bufoff) + ldsw + _i * 8192), 16, 0, 0); } while (0)
; #define PG8_LDA(dst, b, h) do { _Pragma("unroll") for (int m = 0; m < 4; ++m) _Pragma("unroll") for (int k = 0; k < 2; ++k) dst[m][k] = *(const PG8_LAS bf16x8*)(lds + PG8_SA(b, h) + aoff + m * 2048 + k * 1024); } while (0)
; #define PG8_LDB(dst, b, h) do { _Pragma("unroll") for (int n = 0; n < 2; ++n) _Pragma("unroll") for (int k = 0; k < 2; ++k) dst[n][k] = *(const PG8_LAS bf16x8*)(lds + PG8_SB(b, h) + boff + n * 2048 + k * 1024); } while (0)
; #define PG8_MMA(ai, bj, At, Bt) do { __builtin_amdgcn_s_setprio(1); _Pragma("unroll") for (int m = 0; m < 4; ++m) _Pragma("unroll") for (int n = 0; n < 2; ++n) _Pragma("unroll") for (int k = 0; k < 2; ++k) \
;         acc[ai][bj][m][n] = __builtin_amdgcn_mfma_f32_16x16x32_bf16(Bt[n][k], At[m][k], acc[ai][bj][m][n], 0, 0, 0); __builtin_amdgcn_s_setprio(0); } while (0)
; #define PG8_WAIT_V(n) asm volatile("s_waitcnt vmcnt(" #n ")" ::: "memory")
; #define PG8_WAIT_L(n) asm volatile("s_waitcnt lgkmcnt(" #n ")" ::: "memory")
; #define PG8_BAR __builtin_amdgcn_s_barrier()
; #define PG8_SCHED __builtin_amdgcn_sched_barrier(0)
; template <class Epi, class Sched, bool ALIGN_EPI = false, bool SP2 = false>
; __device__ __forceinline__ void gemm_phase(PG8_LAS unsigned char* lds, const Gemm g, const Sched& S, const Epi& E) {
;     ...
;             PG8_WAIT_V(8); PG8_WAIT_L(0); PG8_BAR; PG8_MMA(1, 0, At, B0); PG8_MMA(1, 1, At, B1); PG8_BAR; PG8_SCHED;
;             PG8_LDB(B0, 1, 0); PG8_LDB(B1, 1, 1); PG8_SCHED; PG8_LDA(At, 1, 0); PG8_STAGE(PG8_SA(0, 1), a2 + hstep, voffA);
;             PG8_WAIT_V(8); PG8_WAIT_L(0); PG8_BAR; PG8_MMA(0, 0, At, B0); PG8_MMA(0, 1, At, B1); PG8_BAR; PG8_SCHED;
	v_mfma_f32_16x16x32_bf16 v[60:63], v[132:135], v[192:195], v[60:63]
	v_mfma_f32_16x16x32_bf16 v[56:59], v[140:143], v[192:195], v[56:59]
	v_mfma_f32_16x16x32_bf16 v[44:47], v[132:135], v[208:211], v[44:47]
	v_mfma_f32_16x16x32_bf16 v[40:43], v[140:143], v[208:211], v[40:43]
	v_mfma_f32_16x16x32_bf16 v[28:31], v[132:135], v[220:223], v[28:31]
	v_mfma_f32_16x16x32_bf16 v[24:27], v[140:143], v[220:223], v[24:27]
	v_mfma_f32_16x16x32_bf16 v[12:15], v[132:135], v[228:231], v[12:15]
	v_mfma_f32_16x16x32_bf16 v[8:11], v[140:143], v[228:231], v[8:11]
	v_mfma_f32_16x16x32_bf16 v[60:63], v[136:139], v[204:207], v[60:63]
	v_mfma_f32_16x16x32_bf16 v[56:59], v[144:147], v[204:207], v[56:59]
	v_mfma_f32_16x16x32_bf16 v[44:47], v[136:139], v[216:219], v[44:47]
	v_mfma_f32_16x16x32_bf16 v[40:43], v[144:147], v[216:219], v[40:43]
	v_mfma_f32_16x16x32_bf16 v[28:31], v[136:139], v[224:227], v[28:31]
	v_mfma_f32_16x16x32_bf16 v[24:27], v[144:147], v[224:227], v[24:27]
	v_mfma_f32_16x16x32_bf16 v[12:15], v[136:139], v[232:235], v[12:15]
	v_mfma_f32_16x16x32_bf16 v[8:11], v[144:147], v[232:235], v[8:11]
	v_mfma_f32_16x16x32_bf16 v[52:55], v[148:151], v[192:195], v[52:55]
	v_mfma_f32_16x16x32_bf16 v[48:51], v[184:187], v[192:195], v[48:51]
	v_mfma_f32_16x16x32_bf16 v[36:39], v[148:151], v[208:211], v[36:39]
	v_mfma_f32_16x16x32_bf16 v[32:35], v[184:187], v[208:211], v[32:35]
	v_mfma_f32_16x16x32_bf16 v[20:23], v[148:151], v[220:223], v[20:23]
	v_mfma_f32_16x16x32_bf16 v[16:19], v[184:187], v[220:223], v[16:19]
	v_mfma_f32_16x16x32_bf16 v[4:7], v[148:151], v[228:231], v[4:7]
	v_mfma_f32_16x16x32_bf16 v[0:3], v[184:187], v[228:231], v[0:3]
	v_mfma_f32_16x16x32_bf16 v[52:55], v[180:183], v[204:207], v[52:55]
	v_mfma_f32_16x16x32_bf16 v[48:51], v[188:191], v[204:207], v[48:51]
	v_mfma_f32_16x16x32_bf16 v[36:39], v[180:183], v[216:219], v[36:39]
	v_mfma_f32_16x16x32_bf16 v[32:35], v[188:191], v[216:219], v[32:35]
	v_mfma_f32_16x16x32_bf16 v[20:23], v[180:183], v[224:227], v[20:23]
	v_mfma_f32_16x16x32_bf16 v[16:19], v[188:191], v[224:227], v[16:19]
	v_mfma_f32_16x16x32_bf16 v[4:7], v[180:183], v[232:235], v[4:7]
	v_mfma_f32_16x16x32_bf16 v[0:3], v[188:191], v[232:235], v[0:3]
	s_barrier
	s_add_i32 s13, 0, 0x18000
	s_add_i32 s29, 0, 0x1c000
	ds_read_b128 v[132:135], v255 offset:16384
	ds_read_b128 v[136:139], v255 offset:17408
	ds_read_b128 v[140:143], v255 offset:18432
	ds_read_b128 v[144:147], v255 offset:19456
	ds_read_b128 v[148:151], v255 offset:32768
	ds_read_b128 v[180:183], v255 offset:33792
	ds_read_b128 v[184:187], v255 offset:34816
	ds_read_b128 v[188:191], v255 offset:35840
	v_lshl_add_u64 v[196:197], v[196:197], 0, s[14:15]
	s_mov_b32 m0, s35
	v_lshl_add_u64 v[244:245], v[196:197], 0, v[162:163]
	ds_read_b128 v[192:195], v202 offset:32768
	ds_read_b128 v[204:207], v202 offset:33792
	ds_read_b128 v[208:211], v202 offset:34816
	ds_read_b128 v[216:219], v202 offset:35840
	ds_read_b128 v[220:223], v202 offset:36864
	ds_read_b128 v[224:227], v202 offset:37888
	ds_read_b128 v[228:231], v202 offset:38912
	ds_read_b128 v[232:235], v202 offset:39936
	global_load_lds_dwordx4 v[244:245], off
	s_mov_b32 m0, s36
	v_lshl_add_u64 v[196:197], v[196:197], 0, v[166:167]
	global_load_lds_dwordx4 v[196:197], off
	s_waitcnt vmcnt(8) lgkmcnt(0)
	s_barrier
	v_mfma_f32_16x16x32_bf16 v[120:123], v[132:135], v[192:195], v[120:123]
	v_mfma_f32_16x16x32_bf16 v[124:127], v[140:143], v[192:195], v[124:127]
	v_mfma_f32_16x16x32_bf16 v[108:111], v[132:135], v[208:211], v[108:111]
	v_mfma_f32_16x16x32_bf16 v[104:107], v[140:143], v[208:211], v[104:107]
	v_mfma_f32_16x16x32_bf16 v[92:95], v[132:135], v[220:223], v[92:95]
	v_mfma_f32_16x16x32_bf16 v[88:91], v[140:143], v[220:223], v[88:91]
	v_mfma_f32_16x16x32_bf16 v[76:79], v[132:135], v[228:231], v[76:79]
	v_mfma_f32_16x16x32_bf16 v[72:75], v[140:143], v[228:231], v[72:75]
	v_mfma_f32_16x16x32_bf16 v[120:123], v[136:139], v[204:207], v[120:123]
	v_mfma_f32_16x16x32_bf16 v[124:127], v[144:147], v[204:207], v[124:127]
	v_mfma_f32_16x16x32_bf16 v[108:111], v[136:139], v[216:219], v[108:111]
	v_mfma_f32_16x16x32_bf16 v[104:107], v[144:147], v[216:219], v[104:107]
	v_mfma_f32_16x16x32_bf16 v[92:95], v[136:139], v[224:227], v[92:95]
	v_mfma_f32_16x16x32_bf16 v[88:91], v[144:147], v[224:227], v[88:91]
	v_mfma_f32_16x16x32_bf16 v[76:79], v[136:139], v[232:235], v[76:79]
	v_mfma_f32_16x16x32_bf16 v[72:75], v[144:147], v[232:235], v[72:75]
	v_mfma_f32_16x16x32_bf16 v[116:119], v[148:151], v[192:195], v[116:119]
	v_mfma_f32_16x16x32_bf16 v[112:115], v[184:187], v[192:195], v[112:115]
	v_mfma_f32_16x16x32_bf16 v[100:103], v[148:151], v[208:211], v[100:103]
	v_mfma_f32_16x16x32_bf16 v[96:99], v[184:187], v[208:211], v[96:99]
	v_mfma_f32_16x16x32_bf16 v[84:87], v[148:151], v[220:223], v[84:87]
	v_mfma_f32_16x16x32_bf16 v[80:83], v[184:187], v[220:223], v[80:83]
	v_mfma_f32_16x16x32_bf16 v[68:71], v[148:151], v[228:231], v[68:71]
	v_mfma_f32_16x16x32_bf16 v[64:67], v[184:187], v[228:231], v[64:67]
	v_mfma_f32_16x16x32_bf16 v[116:119], v[180:183], v[204:207], v[116:119]
	v_mfma_f32_16x16x32_bf16 v[112:115], v[188:191], v[204:207], v[112:115]
	v_mfma_f32_16x16x32_bf16 v[100:103], v[180:183], v[216:219], v[100:103]
	v_mfma_f32_16x16x32_bf16 v[96:99], v[188:191], v[216:219], v[96:99]
	v_mfma_f32_16x16x32_bf16 v[84:87], v[180:183], v[224:227], v[84:87]
	v_mfma_f32_16x16x32_bf16 v[80:83], v[188:191], v[224:227], v[80:83]
	v_mfma_f32_16x16x32_bf16 v[68:71], v[180:183], v[232:235], v[68:71]
	v_mfma_f32_16x16x32_bf16 v[64:67], v[188:191], v[232:235], v[64:67]
	s_barrier
; #define PG8_STAGE(bufoff, gbase, voff) do { _Pragma("unroll") for (int _i = 0; _i < 2; ++_i) \
;         __builtin_amdgcn_global_load_lds((const unsigned*)((const char*)(gbase) + (voff)[_i]), (PG8_LAS unsigned*)(lds + (bufoff) + ldsw + _i * 8192), 16, 0, 0); } while (0)
; #define PG8_LDA(dst, b, h) do { _Pragma("unroll") for (int m = 0; m < 4; ++m) _Pragma("unroll") for (int k = 0; k < 2; ++k) dst[m][k] = *(const PG8_LAS bf16x8*)(lds + PG8_SA(b, h) + aoff + m * 2048 + k * 1024); } while (0)
; #define PG8_MMA(ai, bj, At, Bt) do { __builtin_amdgcn_s_setprio(1); _Pragma("unroll") for (int m = 0; m < 4; ++m) _Pragma("unroll") for (int n = 0; n < 2; ++n) _Pragma("unroll") for (int k = 0; k < 2; ++k) \
;         acc[ai][bj][m][n] = __builtin_amdgcn_mfma_f32_16x16x32_bf16(Bt[n][k], At[m][k], acc[ai][bj][m][n], 0, 0, 0); __builtin_amdgcn_s_setprio(0); } while (0)
; #define PG8_WAIT_V(n) asm volatile("s_waitcnt vmcnt(" #n ")" ::: "memory")
; #define PG8_WAIT_L(n) asm volatile("s_waitcnt lgkmcnt(" #n ")" ::: "memory")
; #define PG8_BAR __builtin_amdgcn_s_barrier()
; #define PG8_SCHED __builtin_amdgcn_sched_barrier(0)
; template <class Epi, class Sched, bool ALIGN_EPI = false, bool SP2 = false>
; __device__ __forceinline__ void gemm_phase(PG8_LAS unsigned char* lds, const Gemm g, const Sched& S, const Epi& E) {
;     ...
;         for (int t = 0; t < nt; t += 2) {
;     ...
;             PG8_LDA(At, 1, 1); PG8_STAGE(PG8_SB(1, 0), b3, voffB); PG8_STAGE(PG8_SB(1, 1), b3 + hstep, voffB); PG8_STAGE(PG8_SA(1, 0), a3, voffA);
;             PG8_WAIT_V(8); PG8_WAIT_L(0); PG8_BAR; PG8_MMA(1, 0, At, B0); PG8_MMA(1, 1, At, B1); PG8_BAR; PG8_SCHED;
	s_add_i32 s13, s13, s30
	s_add_i32 m0, s13, 0xffffff80
	ds_read_b128 v[192:195], v202 offset:49152
	ds_read_b128 v[204:207], v202 offset:50176
	ds_read_b128 v[208:211], v202 offset:51200
	ds_read_b128 v[216:219], v202 offset:52224
	global_load_lds_dwordx4 v[214:215], off offset:128
	s_add_i32 m0, s13, 0x1f80
	s_add_i32 s13, s29, s30
	global_load_lds_dwordx4 v[236:237], off offset:128
	s_add_i32 m0, s13, 0xffffff80
	ds_read_b128 v[232:235], v202 offset:56320
	global_load_lds_dwordx4 v[238:239], off offset:128
	s_add_i32 m0, s13, 0x1f80
	ds_read_b128 v[228:231], v202 offset:55296
	global_load_lds_dwordx4 v[212:213], off offset:128
	s_add_i32 m0, s37, 0xffffff80
	ds_read_b128 v[224:227], v202 offset:54272
	global_load_lds_dwordx4 v[240:241], off offset:128
	s_add_i32 m0, s41, 0xffffff80
	ds_read_b128 v[220:223], v202 offset:53248
	global_load_lds_dwordx4 v[242:243], off offset:128
	s_waitcnt vmcnt(8) lgkmcnt(0)
	s_barrier
	v_mfma_f32_16x16x32_bf16 v[60:63], v[132:135], v[192:195], v[60:63]
	v_mfma_f32_16x16x32_bf16 v[56:59], v[140:143], v[192:195], v[56:59]
	v_mfma_f32_16x16x32_bf16 v[44:47], v[132:135], v[208:211], v[44:47]
	v_mfma_f32_16x16x32_bf16 v[40:43], v[140:143], v[208:211], v[40:43]
	v_mfma_f32_16x16x32_bf16 v[28:31], v[132:135], v[220:223], v[28:31]
	v_mfma_f32_16x16x32_bf16 v[24:27], v[140:143], v[220:223], v[24:27]
	v_mfma_f32_16x16x32_bf16 v[12:15], v[132:135], v[228:231], v[12:15]
	v_mfma_f32_16x16x32_bf16 v[8:11], v[140:143], v[228:231], v[8:11]
	v_mfma_f32_16x16x32_bf16 v[60:63], v[136:139], v[204:207], v[60:63]
	v_mfma_f32_16x16x32_bf16 v[56:59], v[144:147], v[204:207], v[56:59]
	v_mfma_f32_16x16x32_bf16 v[44:47], v[136:139], v[216:219], v[44:47]
	v_mfma_f32_16x16x32_bf16 v[40:43], v[144:147], v[216:219], v[40:43]
	v_mfma_f32_16x16x32_bf16 v[28:31], v[136:139], v[224:227], v[28:31]
	v_mfma_f32_16x16x32_bf16 v[24:27], v[144:147], v[224:227], v[24:27]
	v_mfma_f32_16x16x32_bf16 v[12:15], v[136:139], v[232:235], v[12:15]
	v_mfma_f32_16x16x32_bf16 v[8:11], v[144:147], v[232:235], v[8:11]
	v_mfma_f32_16x16x32_bf16 v[52:55], v[148:151], v[192:195], v[52:55]
	v_mfma_f32_16x16x32_bf16 v[48:51], v[184:187], v[192:195], v[48:51]
	v_mfma_f32_16x16x32_bf16 v[36:39], v[148:151], v[208:211], v[36:39]
	v_mfma_f32_16x16x32_bf16 v[32:35], v[184:187], v[208:211], v[32:35]
	v_mfma_f32_16x16x32_bf16 v[20:23], v[148:151], v[220:223], v[20:23]
	v_mfma_f32_16x16x32_bf16 v[16:19], v[184:187], v[220:223], v[16:19]
	v_mfma_f32_16x16x32_bf16 v[4:7], v[148:151], v[228:231], v[4:7]
	v_mfma_f32_16x16x32_bf16 v[0:3], v[184:187], v[228:231], v[0:3]
	v_mfma_f32_16x16x32_bf16 v[52:55], v[180:183], v[204:207], v[52:55]
	v_mfma_f32_16x16x32_bf16 v[48:51], v[188:191], v[204:207], v[48:51]
	v_mfma_f32_16x16x32_bf16 v[36:39], v[180:183], v[216:219], v[36:39]
	v_mfma_f32_16x16x32_bf16 v[32:35], v[188:191], v[216:219], v[32:35]
	v_mfma_f32_16x16x32_bf16 v[20:23], v[180:183], v[224:227], v[20:23]
	v_mfma_f32_16x16x32_bf16 v[16:19], v[188:191], v[224:227], v[16:19]
	v_mfma_f32_16x16x32_bf16 v[4:7], v[180:183], v[232:235], v[4:7]
	v_mfma_f32_16x16x32_bf16 v[0:3], v[188:191], v[232:235], v[0:3]
	s_barrier
	v_lshl_add_u64 v[128:129], v[128:129], 0, s[26:27]
	s_cmp_ge_i32 s12, s47
	v_lshl_add_u64 v[130:131], v[130:131], 0, s[26:27]
	s_cbranch_scc0 .LBB0_940

; #define PG8_STAGE(bufoff, gbase, voff) do { _Pragma("unroll") for (int _i = 0; _i < 2; ++_i) \
;         __builtin_amdgcn_global_load_lds((const unsigned*)((const char*)(gbase) + (voff)[_i]), (PG8_LAS unsigned*)(lds + (bufoff) + ldsw + _i * 8192), 16, 0, 0); } while (0)
; #define PG8_LDA(dst, b, h) do { _Pragma("unroll") for (int m = 0; m < 4; ++m) _Pragma("unroll") for (int k = 0; k < 2; ++k) dst[m][k] = *(const PG8_LAS bf16x8*)(lds + PG8_SA(b, h) + aoff + m * 2048 + k * 1024); } while (0)
; #define PG8_LDB(dst, b, h) do { _Pragma("unroll") for (int n = 0; n < 2; ++n) _Pragma("unroll") for (int k = 0; k < 2; ++k) dst[n][k] = *(const PG8_LAS bf16x8*)(lds + PG8_SB(b, h) + boff + n * 2048 + k * 1024); } while (0)
; #define PG8_MMA(ai, bj, At, Bt) do { __builtin_amdgcn_s_setprio(1); _Pragma("unroll") for (int m = 0; m < 4; ++m) _Pragma("unroll") for (int n = 0; n < 2; ++n) _Pragma("unroll") for (int k = 0; k < 2; ++k) \
;         acc[ai][bj][m][n] = __builtin_amdgcn_mfma_f32_16x16x32_bf16(Bt[n][k], At[m][k], acc[ai][bj][m][n], 0, 0, 0); __builtin_amdgcn_s_setprio(0); } while (0)
; #define PG8_WAIT_V(n) asm volatile("s_waitcnt vmcnt(" #n ")" ::: "memory")
; #define PG8_BAR __builtin_amdgcn_s_barrier()
; template <class Epi, class Sched, bool ALIGN_EPI = false, bool SP2 = false>
; __device__ __forceinline__ void gemm_phase(PG8_LAS unsigned char* lds, const Gemm g, const Sched& S, const Epi& E) {
;     ...
;         for (int t = 0; t < nt; t += 2) {
;             const bool last = (t == nt - 2);
;             const char* a1 = cA + (size_t)(t + 1) * kstep;
;             const char* a2 = last ? nA : cA + (size_t)(t + 2) * kstep; const char* b2 = last ? nB : cB + (size_t)(t + 2) * kstep;
;             const char* a3 = a2 + kstep; const char* b3 = b2 + kstep;
;             if (last && has_next) S.a_ready(nxt);
;             if constexpr (SP2) {
;             PG8_LDB(B0, 0, 0); PG8_LDB(B1, 0, 1); PG8_SCHED; PG8_LDA(At, 0, 0); PG8_STAGE(PG8_SA(1, 1), a1 + hstep, voffA);
;             PG8_WAIT_V(8); PG8_WAIT_L(0); PG8_BAR; PG8_MMA(0, 0, At, B0); PG8_MMA(0, 1, At, B1); PG8_BAR; PG8_SCHED;
;             PG8_LDA(At, 0, 1); PG8_STAGE(PG8_SB(0, 0), b2, voffB); PG8_STAGE(PG8_SB(0, 1), b2 + hstep, voffB); PG8_STAGE(PG8_SA(0, 0), a2, voffA);
;             PG8_WAIT_V(8); PG8_WAIT_L(0); PG8_BAR; PG8_MMA(1, 0, At, B0); PG8_MMA(1, 1, At, B1); PG8_BAR; PG8_SCHED;
.LBB0_1021:
	v_add_u32_e32 v166, s55, v169
	ds_read_b128 v[162:165], v166
	ds_read_b128 v[182:185], v166 offset:1024
	ds_read_b128 v[186:189], v166 offset:2048
	ds_read_b128 v[190:193], v166 offset:3072
	ds_read_b128 v[194:197], v166 offset:16384
	ds_read_b128 v[198:201], v166 offset:17408
	ds_read_b128 v[202:205], v166 offset:18432
	ds_read_b128 v[206:209], v166 offset:19456
	s_cmp_eq_u32 s54, s10
	v_lshl_add_u64 v[172:173], v[160:161], 0, s[22:23]
	s_cselect_b64 vcc, -1, 0
	s_add_i32 s10, s10, 2
	v_cndmask_b32_e32 v173, v173, v153, vcc
	v_cndmask_b32_e32 v172, v172, v152, vcc
	v_cndmask_b32_e32 v215, v159, v155, vcc
	v_cndmask_b32_e32 v214, v158, v154, vcc
	s_mov_b32 m0, s57
	v_lshl_add_u64 v[244:245], v[160:161], 0, v[148:149]
	ds_read_b128 v[210:213], v179
	ds_read_b128 v[216:219], v179 offset:1024
	ds_read_b128 v[220:223], v179 offset:2048
	ds_read_b128 v[224:227], v179 offset:3072
	ds_read_b128 v[228:231], v179 offset:4096
	ds_read_b128 v[232:235], v179 offset:5120
	ds_read_b128 v[236:239], v179 offset:6144
	ds_read_b128 v[240:243], v179 offset:7168
	global_load_lds_dwordx4 v[244:245], off
	s_mov_b32 m0, s58
	v_lshl_add_u64 v[244:245], v[160:161], 0, v[146:147]
	global_load_lds_dwordx4 v[244:245], off
	s_waitcnt vmcnt(8) lgkmcnt(0)
	s_barrier
	v_mfma_f32_16x16x32_bf16 v[124:127], v[162:165], v[210:213], v[124:127]
	v_mfma_f32_16x16x32_bf16 v[116:119], v[186:189], v[210:213], v[116:119]
	v_mfma_f32_16x16x32_bf16 v[108:111], v[162:165], v[220:223], v[108:111]
	v_mfma_f32_16x16x32_bf16 v[100:103], v[186:189], v[220:223], v[100:103]
	v_mfma_f32_16x16x32_bf16 v[92:95], v[162:165], v[228:231], v[92:95]
	v_mfma_f32_16x16x32_bf16 v[84:87], v[186:189], v[228:231], v[84:87]
	v_mfma_f32_16x16x32_bf16 v[76:79], v[162:165], v[236:239], v[76:79]
	v_mfma_f32_16x16x32_bf16 v[68:71], v[186:189], v[236:239], v[68:71]
	v_mfma_f32_16x16x32_bf16 v[124:127], v[182:185], v[216:219], v[124:127]
	v_mfma_f32_16x16x32_bf16 v[116:119], v[190:193], v[216:219], v[116:119]
	v_mfma_f32_16x16x32_bf16 v[108:111], v[182:185], v[224:227], v[108:111]
	v_mfma_f32_16x16x32_bf16 v[100:103], v[190:193], v[224:227], v[100:103]
	v_mfma_f32_16x16x32_bf16 v[92:95], v[182:185], v[232:235], v[92:95]
	v_mfma_f32_16x16x32_bf16 v[84:87], v[190:193], v[232:235], v[84:87]
	v_mfma_f32_16x16x32_bf16 v[76:79], v[182:185], v[240:243], v[76:79]
	v_mfma_f32_16x16x32_bf16 v[68:71], v[190:193], v[240:243], v[68:71]
	v_mfma_f32_16x16x32_bf16 v[120:123], v[194:197], v[210:213], v[120:123]
	v_mfma_f32_16x16x32_bf16 v[112:115], v[202:205], v[210:213], v[112:115]
	v_mfma_f32_16x16x32_bf16 v[104:107], v[194:197], v[220:223], v[104:107]
	v_mfma_f32_16x16x32_bf16 v[96:99], v[202:205], v[220:223], v[96:99]
	v_mfma_f32_16x16x32_bf16 v[88:91], v[194:197], v[228:231], v[88:91]
	v_mfma_f32_16x16x32_bf16 v[80:83], v[202:205], v[228:231], v[80:83]
	v_mfma_f32_16x16x32_bf16 v[72:75], v[194:197], v[236:239], v[72:75]
	v_mfma_f32_16x16x32_bf16 v[64:67], v[202:205], v[236:239], v[64:67]
	v_mfma_f32_16x16x32_bf16 v[120:123], v[198:201], v[216:219], v[120:123]
	v_mfma_f32_16x16x32_bf16 v[112:115], v[206:209], v[216:219], v[112:115]
	v_mfma_f32_16x16x32_bf16 v[104:107], v[198:201], v[224:227], v[104:107]
	v_mfma_f32_16x16x32_bf16 v[96:99], v[206:209], v[224:227], v[96:99]
	v_mfma_f32_16x16x32_bf16 v[88:91], v[198:201], v[232:235], v[88:91]
	v_mfma_f32_16x16x32_bf16 v[80:83], v[206:209], v[232:235], v[80:83]
	v_mfma_f32_16x16x32_bf16 v[72:75], v[198:201], v[240:243], v[72:75]
	v_mfma_f32_16x16x32_bf16 v[64:67], v[206:209], v[240:243], v[64:67]
	s_barrier
	s_mov_b32 m0, s61
	v_lshl_add_u64 v[244:245], v[214:215], 0, v[138:139]
	ds_read_b128 v[210:213], v179 offset:16384
	ds_read_b128 v[216:219], v179 offset:17408
	ds_read_b128 v[220:223], v179 offset:18432
	ds_read_b128 v[224:227], v179 offset:19456
	ds_read_b128 v[228:231], v179 offset:20480
	ds_read_b128 v[232:235], v179 offset:21504
	ds_read_b128 v[236:239], v179 offset:22528
	ds_read_b128 v[240:243], v179 offset:23552
	global_load_lds_dwordx4 v[244:245], off
	v_lshl_add_u64 v[246:247], v[214:215], 0, v[134:135]
	s_mov_b32 m0, s62
	v_lshl_add_u64 v[214:215], v[214:215], 0, s[14:15]
	global_load_lds_dwordx4 v[246:247], off
	v_lshl_add_u64 v[248:249], v[214:215], 0, v[138:139]
	s_mov_b32 m0, s63
	v_lshl_add_u64 v[214:215], v[214:215], 0, v[134:135]
	global_load_lds_dwordx4 v[248:249], off
	s_add_i32 m0, s63, 0x2000
	v_lshl_add_u64 v[250:251], v[172:173], 0, v[140:141]
	global_load_lds_dwordx4 v[214:215], off
	s_mov_b32 m0, s46
	v_lshl_add_u64 v[252:253], v[172:173], 0, v[136:137]
	global_load_lds_dwordx4 v[250:251], off
	s_mov_b32 m0, s47
	s_nop 0
	global_load_lds_dwordx4 v[252:253], off
	s_waitcnt vmcnt(8) lgkmcnt(0)
	s_barrier
; #define PG8_STAGE(bufoff, gbase, voff) do { _Pragma("unroll") for (int _i = 0; _i < 2; ++_i) \
;         __builtin_amdgcn_global_load_lds((const unsigned*)((const char*)(gbase) + (voff)[_i]), (PG8_LAS unsigned*)(lds + (bufoff) + ldsw + _i * 8192), 16, 0, 0); } while (0)
; #define PG8_LDA(dst, b, h) do { _Pragma("unroll") for (int m = 0; m < 4; ++m) _Pragma("unroll") for (int k = 0; k < 2; ++k) dst[m][k] = *(const PG8_LAS bf16x8*)(lds + PG8_SA(b, h) + aoff + m * 2048 + k * 1024); } while (0)
; #define PG8_LDB(dst, b, h) do { _Pragma("unroll") for (int n = 0; n < 2; ++n) _Pragma("unroll") for (int k = 0; k < 2; ++k) dst[n][k] = *(const PG8_LAS bf16x8*)(lds + PG8_SB(b, h) + boff + n * 2048 + k * 1024); } while (0)
; #define PG8_MMA(ai, bj, At, Bt) do { __builtin_amdgcn_s_setprio(1); _Pragma("unroll") for (int m = 0; m < 4; ++m) _Pragma("unroll") for (int n = 0; n < 2; ++n) _Pragma("unroll") for (int k = 0; k < 2; ++k) \
;         acc[ai][bj][m][n] = __builtin_amdgcn_mfma_f32_16x16x32_bf16(Bt[n][k], At[m][k], acc[ai][bj][m][n], 0, 0, 0); __builtin_amdgcn_s_setprio(0); } while (0)
; #define PG8_WAIT_V(n) asm volatile("s_waitcnt vmcnt(" #n ")" ::: "memory")
; #define PG8_WAIT_L(n) asm volatile("s_waitcnt lgkmcnt(" #n ")" ::: "memory")
; #define PG8_BAR __builtin_amdgcn_s_barrier()
; #define PG8_SCHED __builtin_amdgcn_sched_barrier(0)
; template <class Epi, class Sched, bool ALIGN_EPI = false, bool SP2 = false>
; __device__ __forceinline__ void gemm_phase(PG8_LAS unsigned char* lds, const Gemm g, const Sched& S, const Epi& E) {
;     ...
;             PG8_WAIT_V(8); PG8_WAIT_L(0); PG8_BAR; PG8_MMA(1, 0, At, B0); PG8_MMA(1, 1, At, B1); PG8_BAR; PG8_SCHED;
;             PG8_LDB(B0, 1, 0); PG8_LDB(B1, 1, 1); PG8_SCHED; PG8_LDA(At, 1, 0); PG8_STAGE(PG8_SA(0, 1), a2 + hstep, voffA);
;             PG8_WAIT_V(8); PG8_WAIT_L(0); PG8_BAR; PG8_MMA(0, 0, At, B0); PG8_MMA(0, 1, At, B1); PG8_BAR; PG8_SCHED;
	v_mfma_f32_16x16x32_bf16 v[60:63], v[162:165], v[210:213], v[60:63]
	v_mfma_f32_16x16x32_bf16 v[52:55], v[186:189], v[210:213], v[52:55]
	v_mfma_f32_16x16x32_bf16 v[44:47], v[162:165], v[220:223], v[44:47]
	v_mfma_f32_16x16x32_bf16 v[36:39], v[186:189], v[220:223], v[36:39]
	v_mfma_f32_16x16x32_bf16 v[28:31], v[162:165], v[228:231], v[28:31]
	v_mfma_f32_16x16x32_bf16 v[20:23], v[186:189], v[228:231], v[20:23]
	v_mfma_f32_16x16x32_bf16 v[12:15], v[162:165], v[236:239], v[12:15]
	v_mfma_f32_16x16x32_bf16 v[4:7], v[186:189], v[236:239], v[4:7]
	v_mfma_f32_16x16x32_bf16 v[60:63], v[182:185], v[216:219], v[60:63]
	v_mfma_f32_16x16x32_bf16 v[52:55], v[190:193], v[216:219], v[52:55]
	v_mfma_f32_16x16x32_bf16 v[44:47], v[182:185], v[224:227], v[44:47]
	v_mfma_f32_16x16x32_bf16 v[36:39], v[190:193], v[224:227], v[36:39]
	v_mfma_f32_16x16x32_bf16 v[28:31], v[182:185], v[232:235], v[28:31]
	v_mfma_f32_16x16x32_bf16 v[20:23], v[190:193], v[232:235], v[20:23]
	v_mfma_f32_16x16x32_bf16 v[12:15], v[182:185], v[240:243], v[12:15]
	v_mfma_f32_16x16x32_bf16 v[4:7], v[190:193], v[240:243], v[4:7]
	v_mfma_f32_16x16x32_bf16 v[56:59], v[194:197], v[210:213], v[56:59]
	v_mfma_f32_16x16x32_bf16 v[48:51], v[202:205], v[210:213], v[48:51]
	v_mfma_f32_16x16x32_bf16 v[40:43], v[194:197], v[220:223], v[40:43]
	v_mfma_f32_16x16x32_bf16 v[32:35], v[202:205], v[220:223], v[32:35]
	v_mfma_f32_16x16x32_bf16 v[24:27], v[194:197], v[228:231], v[24:27]
	v_mfma_f32_16x16x32_bf16 v[16:19], v[202:205], v[228:231], v[16:19]
	v_mfma_f32_16x16x32_bf16 v[8:11], v[194:197], v[236:239], v[8:11]
	v_mfma_f32_16x16x32_bf16 v[0:3], v[202:205], v[236:239], v[0:3]
	v_mfma_f32_16x16x32_bf16 v[56:59], v[198:201], v[216:219], v[56:59]
	v_mfma_f32_16x16x32_bf16 v[48:51], v[206:209], v[216:219], v[48:51]
	v_mfma_f32_16x16x32_bf16 v[40:43], v[198:201], v[224:227], v[40:43]
	v_mfma_f32_16x16x32_bf16 v[32:35], v[206:209], v[224:227], v[32:35]
	v_mfma_f32_16x16x32_bf16 v[24:27], v[198:201], v[232:235], v[24:27]
	v_mfma_f32_16x16x32_bf16 v[16:19], v[206:209], v[232:235], v[16:19]
	v_mfma_f32_16x16x32_bf16 v[8:11], v[198:201], v[240:243], v[8:11]
	v_mfma_f32_16x16x32_bf16 v[0:3], v[206:209], v[240:243], v[0:3]
	s_barrier
	s_add_i32 s11, 0, 0x18000
	s_add_i32 s13, 0, 0x1c000
	ds_read_b128 v[162:165], v166 offset:32768
	ds_read_b128 v[182:185], v166 offset:33792
	ds_read_b128 v[186:189], v166 offset:34816
	ds_read_b128 v[190:193], v166 offset:35840
	ds_read_b128 v[194:197], v166 offset:49152
	ds_read_b128 v[198:201], v166 offset:50176
	ds_read_b128 v[202:205], v166 offset:51200
	ds_read_b128 v[206:209], v166 offset:52224
	v_lshl_add_u64 v[172:173], v[172:173], 0, s[14:15]
	s_mov_b32 m0, s48
	v_lshl_add_u64 v[170:171], v[172:173], 0, v[140:141]
	ds_read_b128 v[210:213], v179 offset:32768
	ds_read_b128 v[216:219], v179 offset:33792
	ds_read_b128 v[220:223], v179 offset:34816
	ds_read_b128 v[224:227], v179 offset:35840
	ds_read_b128 v[228:231], v179 offset:36864
	ds_read_b128 v[232:235], v179 offset:37888
	ds_read_b128 v[236:239], v179 offset:38912
	ds_read_b128 v[240:243], v179 offset:39936
	global_load_lds_dwordx4 v[170:171], off
	s_mov_b32 m0, s49
	v_lshl_add_u64 v[170:171], v[172:173], 0, v[136:137]
	global_load_lds_dwordx4 v[170:171], off
	s_waitcnt vmcnt(8) lgkmcnt(0)
	s_barrier
	v_mfma_f32_16x16x32_bf16 v[124:127], v[162:165], v[210:213], v[124:127]
	v_mfma_f32_16x16x32_bf16 v[116:119], v[186:189], v[210:213], v[116:119]
	v_mfma_f32_16x16x32_bf16 v[108:111], v[162:165], v[220:223], v[108:111]
	v_mfma_f32_16x16x32_bf16 v[100:103], v[186:189], v[220:223], v[100:103]
	v_mfma_f32_16x16x32_bf16 v[92:95], v[162:165], v[228:231], v[92:95]
	v_mfma_f32_16x16x32_bf16 v[84:87], v[186:189], v[228:231], v[84:87]
	v_mfma_f32_16x16x32_bf16 v[76:79], v[162:165], v[236:239], v[76:79]
	v_mfma_f32_16x16x32_bf16 v[68:71], v[186:189], v[236:239], v[68:71]
	v_mfma_f32_16x16x32_bf16 v[124:127], v[182:185], v[216:219], v[124:127]
	v_mfma_f32_16x16x32_bf16 v[116:119], v[190:193], v[216:219], v[116:119]
	v_mfma_f32_16x16x32_bf16 v[108:111], v[182:185], v[224:227], v[108:111]
	v_mfma_f32_16x16x32_bf16 v[100:103], v[190:193], v[224:227], v[100:103]
	v_mfma_f32_16x16x32_bf16 v[92:95], v[182:185], v[232:235], v[92:95]
	v_mfma_f32_16x16x32_bf16 v[84:87], v[190:193], v[232:235], v[84:87]
	v_mfma_f32_16x16x32_bf16 v[76:79], v[182:185], v[240:243], v[76:79]
	v_mfma_f32_16x16x32_bf16 v[68:71], v[190:193], v[240:243], v[68:71]
	v_mfma_f32_16x16x32_bf16 v[120:123], v[194:197], v[210:213], v[120:123]
	v_mfma_f32_16x16x32_bf16 v[112:115], v[202:205], v[210:213], v[112:115]
	v_mfma_f32_16x16x32_bf16 v[104:107], v[194:197], v[220:223], v[104:107]
	v_mfma_f32_16x16x32_bf16 v[96:99], v[202:205], v[220:223], v[96:99]
	v_mfma_f32_16x16x32_bf16 v[88:91], v[194:197], v[228:231], v[88:91]
	v_mfma_f32_16x16x32_bf16 v[80:83], v[202:205], v[228:231], v[80:83]
	v_mfma_f32_16x16x32_bf16 v[72:75], v[194:197], v[236:239], v[72:75]
	v_mfma_f32_16x16x32_bf16 v[64:67], v[202:205], v[236:239], v[64:67]
	v_mfma_f32_16x16x32_bf16 v[120:123], v[198:201], v[216:219], v[120:123]
	v_mfma_f32_16x16x32_bf16 v[112:115], v[206:209], v[216:219], v[112:115]
	v_mfma_f32_16x16x32_bf16 v[104:107], v[198:201], v[224:227], v[104:107]
	v_mfma_f32_16x16x32_bf16 v[96:99], v[206:209], v[224:227], v[96:99]
	v_mfma_f32_16x16x32_bf16 v[88:91], v[198:201], v[232:235], v[88:91]
	v_mfma_f32_16x16x32_bf16 v[80:83], v[206:209], v[232:235], v[80:83]
	v_mfma_f32_16x16x32_bf16 v[72:75], v[198:201], v[240:243], v[72:75]
	v_mfma_f32_16x16x32_bf16 v[64:67], v[206:209], v[240:243], v[64:67]
	s_barrier
; #define PG8_STAGE(bufoff, gbase, voff) do { _Pragma("unroll") for (int _i = 0; _i < 2; ++_i) \
;         __builtin_amdgcn_global_load_lds((const unsigned*)((const char*)(gbase) + (voff)[_i]), (PG8_LAS unsigned*)(lds + (bufoff) + ldsw + _i * 8192), 16, 0, 0); } while (0)
; #define PG8_LDA(dst, b, h) do { _Pragma("unroll") for (int m = 0; m < 4; ++m) _Pragma("unroll") for (int k = 0; k < 2; ++k) dst[m][k] = *(const PG8_LAS bf16x8*)(lds + PG8_SA(b, h) + aoff + m * 2048 + k * 1024); } while (0)
; #define PG8_MMA(ai, bj, At, Bt) do { __builtin_amdgcn_s_setprio(1); _Pragma("unroll") for (int m = 0; m < 4; ++m) _Pragma("unroll") for (int n = 0; n < 2; ++n) _Pragma("unroll") for (int k = 0; k < 2; ++k) \
;         acc[ai][bj][m][n] = __builtin_amdgcn_mfma_f32_16x16x32_bf16(Bt[n][k], At[m][k], acc[ai][bj][m][n], 0, 0, 0); __builtin_amdgcn_s_setprio(0); } while (0)
; #define PG8_WAIT_V(n) asm volatile("s_waitcnt vmcnt(" #n ")" ::: "memory")
; #define PG8_WAIT_L(n) asm volatile("s_waitcnt lgkmcnt(" #n ")" ::: "memory")
; #define PG8_BAR __builtin_amdgcn_s_barrier()
; #define PG8_SCHED __builtin_amdgcn_sched_barrier(0)
; template <class Epi, class Sched, bool ALIGN_EPI = false, bool SP2 = false>
; __device__ __forceinline__ void gemm_phase(PG8_LAS unsigned char* lds, const Gemm g, const Sched& S, const Epi& E) {
;     ...
;         for (int t = 0; t < nt; t += 2) {
;     ...
;             PG8_LDA(At, 1, 1); PG8_STAGE(PG8_SB(1, 0), b3, voffB); PG8_STAGE(PG8_SB(1, 1), b3 + hstep, voffB); PG8_STAGE(PG8_SA(1, 0), a3, voffA);
;             PG8_WAIT_V(8); PG8_WAIT_L(0); PG8_BAR; PG8_MMA(1, 0, At, B0); PG8_MMA(1, 1, At, B1); PG8_BAR; PG8_SCHED;
	s_add_i32 s11, s11, s29
	s_add_i32 m0, s11, 0xffffff80
	ds_read_b128 v[210:213], v179 offset:49152
	ds_read_b128 v[216:219], v179 offset:50176
	ds_read_b128 v[220:223], v179 offset:51200
	ds_read_b128 v[224:227], v179 offset:52224
	global_load_lds_dwordx4 v[244:245], off offset:128
	s_add_i32 m0, s11, 0x1f80
	s_add_i32 s11, s13, s29
	global_load_lds_dwordx4 v[246:247], off offset:128
	s_add_i32 m0, s11, 0xffffff80
	ds_read_b128 v[240:243], v179 offset:56320
	global_load_lds_dwordx4 v[248:249], off offset:128
	s_add_i32 m0, s11, 0x1f80
	ds_read_b128 v[236:239], v179 offset:55296
	global_load_lds_dwordx4 v[214:215], off offset:128
	s_add_i32 m0, s50, 0xffffff80
	ds_read_b128 v[232:235], v179 offset:54272
	global_load_lds_dwordx4 v[250:251], off offset:128
	s_add_i32 m0, s51, 0xffffff80
	ds_read_b128 v[228:231], v179 offset:53248
	global_load_lds_dwordx4 v[252:253], off offset:128
	s_waitcnt vmcnt(8) lgkmcnt(0)
	s_barrier
	v_mfma_f32_16x16x32_bf16 v[60:63], v[162:165], v[210:213], v[60:63]
	v_mfma_f32_16x16x32_bf16 v[52:55], v[186:189], v[210:213], v[52:55]
	v_mfma_f32_16x16x32_bf16 v[44:47], v[162:165], v[220:223], v[44:47]
	v_mfma_f32_16x16x32_bf16 v[36:39], v[186:189], v[220:223], v[36:39]
	v_mfma_f32_16x16x32_bf16 v[28:31], v[162:165], v[228:231], v[28:31]
	v_mfma_f32_16x16x32_bf16 v[20:23], v[186:189], v[228:231], v[20:23]
	v_mfma_f32_16x16x32_bf16 v[12:15], v[162:165], v[236:239], v[12:15]
	v_mfma_f32_16x16x32_bf16 v[4:7], v[186:189], v[236:239], v[4:7]
	v_mfma_f32_16x16x32_bf16 v[60:63], v[182:185], v[216:219], v[60:63]
	v_mfma_f32_16x16x32_bf16 v[52:55], v[190:193], v[216:219], v[52:55]
	v_mfma_f32_16x16x32_bf16 v[44:47], v[182:185], v[224:227], v[44:47]
	v_mfma_f32_16x16x32_bf16 v[36:39], v[190:193], v[224:227], v[36:39]
	v_mfma_f32_16x16x32_bf16 v[28:31], v[182:185], v[232:235], v[28:31]
	v_mfma_f32_16x16x32_bf16 v[20:23], v[190:193], v[232:235], v[20:23]
	v_mfma_f32_16x16x32_bf16 v[12:15], v[182:185], v[240:243], v[12:15]
	v_mfma_f32_16x16x32_bf16 v[4:7], v[190:193], v[240:243], v[4:7]
	v_mfma_f32_16x16x32_bf16 v[56:59], v[194:197], v[210:213], v[56:59]
	v_mfma_f32_16x16x32_bf16 v[48:51], v[202:205], v[210:213], v[48:51]
	v_mfma_f32_16x16x32_bf16 v[40:43], v[194:197], v[220:223], v[40:43]
	v_mfma_f32_16x16x32_bf16 v[32:35], v[202:205], v[220:223], v[32:35]
	v_mfma_f32_16x16x32_bf16 v[24:27], v[194:197], v[228:231], v[24:27]
	v_mfma_f32_16x16x32_bf16 v[16:19], v[202:205], v[228:231], v[16:19]
	v_mfma_f32_16x16x32_bf16 v[8:11], v[194:197], v[236:239], v[8:11]
	v_mfma_f32_16x16x32_bf16 v[0:3], v[202:205], v[236:239], v[0:3]
	v_mfma_f32_16x16x32_bf16 v[56:59], v[198:201], v[216:219], v[56:59]
	v_mfma_f32_16x16x32_bf16 v[48:51], v[206:209], v[216:219], v[48:51]
	v_mfma_f32_16x16x32_bf16 v[40:43], v[198:201], v[224:227], v[40:43]
	v_mfma_f32_16x16x32_bf16 v[32:35], v[206:209], v[224:227], v[32:35]
	v_mfma_f32_16x16x32_bf16 v[24:27], v[198:201], v[232:235], v[24:27]
	v_mfma_f32_16x16x32_bf16 v[16:19], v[206:209], v[232:235], v[16:19]
	v_mfma_f32_16x16x32_bf16 v[8:11], v[198:201], v[240:243], v[8:11]
	v_mfma_f32_16x16x32_bf16 v[0:3], v[206:209], v[240:243], v[0:3]
	s_barrier
	v_lshl_add_u64 v[158:159], v[158:159], 0, s[26:27]
	s_cmp_ge_i32 s10, s52
	v_lshl_add_u64 v[160:161], v[160:161], 0, s[26:27]
	s_cbranch_scc0 .LBB0_1021

; #define PG8_STAGE(bufoff, gbase, voff) do { _Pragma("unroll") for (int _i = 0; _i < 2; ++_i) \
;         __builtin_amdgcn_global_load_lds((const unsigned*)((const char*)(gbase) + (voff)[_i]), (PG8_LAS unsigned*)(lds + (bufoff) + ldsw + _i * 8192), 16, 0, 0); } while (0)
; #define PG8_LDA(dst, b, h) do { _Pragma("unroll") for (int m = 0; m < 4; ++m) _Pragma("unroll") for (int k = 0; k < 2; ++k) dst[m][k] = *(const PG8_LAS bf16x8*)(lds + PG8_SA(b, h) + aoff + m * 2048 + k * 1024); } while (0)
; #define PG8_LDB(dst, b, h) do { _Pragma("unroll") for (int n = 0; n < 2; ++n) _Pragma("unroll") for (int k = 0; k < 2; ++k) dst[n][k] = *(const PG8_LAS bf16x8*)(lds + PG8_SB(b, h) + boff + n * 2048 + k * 1024); } while (0)
; #define PG8_MMA(ai, bj, At, Bt) do { __builtin_amdgcn_s_setprio(1); _Pragma("unroll") for (int m = 0; m < 4; ++m) _Pragma("unroll") for (int n = 0; n < 2; ++n) _Pragma("unroll") for (int k = 0; k < 2; ++k) \
;         acc[ai][bj][m][n] = __builtin_amdgcn_mfma_f32_16x16x32_bf16(Bt[n][k], At[m][k], acc[ai][bj][m][n], 0, 0, 0); __builtin_amdgcn_s_setprio(0); } while (0)
; #define PG8_WAIT_V(n) asm volatile("s_waitcnt vmcnt(" #n ")" ::: "memory")
; #define PG8_WAIT_L(n) asm volatile("s_waitcnt lgkmcnt(" #n ")" ::: "memory")
; #define PG8_BAR __builtin_amdgcn_s_barrier()
; template <class Epi, class Sched, bool ALIGN_EPI = false, bool SP2 = false>
; __device__ __forceinline__ void gemm_phase(PG8_LAS unsigned char* lds, const Gemm g, const Sched& S, const Epi& E) {
;     ...
;             const char* a1 = cA + (size_t)(t + 1) * kstep;
;             const char* a2 = last ? nA : cA + (size_t)(t + 2) * kstep; const char* b2 = last ? nB : cB + (size_t)(t + 2) * kstep;
;             const char* a3 = a2 + kstep; const char* b3 = b2 + kstep;
;             if (last && has_next) S.a_ready(nxt);
;             if constexpr (SP2) {
;             PG8_LDB(B0, 0, 0); PG8_LDB(B1, 0, 1); PG8_SCHED; PG8_LDA(At, 0, 0); PG8_STAGE(PG8_SA(1, 1), a1 + hstep, voffA);
;             PG8_WAIT_V(8); PG8_WAIT_L(0); PG8_BAR; PG8_MMA(0, 0, At, B0); PG8_MMA(0, 1, At, B1); PG8_BAR; PG8_SCHED;
;             PG8_LDA(At, 0, 1); PG8_STAGE(PG8_SB(0, 0), b2, voffB); PG8_STAGE(PG8_SB(0, 1), b2 + hstep, voffB); PG8_STAGE(PG8_SA(0, 0), a2, voffA);
;             PG8_WAIT_V(8); PG8_WAIT_L(0); PG8_BAR; PG8_MMA(1, 0, At, B0); PG8_MMA(1, 1, At, B1); PG8_BAR; PG8_SCHED;
.LBB0_1169:
	v_add_u32_e32 v255, s52, v161
	ds_read_b128 v[164:167], v162
	ds_read_b128 v[168:171], v162 offset:1024
	ds_read_b128 v[172:175], v162 offset:2048
	ds_read_b128 v[176:179], v162 offset:3072
	ds_read_b128 v[180:183], v255
	ds_read_b128 v[184:187], v255 offset:1024
	ds_read_b128 v[188:191], v255 offset:2048
	ds_read_b128 v[192:195], v255 offset:3072
	s_cmp_eq_u32 s51, s10
	v_lshl_add_u64 v[196:197], v[158:159], 0, s[24:25]
	s_cselect_b64 vcc, -1, 0
	s_add_i32 s10, s10, 2
	v_cndmask_b32_e32 v213, v197, v151, vcc
	v_cndmask_b32_e32 v212, v196, v150, vcc
	v_cndmask_b32_e32 v215, v155, v153, vcc
	v_cndmask_b32_e32 v214, v154, v152, vcc
	s_mov_b32 m0, s54
	v_lshl_add_u64 v[232:233], v[158:159], 0, v[146:147]
	ds_read_b128 v[196:199], v163
	ds_read_b128 v[200:203], v163 offset:1024
	ds_read_b128 v[204:207], v163 offset:2048
	ds_read_b128 v[208:211], v163 offset:3072
	ds_read_b128 v[216:219], v163 offset:4096
	ds_read_b128 v[220:223], v163 offset:5120
	ds_read_b128 v[224:227], v163 offset:6144
	ds_read_b128 v[228:231], v163 offset:7168
	global_load_lds_dwordx4 v[232:233], off
	s_mov_b32 m0, s55
	v_lshl_add_u64 v[232:233], v[158:159], 0, v[144:145]
	global_load_lds_dwordx4 v[232:233], off
	s_waitcnt vmcnt(8) lgkmcnt(0)
	s_barrier
	v_mfma_f32_16x16x32_bf16 v[124:127], v[164:167], v[196:199], v[124:127]
	v_mfma_f32_16x16x32_bf16 v[120:123], v[172:175], v[196:199], v[120:123]
	v_mfma_f32_16x16x32_bf16 v[108:111], v[164:167], v[204:207], v[108:111]
	v_mfma_f32_16x16x32_bf16 v[104:107], v[172:175], v[204:207], v[104:107]
	v_mfma_f32_16x16x32_bf16 v[92:95], v[164:167], v[216:219], v[92:95]
	v_mfma_f32_16x16x32_bf16 v[88:91], v[172:175], v[216:219], v[88:91]
	v_mfma_f32_16x16x32_bf16 v[76:79], v[164:167], v[224:227], v[76:79]
	v_mfma_f32_16x16x32_bf16 v[72:75], v[172:175], v[224:227], v[72:75]
	v_mfma_f32_16x16x32_bf16 v[124:127], v[168:171], v[200:203], v[124:127]
	v_mfma_f32_16x16x32_bf16 v[120:123], v[176:179], v[200:203], v[120:123]
	v_mfma_f32_16x16x32_bf16 v[108:111], v[168:171], v[208:211], v[108:111]
	v_mfma_f32_16x16x32_bf16 v[104:107], v[176:179], v[208:211], v[104:107]
	v_mfma_f32_16x16x32_bf16 v[92:95], v[168:171], v[220:223], v[92:95]
	v_mfma_f32_16x16x32_bf16 v[88:91], v[176:179], v[220:223], v[88:91]
	v_mfma_f32_16x16x32_bf16 v[76:79], v[168:171], v[228:231], v[76:79]
	v_mfma_f32_16x16x32_bf16 v[72:75], v[176:179], v[228:231], v[72:75]
	v_mfma_f32_16x16x32_bf16 v[116:119], v[180:183], v[196:199], v[116:119]
	v_mfma_f32_16x16x32_bf16 v[112:115], v[188:191], v[196:199], v[112:115]
	v_mfma_f32_16x16x32_bf16 v[100:103], v[180:183], v[204:207], v[100:103]
	v_mfma_f32_16x16x32_bf16 v[96:99], v[188:191], v[204:207], v[96:99]
	v_mfma_f32_16x16x32_bf16 v[84:87], v[180:183], v[216:219], v[84:87]
	v_mfma_f32_16x16x32_bf16 v[80:83], v[188:191], v[216:219], v[80:83]
	v_mfma_f32_16x16x32_bf16 v[68:71], v[180:183], v[224:227], v[68:71]
	v_mfma_f32_16x16x32_bf16 v[64:67], v[188:191], v[224:227], v[64:67]
	v_mfma_f32_16x16x32_bf16 v[116:119], v[184:187], v[200:203], v[116:119]
	v_mfma_f32_16x16x32_bf16 v[112:115], v[192:195], v[200:203], v[112:115]
	v_mfma_f32_16x16x32_bf16 v[100:103], v[184:187], v[208:211], v[100:103]
	v_mfma_f32_16x16x32_bf16 v[96:99], v[192:195], v[208:211], v[96:99]
	v_mfma_f32_16x16x32_bf16 v[84:87], v[184:187], v[220:223], v[84:87]
	v_mfma_f32_16x16x32_bf16 v[80:83], v[192:195], v[220:223], v[80:83]
	v_mfma_f32_16x16x32_bf16 v[68:71], v[184:187], v[228:231], v[68:71]
	v_mfma_f32_16x16x32_bf16 v[64:67], v[192:195], v[228:231], v[64:67]
	s_barrier
	s_mov_b32 m0, s56
	v_lshl_add_u64 v[232:233], v[214:215], 0, v[138:139]
	ds_read_b128 v[196:199], v163 offset:16384
	ds_read_b128 v[200:203], v163 offset:17408
	ds_read_b128 v[204:207], v163 offset:18432
	ds_read_b128 v[208:211], v163 offset:19456
	ds_read_b128 v[216:219], v163 offset:20480
	ds_read_b128 v[220:223], v163 offset:21504
	ds_read_b128 v[224:227], v163 offset:22528
	ds_read_b128 v[228:231], v163 offset:23552
	global_load_lds_dwordx4 v[232:233], off
	v_lshl_add_u64 v[234:235], v[214:215], 0, v[134:135]
	s_mov_b32 m0, s57
	v_lshl_add_u64 v[214:215], v[214:215], 0, s[14:15]
	global_load_lds_dwordx4 v[234:235], off
	v_lshl_add_u64 v[236:237], v[214:215], 0, v[138:139]
	s_mov_b32 m0, s58
	v_lshl_add_u64 v[214:215], v[214:215], 0, v[134:135]
	global_load_lds_dwordx4 v[236:237], off
	s_mov_b32 m0, s59
	v_lshl_add_u64 v[238:239], v[212:213], 0, v[140:141]
	global_load_lds_dwordx4 v[214:215], off
	s_mov_b32 m0, s37
	v_lshl_add_u64 v[240:241], v[212:213], 0, v[136:137]
	global_load_lds_dwordx4 v[238:239], off
	s_mov_b32 m0, s41
	s_nop 0
	global_load_lds_dwordx4 v[240:241], off
	s_waitcnt vmcnt(8) lgkmcnt(0)
	s_barrier
; #define PG8_STAGE(bufoff, gbase, voff) do { _Pragma("unroll") for (int _i = 0; _i < 2; ++_i) \
;         __builtin_amdgcn_global_load_lds((const unsigned*)((const char*)(gbase) + (voff)[_i]), (PG8_LAS unsigned*)(lds + (bufoff) + ldsw + _i * 8192), 16, 0, 0); } while (0)
; #define PG8_LDA(dst, b, h) do { _Pragma("unroll") for (int m = 0; m < 4; ++m) _Pragma("unroll") for (int k = 0; k < 2; ++k) dst[m][k] = *(const PG8_LAS bf16x8*)(lds + PG8_SA(b, h) + aoff + m * 2048 + k * 1024); } while (0)
; #define PG8_LDB(dst, b, h) do { _Pragma("unroll") for (int n = 0; n < 2; ++n) _Pragma("unroll") for (int k = 0; k < 2; ++k) dst[n][k] = *(const PG8_LAS bf16x8*)(lds + PG8_SB(b, h) + boff + n * 2048 + k * 1024); } while (0)
; #define PG8_MMA(ai, bj, At, Bt) do { __builtin_amdgcn_s_setprio(1); _Pragma("unroll") for (int m = 0; m < 4; ++m) _Pragma("unroll") for (int n = 0; n < 2; ++n) _Pragma("unroll") for (int k = 0; k < 2; ++k) \
;         acc[ai][bj][m][n] = __builtin_amdgcn_mfma_f32_16x16x32_bf16(Bt[n][k], At[m][k], acc[ai][bj][m][n], 0, 0, 0); __builtin_amdgcn_s_setprio(0); } while (0)
; #define PG8_WAIT_V(n) asm volatile("s_waitcnt vmcnt(" #n ")" ::: "memory")
; #define PG8_WAIT_L(n) asm volatile("s_waitcnt lgkmcnt(" #n ")" ::: "memory")
; #define PG8_BAR __builtin_amdgcn_s_barrier()
; #define PG8_SCHED __builtin_amdgcn_sched_barrier(0)
; template <class Epi, class Sched, bool ALIGN_EPI = false, bool SP2 = false>
; __device__ __forceinline__ void gemm_phase(PG8_LAS unsigned char* lds, const Gemm g, const Sched& S, const Epi& E) {
;     ...
;             PG8_WAIT_V(8); PG8_WAIT_L(0); PG8_BAR; PG8_MMA(1, 0, At, B0); PG8_MMA(1, 1, At, B1); PG8_BAR; PG8_SCHED;
;             PG8_LDB(B0, 1, 0); PG8_LDB(B1, 1, 1); PG8_SCHED; PG8_LDA(At, 1, 0); PG8_STAGE(PG8_SA(0, 1), a2 + hstep, voffA);
;             PG8_WAIT_V(8); PG8_WAIT_L(0); PG8_BAR; PG8_MMA(0, 0, At, B0); PG8_MMA(0, 1, At, B1); PG8_BAR; PG8_SCHED;
	v_mfma_f32_16x16x32_bf16 v[60:63], v[164:167], v[196:199], v[60:63]
	v_mfma_f32_16x16x32_bf16 v[56:59], v[172:175], v[196:199], v[56:59]
	v_mfma_f32_16x16x32_bf16 v[44:47], v[164:167], v[204:207], v[44:47]
	v_mfma_f32_16x16x32_bf16 v[40:43], v[172:175], v[204:207], v[40:43]
	v_mfma_f32_16x16x32_bf16 v[28:31], v[164:167], v[216:219], v[28:31]
	v_mfma_f32_16x16x32_bf16 v[24:27], v[172:175], v[216:219], v[24:27]
	v_mfma_f32_16x16x32_bf16 v[12:15], v[164:167], v[224:227], v[12:15]
	v_mfma_f32_16x16x32_bf16 v[8:11], v[172:175], v[224:227], v[8:11]
	v_mfma_f32_16x16x32_bf16 v[60:63], v[168:171], v[200:203], v[60:63]
	v_mfma_f32_16x16x32_bf16 v[56:59], v[176:179], v[200:203], v[56:59]
	v_mfma_f32_16x16x32_bf16 v[44:47], v[168:171], v[208:211], v[44:47]
	v_mfma_f32_16x16x32_bf16 v[40:43], v[176:179], v[208:211], v[40:43]
	v_mfma_f32_16x16x32_bf16 v[28:31], v[168:171], v[220:223], v[28:31]
	v_mfma_f32_16x16x32_bf16 v[24:27], v[176:179], v[220:223], v[24:27]
	v_mfma_f32_16x16x32_bf16 v[12:15], v[168:171], v[228:231], v[12:15]
	v_mfma_f32_16x16x32_bf16 v[8:11], v[176:179], v[228:231], v[8:11]
	v_mfma_f32_16x16x32_bf16 v[52:55], v[180:183], v[196:199], v[52:55]
	v_mfma_f32_16x16x32_bf16 v[48:51], v[188:191], v[196:199], v[48:51]
	v_mfma_f32_16x16x32_bf16 v[36:39], v[180:183], v[204:207], v[36:39]
	v_mfma_f32_16x16x32_bf16 v[32:35], v[188:191], v[204:207], v[32:35]
	v_mfma_f32_16x16x32_bf16 v[20:23], v[180:183], v[216:219], v[20:23]
	v_mfma_f32_16x16x32_bf16 v[16:19], v[188:191], v[216:219], v[16:19]
	v_mfma_f32_16x16x32_bf16 v[4:7], v[180:183], v[224:227], v[4:7]
	v_mfma_f32_16x16x32_bf16 v[0:3], v[188:191], v[224:227], v[0:3]
	v_mfma_f32_16x16x32_bf16 v[52:55], v[184:187], v[200:203], v[52:55]
	v_mfma_f32_16x16x32_bf16 v[48:51], v[192:195], v[200:203], v[48:51]
	v_mfma_f32_16x16x32_bf16 v[36:39], v[184:187], v[208:211], v[36:39]
	v_mfma_f32_16x16x32_bf16 v[32:35], v[192:195], v[208:211], v[32:35]
	v_mfma_f32_16x16x32_bf16 v[20:23], v[184:187], v[220:223], v[20:23]
	v_mfma_f32_16x16x32_bf16 v[16:19], v[192:195], v[220:223], v[16:19]
	v_mfma_f32_16x16x32_bf16 v[4:7], v[184:187], v[228:231], v[4:7]
	v_mfma_f32_16x16x32_bf16 v[0:3], v[192:195], v[228:231], v[0:3]
	s_barrier
	ds_read_b128 v[164:167], v255 offset:16384
	ds_read_b128 v[168:171], v255 offset:17408
	ds_read_b128 v[172:175], v255 offset:18432
	ds_read_b128 v[176:179], v255 offset:19456
	ds_read_b128 v[180:183], v255 offset:32768
	ds_read_b128 v[184:187], v255 offset:33792
	ds_read_b128 v[188:191], v255 offset:34816
	ds_read_b128 v[192:195], v255 offset:35840
	v_lshl_add_u64 v[212:213], v[212:213], 0, s[14:15]
	s_mov_b32 m0, s46
	v_lshl_add_u64 v[242:243], v[212:213], 0, v[140:141]
	ds_read_b128 v[196:199], v163 offset:32768
	ds_read_b128 v[200:203], v163 offset:33792
	ds_read_b128 v[204:207], v163 offset:34816
	ds_read_b128 v[208:211], v163 offset:35840
	ds_read_b128 v[216:219], v163 offset:36864
	ds_read_b128 v[220:223], v163 offset:37888
	ds_read_b128 v[224:227], v163 offset:38912
	ds_read_b128 v[228:231], v163 offset:39936
	global_load_lds_dwordx4 v[242:243], off
	s_mov_b32 m0, s47
	v_lshl_add_u64 v[212:213], v[212:213], 0, v[136:137]
	global_load_lds_dwordx4 v[212:213], off
	s_waitcnt vmcnt(8) lgkmcnt(0)
	s_barrier
	v_mfma_f32_16x16x32_bf16 v[124:127], v[164:167], v[196:199], v[124:127]
	v_mfma_f32_16x16x32_bf16 v[120:123], v[172:175], v[196:199], v[120:123]
	v_mfma_f32_16x16x32_bf16 v[108:111], v[164:167], v[204:207], v[108:111]
	v_mfma_f32_16x16x32_bf16 v[104:107], v[172:175], v[204:207], v[104:107]
	v_mfma_f32_16x16x32_bf16 v[92:95], v[164:167], v[216:219], v[92:95]
	v_mfma_f32_16x16x32_bf16 v[88:91], v[172:175], v[216:219], v[88:91]
	v_mfma_f32_16x16x32_bf16 v[76:79], v[164:167], v[224:227], v[76:79]
	v_mfma_f32_16x16x32_bf16 v[72:75], v[172:175], v[224:227], v[72:75]
	v_mfma_f32_16x16x32_bf16 v[124:127], v[168:171], v[200:203], v[124:127]
	v_mfma_f32_16x16x32_bf16 v[120:123], v[176:179], v[200:203], v[120:123]
	v_mfma_f32_16x16x32_bf16 v[108:111], v[168:171], v[208:211], v[108:111]
	v_mfma_f32_16x16x32_bf16 v[104:107], v[176:179], v[208:211], v[104:107]
	v_mfma_f32_16x16x32_bf16 v[92:95], v[168:171], v[220:223], v[92:95]
	v_mfma_f32_16x16x32_bf16 v[88:91], v[176:179], v[220:223], v[88:91]
	v_mfma_f32_16x16x32_bf16 v[76:79], v[168:171], v[228:231], v[76:79]
	v_mfma_f32_16x16x32_bf16 v[72:75], v[176:179], v[228:231], v[72:75]
	v_mfma_f32_16x16x32_bf16 v[116:119], v[180:183], v[196:199], v[116:119]
	v_mfma_f32_16x16x32_bf16 v[112:115], v[188:191], v[196:199], v[112:115]
	v_mfma_f32_16x16x32_bf16 v[100:103], v[180:183], v[204:207], v[100:103]
	v_mfma_f32_16x16x32_bf16 v[96:99], v[188:191], v[204:207], v[96:99]
	v_mfma_f32_16x16x32_bf16 v[84:87], v[180:183], v[216:219], v[84:87]
	v_mfma_f32_16x16x32_bf16 v[80:83], v[188:191], v[216:219], v[80:83]
	v_mfma_f32_16x16x32_bf16 v[68:71], v[180:183], v[224:227], v[68:71]
	v_mfma_f32_16x16x32_bf16 v[64:67], v[188:191], v[224:227], v[64:67]
	v_mfma_f32_16x16x32_bf16 v[116:119], v[184:187], v[200:203], v[116:119]
	v_mfma_f32_16x16x32_bf16 v[112:115], v[192:195], v[200:203], v[112:115]
	v_mfma_f32_16x16x32_bf16 v[100:103], v[184:187], v[208:211], v[100:103]
	v_mfma_f32_16x16x32_bf16 v[96:99], v[192:195], v[208:211], v[96:99]
	v_mfma_f32_16x16x32_bf16 v[84:87], v[184:187], v[220:223], v[84:87]
	v_mfma_f32_16x16x32_bf16 v[80:83], v[192:195], v[220:223], v[80:83]
	v_mfma_f32_16x16x32_bf16 v[68:71], v[184:187], v[228:231], v[68:71]
	v_mfma_f32_16x16x32_bf16 v[64:67], v[192:195], v[228:231], v[64:67]
	s_barrier
; #define PG8_STAGE(bufoff, gbase, voff) do { _Pragma("unroll") for (int _i = 0; _i < 2; ++_i) \
;         __builtin_amdgcn_global_load_lds((const unsigned*)((const char*)(gbase) + (voff)[_i]), (PG8_LAS unsigned*)(lds + (bufoff) + ldsw + _i * 8192), 16, 0, 0); } while (0)
; #define PG8_LDA(dst, b, h) do { _Pragma("unroll") for (int m = 0; m < 4; ++m) _Pragma("unroll") for (int k = 0; k < 2; ++k) dst[m][k] = *(const PG8_LAS bf16x8*)(lds + PG8_SA(b, h) + aoff + m * 2048 + k * 1024); } while (0)
; #define PG8_MMA(ai, bj, At, Bt) do { __builtin_amdgcn_s_setprio(1); _Pragma("unroll") for (int m = 0; m < 4; ++m) _Pragma("unroll") for (int n = 0; n < 2; ++n) _Pragma("unroll") for (int k = 0; k < 2; ++k) \
;         acc[ai][bj][m][n] = __builtin_amdgcn_mfma_f32_16x16x32_bf16(Bt[n][k], At[m][k], acc[ai][bj][m][n], 0, 0, 0); __builtin_amdgcn_s_setprio(0); } while (0)
; #define PG8_WAIT_V(n) asm volatile("s_waitcnt vmcnt(" #n ")" ::: "memory")
; #define PG8_WAIT_L(n) asm volatile("s_waitcnt lgkmcnt(" #n ")" ::: "memory")
; #define PG8_BAR __builtin_amdgcn_s_barrier()
; #define PG8_SCHED __builtin_amdgcn_sched_barrier(0)
; template <class Epi, class Sched, bool ALIGN_EPI = false, bool SP2 = false>
; __device__ __forceinline__ void gemm_phase(PG8_LAS unsigned char* lds, const Gemm g, const Sched& S, const Epi& E) {
;     ...
;         for (int t = 0; t < nt; t += 2) {
;     ...
;             PG8_LDA(At, 1, 1); PG8_STAGE(PG8_SB(1, 0), b3, voffB); PG8_STAGE(PG8_SB(1, 1), b3 + hstep, voffB); PG8_STAGE(PG8_SA(1, 0), a3, voffA);
;             PG8_WAIT_V(8); PG8_WAIT_L(0); PG8_BAR; PG8_MMA(1, 0, At, B0); PG8_MMA(1, 1, At, B1); PG8_BAR; PG8_SCHED;
	s_add_i32 m0, s62, 0xffffff80
	ds_read_b128 v[196:199], v163 offset:49152
	ds_read_b128 v[200:203], v163 offset:50176
	ds_read_b128 v[204:207], v163 offset:51200
	global_load_lds_dwordx4 v[232:233], off offset:128
	s_add_i32 m0, s63, 0xffffff80
	ds_read_b128 v[228:231], v163 offset:56320
	global_load_lds_dwordx4 v[234:235], off offset:128
	s_add_i32 m0, s64, 0xffffff80
	ds_read_b128 v[224:227], v163 offset:55296
	global_load_lds_dwordx4 v[236:237], off offset:128
	s_add_i32 m0, s65, 0xffffff80
	ds_read_b128 v[220:223], v163 offset:54272
	global_load_lds_dwordx4 v[214:215], off offset:128
	s_add_i32 m0, s48, 0xffffff80
	ds_read_b128 v[216:219], v163 offset:53248
	global_load_lds_dwordx4 v[238:239], off offset:128
	s_add_i32 m0, s49, 0xffffff80
	ds_read_b128 v[208:211], v163 offset:52224
	global_load_lds_dwordx4 v[240:241], off offset:128
	s_waitcnt vmcnt(8) lgkmcnt(0)
	s_barrier
	v_mfma_f32_16x16x32_bf16 v[60:63], v[164:167], v[196:199], v[60:63]
	v_mfma_f32_16x16x32_bf16 v[56:59], v[172:175], v[196:199], v[56:59]
	v_mfma_f32_16x16x32_bf16 v[44:47], v[164:167], v[204:207], v[44:47]
	v_mfma_f32_16x16x32_bf16 v[40:43], v[172:175], v[204:207], v[40:43]
	v_mfma_f32_16x16x32_bf16 v[28:31], v[164:167], v[216:219], v[28:31]
	v_mfma_f32_16x16x32_bf16 v[24:27], v[172:175], v[216:219], v[24:27]
	v_mfma_f32_16x16x32_bf16 v[12:15], v[164:167], v[224:227], v[12:15]
	v_mfma_f32_16x16x32_bf16 v[8:11], v[172:175], v[224:227], v[8:11]
	v_mfma_f32_16x16x32_bf16 v[60:63], v[168:171], v[200:203], v[60:63]
	v_mfma_f32_16x16x32_bf16 v[56:59], v[176:179], v[200:203], v[56:59]
	v_mfma_f32_16x16x32_bf16 v[44:47], v[168:171], v[208:211], v[44:47]
	v_mfma_f32_16x16x32_bf16 v[40:43], v[176:179], v[208:211], v[40:43]
	v_mfma_f32_16x16x32_bf16 v[28:31], v[168:171], v[220:223], v[28:31]
	v_mfma_f32_16x16x32_bf16 v[24:27], v[176:179], v[220:223], v[24:27]
	v_mfma_f32_16x16x32_bf16 v[12:15], v[168:171], v[228:231], v[12:15]
	v_mfma_f32_16x16x32_bf16 v[8:11], v[176:179], v[228:231], v[8:11]
	v_mfma_f32_16x16x32_bf16 v[52:55], v[180:183], v[196:199], v[52:55]
	v_mfma_f32_16x16x32_bf16 v[48:51], v[188:191], v[196:199], v[48:51]
	v_mfma_f32_16x16x32_bf16 v[36:39], v[180:183], v[204:207], v[36:39]
	v_mfma_f32_16x16x32_bf16 v[32:35], v[188:191], v[204:207], v[32:35]
	v_mfma_f32_16x16x32_bf16 v[20:23], v[180:183], v[216:219], v[20:23]
	v_mfma_f32_16x16x32_bf16 v[16:19], v[188:191], v[216:219], v[16:19]
	v_mfma_f32_16x16x32_bf16 v[4:7], v[180:183], v[224:227], v[4:7]
	v_mfma_f32_16x16x32_bf16 v[0:3], v[188:191], v[224:227], v[0:3]
	v_mfma_f32_16x16x32_bf16 v[52:55], v[184:187], v[200:203], v[52:55]
	v_mfma_f32_16x16x32_bf16 v[48:51], v[192:195], v[200:203], v[48:51]
	v_mfma_f32_16x16x32_bf16 v[36:39], v[184:187], v[208:211], v[36:39]
	v_mfma_f32_16x16x32_bf16 v[32:35], v[192:195], v[208:211], v[32:35]
	v_mfma_f32_16x16x32_bf16 v[20:23], v[184:187], v[220:223], v[20:23]
	v_mfma_f32_16x16x32_bf16 v[16:19], v[192:195], v[220:223], v[16:19]
	v_mfma_f32_16x16x32_bf16 v[4:7], v[184:187], v[228:231], v[4:7]
	v_mfma_f32_16x16x32_bf16 v[0:3], v[192:195], v[228:231], v[0:3]
	s_barrier
	v_lshl_add_u64 v[154:155], v[154:155], 0, s[28:29]
	s_cmp_ge_i32 s10, s50
	v_lshl_add_u64 v[158:159], v[158:159], 0, s[28:29]
	s_cbranch_scc0 .LBB0_1169

; #define PG8_STAGE(bufoff, gbase, voff) do { _Pragma("unroll") for (int _i = 0; _i < 2; ++_i) \
;         __builtin_amdgcn_global_load_lds((const unsigned*)((const char*)(gbase) + (voff)[_i]), (PG8_LAS unsigned*)(lds + (bufoff) + ldsw + _i * 8192), 16, 0, 0); } while (0)
; #define PG8_LDA(dst, b, h) do { _Pragma("unroll") for (int m = 0; m < 4; ++m) _Pragma("unroll") for (int k = 0; k < 2; ++k) dst[m][k] = *(const PG8_LAS bf16x8*)(lds + PG8_SA(b, h) + aoff + m * 2048 + k * 1024); } while (0)
; #define PG8_LDB(dst, b, h) do { _Pragma("unroll") for (int n = 0; n < 2; ++n) _Pragma("unroll") for (int k = 0; k < 2; ++k) dst[n][k] = *(const PG8_LAS bf16x8*)(lds + PG8_SB(b, h) + boff + n * 2048 + k * 1024); } while (0)
; #define PG8_MMA(ai, bj, At, Bt) do { __builtin_amdgcn_s_setprio(1); _Pragma("unroll") for (int m = 0; m < 4; ++m) _Pragma("unroll") for (int n = 0; n < 2; ++n) _Pragma("unroll") for (int k = 0; k < 2; ++k) \
;         acc[ai][bj][m][n] = __builtin_amdgcn_mfma_f32_16x16x32_bf16(Bt[n][k], At[m][k], acc[ai][bj][m][n], 0, 0, 0); __builtin_amdgcn_s_setprio(0); } while (0)
; #define PG8_WAIT_V(n) asm volatile("s_waitcnt vmcnt(" #n ")" ::: "memory")
; #define PG8_WAIT_L(n) asm volatile("s_waitcnt lgkmcnt(" #n ")" ::: "memory")
; #define PG8_BAR __builtin_amdgcn_s_barrier()
; template <class Epi, class Sched, bool ALIGN_EPI = false, bool SP2 = false>
; __device__ __forceinline__ void gemm_phase(PG8_LAS unsigned char* lds, const Gemm g, const Sched& S, const Epi& E) {
;     ...
;             const char* a1 = cA + (size_t)(t + 1) * kstep;
;             const char* a2 = last ? nA : cA + (size_t)(t + 2) * kstep; const char* b2 = last ? nB : cB + (size_t)(t + 2) * kstep;
;             const char* a3 = a2 + kstep; const char* b3 = b2 + kstep;
;             if (last && has_next) S.a_ready(nxt);
;             if constexpr (SP2) {
;             PG8_LDB(B0, 0, 0); PG8_LDB(B1, 0, 1); PG8_SCHED; PG8_LDA(At, 0, 0); PG8_STAGE(PG8_SA(1, 1), a1 + hstep, voffA);
;             PG8_WAIT_V(8); PG8_WAIT_L(0); PG8_BAR; PG8_MMA(0, 0, At, B0); PG8_MMA(0, 1, At, B1); PG8_BAR; PG8_SCHED;
;             PG8_LDA(At, 0, 1); PG8_STAGE(PG8_SB(0, 0), b2, voffB); PG8_STAGE(PG8_SB(0, 1), b2 + hstep, voffB); PG8_STAGE(PG8_SA(0, 0), a2, voffA);
;             PG8_WAIT_V(8); PG8_WAIT_L(0); PG8_BAR; PG8_MMA(1, 0, At, B0); PG8_MMA(1, 1, At, B1); PG8_BAR; PG8_SCHED;
.LBB0_1192:
	v_add_u32_e32 v255, s56, v216
	ds_read_b128 v[138:141], v255
	ds_read_b128 v[142:145], v255 offset:1024
	ds_read_b128 v[146:149], v255 offset:2048
	ds_read_b128 v[178:181], v255 offset:3072
	ds_read_b128 v[182:185], v255 offset:16384
	ds_read_b128 v[186:189], v255 offset:17408
	ds_read_b128 v[190:193], v255 offset:18432
	ds_read_b128 v[194:197], v255 offset:19456
	s_cmp_eq_u32 s49, s10
	v_lshl_add_u64 v[198:199], v[136:137], 0, s[20:21]
	s_cselect_b64 vcc, -1, 0
	s_add_i32 s10, s10, 2
	v_cndmask_b32_e32 v215, v199, v175, vcc
	v_cndmask_b32_e32 v214, v198, v174, vcc
	v_cndmask_b32_e32 v237, v135, v177, vcc
	v_cndmask_b32_e32 v236, v134, v176, vcc
	v_lshl_add_u64 v[238:239], v[136:137], 0, v[168:169]
	s_add_i32 m0, s34, 0xc000
	ds_read_b128 v[198:201], v218
	ds_read_b128 v[202:205], v218 offset:1024
	ds_read_b128 v[206:209], v218 offset:2048
	ds_read_b128 v[210:213], v218 offset:3072
	ds_read_b128 v[220:223], v218 offset:4096
	ds_read_b128 v[224:227], v218 offset:5120
	ds_read_b128 v[228:231], v218 offset:6144
	ds_read_b128 v[232:235], v218 offset:7168
	global_load_lds_dwordx4 v[238:239], off
	s_add_i32 m0, s34, 0xe000
	v_lshl_add_u64 v[238:239], v[136:137], 0, v[166:167]
	global_load_lds_dwordx4 v[238:239], off
	s_waitcnt vmcnt(8) lgkmcnt(0)
	s_barrier
	v_mfma_f32_16x16x32_bf16 v[130:133], v[138:141], v[198:201], v[130:133]
	v_mfma_f32_16x16x32_bf16 v[126:129], v[146:149], v[198:201], v[126:129]
	v_mfma_f32_16x16x32_bf16 v[114:117], v[138:141], v[206:209], v[114:117]
	v_mfma_f32_16x16x32_bf16 v[110:113], v[146:149], v[206:209], v[110:113]
	v_mfma_f32_16x16x32_bf16 v[98:101], v[138:141], v[220:223], v[98:101]
	v_mfma_f32_16x16x32_bf16 v[94:97], v[146:149], v[220:223], v[94:97]
	v_mfma_f32_16x16x32_bf16 v[82:85], v[138:141], v[228:231], v[82:85]
	v_mfma_f32_16x16x32_bf16 v[78:81], v[146:149], v[228:231], v[78:81]
	v_mfma_f32_16x16x32_bf16 v[130:133], v[142:145], v[202:205], v[130:133]
	v_mfma_f32_16x16x32_bf16 v[126:129], v[178:181], v[202:205], v[126:129]
	v_mfma_f32_16x16x32_bf16 v[114:117], v[142:145], v[210:213], v[114:117]
	v_mfma_f32_16x16x32_bf16 v[110:113], v[178:181], v[210:213], v[110:113]
	v_mfma_f32_16x16x32_bf16 v[98:101], v[142:145], v[224:227], v[98:101]
	v_mfma_f32_16x16x32_bf16 v[94:97], v[178:181], v[224:227], v[94:97]
	v_mfma_f32_16x16x32_bf16 v[82:85], v[142:145], v[232:235], v[82:85]
	v_mfma_f32_16x16x32_bf16 v[78:81], v[178:181], v[232:235], v[78:81]
	v_mfma_f32_16x16x32_bf16 v[122:125], v[182:185], v[198:201], v[122:125]
	v_mfma_f32_16x16x32_bf16 v[118:121], v[190:193], v[198:201], v[118:121]
	v_mfma_f32_16x16x32_bf16 v[106:109], v[182:185], v[206:209], v[106:109]
	v_mfma_f32_16x16x32_bf16 v[102:105], v[190:193], v[206:209], v[102:105]
	v_mfma_f32_16x16x32_bf16 v[90:93], v[182:185], v[220:223], v[90:93]
	v_mfma_f32_16x16x32_bf16 v[86:89], v[190:193], v[220:223], v[86:89]
	v_mfma_f32_16x16x32_bf16 v[74:77], v[182:185], v[228:231], v[74:77]
	v_mfma_f32_16x16x32_bf16 v[70:73], v[190:193], v[228:231], v[70:73]
	v_mfma_f32_16x16x32_bf16 v[122:125], v[186:189], v[202:205], v[122:125]
	v_mfma_f32_16x16x32_bf16 v[118:121], v[194:197], v[202:205], v[118:121]
	v_mfma_f32_16x16x32_bf16 v[106:109], v[186:189], v[210:213], v[106:109]
	v_mfma_f32_16x16x32_bf16 v[102:105], v[194:197], v[210:213], v[102:105]
	v_mfma_f32_16x16x32_bf16 v[90:93], v[186:189], v[224:227], v[90:93]
	v_mfma_f32_16x16x32_bf16 v[86:89], v[194:197], v[224:227], v[86:89]
	v_mfma_f32_16x16x32_bf16 v[74:77], v[186:189], v[232:235], v[74:77]
	v_mfma_f32_16x16x32_bf16 v[70:73], v[194:197], v[232:235], v[70:73]
	s_barrier
	s_add_i32 s11, s56, s29
	v_lshl_add_u64 v[238:239], v[236:237], 0, v[158:159]
	s_mov_b32 m0, s11
	ds_read_b128 v[198:201], v218 offset:16384
	ds_read_b128 v[202:205], v218 offset:17408
	ds_read_b128 v[206:209], v218 offset:18432
	ds_read_b128 v[210:213], v218 offset:19456
	ds_read_b128 v[220:223], v218 offset:20480
	ds_read_b128 v[224:227], v218 offset:21504
	ds_read_b128 v[228:231], v218 offset:22528
	ds_read_b128 v[232:235], v218 offset:23552
	global_load_lds_dwordx4 v[238:239], off
	v_lshl_add_u64 v[240:241], v[236:237], 0, v[162:163]
	s_add_i32 m0, s11, 0x2000
	v_lshl_add_u64 v[236:237], v[236:237], 0, s[12:13]
	s_add_i32 s11, s57, s29
	global_load_lds_dwordx4 v[240:241], off
	v_lshl_add_u64 v[242:243], v[236:237], 0, v[158:159]
	s_mov_b32 m0, s11
	v_lshl_add_u64 v[236:237], v[236:237], 0, v[162:163]
	global_load_lds_dwordx4 v[242:243], off
	s_add_i32 m0, s11, 0x2000
	v_lshl_add_u64 v[244:245], v[214:215], 0, v[154:155]
	global_load_lds_dwordx4 v[236:237], off
	s_mov_b32 m0, s34
	v_lshl_add_u64 v[246:247], v[214:215], 0, v[160:161]
	global_load_lds_dwordx4 v[244:245], off
	s_mov_b32 m0, s35
	s_nop 0
	global_load_lds_dwordx4 v[246:247], off
	s_waitcnt vmcnt(8) lgkmcnt(0)
	s_barrier
; #define PG8_STAGE(bufoff, gbase, voff) do { _Pragma("unroll") for (int _i = 0; _i < 2; ++_i) \
;         __builtin_amdgcn_global_load_lds((const unsigned*)((const char*)(gbase) + (voff)[_i]), (PG8_LAS unsigned*)(lds + (bufoff) + ldsw + _i * 8192), 16, 0, 0); } while (0)
; #define PG8_LDA(dst, b, h) do { _Pragma("unroll") for (int m = 0; m < 4; ++m) _Pragma("unroll") for (int k = 0; k < 2; ++k) dst[m][k] = *(const PG8_LAS bf16x8*)(lds + PG8_SA(b, h) + aoff + m * 2048 + k * 1024); } while (0)
; #define PG8_LDB(dst, b, h) do { _Pragma("unroll") for (int n = 0; n < 2; ++n) _Pragma("unroll") for (int k = 0; k < 2; ++k) dst[n][k] = *(const PG8_LAS bf16x8*)(lds + PG8_SB(b, h) + boff + n * 2048 + k * 1024); } while (0)
; #define PG8_MMA(ai, bj, At, Bt) do { __builtin_amdgcn_s_setprio(1); _Pragma("unroll") for (int m = 0; m < 4; ++m) _Pragma("unroll") for (int n = 0; n < 2; ++n) _Pragma("unroll") for (int k = 0; k < 2; ++k) \
;         acc[ai][bj][m][n] = __builtin_amdgcn_mfma_f32_16x16x32_bf16(Bt[n][k], At[m][k], acc[ai][bj][m][n], 0, 0, 0); __builtin_amdgcn_s_setprio(0); } while (0)
; #define PG8_WAIT_V(n) asm volatile("s_waitcnt vmcnt(" #n ")" ::: "memory")
; #define PG8_WAIT_L(n) asm volatile("s_waitcnt lgkmcnt(" #n ")" ::: "memory")
; #define PG8_BAR __builtin_amdgcn_s_barrier()
; #define PG8_SCHED __builtin_amdgcn_sched_barrier(0)
; template <class Epi, class Sched, bool ALIGN_EPI = false, bool SP2 = false>
; __device__ __forceinline__ void gemm_phase(PG8_LAS unsigned char* lds, const Gemm g, const Sched& S, const Epi& E) {
;     ...
;             PG8_WAIT_V(8); PG8_WAIT_L(0); PG8_BAR; PG8_MMA(1, 0, At, B0); PG8_MMA(1, 1, At, B1); PG8_BAR; PG8_SCHED;
;             PG8_LDB(B0, 1, 0); PG8_LDB(B1, 1, 1); PG8_SCHED; PG8_LDA(At, 1, 0); PG8_STAGE(PG8_SA(0, 1), a2 + hstep, voffA);
;             PG8_WAIT_V(8); PG8_WAIT_L(0); PG8_BAR; PG8_MMA(0, 0, At, B0); PG8_MMA(0, 1, At, B1); PG8_BAR; PG8_SCHED;
	v_mfma_f32_16x16x32_bf16 v[66:69], v[138:141], v[198:201], v[66:69]
	v_mfma_f32_16x16x32_bf16 v[62:65], v[146:149], v[198:201], v[62:65]
	v_mfma_f32_16x16x32_bf16 v[50:53], v[138:141], v[206:209], v[50:53]
	v_mfma_f32_16x16x32_bf16 v[46:49], v[146:149], v[206:209], v[46:49]
	v_mfma_f32_16x16x32_bf16 v[34:37], v[138:141], v[220:223], v[34:37]
	v_mfma_f32_16x16x32_bf16 v[30:33], v[146:149], v[220:223], v[30:33]
	v_mfma_f32_16x16x32_bf16 v[18:21], v[138:141], v[228:231], v[18:21]
	v_mfma_f32_16x16x32_bf16 v[14:17], v[146:149], v[228:231], v[14:17]
	v_mfma_f32_16x16x32_bf16 v[66:69], v[142:145], v[202:205], v[66:69]
	v_mfma_f32_16x16x32_bf16 v[62:65], v[178:181], v[202:205], v[62:65]
	v_mfma_f32_16x16x32_bf16 v[50:53], v[142:145], v[210:213], v[50:53]
	v_mfma_f32_16x16x32_bf16 v[46:49], v[178:181], v[210:213], v[46:49]
	v_mfma_f32_16x16x32_bf16 v[34:37], v[142:145], v[224:227], v[34:37]
	v_mfma_f32_16x16x32_bf16 v[30:33], v[178:181], v[224:227], v[30:33]
	v_mfma_f32_16x16x32_bf16 v[18:21], v[142:145], v[232:235], v[18:21]
	v_mfma_f32_16x16x32_bf16 v[14:17], v[178:181], v[232:235], v[14:17]
	v_mfma_f32_16x16x32_bf16 v[58:61], v[182:185], v[198:201], v[58:61]
	v_mfma_f32_16x16x32_bf16 v[54:57], v[190:193], v[198:201], v[54:57]
	v_mfma_f32_16x16x32_bf16 v[42:45], v[182:185], v[206:209], v[42:45]
	v_mfma_f32_16x16x32_bf16 v[38:41], v[190:193], v[206:209], v[38:41]
	v_mfma_f32_16x16x32_bf16 v[26:29], v[182:185], v[220:223], v[26:29]
	v_mfma_f32_16x16x32_bf16 v[22:25], v[190:193], v[220:223], v[22:25]
	v_mfma_f32_16x16x32_bf16 v[10:13], v[182:185], v[228:231], v[10:13]
	v_mfma_f32_16x16x32_bf16 v[6:9], v[190:193], v[228:231], v[6:9]
	v_mfma_f32_16x16x32_bf16 v[58:61], v[186:189], v[202:205], v[58:61]
	v_mfma_f32_16x16x32_bf16 v[54:57], v[194:197], v[202:205], v[54:57]
	v_mfma_f32_16x16x32_bf16 v[42:45], v[186:189], v[210:213], v[42:45]
	v_mfma_f32_16x16x32_bf16 v[38:41], v[194:197], v[210:213], v[38:41]
	v_mfma_f32_16x16x32_bf16 v[26:29], v[186:189], v[224:227], v[26:29]
	v_mfma_f32_16x16x32_bf16 v[22:25], v[194:197], v[224:227], v[22:25]
	v_mfma_f32_16x16x32_bf16 v[10:13], v[186:189], v[232:235], v[10:13]
	v_mfma_f32_16x16x32_bf16 v[6:9], v[194:197], v[232:235], v[6:9]
	s_barrier
	s_add_i32 s11, 0, 0x18000
	s_add_i32 s31, 0, 0x1c000
	ds_read_b128 v[138:141], v255 offset:32768
	ds_read_b128 v[142:145], v255 offset:33792
	ds_read_b128 v[146:149], v255 offset:34816
	ds_read_b128 v[178:181], v255 offset:35840
	ds_read_b128 v[182:185], v255 offset:49152
	ds_read_b128 v[186:189], v255 offset:50176
	ds_read_b128 v[190:193], v255 offset:51200
	ds_read_b128 v[194:197], v255 offset:52224
	v_lshl_add_u64 v[214:215], v[214:215], 0, s[12:13]
	s_mov_b32 m0, s36
	v_lshl_add_u64 v[248:249], v[214:215], 0, v[154:155]
	ds_read_b128 v[198:201], v218 offset:32768
	ds_read_b128 v[202:205], v218 offset:33792
	ds_read_b128 v[206:209], v218 offset:34816
	ds_read_b128 v[210:213], v218 offset:35840
	ds_read_b128 v[220:223], v218 offset:36864
	ds_read_b128 v[224:227], v218 offset:37888
	ds_read_b128 v[228:231], v218 offset:38912
	ds_read_b128 v[232:235], v218 offset:39936
	global_load_lds_dwordx4 v[248:249], off
	s_mov_b32 m0, s37
	v_lshl_add_u64 v[214:215], v[214:215], 0, v[160:161]
	global_load_lds_dwordx4 v[214:215], off
	s_waitcnt vmcnt(8) lgkmcnt(0)
	s_barrier
	v_mfma_f32_16x16x32_bf16 v[130:133], v[138:141], v[198:201], v[130:133]
	v_mfma_f32_16x16x32_bf16 v[126:129], v[146:149], v[198:201], v[126:129]
	v_mfma_f32_16x16x32_bf16 v[114:117], v[138:141], v[206:209], v[114:117]
	v_mfma_f32_16x16x32_bf16 v[110:113], v[146:149], v[206:209], v[110:113]
	v_mfma_f32_16x16x32_bf16 v[98:101], v[138:141], v[220:223], v[98:101]
	v_mfma_f32_16x16x32_bf16 v[94:97], v[146:149], v[220:223], v[94:97]
	v_mfma_f32_16x16x32_bf16 v[82:85], v[138:141], v[228:231], v[82:85]
	v_mfma_f32_16x16x32_bf16 v[78:81], v[146:149], v[228:231], v[78:81]
	v_mfma_f32_16x16x32_bf16 v[130:133], v[142:145], v[202:205], v[130:133]
	v_mfma_f32_16x16x32_bf16 v[126:129], v[178:181], v[202:205], v[126:129]
	v_mfma_f32_16x16x32_bf16 v[114:117], v[142:145], v[210:213], v[114:117]
	v_mfma_f32_16x16x32_bf16 v[110:113], v[178:181], v[210:213], v[110:113]
	v_mfma_f32_16x16x32_bf16 v[98:101], v[142:145], v[224:227], v[98:101]
	v_mfma_f32_16x16x32_bf16 v[94:97], v[178:181], v[224:227], v[94:97]
	v_mfma_f32_16x16x32_bf16 v[82:85], v[142:145], v[232:235], v[82:85]
	v_mfma_f32_16x16x32_bf16 v[78:81], v[178:181], v[232:235], v[78:81]
	v_mfma_f32_16x16x32_bf16 v[122:125], v[182:185], v[198:201], v[122:125]
	v_mfma_f32_16x16x32_bf16 v[118:121], v[190:193], v[198:201], v[118:121]
	v_mfma_f32_16x16x32_bf16 v[106:109], v[182:185], v[206:209], v[106:109]
	v_mfma_f32_16x16x32_bf16 v[102:105], v[190:193], v[206:209], v[102:105]
	v_mfma_f32_16x16x32_bf16 v[90:93], v[182:185], v[220:223], v[90:93]
	v_mfma_f32_16x16x32_bf16 v[86:89], v[190:193], v[220:223], v[86:89]
	v_mfma_f32_16x16x32_bf16 v[74:77], v[182:185], v[228:231], v[74:77]
	v_mfma_f32_16x16x32_bf16 v[70:73], v[190:193], v[228:231], v[70:73]
	v_mfma_f32_16x16x32_bf16 v[122:125], v[186:189], v[202:205], v[122:125]
	v_mfma_f32_16x16x32_bf16 v[118:121], v[194:197], v[202:205], v[118:121]
	v_mfma_f32_16x16x32_bf16 v[106:109], v[186:189], v[210:213], v[106:109]
	v_mfma_f32_16x16x32_bf16 v[102:105], v[194:197], v[210:213], v[102:105]
	v_mfma_f32_16x16x32_bf16 v[90:93], v[186:189], v[224:227], v[90:93]
	v_mfma_f32_16x16x32_bf16 v[86:89], v[194:197], v[224:227], v[86:89]
	v_mfma_f32_16x16x32_bf16 v[74:77], v[186:189], v[232:235], v[74:77]
	v_mfma_f32_16x16x32_bf16 v[70:73], v[194:197], v[232:235], v[70:73]
	s_barrier
; #define PG8_STAGE(bufoff, gbase, voff) do { _Pragma("unroll") for (int _i = 0; _i < 2; ++_i) \
;         __builtin_amdgcn_global_load_lds((const unsigned*)((const char*)(gbase) + (voff)[_i]), (PG8_LAS unsigned*)(lds + (bufoff) + ldsw + _i * 8192), 16, 0, 0); } while (0)
; #define PG8_LDA(dst, b, h) do { _Pragma("unroll") for (int m = 0; m < 4; ++m) _Pragma("unroll") for (int k = 0; k < 2; ++k) dst[m][k] = *(const PG8_LAS bf16x8*)(lds + PG8_SA(b, h) + aoff + m * 2048 + k * 1024); } while (0)
; #define PG8_MMA(ai, bj, At, Bt) do { __builtin_amdgcn_s_setprio(1); _Pragma("unroll") for (int m = 0; m < 4; ++m) _Pragma("unroll") for (int n = 0; n < 2; ++n) _Pragma("unroll") for (int k = 0; k < 2; ++k) \
;         acc[ai][bj][m][n] = __builtin_amdgcn_mfma_f32_16x16x32_bf16(Bt[n][k], At[m][k], acc[ai][bj][m][n], 0, 0, 0); __builtin_amdgcn_s_setprio(0); } while (0)
; #define PG8_WAIT_V(n) asm volatile("s_waitcnt vmcnt(" #n ")" ::: "memory")
; #define PG8_WAIT_L(n) asm volatile("s_waitcnt lgkmcnt(" #n ")" ::: "memory")
; #define PG8_BAR __builtin_amdgcn_s_barrier()
; #define PG8_SCHED __builtin_amdgcn_sched_barrier(0)
; template <class Epi, class Sched, bool ALIGN_EPI = false, bool SP2 = false>
; __device__ __forceinline__ void gemm_phase(PG8_LAS unsigned char* lds, const Gemm g, const Sched& S, const Epi& E) {
;     ...
;         for (int t = 0; t < nt; t += 2) {
;     ...
;             PG8_LDA(At, 1, 1); PG8_STAGE(PG8_SB(1, 0), b3, voffB); PG8_STAGE(PG8_SB(1, 1), b3 + hstep, voffB); PG8_STAGE(PG8_SA(1, 0), a3, voffA);
;             PG8_WAIT_V(8); PG8_WAIT_L(0); PG8_BAR; PG8_MMA(1, 0, At, B0); PG8_MMA(1, 1, At, B1); PG8_BAR; PG8_SCHED;
	s_add_i32 s11, s11, s29
	s_add_i32 m0, s11, 0xffffff80
	ds_read_b128 v[198:201], v218 offset:49152
	ds_read_b128 v[202:205], v218 offset:50176
	ds_read_b128 v[206:209], v218 offset:51200
	ds_read_b128 v[210:213], v218 offset:52224
	global_load_lds_dwordx4 v[238:239], off offset:128
	s_add_i32 m0, s11, 0x1f80
	s_add_i32 s11, s31, s29
	global_load_lds_dwordx4 v[240:241], off offset:128
	s_add_i32 m0, s11, 0xffffff80
	ds_read_b128 v[232:235], v218 offset:56320
	global_load_lds_dwordx4 v[242:243], off offset:128
	s_add_i32 m0, s11, 0x1f80
	ds_read_b128 v[228:231], v218 offset:55296
	global_load_lds_dwordx4 v[236:237], off offset:128
	s_add_i32 m0, s41, 0xffffff80
	ds_read_b128 v[224:227], v218 offset:54272
	global_load_lds_dwordx4 v[244:245], off offset:128
	s_add_i32 m0, s46, 0xffffff80
	ds_read_b128 v[220:223], v218 offset:53248
	global_load_lds_dwordx4 v[246:247], off offset:128
	s_waitcnt vmcnt(8) lgkmcnt(0)
	s_barrier
	v_mfma_f32_16x16x32_bf16 v[66:69], v[138:141], v[198:201], v[66:69]
	v_mfma_f32_16x16x32_bf16 v[62:65], v[146:149], v[198:201], v[62:65]
	v_mfma_f32_16x16x32_bf16 v[50:53], v[138:141], v[206:209], v[50:53]
	v_mfma_f32_16x16x32_bf16 v[46:49], v[146:149], v[206:209], v[46:49]
	v_mfma_f32_16x16x32_bf16 v[34:37], v[138:141], v[220:223], v[34:37]
	v_mfma_f32_16x16x32_bf16 v[30:33], v[146:149], v[220:223], v[30:33]
	v_mfma_f32_16x16x32_bf16 v[18:21], v[138:141], v[228:231], v[18:21]
	v_mfma_f32_16x16x32_bf16 v[14:17], v[146:149], v[228:231], v[14:17]
	v_mfma_f32_16x16x32_bf16 v[66:69], v[142:145], v[202:205], v[66:69]
	v_mfma_f32_16x16x32_bf16 v[62:65], v[178:181], v[202:205], v[62:65]
	v_mfma_f32_16x16x32_bf16 v[50:53], v[142:145], v[210:213], v[50:53]
	v_mfma_f32_16x16x32_bf16 v[46:49], v[178:181], v[210:213], v[46:49]
	v_mfma_f32_16x16x32_bf16 v[34:37], v[142:145], v[224:227], v[34:37]
	v_mfma_f32_16x16x32_bf16 v[30:33], v[178:181], v[224:227], v[30:33]
	v_mfma_f32_16x16x32_bf16 v[18:21], v[142:145], v[232:235], v[18:21]
	v_mfma_f32_16x16x32_bf16 v[14:17], v[178:181], v[232:235], v[14:17]
	v_mfma_f32_16x16x32_bf16 v[58:61], v[182:185], v[198:201], v[58:61]
	v_mfma_f32_16x16x32_bf16 v[54:57], v[190:193], v[198:201], v[54:57]
	v_mfma_f32_16x16x32_bf16 v[42:45], v[182:185], v[206:209], v[42:45]
	v_mfma_f32_16x16x32_bf16 v[38:41], v[190:193], v[206:209], v[38:41]
	v_mfma_f32_16x16x32_bf16 v[26:29], v[182:185], v[220:223], v[26:29]
	v_mfma_f32_16x16x32_bf16 v[22:25], v[190:193], v[220:223], v[22:25]
	v_mfma_f32_16x16x32_bf16 v[10:13], v[182:185], v[228:231], v[10:13]
	v_mfma_f32_16x16x32_bf16 v[6:9], v[190:193], v[228:231], v[6:9]
	v_mfma_f32_16x16x32_bf16 v[58:61], v[186:189], v[202:205], v[58:61]
	v_mfma_f32_16x16x32_bf16 v[54:57], v[194:197], v[202:205], v[54:57]
	v_mfma_f32_16x16x32_bf16 v[42:45], v[186:189], v[210:213], v[42:45]
	v_mfma_f32_16x16x32_bf16 v[38:41], v[194:197], v[210:213], v[38:41]
	v_mfma_f32_16x16x32_bf16 v[26:29], v[186:189], v[224:227], v[26:29]
	v_mfma_f32_16x16x32_bf16 v[22:25], v[194:197], v[224:227], v[22:25]
	v_mfma_f32_16x16x32_bf16 v[10:13], v[186:189], v[232:235], v[10:13]
	v_mfma_f32_16x16x32_bf16 v[6:9], v[194:197], v[232:235], v[6:9]
	s_barrier
	v_lshl_add_u64 v[134:135], v[134:135], 0, s[26:27]
	s_cmp_ge_i32 s10, s48
	v_lshl_add_u64 v[136:137], v[136:137], 0, s[26:27]
	s_cbranch_scc0 .LBB0_1192

; #define PG8_STAGE(bufoff, gbase, voff) do { _Pragma("unroll") for (int _i = 0; _i < 2; ++_i) \
;         __builtin_amdgcn_global_load_lds((const unsigned*)((const char*)(gbase) + (voff)[_i]), (PG8_LAS unsigned*)(lds + (bufoff) + ldsw + _i * 8192), 16, 0, 0); } while (0)
; #define PG8_LDA(dst, b, h) do { _Pragma("unroll") for (int m = 0; m < 4; ++m) _Pragma("unroll") for (int k = 0; k < 2; ++k) dst[m][k] = *(const PG8_LAS bf16x8*)(lds + PG8_SA(b, h) + aoff + m * 2048 + k * 1024); } while (0)
; #define PG8_LDB(dst, b, h) do { _Pragma("unroll") for (int n = 0; n < 2; ++n) _Pragma("unroll") for (int k = 0; k < 2; ++k) dst[n][k] = *(const PG8_LAS bf16x8*)(lds + PG8_SB(b, h) + boff + n * 2048 + k * 1024); } while (0)
; #define PG8_MMA(ai, bj, At, Bt) do { __builtin_amdgcn_s_setprio(1); _Pragma("unroll") for (int m = 0; m < 4; ++m) _Pragma("unroll") for (int n = 0; n < 2; ++n) _Pragma("unroll") for (int k = 0; k < 2; ++k) \
;         acc[ai][bj][m][n] = __builtin_amdgcn_mfma_f32_16x16x32_bf16(Bt[n][k], At[m][k], acc[ai][bj][m][n], 0, 0, 0); __builtin_amdgcn_s_setprio(0); } while (0)
; #define PG8_WAIT_V(n) asm volatile("s_waitcnt vmcnt(" #n ")" ::: "memory")
; #define PG8_WAIT_L(n) asm volatile("s_waitcnt lgkmcnt(" #n ")" ::: "memory")
; #define PG8_BAR __builtin_amdgcn_s_barrier()
; template <class Epi, class Sched, bool ALIGN_EPI = false, bool SP2 = false>
; __device__ __forceinline__ void gemm_phase(PG8_LAS unsigned char* lds, const Gemm g, const Sched& S, const Epi& E) {
;     ...
;             const char* a1 = cA + (size_t)(t + 1) * kstep;
;             const char* a2 = last ? nA : cA + (size_t)(t + 2) * kstep; const char* b2 = last ? nB : cB + (size_t)(t + 2) * kstep;
;             const char* a3 = a2 + kstep; const char* b3 = b2 + kstep;
;             if (last && has_next) S.a_ready(nxt);
;             if constexpr (SP2) {
;             PG8_LDB(B0, 0, 0); PG8_LDB(B1, 0, 1); PG8_SCHED; PG8_LDA(At, 0, 0); PG8_STAGE(PG8_SA(1, 1), a1 + hstep, voffA);
;             PG8_WAIT_V(8); PG8_WAIT_L(0); PG8_BAR; PG8_MMA(0, 0, At, B0); PG8_MMA(0, 1, At, B1); PG8_BAR; PG8_SCHED;
;             PG8_LDA(At, 0, 1); PG8_STAGE(PG8_SB(0, 0), b2, voffB); PG8_STAGE(PG8_SB(0, 1), b2 + hstep, voffB); PG8_STAGE(PG8_SA(0, 0), a2, voffA);
;             PG8_WAIT_V(8); PG8_WAIT_L(0); PG8_BAR; PG8_MMA(1, 0, At, B0); PG8_MMA(1, 1, At, B1); PG8_BAR; PG8_SCHED;
.LBB0_1340:
	v_add_u32_e32 v255, s55, v201
	ds_read_b128 v[136:139], v255
	ds_read_b128 v[140:143], v255 offset:1024
	ds_read_b128 v[144:147], v255 offset:2048
	ds_read_b128 v[148:151], v255 offset:3072
	ds_read_b128 v[152:155], v255 offset:16384
	ds_read_b128 v[182:185], v255 offset:17408
	ds_read_b128 v[186:189], v255 offset:18432
	ds_read_b128 v[190:193], v255 offset:19456
	s_cmp_eq_u32 s48, s12
	v_lshl_add_u64 v[194:195], v[134:135], 0, s[22:23]
	s_cselect_b64 vcc, -1, 0
	s_add_i32 s12, s12, 2
	v_cndmask_b32_e32 v199, v195, v179, vcc
	v_cndmask_b32_e32 v198, v194, v178, vcc
	v_cndmask_b32_e32 v215, v133, v181, vcc
	v_cndmask_b32_e32 v214, v132, v180, vcc
	s_mov_b32 m0, s57
	v_lshl_add_u64 v[236:237], v[134:135], 0, v[174:175]
	ds_read_b128 v[194:197], v203
	ds_read_b128 v[206:209], v203 offset:1024
	ds_read_b128 v[210:213], v203 offset:2048
	ds_read_b128 v[216:219], v203 offset:3072
	ds_read_b128 v[220:223], v203 offset:4096
	ds_read_b128 v[224:227], v203 offset:5120
	ds_read_b128 v[228:231], v203 offset:6144
	ds_read_b128 v[232:235], v203 offset:7168
	global_load_lds_dwordx4 v[236:237], off
	s_mov_b32 m0, s58
	v_lshl_add_u64 v[236:237], v[134:135], 0, v[172:173]
	global_load_lds_dwordx4 v[236:237], off
	s_waitcnt vmcnt(8) lgkmcnt(0)
	s_barrier
	v_mfma_f32_16x16x32_bf16 v[124:127], v[136:139], v[194:197], v[124:127]
	v_mfma_f32_16x16x32_bf16 v[128:131], v[144:147], v[194:197], v[128:131]
	v_mfma_f32_16x16x32_bf16 v[112:115], v[136:139], v[210:213], v[112:115]
	v_mfma_f32_16x16x32_bf16 v[108:111], v[144:147], v[210:213], v[108:111]
	v_mfma_f32_16x16x32_bf16 v[96:99], v[136:139], v[220:223], v[96:99]
	v_mfma_f32_16x16x32_bf16 v[92:95], v[144:147], v[220:223], v[92:95]
	v_mfma_f32_16x16x32_bf16 v[80:83], v[136:139], v[228:231], v[80:83]
	v_mfma_f32_16x16x32_bf16 v[76:79], v[144:147], v[228:231], v[76:79]
	v_mfma_f32_16x16x32_bf16 v[124:127], v[140:143], v[206:209], v[124:127]
	v_mfma_f32_16x16x32_bf16 v[128:131], v[148:151], v[206:209], v[128:131]
	v_mfma_f32_16x16x32_bf16 v[112:115], v[140:143], v[216:219], v[112:115]
	v_mfma_f32_16x16x32_bf16 v[108:111], v[148:151], v[216:219], v[108:111]
	v_mfma_f32_16x16x32_bf16 v[96:99], v[140:143], v[224:227], v[96:99]
	v_mfma_f32_16x16x32_bf16 v[92:95], v[148:151], v[224:227], v[92:95]
	v_mfma_f32_16x16x32_bf16 v[80:83], v[140:143], v[232:235], v[80:83]
	v_mfma_f32_16x16x32_bf16 v[76:79], v[148:151], v[232:235], v[76:79]
	v_mfma_f32_16x16x32_bf16 v[120:123], v[152:155], v[194:197], v[120:123]
	v_mfma_f32_16x16x32_bf16 v[116:119], v[186:189], v[194:197], v[116:119]
	v_mfma_f32_16x16x32_bf16 v[104:107], v[152:155], v[210:213], v[104:107]
	v_mfma_f32_16x16x32_bf16 v[100:103], v[186:189], v[210:213], v[100:103]
	v_mfma_f32_16x16x32_bf16 v[88:91], v[152:155], v[220:223], v[88:91]
	v_mfma_f32_16x16x32_bf16 v[84:87], v[186:189], v[220:223], v[84:87]
	v_mfma_f32_16x16x32_bf16 v[72:75], v[152:155], v[228:231], v[72:75]
	v_mfma_f32_16x16x32_bf16 v[68:71], v[186:189], v[228:231], v[68:71]
	v_mfma_f32_16x16x32_bf16 v[120:123], v[182:185], v[206:209], v[120:123]
	v_mfma_f32_16x16x32_bf16 v[116:119], v[190:193], v[206:209], v[116:119]
	v_mfma_f32_16x16x32_bf16 v[104:107], v[182:185], v[216:219], v[104:107]
	v_mfma_f32_16x16x32_bf16 v[100:103], v[190:193], v[216:219], v[100:103]
	v_mfma_f32_16x16x32_bf16 v[88:91], v[182:185], v[224:227], v[88:91]
	v_mfma_f32_16x16x32_bf16 v[84:87], v[190:193], v[224:227], v[84:87]
	v_mfma_f32_16x16x32_bf16 v[72:75], v[182:185], v[232:235], v[72:75]
	v_mfma_f32_16x16x32_bf16 v[68:71], v[190:193], v[232:235], v[68:71]
	s_barrier
	s_mov_b32 m0, s59
	v_lshl_add_u64 v[236:237], v[214:215], 0, v[166:167]
	ds_read_b128 v[194:197], v203 offset:16384
	ds_read_b128 v[206:209], v203 offset:17408
	ds_read_b128 v[210:213], v203 offset:18432
	ds_read_b128 v[216:219], v203 offset:19456
	ds_read_b128 v[220:223], v203 offset:20480
	ds_read_b128 v[224:227], v203 offset:21504
	ds_read_b128 v[228:231], v203 offset:22528
	ds_read_b128 v[232:235], v203 offset:23552
	global_load_lds_dwordx4 v[236:237], off
	v_lshl_add_u64 v[238:239], v[214:215], 0, v[170:171]
	s_mov_b32 m0, s60
	v_lshl_add_u64 v[214:215], v[214:215], 0, s[14:15]
	s_add_i32 s13, s56, s30
	global_load_lds_dwordx4 v[238:239], off
	v_lshl_add_u64 v[240:241], v[214:215], 0, v[166:167]
	s_mov_b32 m0, s13
	v_lshl_add_u64 v[214:215], v[214:215], 0, v[170:171]
	global_load_lds_dwordx4 v[240:241], off
	s_add_i32 m0, s13, 0x2000
	v_lshl_add_u64 v[242:243], v[198:199], 0, v[164:165]
	global_load_lds_dwordx4 v[214:215], off
	s_mov_b32 m0, s31
	v_lshl_add_u64 v[244:245], v[198:199], 0, v[168:169]
	global_load_lds_dwordx4 v[242:243], off
	s_mov_b32 m0, s34
	s_nop 0
	global_load_lds_dwordx4 v[244:245], off
	s_waitcnt vmcnt(8) lgkmcnt(0)
	s_barrier
; #define PG8_STAGE(bufoff, gbase, voff) do { _Pragma("unroll") for (int _i = 0; _i < 2; ++_i) \
;         __builtin_amdgcn_global_load_lds((const unsigned*)((const char*)(gbase) + (voff)[_i]), (PG8_LAS unsigned*)(lds + (bufoff) + ldsw + _i * 8192), 16, 0, 0); } while (0)
; #define PG8_LDA(dst, b, h) do { _Pragma("unroll") for (int m = 0; m < 4; ++m) _Pragma("unroll") for (int k = 0; k < 2; ++k) dst[m][k] = *(const PG8_LAS bf16x8*)(lds + PG8_SA(b, h) + aoff + m * 2048 + k * 1024); } while (0)
; #define PG8_LDB(dst, b, h) do { _Pragma("unroll") for (int n = 0; n < 2; ++n) _Pragma("unroll") for (int k = 0; k < 2; ++k) dst[n][k] = *(const PG8_LAS bf16x8*)(lds + PG8_SB(b, h) + boff + n * 2048 + k * 1024); } while (0)
; #define PG8_MMA(ai, bj, At, Bt) do { __builtin_amdgcn_s_setprio(1); _Pragma("unroll") for (int m = 0; m < 4; ++m) _Pragma("unroll") for (int n = 0; n < 2; ++n) _Pragma("unroll") for (int k = 0; k < 2; ++k) \
;         acc[ai][bj][m][n] = __builtin_amdgcn_mfma_f32_16x16x32_bf16(Bt[n][k], At[m][k], acc[ai][bj][m][n], 0, 0, 0); __builtin_amdgcn_s_setprio(0); } while (0)
; #define PG8_WAIT_V(n) asm volatile("s_waitcnt vmcnt(" #n ")" ::: "memory")
; #define PG8_WAIT_L(n) asm volatile("s_waitcnt lgkmcnt(" #n ")" ::: "memory")
; #define PG8_BAR __builtin_amdgcn_s_barrier()
; #define PG8_SCHED __builtin_amdgcn_sched_barrier(0)
; template <class Epi, class Sched, bool ALIGN_EPI = false, bool SP2 = false>
; __device__ __forceinline__ void gemm_phase(PG8_LAS unsigned char* lds, const Gemm g, const Sched& S, const Epi& E) {
;     ...
;             PG8_WAIT_V(8); PG8_WAIT_L(0); PG8_BAR; PG8_MMA(1, 0, At, B0); PG8_MMA(1, 1, At, B1); PG8_BAR; PG8_SCHED;
;             PG8_LDB(B0, 1, 0); PG8_LDB(B1, 1, 1); PG8_SCHED; PG8_LDA(At, 1, 0); PG8_STAGE(PG8_SA(0, 1), a2 + hstep, voffA);
;             PG8_WAIT_V(8); PG8_WAIT_L(0); PG8_BAR; PG8_MMA(0, 0, At, B0); PG8_MMA(0, 1, At, B1); PG8_BAR; PG8_SCHED;
	v_mfma_f32_16x16x32_bf16 v[64:67], v[136:139], v[194:197], v[64:67]
	v_mfma_f32_16x16x32_bf16 v[60:63], v[144:147], v[194:197], v[60:63]
	v_mfma_f32_16x16x32_bf16 v[48:51], v[136:139], v[210:213], v[48:51]
	v_mfma_f32_16x16x32_bf16 v[44:47], v[144:147], v[210:213], v[44:47]
	v_mfma_f32_16x16x32_bf16 v[32:35], v[136:139], v[220:223], v[32:35]
	v_mfma_f32_16x16x32_bf16 v[28:31], v[144:147], v[220:223], v[28:31]
	v_mfma_f32_16x16x32_bf16 v[16:19], v[136:139], v[228:231], v[16:19]
	v_mfma_f32_16x16x32_bf16 v[12:15], v[144:147], v[228:231], v[12:15]
	v_mfma_f32_16x16x32_bf16 v[64:67], v[140:143], v[206:209], v[64:67]
	v_mfma_f32_16x16x32_bf16 v[60:63], v[148:151], v[206:209], v[60:63]
	v_mfma_f32_16x16x32_bf16 v[48:51], v[140:143], v[216:219], v[48:51]
	v_mfma_f32_16x16x32_bf16 v[44:47], v[148:151], v[216:219], v[44:47]
	v_mfma_f32_16x16x32_bf16 v[32:35], v[140:143], v[224:227], v[32:35]
	v_mfma_f32_16x16x32_bf16 v[28:31], v[148:151], v[224:227], v[28:31]
	v_mfma_f32_16x16x32_bf16 v[16:19], v[140:143], v[232:235], v[16:19]
	v_mfma_f32_16x16x32_bf16 v[12:15], v[148:151], v[232:235], v[12:15]
	v_mfma_f32_16x16x32_bf16 v[56:59], v[152:155], v[194:197], v[56:59]
	v_mfma_f32_16x16x32_bf16 v[52:55], v[186:189], v[194:197], v[52:55]
	v_mfma_f32_16x16x32_bf16 v[40:43], v[152:155], v[210:213], v[40:43]
	v_mfma_f32_16x16x32_bf16 v[36:39], v[186:189], v[210:213], v[36:39]
	v_mfma_f32_16x16x32_bf16 v[24:27], v[152:155], v[220:223], v[24:27]
	v_mfma_f32_16x16x32_bf16 v[20:23], v[186:189], v[220:223], v[20:23]
	v_mfma_f32_16x16x32_bf16 v[8:11], v[152:155], v[228:231], v[8:11]
	v_mfma_f32_16x16x32_bf16 v[4:7], v[186:189], v[228:231], v[4:7]
	v_mfma_f32_16x16x32_bf16 v[56:59], v[182:185], v[206:209], v[56:59]
	v_mfma_f32_16x16x32_bf16 v[52:55], v[190:193], v[206:209], v[52:55]
	v_mfma_f32_16x16x32_bf16 v[40:43], v[182:185], v[216:219], v[40:43]
	v_mfma_f32_16x16x32_bf16 v[36:39], v[190:193], v[216:219], v[36:39]
	v_mfma_f32_16x16x32_bf16 v[24:27], v[182:185], v[224:227], v[24:27]
	v_mfma_f32_16x16x32_bf16 v[20:23], v[190:193], v[224:227], v[20:23]
	v_mfma_f32_16x16x32_bf16 v[8:11], v[182:185], v[232:235], v[8:11]
	v_mfma_f32_16x16x32_bf16 v[4:7], v[190:193], v[232:235], v[4:7]
	s_barrier
	s_add_i32 s13, 0, 0x18000
	s_add_i32 s29, 0, 0x1c000
	ds_read_b128 v[136:139], v255 offset:32768
	ds_read_b128 v[140:143], v255 offset:33792
	ds_read_b128 v[144:147], v255 offset:34816
	ds_read_b128 v[148:151], v255 offset:35840
	ds_read_b128 v[152:155], v255 offset:49152
	ds_read_b128 v[182:185], v255 offset:50176
	ds_read_b128 v[186:189], v255 offset:51200
	ds_read_b128 v[190:193], v255 offset:52224
	v_lshl_add_u64 v[198:199], v[198:199], 0, s[14:15]
	s_mov_b32 m0, s35
	v_lshl_add_u64 v[246:247], v[198:199], 0, v[164:165]
	ds_read_b128 v[194:197], v203 offset:32768
	ds_read_b128 v[206:209], v203 offset:33792
	ds_read_b128 v[210:213], v203 offset:34816
	ds_read_b128 v[216:219], v203 offset:35840
	ds_read_b128 v[220:223], v203 offset:36864
	ds_read_b128 v[224:227], v203 offset:37888
	ds_read_b128 v[228:231], v203 offset:38912
	ds_read_b128 v[232:235], v203 offset:39936
	global_load_lds_dwordx4 v[246:247], off
	s_mov_b32 m0, s36
	v_lshl_add_u64 v[198:199], v[198:199], 0, v[168:169]
	global_load_lds_dwordx4 v[198:199], off
	s_waitcnt vmcnt(8) lgkmcnt(0)
	s_barrier
	v_mfma_f32_16x16x32_bf16 v[124:127], v[136:139], v[194:197], v[124:127]
	v_mfma_f32_16x16x32_bf16 v[128:131], v[144:147], v[194:197], v[128:131]
	v_mfma_f32_16x16x32_bf16 v[112:115], v[136:139], v[210:213], v[112:115]
	v_mfma_f32_16x16x32_bf16 v[108:111], v[144:147], v[210:213], v[108:111]
	v_mfma_f32_16x16x32_bf16 v[96:99], v[136:139], v[220:223], v[96:99]
	v_mfma_f32_16x16x32_bf16 v[92:95], v[144:147], v[220:223], v[92:95]
	v_mfma_f32_16x16x32_bf16 v[80:83], v[136:139], v[228:231], v[80:83]
	v_mfma_f32_16x16x32_bf16 v[76:79], v[144:147], v[228:231], v[76:79]
	v_mfma_f32_16x16x32_bf16 v[124:127], v[140:143], v[206:209], v[124:127]
	v_mfma_f32_16x16x32_bf16 v[128:131], v[148:151], v[206:209], v[128:131]
	v_mfma_f32_16x16x32_bf16 v[112:115], v[140:143], v[216:219], v[112:115]
	v_mfma_f32_16x16x32_bf16 v[108:111], v[148:151], v[216:219], v[108:111]
	v_mfma_f32_16x16x32_bf16 v[96:99], v[140:143], v[224:227], v[96:99]
	v_mfma_f32_16x16x32_bf16 v[92:95], v[148:151], v[224:227], v[92:95]
	v_mfma_f32_16x16x32_bf16 v[80:83], v[140:143], v[232:235], v[80:83]
	v_mfma_f32_16x16x32_bf16 v[76:79], v[148:151], v[232:235], v[76:79]
	v_mfma_f32_16x16x32_bf16 v[120:123], v[152:155], v[194:197], v[120:123]
	v_mfma_f32_16x16x32_bf16 v[116:119], v[186:189], v[194:197], v[116:119]
	v_mfma_f32_16x16x32_bf16 v[104:107], v[152:155], v[210:213], v[104:107]
	v_mfma_f32_16x16x32_bf16 v[100:103], v[186:189], v[210:213], v[100:103]
	v_mfma_f32_16x16x32_bf16 v[88:91], v[152:155], v[220:223], v[88:91]
	v_mfma_f32_16x16x32_bf16 v[84:87], v[186:189], v[220:223], v[84:87]
	v_mfma_f32_16x16x32_bf16 v[72:75], v[152:155], v[228:231], v[72:75]
	v_mfma_f32_16x16x32_bf16 v[68:71], v[186:189], v[228:231], v[68:71]
	v_mfma_f32_16x16x32_bf16 v[120:123], v[182:185], v[206:209], v[120:123]
	v_mfma_f32_16x16x32_bf16 v[116:119], v[190:193], v[206:209], v[116:119]
	v_mfma_f32_16x16x32_bf16 v[104:107], v[182:185], v[216:219], v[104:107]
	v_mfma_f32_16x16x32_bf16 v[100:103], v[190:193], v[216:219], v[100:103]
	v_mfma_f32_16x16x32_bf16 v[88:91], v[182:185], v[224:227], v[88:91]
	v_mfma_f32_16x16x32_bf16 v[84:87], v[190:193], v[224:227], v[84:87]
	v_mfma_f32_16x16x32_bf16 v[72:75], v[182:185], v[232:235], v[72:75]
	v_mfma_f32_16x16x32_bf16 v[68:71], v[190:193], v[232:235], v[68:71]
	s_barrier
; #define PG8_STAGE(bufoff, gbase, voff) do { _Pragma("unroll") for (int _i = 0; _i < 2; ++_i) \
;         __builtin_amdgcn_global_load_lds((const unsigned*)((const char*)(gbase) + (voff)[_i]), (PG8_LAS unsigned*)(lds + (bufoff) + ldsw + _i * 8192), 16, 0, 0); } while (0)
; #define PG8_LDA(dst, b, h) do { _Pragma("unroll") for (int m = 0; m < 4; ++m) _Pragma("unroll") for (int k = 0; k < 2; ++k) dst[m][k] = *(const PG8_LAS bf16x8*)(lds + PG8_SA(b, h) + aoff + m * 2048 + k * 1024); } while (0)
; #define PG8_MMA(ai, bj, At, Bt) do { __builtin_amdgcn_s_setprio(1); _Pragma("unroll") for (int m = 0; m < 4; ++m) _Pragma("unroll") for (int n = 0; n < 2; ++n) _Pragma("unroll") for (int k = 0; k < 2; ++k) \
;         acc[ai][bj][m][n] = __builtin_amdgcn_mfma_f32_16x16x32_bf16(Bt[n][k], At[m][k], acc[ai][bj][m][n], 0, 0, 0); __builtin_amdgcn_s_setprio(0); } while (0)
; #define PG8_WAIT_V(n) asm volatile("s_waitcnt vmcnt(" #n ")" ::: "memory")
; #define PG8_WAIT_L(n) asm volatile("s_waitcnt lgkmcnt(" #n ")" ::: "memory")
; #define PG8_BAR __builtin_amdgcn_s_barrier()
; #define PG8_SCHED __builtin_amdgcn_sched_barrier(0)
; template <class Epi, class Sched, bool ALIGN_EPI = false, bool SP2 = false>
; __device__ __forceinline__ void gemm_phase(PG8_LAS unsigned char* lds, const Gemm g, const Sched& S, const Epi& E) {
;     ...
;         for (int t = 0; t < nt; t += 2) {
;     ...
;             PG8_LDA(At, 1, 1); PG8_STAGE(PG8_SB(1, 0), b3, voffB); PG8_STAGE(PG8_SB(1, 1), b3 + hstep, voffB); PG8_STAGE(PG8_SA(1, 0), a3, voffA);
;             PG8_WAIT_V(8); PG8_WAIT_L(0); PG8_BAR; PG8_MMA(1, 0, At, B0); PG8_MMA(1, 1, At, B1); PG8_BAR; PG8_SCHED;
	s_add_i32 s13, s13, s30
	s_add_i32 m0, s13, 0xffffff80
	ds_read_b128 v[194:197], v203 offset:49152
	ds_read_b128 v[206:209], v203 offset:50176
	ds_read_b128 v[210:213], v203 offset:51200
	ds_read_b128 v[216:219], v203 offset:52224
	global_load_lds_dwordx4 v[236:237], off offset:128
	s_add_i32 m0, s13, 0x1f80
	s_add_i32 s13, s29, s30
	global_load_lds_dwordx4 v[238:239], off offset:128
	s_add_i32 m0, s13, 0xffffff80
	ds_read_b128 v[232:235], v203 offset:56320
	global_load_lds_dwordx4 v[240:241], off offset:128
	s_add_i32 m0, s13, 0x1f80
	ds_read_b128 v[228:231], v203 offset:55296
	global_load_lds_dwordx4 v[214:215], off offset:128
	s_add_i32 m0, s37, 0xffffff80
	ds_read_b128 v[224:227], v203 offset:54272
	global_load_lds_dwordx4 v[242:243], off offset:128
	s_add_i32 m0, s41, 0xffffff80
	ds_read_b128 v[220:223], v203 offset:53248
	global_load_lds_dwordx4 v[244:245], off offset:128
	s_waitcnt vmcnt(8) lgkmcnt(0)
	s_barrier
	v_mfma_f32_16x16x32_bf16 v[64:67], v[136:139], v[194:197], v[64:67]
	v_mfma_f32_16x16x32_bf16 v[60:63], v[144:147], v[194:197], v[60:63]
	v_mfma_f32_16x16x32_bf16 v[48:51], v[136:139], v[210:213], v[48:51]
	v_mfma_f32_16x16x32_bf16 v[44:47], v[144:147], v[210:213], v[44:47]
	v_mfma_f32_16x16x32_bf16 v[32:35], v[136:139], v[220:223], v[32:35]
	v_mfma_f32_16x16x32_bf16 v[28:31], v[144:147], v[220:223], v[28:31]
	v_mfma_f32_16x16x32_bf16 v[16:19], v[136:139], v[228:231], v[16:19]
	v_mfma_f32_16x16x32_bf16 v[12:15], v[144:147], v[228:231], v[12:15]
	v_mfma_f32_16x16x32_bf16 v[64:67], v[140:143], v[206:209], v[64:67]
	v_mfma_f32_16x16x32_bf16 v[60:63], v[148:151], v[206:209], v[60:63]
	v_mfma_f32_16x16x32_bf16 v[48:51], v[140:143], v[216:219], v[48:51]
	v_mfma_f32_16x16x32_bf16 v[44:47], v[148:151], v[216:219], v[44:47]
	v_mfma_f32_16x16x32_bf16 v[32:35], v[140:143], v[224:227], v[32:35]
	v_mfma_f32_16x16x32_bf16 v[28:31], v[148:151], v[224:227], v[28:31]
	v_mfma_f32_16x16x32_bf16 v[16:19], v[140:143], v[232:235], v[16:19]
	v_mfma_f32_16x16x32_bf16 v[12:15], v[148:151], v[232:235], v[12:15]
	v_mfma_f32_16x16x32_bf16 v[56:59], v[152:155], v[194:197], v[56:59]
	v_mfma_f32_16x16x32_bf16 v[52:55], v[186:189], v[194:197], v[52:55]
	v_mfma_f32_16x16x32_bf16 v[40:43], v[152:155], v[210:213], v[40:43]
	v_mfma_f32_16x16x32_bf16 v[36:39], v[186:189], v[210:213], v[36:39]
	v_mfma_f32_16x16x32_bf16 v[24:27], v[152:155], v[220:223], v[24:27]
	v_mfma_f32_16x16x32_bf16 v[20:23], v[186:189], v[220:223], v[20:23]
	v_mfma_f32_16x16x32_bf16 v[8:11], v[152:155], v[228:231], v[8:11]
	v_mfma_f32_16x16x32_bf16 v[4:7], v[186:189], v[228:231], v[4:7]
	v_mfma_f32_16x16x32_bf16 v[56:59], v[182:185], v[206:209], v[56:59]
	v_mfma_f32_16x16x32_bf16 v[52:55], v[190:193], v[206:209], v[52:55]
	v_mfma_f32_16x16x32_bf16 v[40:43], v[182:185], v[216:219], v[40:43]
	v_mfma_f32_16x16x32_bf16 v[36:39], v[190:193], v[216:219], v[36:39]
	v_mfma_f32_16x16x32_bf16 v[24:27], v[182:185], v[224:227], v[24:27]
	v_mfma_f32_16x16x32_bf16 v[20:23], v[190:193], v[224:227], v[20:23]
	v_mfma_f32_16x16x32_bf16 v[8:11], v[182:185], v[232:235], v[8:11]
	v_mfma_f32_16x16x32_bf16 v[4:7], v[190:193], v[232:235], v[4:7]
	s_barrier
	v_lshl_add_u64 v[132:133], v[132:133], 0, s[26:27]
	s_cmp_ge_i32 s12, s47
	v_lshl_add_u64 v[134:135], v[134:135], 0, s[26:27]
	s_cbranch_scc0 .LBB0_1340

; #define PG8_STAGE(bufoff, gbase, voff) do { _Pragma("unroll") for (int _i = 0; _i < 2; ++_i) \
;         __builtin_amdgcn_global_load_lds((const unsigned*)((const char*)(gbase) + (voff)[_i]), (PG8_LAS unsigned*)(lds + (bufoff) + ldsw + _i * 8192), 16, 0, 0); } while (0)
; #define PG8_LDA(dst, b, h) do { _Pragma("unroll") for (int m = 0; m < 4; ++m) _Pragma("unroll") for (int k = 0; k < 2; ++k) dst[m][k] = *(const PG8_LAS bf16x8*)(lds + PG8_SA(b, h) + aoff + m * 2048 + k * 1024); } while (0)
; #define PG8_LDB(dst, b, h) do { _Pragma("unroll") for (int n = 0; n < 2; ++n) _Pragma("unroll") for (int k = 0; k < 2; ++k) dst[n][k] = *(const PG8_LAS bf16x8*)(lds + PG8_SB(b, h) + boff + n * 2048 + k * 1024); } while (0)
; #define PG8_MMA(ai, bj, At, Bt) do { __builtin_amdgcn_s_setprio(1); _Pragma("unroll") for (int m = 0; m < 4; ++m) _Pragma("unroll") for (int n = 0; n < 2; ++n) _Pragma("unroll") for (int k = 0; k < 2; ++k) \
;         acc[ai][bj][m][n] = __builtin_amdgcn_mfma_f32_16x16x32_bf16(Bt[n][k], At[m][k], acc[ai][bj][m][n], 0, 0, 0); __builtin_amdgcn_s_setprio(0); } while (0)
; #define PG8_WAIT_V(n) asm volatile("s_waitcnt vmcnt(" #n ")" ::: "memory")
; #define PG8_WAIT_L(n) asm volatile("s_waitcnt lgkmcnt(" #n ")" ::: "memory")
; #define PG8_BAR __builtin_amdgcn_s_barrier()
; template <class Epi, class Sched, bool ALIGN_EPI = false, bool SP2 = false>
; __device__ __forceinline__ void gemm_phase(PG8_LAS unsigned char* lds, const Gemm g, const Sched& S, const Epi& E) {
;     ...
;             const char* a1 = cA + (size_t)(t + 1) * kstep;
;             const char* a2 = last ? nA : cA + (size_t)(t + 2) * kstep; const char* b2 = last ? nB : cB + (size_t)(t + 2) * kstep;
;             const char* a3 = a2 + kstep; const char* b3 = b2 + kstep;
;             if (last && has_next) S.a_ready(nxt);
;             if constexpr (SP2) {
;             PG8_LDB(B0, 0, 0); PG8_LDB(B1, 0, 1); PG8_SCHED; PG8_LDA(At, 0, 0); PG8_STAGE(PG8_SA(1, 1), a1 + hstep, voffA);
;             PG8_WAIT_V(8); PG8_WAIT_L(0); PG8_BAR; PG8_MMA(0, 0, At, B0); PG8_MMA(0, 1, At, B1); PG8_BAR; PG8_SCHED;
;             PG8_LDA(At, 0, 1); PG8_STAGE(PG8_SB(0, 0), b2, voffB); PG8_STAGE(PG8_SB(0, 1), b2 + hstep, voffB); PG8_STAGE(PG8_SA(0, 0), a2, voffA);
;             PG8_WAIT_V(8); PG8_WAIT_L(0); PG8_BAR; PG8_MMA(1, 0, At, B0); PG8_MMA(1, 1, At, B1); PG8_BAR; PG8_SCHED;
.LBB0_1423:
	v_add_u32_e32 v152, s81, v169
	ds_read_b128 v[132:135], v152
	ds_read_b128 v[136:139], v152 offset:1024
	ds_read_b128 v[174:177], v152 offset:2048
	ds_read_b128 v[178:181], v152 offset:3072
	ds_read_b128 v[182:185], v152 offset:16384
	ds_read_b128 v[186:189], v152 offset:17408
	ds_read_b128 v[190:193], v152 offset:18432
	ds_read_b128 v[194:197], v152 offset:19456
	s_cmp_eq_u32 s74, s10
	v_lshl_add_u64 v[198:199], v[130:131], 0, s[26:27]
	s_cselect_b64 vcc, -1, 0
	s_add_i32 s10, s10, 2
	v_cndmask_b32_e32 v211, v199, v171, vcc
	v_cndmask_b32_e32 v210, v198, v170, vcc
	v_cndmask_b32_e32 v215, v129, v173, vcc
	v_cndmask_b32_e32 v214, v128, v172, vcc
	v_lshl_add_u64 v[240:241], v[130:131], 0, v[160:161]
	s_add_i32 m0, s47, 0xc000
	ds_read_b128 v[198:201], v213
	ds_read_b128 v[202:205], v213 offset:1024
	ds_read_b128 v[206:209], v213 offset:2048
	ds_read_b128 v[220:223], v213 offset:3072
	ds_read_b128 v[224:227], v213 offset:4096
	ds_read_b128 v[228:231], v213 offset:5120
	ds_read_b128 v[232:235], v213 offset:6144
	ds_read_b128 v[236:239], v213 offset:7168
	global_load_lds_dwordx4 v[240:241], off
	s_add_i32 m0, s47, 0xe000
	v_lshl_add_u64 v[240:241], v[130:131], 0, v[158:159]
	global_load_lds_dwordx4 v[240:241], off
	s_waitcnt vmcnt(8) lgkmcnt(0)
	s_barrier
	v_mfma_f32_16x16x32_bf16 v[124:127], v[132:135], v[198:201], v[124:127]
	v_mfma_f32_16x16x32_bf16 v[120:123], v[174:177], v[198:201], v[120:123]
	v_mfma_f32_16x16x32_bf16 v[108:111], v[132:135], v[206:209], v[108:111]
	v_mfma_f32_16x16x32_bf16 v[104:107], v[174:177], v[206:209], v[104:107]
	v_mfma_f32_16x16x32_bf16 v[92:95], v[132:135], v[224:227], v[92:95]
	v_mfma_f32_16x16x32_bf16 v[88:91], v[174:177], v[224:227], v[88:91]
	v_mfma_f32_16x16x32_bf16 v[76:79], v[132:135], v[232:235], v[76:79]
	v_mfma_f32_16x16x32_bf16 v[72:75], v[174:177], v[232:235], v[72:75]
	v_mfma_f32_16x16x32_bf16 v[124:127], v[136:139], v[202:205], v[124:127]
	v_mfma_f32_16x16x32_bf16 v[120:123], v[178:181], v[202:205], v[120:123]
	v_mfma_f32_16x16x32_bf16 v[108:111], v[136:139], v[220:223], v[108:111]
	v_mfma_f32_16x16x32_bf16 v[104:107], v[178:181], v[220:223], v[104:107]
	v_mfma_f32_16x16x32_bf16 v[92:95], v[136:139], v[228:231], v[92:95]
	v_mfma_f32_16x16x32_bf16 v[88:91], v[178:181], v[228:231], v[88:91]
	v_mfma_f32_16x16x32_bf16 v[76:79], v[136:139], v[236:239], v[76:79]
	v_mfma_f32_16x16x32_bf16 v[72:75], v[178:181], v[236:239], v[72:75]
	s_cmp_eq_u32 s22, 12
	s_cbranch_scc1 .Lio_skipk0
	v_mfma_f32_16x16x32_bf16 v[116:119], v[182:185], v[198:201], v[116:119]
	v_mfma_f32_16x16x32_bf16 v[112:115], v[190:193], v[198:201], v[112:115]
	v_mfma_f32_16x16x32_bf16 v[100:103], v[182:185], v[206:209], v[100:103]
	v_mfma_f32_16x16x32_bf16 v[96:99], v[190:193], v[206:209], v[96:99]
	v_mfma_f32_16x16x32_bf16 v[84:87], v[182:185], v[224:227], v[84:87]
	v_mfma_f32_16x16x32_bf16 v[80:83], v[190:193], v[224:227], v[80:83]
	v_mfma_f32_16x16x32_bf16 v[68:71], v[182:185], v[232:235], v[68:71]
	v_mfma_f32_16x16x32_bf16 v[64:67], v[190:193], v[232:235], v[64:67]
	v_mfma_f32_16x16x32_bf16 v[116:119], v[186:189], v[202:205], v[116:119]
	v_mfma_f32_16x16x32_bf16 v[112:115], v[194:197], v[202:205], v[112:115]
	v_mfma_f32_16x16x32_bf16 v[100:103], v[186:189], v[220:223], v[100:103]
	v_mfma_f32_16x16x32_bf16 v[96:99], v[194:197], v[220:223], v[96:99]
	v_mfma_f32_16x16x32_bf16 v[84:87], v[186:189], v[228:231], v[84:87]
	v_mfma_f32_16x16x32_bf16 v[80:83], v[194:197], v[228:231], v[80:83]
	v_mfma_f32_16x16x32_bf16 v[68:71], v[186:189], v[236:239], v[68:71]
	v_mfma_f32_16x16x32_bf16 v[64:67], v[194:197], v[236:239], v[64:67]
.Lio_skipk0:
	s_barrier
	s_add_i32 s11, s81, s41
	v_lshl_add_u64 v[240:241], v[214:215], 0, v[146:147]
	s_mov_b32 m0, s11
	ds_read_b128 v[198:201], v213 offset:16384
	ds_read_b128 v[202:205], v213 offset:17408
	ds_read_b128 v[206:209], v213 offset:18432
	ds_read_b128 v[220:223], v213 offset:19456
	ds_read_b128 v[224:227], v213 offset:20480
	ds_read_b128 v[228:231], v213 offset:21504
	ds_read_b128 v[232:235], v213 offset:22528
	ds_read_b128 v[236:239], v213 offset:23552
	global_load_lds_dwordx4 v[240:241], off
	v_lshl_add_u64 v[242:243], v[214:215], 0, v[150:151]
	s_add_i32 m0, s11, 0x2000
	v_lshl_add_u64 v[214:215], v[214:215], 0, s[18:19]
	s_add_i32 s11, s82, s41
	global_load_lds_dwordx4 v[242:243], off
	v_lshl_add_u64 v[244:245], v[214:215], 0, v[146:147]
	s_mov_b32 m0, s11
	v_lshl_add_u64 v[214:215], v[214:215], 0, v[150:151]
	global_load_lds_dwordx4 v[244:245], off
	s_add_i32 m0, s11, 0x2000
	v_lshl_add_u64 v[246:247], v[210:211], 0, v[144:145]
	global_load_lds_dwordx4 v[214:215], off
	s_mov_b32 m0, s47
	v_lshl_add_u64 v[248:249], v[210:211], 0, v[148:149]
	global_load_lds_dwordx4 v[246:247], off
	s_mov_b32 m0, s55
	s_nop 0
	global_load_lds_dwordx4 v[248:249], off
	s_waitcnt vmcnt(8) lgkmcnt(0)
	s_barrier
	v_mfma_f32_16x16x32_bf16 v[60:63], v[132:135], v[198:201], v[60:63]
	v_mfma_f32_16x16x32_bf16 v[56:59], v[174:177], v[198:201], v[56:59]
	v_mfma_f32_16x16x32_bf16 v[44:47], v[132:135], v[206:209], v[44:47]
	v_mfma_f32_16x16x32_bf16 v[40:43], v[174:177], v[206:209], v[40:43]
	v_mfma_f32_16x16x32_bf16 v[28:31], v[132:135], v[224:227], v[28:31]
	v_mfma_f32_16x16x32_bf16 v[24:27], v[174:177], v[224:227], v[24:27]
	v_mfma_f32_16x16x32_bf16 v[12:15], v[132:135], v[232:235], v[12:15]
	v_mfma_f32_16x16x32_bf16 v[8:11], v[174:177], v[232:235], v[8:11]
	v_mfma_f32_16x16x32_bf16 v[60:63], v[136:139], v[202:205], v[60:63]
	v_mfma_f32_16x16x32_bf16 v[56:59], v[178:181], v[202:205], v[56:59]
	v_mfma_f32_16x16x32_bf16 v[44:47], v[136:139], v[220:223], v[44:47]
	v_mfma_f32_16x16x32_bf16 v[40:43], v[178:181], v[220:223], v[40:43]
	v_mfma_f32_16x16x32_bf16 v[28:31], v[136:139], v[228:231], v[28:31]
	v_mfma_f32_16x16x32_bf16 v[24:27], v[178:181], v[228:231], v[24:27]
	v_mfma_f32_16x16x32_bf16 v[12:15], v[136:139], v[236:239], v[12:15]
	v_mfma_f32_16x16x32_bf16 v[8:11], v[178:181], v[236:239], v[8:11]
	s_cmp_eq_u32 s22, 12
	s_cbranch_scc1 .Lio_skipk1
; #define PG8_STAGE(bufoff, gbase, voff) do { _Pragma("unroll") for (int _i = 0; _i < 2; ++_i) \
;         __builtin_amdgcn_global_load_lds((const unsigned*)((const char*)(gbase) + (voff)[_i]), (PG8_LAS unsigned*)(lds + (bufoff) + ldsw + _i * 8192), 16, 0, 0); } while (0)
; #define PG8_LDA(dst, b, h) do { _Pragma("unroll") for (int m = 0; m < 4; ++m) _Pragma("unroll") for (int k = 0; k < 2; ++k) dst[m][k] = *(const PG8_LAS bf16x8*)(lds + PG8_SA(b, h) + aoff + m * 2048 + k * 1024); } while (0)
; #define PG8_LDB(dst, b, h) do { _Pragma("unroll") for (int n = 0; n < 2; ++n) _Pragma("unroll") for (int k = 0; k < 2; ++k) dst[n][k] = *(const PG8_LAS bf16x8*)(lds + PG8_SB(b, h) + boff + n * 2048 + k * 1024); } while (0)
; #define PG8_MMA(ai, bj, At, Bt) do { __builtin_amdgcn_s_setprio(1); _Pragma("unroll") for (int m = 0; m < 4; ++m) _Pragma("unroll") for (int n = 0; n < 2; ++n) _Pragma("unroll") for (int k = 0; k < 2; ++k) \
;         acc[ai][bj][m][n] = __builtin_amdgcn_mfma_f32_16x16x32_bf16(Bt[n][k], At[m][k], acc[ai][bj][m][n], 0, 0, 0); __builtin_amdgcn_s_setprio(0); } while (0)
; #define PG8_WAIT_V(n) asm volatile("s_waitcnt vmcnt(" #n ")" ::: "memory")
; #define PG8_WAIT_L(n) asm volatile("s_waitcnt lgkmcnt(" #n ")" ::: "memory")
; #define PG8_BAR __builtin_amdgcn_s_barrier()
; #define PG8_SCHED __builtin_amdgcn_sched_barrier(0)
; template <class Epi, class Sched, bool ALIGN_EPI = false, bool SP2 = false>
; __device__ __forceinline__ void gemm_phase(PG8_LAS unsigned char* lds, const Gemm g, const Sched& S, const Epi& E) {
;     ...
;             PG8_WAIT_V(8); PG8_WAIT_L(0); PG8_BAR; PG8_MMA(1, 0, At, B0); PG8_MMA(1, 1, At, B1); PG8_BAR; PG8_SCHED;
;             PG8_LDB(B0, 1, 0); PG8_LDB(B1, 1, 1); PG8_SCHED; PG8_LDA(At, 1, 0); PG8_STAGE(PG8_SA(0, 1), a2 + hstep, voffA);
;             PG8_WAIT_V(8); PG8_WAIT_L(0); PG8_BAR; PG8_MMA(0, 0, At, B0); PG8_MMA(0, 1, At, B1); PG8_BAR; PG8_SCHED;
	v_mfma_f32_16x16x32_bf16 v[52:55], v[182:185], v[198:201], v[52:55]
	v_mfma_f32_16x16x32_bf16 v[48:51], v[190:193], v[198:201], v[48:51]
	v_mfma_f32_16x16x32_bf16 v[36:39], v[182:185], v[206:209], v[36:39]
	v_mfma_f32_16x16x32_bf16 v[32:35], v[190:193], v[206:209], v[32:35]
	v_mfma_f32_16x16x32_bf16 v[20:23], v[182:185], v[224:227], v[20:23]
	v_mfma_f32_16x16x32_bf16 v[16:19], v[190:193], v[224:227], v[16:19]
	v_mfma_f32_16x16x32_bf16 v[4:7], v[182:185], v[232:235], v[4:7]
	v_mfma_f32_16x16x32_bf16 v[0:3], v[190:193], v[232:235], v[0:3]
	v_mfma_f32_16x16x32_bf16 v[52:55], v[186:189], v[202:205], v[52:55]
	v_mfma_f32_16x16x32_bf16 v[48:51], v[194:197], v[202:205], v[48:51]
	v_mfma_f32_16x16x32_bf16 v[36:39], v[186:189], v[220:223], v[36:39]
	v_mfma_f32_16x16x32_bf16 v[32:35], v[194:197], v[220:223], v[32:35]
	v_mfma_f32_16x16x32_bf16 v[20:23], v[186:189], v[228:231], v[20:23]
	v_mfma_f32_16x16x32_bf16 v[16:19], v[194:197], v[228:231], v[16:19]
	v_mfma_f32_16x16x32_bf16 v[4:7], v[186:189], v[236:239], v[4:7]
	v_mfma_f32_16x16x32_bf16 v[0:3], v[194:197], v[236:239], v[0:3]
.Lio_skipk1:
	s_barrier
	s_add_i32 s11, 0, 0x18000
	s_add_i32 s13, 0, 0x1c000
	ds_read_b128 v[132:135], v152 offset:32768
	ds_read_b128 v[136:139], v152 offset:33792
	ds_read_b128 v[174:177], v152 offset:34816
	ds_read_b128 v[178:181], v152 offset:35840
	ds_read_b128 v[182:185], v152 offset:49152
	ds_read_b128 v[186:189], v152 offset:50176
	ds_read_b128 v[190:193], v152 offset:51200
	ds_read_b128 v[194:197], v152 offset:52224
	v_lshl_add_u64 v[210:211], v[210:211], 0, s[18:19]
	s_mov_b32 m0, s57
	v_lshl_add_u64 v[250:251], v[210:211], 0, v[144:145]
	ds_read_b128 v[198:201], v213 offset:32768
	ds_read_b128 v[202:205], v213 offset:33792
	ds_read_b128 v[206:209], v213 offset:34816
	ds_read_b128 v[220:223], v213 offset:35840
	ds_read_b128 v[224:227], v213 offset:36864
	ds_read_b128 v[228:231], v213 offset:37888
	ds_read_b128 v[232:235], v213 offset:38912
	ds_read_b128 v[236:239], v213 offset:39936
	global_load_lds_dwordx4 v[250:251], off
	s_mov_b32 m0, s59
	v_lshl_add_u64 v[210:211], v[210:211], 0, v[148:149]
	global_load_lds_dwordx4 v[210:211], off
	s_waitcnt vmcnt(8) lgkmcnt(0)
	s_barrier
	v_mfma_f32_16x16x32_bf16 v[124:127], v[132:135], v[198:201], v[124:127]
	v_mfma_f32_16x16x32_bf16 v[120:123], v[174:177], v[198:201], v[120:123]
	v_mfma_f32_16x16x32_bf16 v[108:111], v[132:135], v[206:209], v[108:111]
	v_mfma_f32_16x16x32_bf16 v[104:107], v[174:177], v[206:209], v[104:107]
	v_mfma_f32_16x16x32_bf16 v[92:95], v[132:135], v[224:227], v[92:95]
	v_mfma_f32_16x16x32_bf16 v[88:91], v[174:177], v[224:227], v[88:91]
	v_mfma_f32_16x16x32_bf16 v[76:79], v[132:135], v[232:235], v[76:79]
	v_mfma_f32_16x16x32_bf16 v[72:75], v[174:177], v[232:235], v[72:75]
	v_mfma_f32_16x16x32_bf16 v[124:127], v[136:139], v[202:205], v[124:127]
	v_mfma_f32_16x16x32_bf16 v[120:123], v[178:181], v[202:205], v[120:123]
	v_mfma_f32_16x16x32_bf16 v[108:111], v[136:139], v[220:223], v[108:111]
	v_mfma_f32_16x16x32_bf16 v[104:107], v[178:181], v[220:223], v[104:107]
	v_mfma_f32_16x16x32_bf16 v[92:95], v[136:139], v[228:231], v[92:95]
	v_mfma_f32_16x16x32_bf16 v[88:91], v[178:181], v[228:231], v[88:91]
	v_mfma_f32_16x16x32_bf16 v[76:79], v[136:139], v[236:239], v[76:79]
	v_mfma_f32_16x16x32_bf16 v[72:75], v[178:181], v[236:239], v[72:75]
	s_cmp_eq_u32 s22, 12
	s_cbranch_scc1 .Lio_skipk2
	v_mfma_f32_16x16x32_bf16 v[116:119], v[182:185], v[198:201], v[116:119]
	v_mfma_f32_16x16x32_bf16 v[112:115], v[190:193], v[198:201], v[112:115]
	v_mfma_f32_16x16x32_bf16 v[100:103], v[182:185], v[206:209], v[100:103]
	v_mfma_f32_16x16x32_bf16 v[96:99], v[190:193], v[206:209], v[96:99]
	v_mfma_f32_16x16x32_bf16 v[84:87], v[182:185], v[224:227], v[84:87]
	v_mfma_f32_16x16x32_bf16 v[80:83], v[190:193], v[224:227], v[80:83]
	v_mfma_f32_16x16x32_bf16 v[68:71], v[182:185], v[232:235], v[68:71]
	v_mfma_f32_16x16x32_bf16 v[64:67], v[190:193], v[232:235], v[64:67]
	v_mfma_f32_16x16x32_bf16 v[116:119], v[186:189], v[202:205], v[116:119]
	v_mfma_f32_16x16x32_bf16 v[112:115], v[194:197], v[202:205], v[112:115]
	v_mfma_f32_16x16x32_bf16 v[100:103], v[186:189], v[220:223], v[100:103]
	v_mfma_f32_16x16x32_bf16 v[96:99], v[194:197], v[220:223], v[96:99]
	v_mfma_f32_16x16x32_bf16 v[84:87], v[186:189], v[228:231], v[84:87]
	v_mfma_f32_16x16x32_bf16 v[80:83], v[194:197], v[228:231], v[80:83]
	v_mfma_f32_16x16x32_bf16 v[68:71], v[186:189], v[236:239], v[68:71]
	v_mfma_f32_16x16x32_bf16 v[64:67], v[194:197], v[236:239], v[64:67]
; #define PG8_STAGE(bufoff, gbase, voff) do { _Pragma("unroll") for (int _i = 0; _i < 2; ++_i) \
;         __builtin_amdgcn_global_load_lds((const unsigned*)((const char*)(gbase) + (voff)[_i]), (PG8_LAS unsigned*)(lds + (bufoff) + ldsw + _i * 8192), 16, 0, 0); } while (0)
; #define PG8_LDA(dst, b, h) do { _Pragma("unroll") for (int m = 0; m < 4; ++m) _Pragma("unroll") for (int k = 0; k < 2; ++k) dst[m][k] = *(const PG8_LAS bf16x8*)(lds + PG8_SA(b, h) + aoff + m * 2048 + k * 1024); } while (0)
; #define PG8_MMA(ai, bj, At, Bt) do { __builtin_amdgcn_s_setprio(1); _Pragma("unroll") for (int m = 0; m < 4; ++m) _Pragma("unroll") for (int n = 0; n < 2; ++n) _Pragma("unroll") for (int k = 0; k < 2; ++k) \
;         acc[ai][bj][m][n] = __builtin_amdgcn_mfma_f32_16x16x32_bf16(Bt[n][k], At[m][k], acc[ai][bj][m][n], 0, 0, 0); __builtin_amdgcn_s_setprio(0); } while (0)
; #define PG8_WAIT_V(n) asm volatile("s_waitcnt vmcnt(" #n ")" ::: "memory")
; #define PG8_WAIT_L(n) asm volatile("s_waitcnt lgkmcnt(" #n ")" ::: "memory")
; #define PG8_BAR __builtin_amdgcn_s_barrier()
; #define PG8_SCHED __builtin_amdgcn_sched_barrier(0)
; template <class Epi, class Sched, bool ALIGN_EPI = false, bool SP2 = false>
; __device__ __forceinline__ void gemm_phase(PG8_LAS unsigned char* lds, const Gemm g, const Sched& S, const Epi& E) {
;     ...
;         for (int t = 0; t < nt; t += 2) {
;     ...
;             PG8_LDA(At, 1, 1); PG8_STAGE(PG8_SB(1, 0), b3, voffB); PG8_STAGE(PG8_SB(1, 1), b3 + hstep, voffB); PG8_STAGE(PG8_SA(1, 0), a3, voffA);
;             PG8_WAIT_V(8); PG8_WAIT_L(0); PG8_BAR; PG8_MMA(1, 0, At, B0); PG8_MMA(1, 1, At, B1); PG8_BAR; PG8_SCHED;
.Lio_skipk2:
	s_barrier
	s_add_i32 s11, s11, s41
	s_add_i32 m0, s11, 0xffffff80
	ds_read_b128 v[198:201], v213 offset:49152
	ds_read_b128 v[202:205], v213 offset:50176
	ds_read_b128 v[206:209], v213 offset:51200
	ds_read_b128 v[220:223], v213 offset:52224
	global_load_lds_dwordx4 v[240:241], off offset:128
	s_add_i32 m0, s11, 0x1f80
	s_add_i32 s11, s13, s41
	global_load_lds_dwordx4 v[242:243], off offset:128
	s_add_i32 m0, s11, 0xffffff80
	ds_read_b128 v[236:239], v213 offset:56320
	global_load_lds_dwordx4 v[244:245], off offset:128
	s_add_i32 m0, s11, 0x1f80
	ds_read_b128 v[232:235], v213 offset:55296
	global_load_lds_dwordx4 v[214:215], off offset:128
	s_add_i32 m0, s69, 0xffffff80
	ds_read_b128 v[228:231], v213 offset:54272
	global_load_lds_dwordx4 v[246:247], off offset:128
	s_add_i32 m0, s70, 0xffffff80
	ds_read_b128 v[224:227], v213 offset:53248
	global_load_lds_dwordx4 v[248:249], off offset:128
	s_waitcnt vmcnt(8) lgkmcnt(0)
	s_barrier
	v_mfma_f32_16x16x32_bf16 v[60:63], v[132:135], v[198:201], v[60:63]
	v_mfma_f32_16x16x32_bf16 v[56:59], v[174:177], v[198:201], v[56:59]
	v_mfma_f32_16x16x32_bf16 v[44:47], v[132:135], v[206:209], v[44:47]
	v_mfma_f32_16x16x32_bf16 v[40:43], v[174:177], v[206:209], v[40:43]
	v_mfma_f32_16x16x32_bf16 v[28:31], v[132:135], v[224:227], v[28:31]
	v_mfma_f32_16x16x32_bf16 v[24:27], v[174:177], v[224:227], v[24:27]
	v_mfma_f32_16x16x32_bf16 v[12:15], v[132:135], v[232:235], v[12:15]
	v_mfma_f32_16x16x32_bf16 v[8:11], v[174:177], v[232:235], v[8:11]
	v_mfma_f32_16x16x32_bf16 v[60:63], v[136:139], v[202:205], v[60:63]
	v_mfma_f32_16x16x32_bf16 v[56:59], v[178:181], v[202:205], v[56:59]
	v_mfma_f32_16x16x32_bf16 v[44:47], v[136:139], v[220:223], v[44:47]
	v_mfma_f32_16x16x32_bf16 v[40:43], v[178:181], v[220:223], v[40:43]
	v_mfma_f32_16x16x32_bf16 v[28:31], v[136:139], v[228:231], v[28:31]
	v_mfma_f32_16x16x32_bf16 v[24:27], v[178:181], v[228:231], v[24:27]
	v_mfma_f32_16x16x32_bf16 v[12:15], v[136:139], v[236:239], v[12:15]
	v_mfma_f32_16x16x32_bf16 v[8:11], v[178:181], v[236:239], v[8:11]
	s_cmp_eq_u32 s22, 12
	s_cbranch_scc1 .Lio_skipk3
	v_mfma_f32_16x16x32_bf16 v[52:55], v[182:185], v[198:201], v[52:55]
	v_mfma_f32_16x16x32_bf16 v[48:51], v[190:193], v[198:201], v[48:51]
	v_mfma_f32_16x16x32_bf16 v[36:39], v[182:185], v[206:209], v[36:39]
	v_mfma_f32_16x16x32_bf16 v[32:35], v[190:193], v[206:209], v[32:35]
	v_mfma_f32_16x16x32_bf16 v[20:23], v[182:185], v[224:227], v[20:23]
	v_mfma_f32_16x16x32_bf16 v[16:19], v[190:193], v[224:227], v[16:19]
	v_mfma_f32_16x16x32_bf16 v[4:7], v[182:185], v[232:235], v[4:7]
	v_mfma_f32_16x16x32_bf16 v[0:3], v[190:193], v[232:235], v[0:3]
	v_mfma_f32_16x16x32_bf16 v[52:55], v[186:189], v[202:205], v[52:55]
	v_mfma_f32_16x16x32_bf16 v[48:51], v[194:197], v[202:205], v[48:51]
	v_mfma_f32_16x16x32_bf16 v[36:39], v[186:189], v[220:223], v[36:39]
	v_mfma_f32_16x16x32_bf16 v[32:35], v[194:197], v[220:223], v[32:35]
	v_mfma_f32_16x16x32_bf16 v[20:23], v[186:189], v[228:231], v[20:23]
	v_mfma_f32_16x16x32_bf16 v[16:19], v[194:197], v[228:231], v[16:19]
	v_mfma_f32_16x16x32_bf16 v[4:7], v[186:189], v[236:239], v[4:7]
	v_mfma_f32_16x16x32_bf16 v[0:3], v[194:197], v[236:239], v[0:3]
.Lio_skipk3:
	s_barrier
	v_lshl_add_u64 v[128:129], v[128:129], 0, s[36:37]
	s_cmp_ge_i32 s10, s67
	v_lshl_add_u64 v[130:131], v[130:131], 0, s[36:37]
	s_cbranch_scc0 .LBB0_1423

; #define PG8_STAGE(bufoff, gbase, voff) do { _Pragma("unroll") for (int _i = 0; _i < 2; ++_i) \
;         __builtin_amdgcn_global_load_lds((const unsigned*)((const char*)(gbase) + (voff)[_i]), (PG8_LAS unsigned*)(lds + (bufoff) + ldsw + _i * 8192), 16, 0, 0); } while (0)
; #define PG8_LDA(dst, b, h) do { _Pragma("unroll") for (int m = 0; m < 4; ++m) _Pragma("unroll") for (int k = 0; k < 2; ++k) dst[m][k] = *(const PG8_LAS bf16x8*)(lds + PG8_SA(b, h) + aoff + m * 2048 + k * 1024); } while (0)
; #define PG8_LDB(dst, b, h) do { _Pragma("unroll") for (int n = 0; n < 2; ++n) _Pragma("unroll") for (int k = 0; k < 2; ++k) dst[n][k] = *(const PG8_LAS bf16x8*)(lds + PG8_SB(b, h) + boff + n * 2048 + k * 1024); } while (0)
; #define PG8_MMA(ai, bj, At, Bt) do { __builtin_amdgcn_s_setprio(1); _Pragma("unroll") for (int m = 0; m < 4; ++m) _Pragma("unroll") for (int n = 0; n < 2; ++n) _Pragma("unroll") for (int k = 0; k < 2; ++k) \
;         acc[ai][bj][m][n] = __builtin_amdgcn_mfma_f32_16x16x32_bf16(Bt[n][k], At[m][k], acc[ai][bj][m][n], 0, 0, 0); __builtin_amdgcn_s_setprio(0); } while (0)
; #define PG8_WAIT_V(n) asm volatile("s_waitcnt vmcnt(" #n ")" ::: "memory")
; #define PG8_WAIT_L(n) asm volatile("s_waitcnt lgkmcnt(" #n ")" ::: "memory")
; #define PG8_BAR __builtin_amdgcn_s_barrier()
; template <class Epi, class Sched, bool ALIGN_EPI = false, bool SP2 = false>
; __device__ __forceinline__ void gemm_phase(PG8_LAS unsigned char* lds, const Gemm g, const Sched& S, const Epi& E) {
;     ...
;             const char* a1 = cA + (size_t)(t + 1) * kstep;
;             const char* a2 = last ? nA : cA + (size_t)(t + 2) * kstep; const char* b2 = last ? nB : cB + (size_t)(t + 2) * kstep;
;             const char* a3 = a2 + kstep; const char* b3 = b2 + kstep;
;             if (last && has_next) S.a_ready(nxt);
;             if constexpr (SP2) {
;             PG8_LDB(B0, 0, 0); PG8_LDB(B1, 0, 1); PG8_SCHED; PG8_LDA(At, 0, 0); PG8_STAGE(PG8_SA(1, 1), a1 + hstep, voffA);
;             PG8_WAIT_V(8); PG8_WAIT_L(0); PG8_BAR; PG8_MMA(0, 0, At, B0); PG8_MMA(0, 1, At, B1); PG8_BAR; PG8_SCHED;
;             PG8_LDA(At, 0, 1); PG8_STAGE(PG8_SB(0, 0), b2, voffB); PG8_STAGE(PG8_SB(0, 1), b2 + hstep, voffB); PG8_STAGE(PG8_SA(0, 0), a2, voffA);
;             PG8_WAIT_V(8); PG8_WAIT_L(0); PG8_BAR; PG8_MMA(1, 0, At, B0); PG8_MMA(1, 1, At, B1); PG8_BAR; PG8_SCHED;
.LBB0_1695:
	v_add_u32_e32 v255, s54, v199
	ds_read_b128 v[132:135], v201
	ds_read_b128 v[136:139], v201 offset:1024
	ds_read_b128 v[140:143], v201 offset:2048
	ds_read_b128 v[144:147], v201 offset:3072
	ds_read_b128 v[148:151], v255
	ds_read_b128 v[180:183], v255 offset:1024
	ds_read_b128 v[184:187], v255 offset:2048
	ds_read_b128 v[188:191], v255 offset:3072
	s_cmp_eq_u32 s48, s12
	v_lshl_add_u64 v[192:193], v[130:131], 0, s[22:23]
	s_cselect_b64 vcc, -1, 0
	s_add_i32 s12, s12, 2
	v_cndmask_b32_e32 v197, v193, v177, vcc
	v_cndmask_b32_e32 v196, v192, v176, vcc
	v_cndmask_b32_e32 v213, v129, v179, vcc
	v_cndmask_b32_e32 v212, v128, v178, vcc
	s_mov_b32 m0, s55
	v_lshl_add_u64 v[214:215], v[130:131], 0, v[172:173]
	ds_read_b128 v[192:195], v202
	ds_read_b128 v[204:207], v202 offset:1024
	ds_read_b128 v[208:211], v202 offset:2048
	ds_read_b128 v[216:219], v202 offset:3072
	ds_read_b128 v[220:223], v202 offset:4096
	ds_read_b128 v[224:227], v202 offset:5120
	ds_read_b128 v[228:231], v202 offset:6144
	ds_read_b128 v[232:235], v202 offset:7168
	global_load_lds_dwordx4 v[214:215], off
	s_mov_b32 m0, s56
	v_lshl_add_u64 v[214:215], v[130:131], 0, v[170:171]
	global_load_lds_dwordx4 v[214:215], off
	s_waitcnt vmcnt(8) lgkmcnt(0)
	s_barrier
	v_mfma_f32_16x16x32_bf16 v[120:123], v[132:135], v[192:195], v[120:123]
	v_mfma_f32_16x16x32_bf16 v[124:127], v[140:143], v[192:195], v[124:127]
	v_mfma_f32_16x16x32_bf16 v[108:111], v[132:135], v[208:211], v[108:111]
	v_mfma_f32_16x16x32_bf16 v[104:107], v[140:143], v[208:211], v[104:107]
	v_mfma_f32_16x16x32_bf16 v[92:95], v[132:135], v[220:223], v[92:95]
	v_mfma_f32_16x16x32_bf16 v[88:91], v[140:143], v[220:223], v[88:91]
	v_mfma_f32_16x16x32_bf16 v[76:79], v[132:135], v[228:231], v[76:79]
	v_mfma_f32_16x16x32_bf16 v[72:75], v[140:143], v[228:231], v[72:75]
	v_mfma_f32_16x16x32_bf16 v[120:123], v[136:139], v[204:207], v[120:123]
	v_mfma_f32_16x16x32_bf16 v[124:127], v[144:147], v[204:207], v[124:127]
	v_mfma_f32_16x16x32_bf16 v[108:111], v[136:139], v[216:219], v[108:111]
	v_mfma_f32_16x16x32_bf16 v[104:107], v[144:147], v[216:219], v[104:107]
	v_mfma_f32_16x16x32_bf16 v[92:95], v[136:139], v[224:227], v[92:95]
	v_mfma_f32_16x16x32_bf16 v[88:91], v[144:147], v[224:227], v[88:91]
	v_mfma_f32_16x16x32_bf16 v[76:79], v[136:139], v[232:235], v[76:79]
	v_mfma_f32_16x16x32_bf16 v[72:75], v[144:147], v[232:235], v[72:75]
	v_mfma_f32_16x16x32_bf16 v[116:119], v[148:151], v[192:195], v[116:119]
	v_mfma_f32_16x16x32_bf16 v[112:115], v[184:187], v[192:195], v[112:115]
	v_mfma_f32_16x16x32_bf16 v[100:103], v[148:151], v[208:211], v[100:103]
	v_mfma_f32_16x16x32_bf16 v[96:99], v[184:187], v[208:211], v[96:99]
	v_mfma_f32_16x16x32_bf16 v[84:87], v[148:151], v[220:223], v[84:87]
	v_mfma_f32_16x16x32_bf16 v[80:83], v[184:187], v[220:223], v[80:83]
	v_mfma_f32_16x16x32_bf16 v[68:71], v[148:151], v[228:231], v[68:71]
	v_mfma_f32_16x16x32_bf16 v[64:67], v[184:187], v[228:231], v[64:67]
	v_mfma_f32_16x16x32_bf16 v[116:119], v[180:183], v[204:207], v[116:119]
	v_mfma_f32_16x16x32_bf16 v[112:115], v[188:191], v[204:207], v[112:115]
	v_mfma_f32_16x16x32_bf16 v[100:103], v[180:183], v[216:219], v[100:103]
	v_mfma_f32_16x16x32_bf16 v[96:99], v[188:191], v[216:219], v[96:99]
	v_mfma_f32_16x16x32_bf16 v[84:87], v[180:183], v[224:227], v[84:87]
	v_mfma_f32_16x16x32_bf16 v[80:83], v[188:191], v[224:227], v[80:83]
	v_mfma_f32_16x16x32_bf16 v[68:71], v[180:183], v[232:235], v[68:71]
	v_mfma_f32_16x16x32_bf16 v[64:67], v[188:191], v[232:235], v[64:67]
	s_barrier
	s_mov_b32 m0, s57
	v_lshl_add_u64 v[214:215], v[212:213], 0, v[164:165]
	ds_read_b128 v[192:195], v202 offset:16384
	ds_read_b128 v[204:207], v202 offset:17408
	ds_read_b128 v[208:211], v202 offset:18432
	ds_read_b128 v[216:219], v202 offset:19456
	ds_read_b128 v[220:223], v202 offset:20480
	ds_read_b128 v[224:227], v202 offset:21504
	ds_read_b128 v[228:231], v202 offset:22528
	ds_read_b128 v[232:235], v202 offset:23552
	global_load_lds_dwordx4 v[214:215], off
	v_lshl_add_u64 v[236:237], v[212:213], 0, v[168:169]
	s_mov_b32 m0, s58
	v_lshl_add_u64 v[212:213], v[212:213], 0, s[14:15]
	s_add_i32 s13, s54, s30
	global_load_lds_dwordx4 v[236:237], off
	v_lshl_add_u64 v[238:239], v[212:213], 0, v[164:165]
	s_mov_b32 m0, s13
	v_lshl_add_u64 v[212:213], v[212:213], 0, v[168:169]
	global_load_lds_dwordx4 v[238:239], off
	s_add_i32 m0, s13, 0x2000
	v_lshl_add_u64 v[240:241], v[196:197], 0, v[162:163]
	global_load_lds_dwordx4 v[212:213], off
	s_mov_b32 m0, s31
	v_lshl_add_u64 v[242:243], v[196:197], 0, v[166:167]
	global_load_lds_dwordx4 v[240:241], off
	s_mov_b32 m0, s34
	s_nop 0
	global_load_lds_dwordx4 v[242:243], off
	s_waitcnt vmcnt(8) lgkmcnt(0)
	s_barrier
; #define PG8_STAGE(bufoff, gbase, voff) do { _Pragma("unroll") for (int _i = 0; _i < 2; ++_i) \
;         __builtin_amdgcn_global_load_lds((const unsigned*)((const char*)(gbase) + (voff)[_i]), (PG8_LAS unsigned*)(lds + (bufoff) + ldsw + _i * 8192), 16, 0, 0); } while (0)
; #define PG8_LDA(dst, b, h) do { _Pragma("unroll") for (int m = 0; m < 4; ++m) _Pragma("unroll") for (int k = 0; k < 2; ++k) dst[m][k] = *(const PG8_LAS bf16x8*)(lds + PG8_SA(b, h) + aoff + m * 2048 + k * 1024); } while (0)
; #define PG8_LDB(dst, b, h) do { _Pragma("unroll") for (int n = 0; n < 2; ++n) _Pragma("unroll") for (int k = 0; k < 2; ++k) dst[n][k] = *(const PG8_LAS bf16x8*)(lds + PG8_SB(b, h) + boff + n * 2048 + k * 1024); } while (0)
; #define PG8_MMA(ai, bj, At, Bt) do { __builtin_amdgcn_s_setprio(1); _Pragma("unroll") for (int m = 0; m < 4; ++m) _Pragma("unroll") for (int n = 0; n < 2; ++n) _Pragma("unroll") for (int k = 0; k < 2; ++k) \
;         acc[ai][bj][m][n] = __builtin_amdgcn_mfma_f32_16x16x32_bf16(Bt[n][k], At[m][k], acc[ai][bj][m][n], 0, 0, 0); __builtin_amdgcn_s_setprio(0); } while (0)
; #define PG8_WAIT_V(n) asm volatile("s_waitcnt vmcnt(" #n ")" ::: "memory")
; #define PG8_WAIT_L(n) asm volatile("s_waitcnt lgkmcnt(" #n ")" ::: "memory")
; #define PG8_BAR __builtin_amdgcn_s_barrier()
; #define PG8_SCHED __builtin_amdgcn_sched_barrier(0)
; template <class Epi, class Sched, bool ALIGN_EPI = false, bool SP2 = false>
; __device__ __forceinline__ void gemm_phase(PG8_LAS unsigned char* lds, const Gemm g, const Sched& S, const Epi& E) {
;     ...
;             PG8_WAIT_V(8); PG8_WAIT_L(0); PG8_BAR; PG8_MMA(1, 0, At, B0); PG8_MMA(1, 1, At, B1); PG8_BAR; PG8_SCHED;
;             PG8_LDB(B0, 1, 0); PG8_LDB(B1, 1, 1); PG8_SCHED; PG8_LDA(At, 1, 0); PG8_STAGE(PG8_SA(0, 1), a2 + hstep, voffA);
;             PG8_WAIT_V(8); PG8_WAIT_L(0); PG8_BAR; PG8_MMA(0, 0, At, B0); PG8_MMA(0, 1, At, B1); PG8_BAR; PG8_SCHED;
	v_mfma_f32_16x16x32_bf16 v[60:63], v[132:135], v[192:195], v[60:63]
	v_mfma_f32_16x16x32_bf16 v[56:59], v[140:143], v[192:195], v[56:59]
	v_mfma_f32_16x16x32_bf16 v[44:47], v[132:135], v[208:211], v[44:47]
	v_mfma_f32_16x16x32_bf16 v[40:43], v[140:143], v[208:211], v[40:43]
	v_mfma_f32_16x16x32_bf16 v[28:31], v[132:135], v[220:223], v[28:31]
	v_mfma_f32_16x16x32_bf16 v[24:27], v[140:143], v[220:223], v[24:27]
	v_mfma_f32_16x16x32_bf16 v[12:15], v[132:135], v[228:231], v[12:15]
	v_mfma_f32_16x16x32_bf16 v[8:11], v[140:143], v[228:231], v[8:11]
	v_mfma_f32_16x16x32_bf16 v[60:63], v[136:139], v[204:207], v[60:63]
	v_mfma_f32_16x16x32_bf16 v[56:59], v[144:147], v[204:207], v[56:59]
	v_mfma_f32_16x16x32_bf16 v[44:47], v[136:139], v[216:219], v[44:47]
	v_mfma_f32_16x16x32_bf16 v[40:43], v[144:147], v[216:219], v[40:43]
	v_mfma_f32_16x16x32_bf16 v[28:31], v[136:139], v[224:227], v[28:31]
	v_mfma_f32_16x16x32_bf16 v[24:27], v[144:147], v[224:227], v[24:27]
	v_mfma_f32_16x16x32_bf16 v[12:15], v[136:139], v[232:235], v[12:15]
	v_mfma_f32_16x16x32_bf16 v[8:11], v[144:147], v[232:235], v[8:11]
	v_mfma_f32_16x16x32_bf16 v[52:55], v[148:151], v[192:195], v[52:55]
	v_mfma_f32_16x16x32_bf16 v[48:51], v[184:187], v[192:195], v[48:51]
	v_mfma_f32_16x16x32_bf16 v[36:39], v[148:151], v[208:211], v[36:39]
	v_mfma_f32_16x16x32_bf16 v[32:35], v[184:187], v[208:211], v[32:35]
	v_mfma_f32_16x16x32_bf16 v[20:23], v[148:151], v[220:223], v[20:23]
	v_mfma_f32_16x16x32_bf16 v[16:19], v[184:187], v[220:223], v[16:19]
	v_mfma_f32_16x16x32_bf16 v[4:7], v[148:151], v[228:231], v[4:7]
	v_mfma_f32_16x16x32_bf16 v[0:3], v[184:187], v[228:231], v[0:3]
	v_mfma_f32_16x16x32_bf16 v[52:55], v[180:183], v[204:207], v[52:55]
	v_mfma_f32_16x16x32_bf16 v[48:51], v[188:191], v[204:207], v[48:51]
	v_mfma_f32_16x16x32_bf16 v[36:39], v[180:183], v[216:219], v[36:39]
	v_mfma_f32_16x16x32_bf16 v[32:35], v[188:191], v[216:219], v[32:35]
	v_mfma_f32_16x16x32_bf16 v[20:23], v[180:183], v[224:227], v[20:23]
	v_mfma_f32_16x16x32_bf16 v[16:19], v[188:191], v[224:227], v[16:19]
	v_mfma_f32_16x16x32_bf16 v[4:7], v[180:183], v[232:235], v[4:7]
	v_mfma_f32_16x16x32_bf16 v[0:3], v[188:191], v[232:235], v[0:3]
	s_barrier
	s_add_i32 s13, 0, 0x18000
	s_add_i32 s29, 0, 0x1c000
	ds_read_b128 v[132:135], v255 offset:16384
	ds_read_b128 v[136:139], v255 offset:17408
	ds_read_b128 v[140:143], v255 offset:18432
	ds_read_b128 v[144:147], v255 offset:19456
	ds_read_b128 v[148:151], v255 offset:32768
	ds_read_b128 v[180:183], v255 offset:33792
	ds_read_b128 v[184:187], v255 offset:34816
	ds_read_b128 v[188:191], v255 offset:35840
	v_lshl_add_u64 v[196:197], v[196:197], 0, s[14:15]
	s_mov_b32 m0, s35
	v_lshl_add_u64 v[244:245], v[196:197], 0, v[162:163]
	ds_read_b128 v[192:195], v202 offset:32768
	ds_read_b128 v[204:207], v202 offset:33792
	ds_read_b128 v[208:211], v202 offset:34816
	ds_read_b128 v[216:219], v202 offset:35840
	ds_read_b128 v[220:223], v202 offset:36864
	ds_read_b128 v[224:227], v202 offset:37888
	ds_read_b128 v[228:231], v202 offset:38912
	ds_read_b128 v[232:235], v202 offset:39936
	global_load_lds_dwordx4 v[244:245], off
	s_mov_b32 m0, s36
	v_lshl_add_u64 v[196:197], v[196:197], 0, v[166:167]
	global_load_lds_dwordx4 v[196:197], off
	s_waitcnt vmcnt(8) lgkmcnt(0)
	s_barrier
	v_mfma_f32_16x16x32_bf16 v[120:123], v[132:135], v[192:195], v[120:123]
	v_mfma_f32_16x16x32_bf16 v[124:127], v[140:143], v[192:195], v[124:127]
	v_mfma_f32_16x16x32_bf16 v[108:111], v[132:135], v[208:211], v[108:111]
	v_mfma_f32_16x16x32_bf16 v[104:107], v[140:143], v[208:211], v[104:107]
	v_mfma_f32_16x16x32_bf16 v[92:95], v[132:135], v[220:223], v[92:95]
	v_mfma_f32_16x16x32_bf16 v[88:91], v[140:143], v[220:223], v[88:91]
	v_mfma_f32_16x16x32_bf16 v[76:79], v[132:135], v[228:231], v[76:79]
	v_mfma_f32_16x16x32_bf16 v[72:75], v[140:143], v[228:231], v[72:75]
	v_mfma_f32_16x16x32_bf16 v[120:123], v[136:139], v[204:207], v[120:123]
	v_mfma_f32_16x16x32_bf16 v[124:127], v[144:147], v[204:207], v[124:127]
	v_mfma_f32_16x16x32_bf16 v[108:111], v[136:139], v[216:219], v[108:111]
	v_mfma_f32_16x16x32_bf16 v[104:107], v[144:147], v[216:219], v[104:107]
	v_mfma_f32_16x16x32_bf16 v[92:95], v[136:139], v[224:227], v[92:95]
	v_mfma_f32_16x16x32_bf16 v[88:91], v[144:147], v[224:227], v[88:91]
	v_mfma_f32_16x16x32_bf16 v[76:79], v[136:139], v[232:235], v[76:79]
	v_mfma_f32_16x16x32_bf16 v[72:75], v[144:147], v[232:235], v[72:75]
	v_mfma_f32_16x16x32_bf16 v[116:119], v[148:151], v[192:195], v[116:119]
	v_mfma_f32_16x16x32_bf16 v[112:115], v[184:187], v[192:195], v[112:115]
	v_mfma_f32_16x16x32_bf16 v[100:103], v[148:151], v[208:211], v[100:103]
	v_mfma_f32_16x16x32_bf16 v[96:99], v[184:187], v[208:211], v[96:99]
	v_mfma_f32_16x16x32_bf16 v[84:87], v[148:151], v[220:223], v[84:87]
	v_mfma_f32_16x16x32_bf16 v[80:83], v[184:187], v[220:223], v[80:83]
	v_mfma_f32_16x16x32_bf16 v[68:71], v[148:151], v[228:231], v[68:71]
	v_mfma_f32_16x16x32_bf16 v[64:67], v[184:187], v[228:231], v[64:67]
	v_mfma_f32_16x16x32_bf16 v[116:119], v[180:183], v[204:207], v[116:119]
	v_mfma_f32_16x16x32_bf16 v[112:115], v[188:191], v[204:207], v[112:115]
	v_mfma_f32_16x16x32_bf16 v[100:103], v[180:183], v[216:219], v[100:103]
	v_mfma_f32_16x16x32_bf16 v[96:99], v[188:191], v[216:219], v[96:99]
	v_mfma_f32_16x16x32_bf16 v[84:87], v[180:183], v[224:227], v[84:87]
	v_mfma_f32_16x16x32_bf16 v[80:83], v[188:191], v[224:227], v[80:83]
	v_mfma_f32_16x16x32_bf16 v[68:71], v[180:183], v[232:235], v[68:71]
	v_mfma_f32_16x16x32_bf16 v[64:67], v[188:191], v[232:235], v[64:67]
	s_barrier
; #define PG8_STAGE(bufoff, gbase, voff) do { _Pragma("unroll") for (int _i = 0; _i < 2; ++_i) \
;         __builtin_amdgcn_global_load_lds((const unsigned*)((const char*)(gbase) + (voff)[_i]), (PG8_LAS unsigned*)(lds + (bufoff) + ldsw + _i * 8192), 16, 0, 0); } while (0)
; #define PG8_LDA(dst, b, h) do { _Pragma("unroll") for (int m = 0; m < 4; ++m) _Pragma("unroll") for (int k = 0; k < 2; ++k) dst[m][k] = *(const PG8_LAS bf16x8*)(lds + PG8_SA(b, h) + aoff + m * 2048 + k * 1024); } while (0)
; #define PG8_MMA(ai, bj, At, Bt) do { __builtin_amdgcn_s_setprio(1); _Pragma("unroll") for (int m = 0; m < 4; ++m) _Pragma("unroll") for (int n = 0; n < 2; ++n) _Pragma("unroll") for (int k = 0; k < 2; ++k) \
;         acc[ai][bj][m][n] = __builtin_amdgcn_mfma_f32_16x16x32_bf16(Bt[n][k], At[m][k], acc[ai][bj][m][n], 0, 0, 0); __builtin_amdgcn_s_setprio(0); } while (0)
; #define PG8_WAIT_V(n) asm volatile("s_waitcnt vmcnt(" #n ")" ::: "memory")
; #define PG8_WAIT_L(n) asm volatile("s_waitcnt lgkmcnt(" #n ")" ::: "memory")
; #define PG8_BAR __builtin_amdgcn_s_barrier()
; #define PG8_SCHED __builtin_amdgcn_sched_barrier(0)
; template <class Epi, class Sched, bool ALIGN_EPI = false, bool SP2 = false>
; __device__ __forceinline__ void gemm_phase(PG8_LAS unsigned char* lds, const Gemm g, const Sched& S, const Epi& E) {
;     ...
;         for (int t = 0; t < nt; t += 2) {
;     ...
;             PG8_LDA(At, 1, 1); PG8_STAGE(PG8_SB(1, 0), b3, voffB); PG8_STAGE(PG8_SB(1, 1), b3 + hstep, voffB); PG8_STAGE(PG8_SA(1, 0), a3, voffA);
;             PG8_WAIT_V(8); PG8_WAIT_L(0); PG8_BAR; PG8_MMA(1, 0, At, B0); PG8_MMA(1, 1, At, B1); PG8_BAR; PG8_SCHED;
	s_add_i32 s13, s13, s30
	s_add_i32 m0, s13, 0xffffff80
	ds_read_b128 v[192:195], v202 offset:49152
	ds_read_b128 v[204:207], v202 offset:50176
	ds_read_b128 v[208:211], v202 offset:51200
	ds_read_b128 v[216:219], v202 offset:52224
	global_load_lds_dwordx4 v[214:215], off offset:128
	s_add_i32 m0, s13, 0x1f80
	s_add_i32 s13, s29, s30
	global_load_lds_dwordx4 v[236:237], off offset:128
	s_add_i32 m0, s13, 0xffffff80
	ds_read_b128 v[232:235], v202 offset:56320
	global_load_lds_dwordx4 v[238:239], off offset:128
	s_add_i32 m0, s13, 0x1f80
	ds_read_b128 v[228:231], v202 offset:55296
	global_load_lds_dwordx4 v[212:213], off offset:128
	s_add_i32 m0, s37, 0xffffff80
	ds_read_b128 v[224:227], v202 offset:54272
	global_load_lds_dwordx4 v[240:241], off offset:128
	s_add_i32 m0, s41, 0xffffff80
	ds_read_b128 v[220:223], v202 offset:53248
	global_load_lds_dwordx4 v[242:243], off offset:128
	s_waitcnt vmcnt(8) lgkmcnt(0)
	s_barrier
	v_mfma_f32_16x16x32_bf16 v[60:63], v[132:135], v[192:195], v[60:63]
	v_mfma_f32_16x16x32_bf16 v[56:59], v[140:143], v[192:195], v[56:59]
	v_mfma_f32_16x16x32_bf16 v[44:47], v[132:135], v[208:211], v[44:47]
	v_mfma_f32_16x16x32_bf16 v[40:43], v[140:143], v[208:211], v[40:43]
	v_mfma_f32_16x16x32_bf16 v[28:31], v[132:135], v[220:223], v[28:31]
	v_mfma_f32_16x16x32_bf16 v[24:27], v[140:143], v[220:223], v[24:27]
	v_mfma_f32_16x16x32_bf16 v[12:15], v[132:135], v[228:231], v[12:15]
	v_mfma_f32_16x16x32_bf16 v[8:11], v[140:143], v[228:231], v[8:11]
	v_mfma_f32_16x16x32_bf16 v[60:63], v[136:139], v[204:207], v[60:63]
	v_mfma_f32_16x16x32_bf16 v[56:59], v[144:147], v[204:207], v[56:59]
	v_mfma_f32_16x16x32_bf16 v[44:47], v[136:139], v[216:219], v[44:47]
	v_mfma_f32_16x16x32_bf16 v[40:43], v[144:147], v[216:219], v[40:43]
	v_mfma_f32_16x16x32_bf16 v[28:31], v[136:139], v[224:227], v[28:31]
	v_mfma_f32_16x16x32_bf16 v[24:27], v[144:147], v[224:227], v[24:27]
	v_mfma_f32_16x16x32_bf16 v[12:15], v[136:139], v[232:235], v[12:15]
	v_mfma_f32_16x16x32_bf16 v[8:11], v[144:147], v[232:235], v[8:11]
	v_mfma_f32_16x16x32_bf16 v[52:55], v[148:151], v[192:195], v[52:55]
	v_mfma_f32_16x16x32_bf16 v[48:51], v[184:187], v[192:195], v[48:51]
	v_mfma_f32_16x16x32_bf16 v[36:39], v[148:151], v[208:211], v[36:39]
	v_mfma_f32_16x16x32_bf16 v[32:35], v[184:187], v[208:211], v[32:35]
	v_mfma_f32_16x16x32_bf16 v[20:23], v[148:151], v[220:223], v[20:23]
	v_mfma_f32_16x16x32_bf16 v[16:19], v[184:187], v[220:223], v[16:19]
	v_mfma_f32_16x16x32_bf16 v[4:7], v[148:151], v[228:231], v[4:7]
	v_mfma_f32_16x16x32_bf16 v[0:3], v[184:187], v[228:231], v[0:3]
	v_mfma_f32_16x16x32_bf16 v[52:55], v[180:183], v[204:207], v[52:55]
	v_mfma_f32_16x16x32_bf16 v[48:51], v[188:191], v[204:207], v[48:51]
	v_mfma_f32_16x16x32_bf16 v[36:39], v[180:183], v[216:219], v[36:39]
	v_mfma_f32_16x16x32_bf16 v[32:35], v[188:191], v[216:219], v[32:35]
	v_mfma_f32_16x16x32_bf16 v[20:23], v[180:183], v[224:227], v[20:23]
	v_mfma_f32_16x16x32_bf16 v[16:19], v[188:191], v[224:227], v[16:19]
	v_mfma_f32_16x16x32_bf16 v[4:7], v[180:183], v[232:235], v[4:7]
	v_mfma_f32_16x16x32_bf16 v[0:3], v[188:191], v[232:235], v[0:3]
	s_barrier
	v_lshl_add_u64 v[128:129], v[128:129], 0, s[26:27]
	s_cmp_ge_i32 s12, s47
	v_lshl_add_u64 v[130:131], v[130:131], 0, s[26:27]
	s_cbranch_scc0 .LBB0_1695

; #define PG8_STAGE(bufoff, gbase, voff) do { _Pragma("unroll") for (int _i = 0; _i < 2; ++_i) \
;         __builtin_amdgcn_global_load_lds((const unsigned*)((const char*)(gbase) + (voff)[_i]), (PG8_LAS unsigned*)(lds + (bufoff) + ldsw + _i * 8192), 16, 0, 0); } while (0)
; #define PG8_LDA(dst, b, h) do { _Pragma("unroll") for (int m = 0; m < 4; ++m) _Pragma("unroll") for (int k = 0; k < 2; ++k) dst[m][k] = *(const PG8_LAS bf16x8*)(lds + PG8_SA(b, h) + aoff + m * 2048 + k * 1024); } while (0)
; #define PG8_LDB(dst, b, h) do { _Pragma("unroll") for (int n = 0; n < 2; ++n) _Pragma("unroll") for (int k = 0; k < 2; ++k) dst[n][k] = *(const PG8_LAS bf16x8*)(lds + PG8_SB(b, h) + boff + n * 2048 + k * 1024); } while (0)
; #define PG8_MMA(ai, bj, At, Bt) do { __builtin_amdgcn_s_setprio(1); _Pragma("unroll") for (int m = 0; m < 4; ++m) _Pragma("unroll") for (int n = 0; n < 2; ++n) _Pragma("unroll") for (int k = 0; k < 2; ++k) \
;         acc[ai][bj][m][n] = __builtin_amdgcn_mfma_f32_16x16x32_bf16(Bt[n][k], At[m][k], acc[ai][bj][m][n], 0, 0, 0); __builtin_amdgcn_s_setprio(0); } while (0)
; #define PG8_WAIT_V(n) asm volatile("s_waitcnt vmcnt(" #n ")" ::: "memory")
; #define PG8_WAIT_L(n) asm volatile("s_waitcnt lgkmcnt(" #n ")" ::: "memory")
; #define PG8_BAR __builtin_amdgcn_s_barrier()
; template <class Epi, class Sched, bool ALIGN_EPI = false, bool SP2 = false>
; __device__ __forceinline__ void gemm_phase(PG8_LAS unsigned char* lds, const Gemm g, const Sched& S, const Epi& E) {
;     ...
;             const char* a1 = cA + (size_t)(t + 1) * kstep;
;             const char* a2 = last ? nA : cA + (size_t)(t + 2) * kstep; const char* b2 = last ? nB : cB + (size_t)(t + 2) * kstep;
;             const char* a3 = a2 + kstep; const char* b3 = b2 + kstep;
;             if (last && has_next) S.a_ready(nxt);
;             if constexpr (SP2) {
;             PG8_LDB(B0, 0, 0); PG8_LDB(B1, 0, 1); PG8_SCHED; PG8_LDA(At, 0, 0); PG8_STAGE(PG8_SA(1, 1), a1 + hstep, voffA);
;             PG8_WAIT_V(8); PG8_WAIT_L(0); PG8_BAR; PG8_MMA(0, 0, At, B0); PG8_MMA(0, 1, At, B1); PG8_BAR; PG8_SCHED;
;             PG8_LDA(At, 0, 1); PG8_STAGE(PG8_SB(0, 0), b2, voffB); PG8_STAGE(PG8_SB(0, 1), b2 + hstep, voffB); PG8_STAGE(PG8_SA(0, 0), a2, voffA);
;             PG8_WAIT_V(8); PG8_WAIT_L(0); PG8_BAR; PG8_MMA(1, 0, At, B0); PG8_MMA(1, 1, At, B1); PG8_BAR; PG8_SCHED;
.LBB0_1776:
	v_add_u32_e32 v166, s54, v169
	ds_read_b128 v[162:165], v166
	ds_read_b128 v[182:185], v166 offset:1024
	ds_read_b128 v[186:189], v166 offset:2048
	ds_read_b128 v[190:193], v166 offset:3072
	ds_read_b128 v[194:197], v166 offset:16384
	ds_read_b128 v[198:201], v166 offset:17408
	ds_read_b128 v[202:205], v166 offset:18432
	ds_read_b128 v[206:209], v166 offset:19456
	s_cmp_eq_u32 s53, s10
	v_lshl_add_u64 v[172:173], v[160:161], 0, s[22:23]
	s_cselect_b64 vcc, -1, 0
	s_add_i32 s10, s10, 2
	v_cndmask_b32_e32 v173, v173, v153, vcc
	v_cndmask_b32_e32 v172, v172, v152, vcc
	v_cndmask_b32_e32 v215, v159, v155, vcc
	v_cndmask_b32_e32 v214, v158, v154, vcc
	s_mov_b32 m0, s56
	v_lshl_add_u64 v[244:245], v[160:161], 0, v[148:149]
	ds_read_b128 v[210:213], v179
	ds_read_b128 v[216:219], v179 offset:1024
	ds_read_b128 v[220:223], v179 offset:2048
	ds_read_b128 v[224:227], v179 offset:3072
	ds_read_b128 v[228:231], v179 offset:4096
	ds_read_b128 v[232:235], v179 offset:5120
	ds_read_b128 v[236:239], v179 offset:6144
	ds_read_b128 v[240:243], v179 offset:7168
	global_load_lds_dwordx4 v[244:245], off
	s_mov_b32 m0, s57
	v_lshl_add_u64 v[244:245], v[160:161], 0, v[146:147]
	global_load_lds_dwordx4 v[244:245], off
	s_waitcnt vmcnt(8) lgkmcnt(0)
	s_barrier
	v_mfma_f32_16x16x32_bf16 v[124:127], v[162:165], v[210:213], v[124:127]
	v_mfma_f32_16x16x32_bf16 v[116:119], v[186:189], v[210:213], v[116:119]
	v_mfma_f32_16x16x32_bf16 v[108:111], v[162:165], v[220:223], v[108:111]
	v_mfma_f32_16x16x32_bf16 v[100:103], v[186:189], v[220:223], v[100:103]
	v_mfma_f32_16x16x32_bf16 v[92:95], v[162:165], v[228:231], v[92:95]
	v_mfma_f32_16x16x32_bf16 v[84:87], v[186:189], v[228:231], v[84:87]
	v_mfma_f32_16x16x32_bf16 v[76:79], v[162:165], v[236:239], v[76:79]
	v_mfma_f32_16x16x32_bf16 v[68:71], v[186:189], v[236:239], v[68:71]
	v_mfma_f32_16x16x32_bf16 v[124:127], v[182:185], v[216:219], v[124:127]
	v_mfma_f32_16x16x32_bf16 v[116:119], v[190:193], v[216:219], v[116:119]
	v_mfma_f32_16x16x32_bf16 v[108:111], v[182:185], v[224:227], v[108:111]
	v_mfma_f32_16x16x32_bf16 v[100:103], v[190:193], v[224:227], v[100:103]
	v_mfma_f32_16x16x32_bf16 v[92:95], v[182:185], v[232:235], v[92:95]
	v_mfma_f32_16x16x32_bf16 v[84:87], v[190:193], v[232:235], v[84:87]
	v_mfma_f32_16x16x32_bf16 v[76:79], v[182:185], v[240:243], v[76:79]
	v_mfma_f32_16x16x32_bf16 v[68:71], v[190:193], v[240:243], v[68:71]
	v_mfma_f32_16x16x32_bf16 v[120:123], v[194:197], v[210:213], v[120:123]
	v_mfma_f32_16x16x32_bf16 v[112:115], v[202:205], v[210:213], v[112:115]
	v_mfma_f32_16x16x32_bf16 v[104:107], v[194:197], v[220:223], v[104:107]
	v_mfma_f32_16x16x32_bf16 v[96:99], v[202:205], v[220:223], v[96:99]
	v_mfma_f32_16x16x32_bf16 v[88:91], v[194:197], v[228:231], v[88:91]
	v_mfma_f32_16x16x32_bf16 v[80:83], v[202:205], v[228:231], v[80:83]
	v_mfma_f32_16x16x32_bf16 v[72:75], v[194:197], v[236:239], v[72:75]
	v_mfma_f32_16x16x32_bf16 v[64:67], v[202:205], v[236:239], v[64:67]
	v_mfma_f32_16x16x32_bf16 v[120:123], v[198:201], v[216:219], v[120:123]
	v_mfma_f32_16x16x32_bf16 v[112:115], v[206:209], v[216:219], v[112:115]
	v_mfma_f32_16x16x32_bf16 v[104:107], v[198:201], v[224:227], v[104:107]
	v_mfma_f32_16x16x32_bf16 v[96:99], v[206:209], v[224:227], v[96:99]
	v_mfma_f32_16x16x32_bf16 v[88:91], v[198:201], v[232:235], v[88:91]
	v_mfma_f32_16x16x32_bf16 v[80:83], v[206:209], v[232:235], v[80:83]
	v_mfma_f32_16x16x32_bf16 v[72:75], v[198:201], v[240:243], v[72:75]
	v_mfma_f32_16x16x32_bf16 v[64:67], v[206:209], v[240:243], v[64:67]
	s_barrier
	s_mov_b32 m0, s60
	v_lshl_add_u64 v[244:245], v[214:215], 0, v[138:139]
	ds_read_b128 v[210:213], v179 offset:16384
	ds_read_b128 v[216:219], v179 offset:17408
	ds_read_b128 v[220:223], v179 offset:18432
	ds_read_b128 v[224:227], v179 offset:19456
	ds_read_b128 v[228:231], v179 offset:20480
	ds_read_b128 v[232:235], v179 offset:21504
	ds_read_b128 v[236:239], v179 offset:22528
	ds_read_b128 v[240:243], v179 offset:23552
	global_load_lds_dwordx4 v[244:245], off
	v_lshl_add_u64 v[246:247], v[214:215], 0, v[134:135]
	s_mov_b32 m0, s61
	v_lshl_add_u64 v[214:215], v[214:215], 0, s[14:15]
	global_load_lds_dwordx4 v[246:247], off
	v_lshl_add_u64 v[248:249], v[214:215], 0, v[138:139]
	s_mov_b32 m0, s62
	v_lshl_add_u64 v[214:215], v[214:215], 0, v[134:135]
	global_load_lds_dwordx4 v[248:249], off
	s_add_i32 m0, s62, 0x2000
	v_lshl_add_u64 v[250:251], v[172:173], 0, v[140:141]
	global_load_lds_dwordx4 v[214:215], off
	s_mov_b32 m0, s46
	v_lshl_add_u64 v[252:253], v[172:173], 0, v[136:137]
	global_load_lds_dwordx4 v[250:251], off
	s_mov_b32 m0, s47
	s_nop 0
	global_load_lds_dwordx4 v[252:253], off
	s_waitcnt vmcnt(8) lgkmcnt(0)
	s_barrier
; #define PG8_STAGE(bufoff, gbase, voff) do { _Pragma("unroll") for (int _i = 0; _i < 2; ++_i) \
;         __builtin_amdgcn_global_load_lds((const unsigned*)((const char*)(gbase) + (voff)[_i]), (PG8_LAS unsigned*)(lds + (bufoff) + ldsw + _i * 8192), 16, 0, 0); } while (0)
; #define PG8_LDA(dst, b, h) do { _Pragma("unroll") for (int m = 0; m < 4; ++m) _Pragma("unroll") for (int k = 0; k < 2; ++k) dst[m][k] = *(const PG8_LAS bf16x8*)(lds + PG8_SA(b, h) + aoff + m * 2048 + k * 1024); } while (0)
; #define PG8_LDB(dst, b, h) do { _Pragma("unroll") for (int n = 0; n < 2; ++n) _Pragma("unroll") for (int k = 0; k < 2; ++k) dst[n][k] = *(const PG8_LAS bf16x8*)(lds + PG8_SB(b, h) + boff + n * 2048 + k * 1024); } while (0)
; #define PG8_MMA(ai, bj, At, Bt) do { __builtin_amdgcn_s_setprio(1); _Pragma("unroll") for (int m = 0; m < 4; ++m) _Pragma("unroll") for (int n = 0; n < 2; ++n) _Pragma("unroll") for (int k = 0; k < 2; ++k) \
;         acc[ai][bj][m][n] = __builtin_amdgcn_mfma_f32_16x16x32_bf16(Bt[n][k], At[m][k], acc[ai][bj][m][n], 0, 0, 0); __builtin_amdgcn_s_setprio(0); } while (0)
; #define PG8_WAIT_V(n) asm volatile("s_waitcnt vmcnt(" #n ")" ::: "memory")
; #define PG8_WAIT_L(n) asm volatile("s_waitcnt lgkmcnt(" #n ")" ::: "memory")
; #define PG8_BAR __builtin_amdgcn_s_barrier()
; #define PG8_SCHED __builtin_amdgcn_sched_barrier(0)
; template <class Epi, class Sched, bool ALIGN_EPI = false, bool SP2 = false>
; __device__ __forceinline__ void gemm_phase(PG8_LAS unsigned char* lds, const Gemm g, const Sched& S, const Epi& E) {
;     ...
;             PG8_WAIT_V(8); PG8_WAIT_L(0); PG8_BAR; PG8_MMA(1, 0, At, B0); PG8_MMA(1, 1, At, B1); PG8_BAR; PG8_SCHED;
;             PG8_LDB(B0, 1, 0); PG8_LDB(B1, 1, 1); PG8_SCHED; PG8_LDA(At, 1, 0); PG8_STAGE(PG8_SA(0, 1), a2 + hstep, voffA);
;             PG8_WAIT_V(8); PG8_WAIT_L(0); PG8_BAR; PG8_MMA(0, 0, At, B0); PG8_MMA(0, 1, At, B1); PG8_BAR; PG8_SCHED;
	v_mfma_f32_16x16x32_bf16 v[60:63], v[162:165], v[210:213], v[60:63]
	v_mfma_f32_16x16x32_bf16 v[52:55], v[186:189], v[210:213], v[52:55]
	v_mfma_f32_16x16x32_bf16 v[44:47], v[162:165], v[220:223], v[44:47]
	v_mfma_f32_16x16x32_bf16 v[36:39], v[186:189], v[220:223], v[36:39]
	v_mfma_f32_16x16x32_bf16 v[28:31], v[162:165], v[228:231], v[28:31]
	v_mfma_f32_16x16x32_bf16 v[20:23], v[186:189], v[228:231], v[20:23]
	v_mfma_f32_16x16x32_bf16 v[12:15], v[162:165], v[236:239], v[12:15]
	v_mfma_f32_16x16x32_bf16 v[4:7], v[186:189], v[236:239], v[4:7]
	v_mfma_f32_16x16x32_bf16 v[60:63], v[182:185], v[216:219], v[60:63]
	v_mfma_f32_16x16x32_bf16 v[52:55], v[190:193], v[216:219], v[52:55]
	v_mfma_f32_16x16x32_bf16 v[44:47], v[182:185], v[224:227], v[44:47]
	v_mfma_f32_16x16x32_bf16 v[36:39], v[190:193], v[224:227], v[36:39]
	v_mfma_f32_16x16x32_bf16 v[28:31], v[182:185], v[232:235], v[28:31]
	v_mfma_f32_16x16x32_bf16 v[20:23], v[190:193], v[232:235], v[20:23]
	v_mfma_f32_16x16x32_bf16 v[12:15], v[182:185], v[240:243], v[12:15]
	v_mfma_f32_16x16x32_bf16 v[4:7], v[190:193], v[240:243], v[4:7]
	v_mfma_f32_16x16x32_bf16 v[56:59], v[194:197], v[210:213], v[56:59]
	v_mfma_f32_16x16x32_bf16 v[48:51], v[202:205], v[210:213], v[48:51]
	v_mfma_f32_16x16x32_bf16 v[40:43], v[194:197], v[220:223], v[40:43]
	v_mfma_f32_16x16x32_bf16 v[32:35], v[202:205], v[220:223], v[32:35]
	v_mfma_f32_16x16x32_bf16 v[24:27], v[194:197], v[228:231], v[24:27]
	v_mfma_f32_16x16x32_bf16 v[16:19], v[202:205], v[228:231], v[16:19]
	v_mfma_f32_16x16x32_bf16 v[8:11], v[194:197], v[236:239], v[8:11]
	v_mfma_f32_16x16x32_bf16 v[0:3], v[202:205], v[236:239], v[0:3]
	v_mfma_f32_16x16x32_bf16 v[56:59], v[198:201], v[216:219], v[56:59]
	v_mfma_f32_16x16x32_bf16 v[48:51], v[206:209], v[216:219], v[48:51]
	v_mfma_f32_16x16x32_bf16 v[40:43], v[198:201], v[224:227], v[40:43]
	v_mfma_f32_16x16x32_bf16 v[32:35], v[206:209], v[224:227], v[32:35]
	v_mfma_f32_16x16x32_bf16 v[24:27], v[198:201], v[232:235], v[24:27]
	v_mfma_f32_16x16x32_bf16 v[16:19], v[206:209], v[232:235], v[16:19]
	v_mfma_f32_16x16x32_bf16 v[8:11], v[198:201], v[240:243], v[8:11]
	v_mfma_f32_16x16x32_bf16 v[0:3], v[206:209], v[240:243], v[0:3]
	s_barrier
	s_add_i32 s11, 0, 0x18000
	s_add_i32 s13, 0, 0x1c000
	ds_read_b128 v[162:165], v166 offset:32768
	ds_read_b128 v[182:185], v166 offset:33792
	ds_read_b128 v[186:189], v166 offset:34816
	ds_read_b128 v[190:193], v166 offset:35840
	ds_read_b128 v[194:197], v166 offset:49152
	ds_read_b128 v[198:201], v166 offset:50176
	ds_read_b128 v[202:205], v166 offset:51200
	ds_read_b128 v[206:209], v166 offset:52224
	v_lshl_add_u64 v[172:173], v[172:173], 0, s[14:15]
	s_mov_b32 m0, s48
	v_lshl_add_u64 v[170:171], v[172:173], 0, v[140:141]
	ds_read_b128 v[210:213], v179 offset:32768
	ds_read_b128 v[216:219], v179 offset:33792
	ds_read_b128 v[220:223], v179 offset:34816
	ds_read_b128 v[224:227], v179 offset:35840
	ds_read_b128 v[228:231], v179 offset:36864
	ds_read_b128 v[232:235], v179 offset:37888
	ds_read_b128 v[236:239], v179 offset:38912
	ds_read_b128 v[240:243], v179 offset:39936
	global_load_lds_dwordx4 v[170:171], off
	s_mov_b32 m0, s49
	v_lshl_add_u64 v[170:171], v[172:173], 0, v[136:137]
	global_load_lds_dwordx4 v[170:171], off
	s_waitcnt vmcnt(8) lgkmcnt(0)
	s_barrier
	v_mfma_f32_16x16x32_bf16 v[124:127], v[162:165], v[210:213], v[124:127]
	v_mfma_f32_16x16x32_bf16 v[116:119], v[186:189], v[210:213], v[116:119]
	v_mfma_f32_16x16x32_bf16 v[108:111], v[162:165], v[220:223], v[108:111]
	v_mfma_f32_16x16x32_bf16 v[100:103], v[186:189], v[220:223], v[100:103]
	v_mfma_f32_16x16x32_bf16 v[92:95], v[162:165], v[228:231], v[92:95]
	v_mfma_f32_16x16x32_bf16 v[84:87], v[186:189], v[228:231], v[84:87]
	v_mfma_f32_16x16x32_bf16 v[76:79], v[162:165], v[236:239], v[76:79]
	v_mfma_f32_16x16x32_bf16 v[68:71], v[186:189], v[236:239], v[68:71]
	v_mfma_f32_16x16x32_bf16 v[124:127], v[182:185], v[216:219], v[124:127]
	v_mfma_f32_16x16x32_bf16 v[116:119], v[190:193], v[216:219], v[116:119]
	v_mfma_f32_16x16x32_bf16 v[108:111], v[182:185], v[224:227], v[108:111]
	v_mfma_f32_16x16x32_bf16 v[100:103], v[190:193], v[224:227], v[100:103]
	v_mfma_f32_16x16x32_bf16 v[92:95], v[182:185], v[232:235], v[92:95]
	v_mfma_f32_16x16x32_bf16 v[84:87], v[190:193], v[232:235], v[84:87]
	v_mfma_f32_16x16x32_bf16 v[76:79], v[182:185], v[240:243], v[76:79]
	v_mfma_f32_16x16x32_bf16 v[68:71], v[190:193], v[240:243], v[68:71]
	v_mfma_f32_16x16x32_bf16 v[120:123], v[194:197], v[210:213], v[120:123]
	v_mfma_f32_16x16x32_bf16 v[112:115], v[202:205], v[210:213], v[112:115]
	v_mfma_f32_16x16x32_bf16 v[104:107], v[194:197], v[220:223], v[104:107]
	v_mfma_f32_16x16x32_bf16 v[96:99], v[202:205], v[220:223], v[96:99]
	v_mfma_f32_16x16x32_bf16 v[88:91], v[194:197], v[228:231], v[88:91]
	v_mfma_f32_16x16x32_bf16 v[80:83], v[202:205], v[228:231], v[80:83]
	v_mfma_f32_16x16x32_bf16 v[72:75], v[194:197], v[236:239], v[72:75]
	v_mfma_f32_16x16x32_bf16 v[64:67], v[202:205], v[236:239], v[64:67]
	v_mfma_f32_16x16x32_bf16 v[120:123], v[198:201], v[216:219], v[120:123]
	v_mfma_f32_16x16x32_bf16 v[112:115], v[206:209], v[216:219], v[112:115]
	v_mfma_f32_16x16x32_bf16 v[104:107], v[198:201], v[224:227], v[104:107]
	v_mfma_f32_16x16x32_bf16 v[96:99], v[206:209], v[224:227], v[96:99]
	v_mfma_f32_16x16x32_bf16 v[88:91], v[198:201], v[232:235], v[88:91]
	v_mfma_f32_16x16x32_bf16 v[80:83], v[206:209], v[232:235], v[80:83]
	v_mfma_f32_16x16x32_bf16 v[72:75], v[198:201], v[240:243], v[72:75]
	v_mfma_f32_16x16x32_bf16 v[64:67], v[206:209], v[240:243], v[64:67]
	s_barrier
; #define PG8_STAGE(bufoff, gbase, voff) do { _Pragma("unroll") for (int _i = 0; _i < 2; ++_i) \
;         __builtin_amdgcn_global_load_lds((const unsigned*)((const char*)(gbase) + (voff)[_i]), (PG8_LAS unsigned*)(lds + (bufoff) + ldsw + _i * 8192), 16, 0, 0); } while (0)
; #define PG8_LDA(dst, b, h) do { _Pragma("unroll") for (int m = 0; m < 4; ++m) _Pragma("unroll") for (int k = 0; k < 2; ++k) dst[m][k] = *(const PG8_LAS bf16x8*)(lds + PG8_SA(b, h) + aoff + m * 2048 + k * 1024); } while (0)
; #define PG8_MMA(ai, bj, At, Bt) do { __builtin_amdgcn_s_setprio(1); _Pragma("unroll") for (int m = 0; m < 4; ++m) _Pragma("unroll") for (int n = 0; n < 2; ++n) _Pragma("unroll") for (int k = 0; k < 2; ++k) \
;         acc[ai][bj][m][n] = __builtin_amdgcn_mfma_f32_16x16x32_bf16(Bt[n][k], At[m][k], acc[ai][bj][m][n], 0, 0, 0); __builtin_amdgcn_s_setprio(0); } while (0)
; #define PG8_WAIT_V(n) asm volatile("s_waitcnt vmcnt(" #n ")" ::: "memory")
; #define PG8_WAIT_L(n) asm volatile("s_waitcnt lgkmcnt(" #n ")" ::: "memory")
; #define PG8_BAR __builtin_amdgcn_s_barrier()
; #define PG8_SCHED __builtin_amdgcn_sched_barrier(0)
; template <class Epi, class Sched, bool ALIGN_EPI = false, bool SP2 = false>
; __device__ __forceinline__ void gemm_phase(PG8_LAS unsigned char* lds, const Gemm g, const Sched& S, const Epi& E) {
;     ...
;         for (int t = 0; t < nt; t += 2) {
;     ...
;             PG8_LDA(At, 1, 1); PG8_STAGE(PG8_SB(1, 0), b3, voffB); PG8_STAGE(PG8_SB(1, 1), b3 + hstep, voffB); PG8_STAGE(PG8_SA(1, 0), a3, voffA);
;             PG8_WAIT_V(8); PG8_WAIT_L(0); PG8_BAR; PG8_MMA(1, 0, At, B0); PG8_MMA(1, 1, At, B1); PG8_BAR; PG8_SCHED;
	s_add_i32 s11, s11, s29
	s_add_i32 m0, s11, 0xffffff80
	ds_read_b128 v[210:213], v179 offset:49152
	ds_read_b128 v[216:219], v179 offset:50176
	ds_read_b128 v[220:223], v179 offset:51200
	ds_read_b128 v[224:227], v179 offset:52224
	global_load_lds_dwordx4 v[244:245], off offset:128
	s_add_i32 m0, s11, 0x1f80
	s_add_i32 s11, s13, s29
	global_load_lds_dwordx4 v[246:247], off offset:128
	s_add_i32 m0, s11, 0xffffff80
	ds_read_b128 v[240:243], v179 offset:56320
	global_load_lds_dwordx4 v[248:249], off offset:128
	s_add_i32 m0, s11, 0x1f80
	ds_read_b128 v[236:239], v179 offset:55296
	global_load_lds_dwordx4 v[214:215], off offset:128
	s_add_i32 m0, s50, 0xffffff80
	ds_read_b128 v[232:235], v179 offset:54272
	global_load_lds_dwordx4 v[250:251], off offset:128
	s_add_i32 m0, s51, 0xffffff80
	ds_read_b128 v[228:231], v179 offset:53248
	global_load_lds_dwordx4 v[252:253], off offset:128
	s_waitcnt vmcnt(8) lgkmcnt(0)
	s_barrier
	v_mfma_f32_16x16x32_bf16 v[60:63], v[162:165], v[210:213], v[60:63]
	v_mfma_f32_16x16x32_bf16 v[52:55], v[186:189], v[210:213], v[52:55]
	v_mfma_f32_16x16x32_bf16 v[44:47], v[162:165], v[220:223], v[44:47]
	v_mfma_f32_16x16x32_bf16 v[36:39], v[186:189], v[220:223], v[36:39]
	v_mfma_f32_16x16x32_bf16 v[28:31], v[162:165], v[228:231], v[28:31]
	v_mfma_f32_16x16x32_bf16 v[20:23], v[186:189], v[228:231], v[20:23]
	v_mfma_f32_16x16x32_bf16 v[12:15], v[162:165], v[236:239], v[12:15]
	v_mfma_f32_16x16x32_bf16 v[4:7], v[186:189], v[236:239], v[4:7]
	v_mfma_f32_16x16x32_bf16 v[60:63], v[182:185], v[216:219], v[60:63]
	v_mfma_f32_16x16x32_bf16 v[52:55], v[190:193], v[216:219], v[52:55]
	v_mfma_f32_16x16x32_bf16 v[44:47], v[182:185], v[224:227], v[44:47]
	v_mfma_f32_16x16x32_bf16 v[36:39], v[190:193], v[224:227], v[36:39]
	v_mfma_f32_16x16x32_bf16 v[28:31], v[182:185], v[232:235], v[28:31]
	v_mfma_f32_16x16x32_bf16 v[20:23], v[190:193], v[232:235], v[20:23]
	v_mfma_f32_16x16x32_bf16 v[12:15], v[182:185], v[240:243], v[12:15]
	v_mfma_f32_16x16x32_bf16 v[4:7], v[190:193], v[240:243], v[4:7]
	v_mfma_f32_16x16x32_bf16 v[56:59], v[194:197], v[210:213], v[56:59]
	v_mfma_f32_16x16x32_bf16 v[48:51], v[202:205], v[210:213], v[48:51]
	v_mfma_f32_16x16x32_bf16 v[40:43], v[194:197], v[220:223], v[40:43]
	v_mfma_f32_16x16x32_bf16 v[32:35], v[202:205], v[220:223], v[32:35]
	v_mfma_f32_16x16x32_bf16 v[24:27], v[194:197], v[228:231], v[24:27]
	v_mfma_f32_16x16x32_bf16 v[16:19], v[202:205], v[228:231], v[16:19]
	v_mfma_f32_16x16x32_bf16 v[8:11], v[194:197], v[236:239], v[8:11]
	v_mfma_f32_16x16x32_bf16 v[0:3], v[202:205], v[236:239], v[0:3]
	v_mfma_f32_16x16x32_bf16 v[56:59], v[198:201], v[216:219], v[56:59]
	v_mfma_f32_16x16x32_bf16 v[48:51], v[206:209], v[216:219], v[48:51]
	v_mfma_f32_16x16x32_bf16 v[40:43], v[198:201], v[224:227], v[40:43]
	v_mfma_f32_16x16x32_bf16 v[32:35], v[206:209], v[224:227], v[32:35]
	v_mfma_f32_16x16x32_bf16 v[24:27], v[198:201], v[232:235], v[24:27]
	v_mfma_f32_16x16x32_bf16 v[16:19], v[206:209], v[232:235], v[16:19]
	v_mfma_f32_16x16x32_bf16 v[8:11], v[198:201], v[240:243], v[8:11]
	v_mfma_f32_16x16x32_bf16 v[0:3], v[206:209], v[240:243], v[0:3]
	s_barrier
	v_lshl_add_u64 v[158:159], v[158:159], 0, s[26:27]
	s_cmp_ge_i32 s10, s52
	v_lshl_add_u64 v[160:161], v[160:161], 0, s[26:27]
	s_cbranch_scc0 .LBB0_1776

; #define PG8_STAGE(bufoff, gbase, voff) do { _Pragma("unroll") for (int _i = 0; _i < 2; ++_i) \
;         __builtin_amdgcn_global_load_lds((const unsigned*)((const char*)(gbase) + (voff)[_i]), (PG8_LAS unsigned*)(lds + (bufoff) + ldsw + _i * 8192), 16, 0, 0); } while (0)
; #define PG8_LDA(dst, b, h) do { _Pragma("unroll") for (int m = 0; m < 4; ++m) _Pragma("unroll") for (int k = 0; k < 2; ++k) dst[m][k] = *(const PG8_LAS bf16x8*)(lds + PG8_SA(b, h) + aoff + m * 2048 + k * 1024); } while (0)
; #define PG8_LDB(dst, b, h) do { _Pragma("unroll") for (int n = 0; n < 2; ++n) _Pragma("unroll") for (int k = 0; k < 2; ++k) dst[n][k] = *(const PG8_LAS bf16x8*)(lds + PG8_SB(b, h) + boff + n * 2048 + k * 1024); } while (0)
; #define PG8_MMA(ai, bj, At, Bt) do { __builtin_amdgcn_s_setprio(1); _Pragma("unroll") for (int m = 0; m < 4; ++m) _Pragma("unroll") for (int n = 0; n < 2; ++n) _Pragma("unroll") for (int k = 0; k < 2; ++k) \
;         acc[ai][bj][m][n] = __builtin_amdgcn_mfma_f32_16x16x32_bf16(Bt[n][k], At[m][k], acc[ai][bj][m][n], 0, 0, 0); __builtin_amdgcn_s_setprio(0); } while (0)
; #define PG8_WAIT_V(n) asm volatile("s_waitcnt vmcnt(" #n ")" ::: "memory")
; #define PG8_WAIT_L(n) asm volatile("s_waitcnt lgkmcnt(" #n ")" ::: "memory")
; #define PG8_BAR __builtin_amdgcn_s_barrier()
; template <class Epi, class Sched, bool ALIGN_EPI = false, bool SP2 = false>
; __device__ __forceinline__ void gemm_phase(PG8_LAS unsigned char* lds, const Gemm g, const Sched& S, const Epi& E) {
;     ...
;             const char* a1 = cA + (size_t)(t + 1) * kstep;
;             const char* a2 = last ? nA : cA + (size_t)(t + 2) * kstep; const char* b2 = last ? nB : cB + (size_t)(t + 2) * kstep;
;             const char* a3 = a2 + kstep; const char* b3 = b2 + kstep;
;             if (last && has_next) S.a_ready(nxt);
;             if constexpr (SP2) {
;             PG8_LDB(B0, 0, 0); PG8_LDB(B1, 0, 1); PG8_SCHED; PG8_LDA(At, 0, 0); PG8_STAGE(PG8_SA(1, 1), a1 + hstep, voffA);
;             PG8_WAIT_V(8); PG8_WAIT_L(0); PG8_BAR; PG8_MMA(0, 0, At, B0); PG8_MMA(0, 1, At, B1); PG8_BAR; PG8_SCHED;
;             PG8_LDA(At, 0, 1); PG8_STAGE(PG8_SB(0, 0), b2, voffB); PG8_STAGE(PG8_SB(0, 1), b2 + hstep, voffB); PG8_STAGE(PG8_SA(0, 0), a2, voffA);
;             PG8_WAIT_V(8); PG8_WAIT_L(0); PG8_BAR; PG8_MMA(1, 0, At, B0); PG8_MMA(1, 1, At, B1); PG8_BAR; PG8_SCHED;
.LBB0_1924:
	v_add_u32_e32 v255, s50, v161
	ds_read_b128 v[164:167], v162
	ds_read_b128 v[168:171], v162 offset:1024
	ds_read_b128 v[172:175], v162 offset:2048
	ds_read_b128 v[176:179], v162 offset:3072
	ds_read_b128 v[180:183], v255
	ds_read_b128 v[184:187], v255 offset:1024
	ds_read_b128 v[188:191], v255 offset:2048
	ds_read_b128 v[192:195], v255 offset:3072
	s_cmp_eq_u32 s49, s10
	v_lshl_add_u64 v[196:197], v[158:159], 0, s[24:25]
	s_cselect_b64 vcc, -1, 0
	s_add_i32 s10, s10, 2
	v_cndmask_b32_e32 v213, v197, v151, vcc
	v_cndmask_b32_e32 v212, v196, v150, vcc
	v_cndmask_b32_e32 v215, v155, v153, vcc
	v_cndmask_b32_e32 v214, v154, v152, vcc
	s_mov_b32 m0, s51
	v_lshl_add_u64 v[232:233], v[158:159], 0, v[146:147]
	ds_read_b128 v[196:199], v163
	ds_read_b128 v[200:203], v163 offset:1024
	ds_read_b128 v[204:207], v163 offset:2048
	ds_read_b128 v[208:211], v163 offset:3072
	ds_read_b128 v[216:219], v163 offset:4096
	ds_read_b128 v[220:223], v163 offset:5120
	ds_read_b128 v[224:227], v163 offset:6144
	ds_read_b128 v[228:231], v163 offset:7168
	global_load_lds_dwordx4 v[232:233], off
	s_mov_b32 m0, s52
	v_lshl_add_u64 v[232:233], v[158:159], 0, v[144:145]
	global_load_lds_dwordx4 v[232:233], off
	s_waitcnt vmcnt(8) lgkmcnt(0)
	s_barrier
	v_mfma_f32_16x16x32_bf16 v[124:127], v[164:167], v[196:199], v[124:127]
	v_mfma_f32_16x16x32_bf16 v[120:123], v[172:175], v[196:199], v[120:123]
	v_mfma_f32_16x16x32_bf16 v[108:111], v[164:167], v[204:207], v[108:111]
	v_mfma_f32_16x16x32_bf16 v[104:107], v[172:175], v[204:207], v[104:107]
	v_mfma_f32_16x16x32_bf16 v[92:95], v[164:167], v[216:219], v[92:95]
	v_mfma_f32_16x16x32_bf16 v[88:91], v[172:175], v[216:219], v[88:91]
	v_mfma_f32_16x16x32_bf16 v[76:79], v[164:167], v[224:227], v[76:79]
	v_mfma_f32_16x16x32_bf16 v[72:75], v[172:175], v[224:227], v[72:75]
	v_mfma_f32_16x16x32_bf16 v[124:127], v[168:171], v[200:203], v[124:127]
	v_mfma_f32_16x16x32_bf16 v[120:123], v[176:179], v[200:203], v[120:123]
	v_mfma_f32_16x16x32_bf16 v[108:111], v[168:171], v[208:211], v[108:111]
	v_mfma_f32_16x16x32_bf16 v[104:107], v[176:179], v[208:211], v[104:107]
	v_mfma_f32_16x16x32_bf16 v[92:95], v[168:171], v[220:223], v[92:95]
	v_mfma_f32_16x16x32_bf16 v[88:91], v[176:179], v[220:223], v[88:91]
	v_mfma_f32_16x16x32_bf16 v[76:79], v[168:171], v[228:231], v[76:79]
	v_mfma_f32_16x16x32_bf16 v[72:75], v[176:179], v[228:231], v[72:75]
	v_mfma_f32_16x16x32_bf16 v[116:119], v[180:183], v[196:199], v[116:119]
	v_mfma_f32_16x16x32_bf16 v[112:115], v[188:191], v[196:199], v[112:115]
	v_mfma_f32_16x16x32_bf16 v[100:103], v[180:183], v[204:207], v[100:103]
	v_mfma_f32_16x16x32_bf16 v[96:99], v[188:191], v[204:207], v[96:99]
	v_mfma_f32_16x16x32_bf16 v[84:87], v[180:183], v[216:219], v[84:87]
	v_mfma_f32_16x16x32_bf16 v[80:83], v[188:191], v[216:219], v[80:83]
	v_mfma_f32_16x16x32_bf16 v[68:71], v[180:183], v[224:227], v[68:71]
	v_mfma_f32_16x16x32_bf16 v[64:67], v[188:191], v[224:227], v[64:67]
	v_mfma_f32_16x16x32_bf16 v[116:119], v[184:187], v[200:203], v[116:119]
	v_mfma_f32_16x16x32_bf16 v[112:115], v[192:195], v[200:203], v[112:115]
	v_mfma_f32_16x16x32_bf16 v[100:103], v[184:187], v[208:211], v[100:103]
	v_mfma_f32_16x16x32_bf16 v[96:99], v[192:195], v[208:211], v[96:99]
	v_mfma_f32_16x16x32_bf16 v[84:87], v[184:187], v[220:223], v[84:87]
	v_mfma_f32_16x16x32_bf16 v[80:83], v[192:195], v[220:223], v[80:83]
	v_mfma_f32_16x16x32_bf16 v[68:71], v[184:187], v[228:231], v[68:71]
	v_mfma_f32_16x16x32_bf16 v[64:67], v[192:195], v[228:231], v[64:67]
	s_barrier
	s_mov_b32 m0, s53
	v_lshl_add_u64 v[232:233], v[214:215], 0, v[138:139]
	ds_read_b128 v[196:199], v163 offset:16384
	ds_read_b128 v[200:203], v163 offset:17408
	ds_read_b128 v[204:207], v163 offset:18432
	ds_read_b128 v[208:211], v163 offset:19456
	ds_read_b128 v[216:219], v163 offset:20480
	ds_read_b128 v[220:223], v163 offset:21504
	ds_read_b128 v[224:227], v163 offset:22528
	ds_read_b128 v[228:231], v163 offset:23552
	global_load_lds_dwordx4 v[232:233], off
	v_lshl_add_u64 v[234:235], v[214:215], 0, v[134:135]
	s_mov_b32 m0, s54
	v_lshl_add_u64 v[214:215], v[214:215], 0, s[14:15]
	global_load_lds_dwordx4 v[234:235], off
	v_lshl_add_u64 v[236:237], v[214:215], 0, v[138:139]
	s_mov_b32 m0, s55
	v_lshl_add_u64 v[214:215], v[214:215], 0, v[134:135]
	global_load_lds_dwordx4 v[236:237], off
	s_mov_b32 m0, s56
	v_lshl_add_u64 v[238:239], v[212:213], 0, v[140:141]
	global_load_lds_dwordx4 v[214:215], off
	s_mov_b32 m0, s37
	v_lshl_add_u64 v[240:241], v[212:213], 0, v[136:137]
	global_load_lds_dwordx4 v[238:239], off
	s_mov_b32 m0, s41
	s_nop 0
	global_load_lds_dwordx4 v[240:241], off
	s_waitcnt vmcnt(8) lgkmcnt(0)
	s_barrier
; #define PG8_STAGE(bufoff, gbase, voff) do { _Pragma("unroll") for (int _i = 0; _i < 2; ++_i) \
;         __builtin_amdgcn_global_load_lds((const unsigned*)((const char*)(gbase) + (voff)[_i]), (PG8_LAS unsigned*)(lds + (bufoff) + ldsw + _i * 8192), 16, 0, 0); } while (0)
; #define PG8_LDA(dst, b, h) do { _Pragma("unroll") for (int m = 0; m < 4; ++m) _Pragma("unroll") for (int k = 0; k < 2; ++k) dst[m][k] = *(const PG8_LAS bf16x8*)(lds + PG8_SA(b, h) + aoff + m * 2048 + k * 1024); } while (0)
; #define PG8_LDB(dst, b, h) do { _Pragma("unroll") for (int n = 0; n < 2; ++n) _Pragma("unroll") for (int k = 0; k < 2; ++k) dst[n][k] = *(const PG8_LAS bf16x8*)(lds + PG8_SB(b, h) + boff + n * 2048 + k * 1024); } while (0)
; #define PG8_MMA(ai, bj, At, Bt) do { __builtin_amdgcn_s_setprio(1); _Pragma("unroll") for (int m = 0; m < 4; ++m) _Pragma("unroll") for (int n = 0; n < 2; ++n) _Pragma("unroll") for (int k = 0; k < 2; ++k) \
;         acc[ai][bj][m][n] = __builtin_amdgcn_mfma_f32_16x16x32_bf16(Bt[n][k], At[m][k], acc[ai][bj][m][n], 0, 0, 0); __builtin_amdgcn_s_setprio(0); } while (0)
; #define PG8_WAIT_V(n) asm volatile("s_waitcnt vmcnt(" #n ")" ::: "memory")
; #define PG8_WAIT_L(n) asm volatile("s_waitcnt lgkmcnt(" #n ")" ::: "memory")
; #define PG8_BAR __builtin_amdgcn_s_barrier()
; #define PG8_SCHED __builtin_amdgcn_sched_barrier(0)
; template <class Epi, class Sched, bool ALIGN_EPI = false, bool SP2 = false>
; __device__ __forceinline__ void gemm_phase(PG8_LAS unsigned char* lds, const Gemm g, const Sched& S, const Epi& E) {
;     ...
;             PG8_WAIT_V(8); PG8_WAIT_L(0); PG8_BAR; PG8_MMA(1, 0, At, B0); PG8_MMA(1, 1, At, B1); PG8_BAR; PG8_SCHED;
;             PG8_LDB(B0, 1, 0); PG8_LDB(B1, 1, 1); PG8_SCHED; PG8_LDA(At, 1, 0); PG8_STAGE(PG8_SA(0, 1), a2 + hstep, voffA);
;             PG8_WAIT_V(8); PG8_WAIT_L(0); PG8_BAR; PG8_MMA(0, 0, At, B0); PG8_MMA(0, 1, At, B1); PG8_BAR; PG8_SCHED;
	v_mfma_f32_16x16x32_bf16 v[60:63], v[164:167], v[196:199], v[60:63]
	v_mfma_f32_16x16x32_bf16 v[56:59], v[172:175], v[196:199], v[56:59]
	v_mfma_f32_16x16x32_bf16 v[44:47], v[164:167], v[204:207], v[44:47]
	v_mfma_f32_16x16x32_bf16 v[40:43], v[172:175], v[204:207], v[40:43]
	v_mfma_f32_16x16x32_bf16 v[28:31], v[164:167], v[216:219], v[28:31]
	v_mfma_f32_16x16x32_bf16 v[24:27], v[172:175], v[216:219], v[24:27]
	v_mfma_f32_16x16x32_bf16 v[12:15], v[164:167], v[224:227], v[12:15]
	v_mfma_f32_16x16x32_bf16 v[8:11], v[172:175], v[224:227], v[8:11]
	v_mfma_f32_16x16x32_bf16 v[60:63], v[168:171], v[200:203], v[60:63]
	v_mfma_f32_16x16x32_bf16 v[56:59], v[176:179], v[200:203], v[56:59]
	v_mfma_f32_16x16x32_bf16 v[44:47], v[168:171], v[208:211], v[44:47]
	v_mfma_f32_16x16x32_bf16 v[40:43], v[176:179], v[208:211], v[40:43]
	v_mfma_f32_16x16x32_bf16 v[28:31], v[168:171], v[220:223], v[28:31]
	v_mfma_f32_16x16x32_bf16 v[24:27], v[176:179], v[220:223], v[24:27]
	v_mfma_f32_16x16x32_bf16 v[12:15], v[168:171], v[228:231], v[12:15]
	v_mfma_f32_16x16x32_bf16 v[8:11], v[176:179], v[228:231], v[8:11]
	v_mfma_f32_16x16x32_bf16 v[52:55], v[180:183], v[196:199], v[52:55]
	v_mfma_f32_16x16x32_bf16 v[48:51], v[188:191], v[196:199], v[48:51]
	v_mfma_f32_16x16x32_bf16 v[36:39], v[180:183], v[204:207], v[36:39]
	v_mfma_f32_16x16x32_bf16 v[32:35], v[188:191], v[204:207], v[32:35]
	v_mfma_f32_16x16x32_bf16 v[20:23], v[180:183], v[216:219], v[20:23]
	v_mfma_f32_16x16x32_bf16 v[16:19], v[188:191], v[216:219], v[16:19]
	v_mfma_f32_16x16x32_bf16 v[4:7], v[180:183], v[224:227], v[4:7]
	v_mfma_f32_16x16x32_bf16 v[0:3], v[188:191], v[224:227], v[0:3]
	v_mfma_f32_16x16x32_bf16 v[52:55], v[184:187], v[200:203], v[52:55]
	v_mfma_f32_16x16x32_bf16 v[48:51], v[192:195], v[200:203], v[48:51]
	v_mfma_f32_16x16x32_bf16 v[36:39], v[184:187], v[208:211], v[36:39]
	v_mfma_f32_16x16x32_bf16 v[32:35], v[192:195], v[208:211], v[32:35]
	v_mfma_f32_16x16x32_bf16 v[20:23], v[184:187], v[220:223], v[20:23]
	v_mfma_f32_16x16x32_bf16 v[16:19], v[192:195], v[220:223], v[16:19]
	v_mfma_f32_16x16x32_bf16 v[4:7], v[184:187], v[228:231], v[4:7]
	v_mfma_f32_16x16x32_bf16 v[0:3], v[192:195], v[228:231], v[0:3]
	s_barrier
	ds_read_b128 v[164:167], v255 offset:16384
	ds_read_b128 v[168:171], v255 offset:17408
	ds_read_b128 v[172:175], v255 offset:18432
	ds_read_b128 v[176:179], v255 offset:19456
	ds_read_b128 v[180:183], v255 offset:32768
	ds_read_b128 v[184:187], v255 offset:33792
	ds_read_b128 v[188:191], v255 offset:34816
	ds_read_b128 v[192:195], v255 offset:35840
	v_lshl_add_u64 v[212:213], v[212:213], 0, s[14:15]
	s_mov_b32 m0, s44
	v_lshl_add_u64 v[242:243], v[212:213], 0, v[140:141]
	ds_read_b128 v[196:199], v163 offset:32768
	ds_read_b128 v[200:203], v163 offset:33792
	ds_read_b128 v[204:207], v163 offset:34816
	ds_read_b128 v[208:211], v163 offset:35840
	ds_read_b128 v[216:219], v163 offset:36864
	ds_read_b128 v[220:223], v163 offset:37888
	ds_read_b128 v[224:227], v163 offset:38912
	ds_read_b128 v[228:231], v163 offset:39936
	global_load_lds_dwordx4 v[242:243], off
	s_mov_b32 m0, s45
	v_lshl_add_u64 v[212:213], v[212:213], 0, v[136:137]
	global_load_lds_dwordx4 v[212:213], off
	s_waitcnt vmcnt(8) lgkmcnt(0)
	s_barrier
	v_mfma_f32_16x16x32_bf16 v[124:127], v[164:167], v[196:199], v[124:127]
	v_mfma_f32_16x16x32_bf16 v[120:123], v[172:175], v[196:199], v[120:123]
	v_mfma_f32_16x16x32_bf16 v[108:111], v[164:167], v[204:207], v[108:111]
	v_mfma_f32_16x16x32_bf16 v[104:107], v[172:175], v[204:207], v[104:107]
	v_mfma_f32_16x16x32_bf16 v[92:95], v[164:167], v[216:219], v[92:95]
	v_mfma_f32_16x16x32_bf16 v[88:91], v[172:175], v[216:219], v[88:91]
	v_mfma_f32_16x16x32_bf16 v[76:79], v[164:167], v[224:227], v[76:79]
	v_mfma_f32_16x16x32_bf16 v[72:75], v[172:175], v[224:227], v[72:75]
	v_mfma_f32_16x16x32_bf16 v[124:127], v[168:171], v[200:203], v[124:127]
	v_mfma_f32_16x16x32_bf16 v[120:123], v[176:179], v[200:203], v[120:123]
	v_mfma_f32_16x16x32_bf16 v[108:111], v[168:171], v[208:211], v[108:111]
	v_mfma_f32_16x16x32_bf16 v[104:107], v[176:179], v[208:211], v[104:107]
	v_mfma_f32_16x16x32_bf16 v[92:95], v[168:171], v[220:223], v[92:95]
	v_mfma_f32_16x16x32_bf16 v[88:91], v[176:179], v[220:223], v[88:91]
	v_mfma_f32_16x16x32_bf16 v[76:79], v[168:171], v[228:231], v[76:79]
	v_mfma_f32_16x16x32_bf16 v[72:75], v[176:179], v[228:231], v[72:75]
	v_mfma_f32_16x16x32_bf16 v[116:119], v[180:183], v[196:199], v[116:119]
	v_mfma_f32_16x16x32_bf16 v[112:115], v[188:191], v[196:199], v[112:115]
	v_mfma_f32_16x16x32_bf16 v[100:103], v[180:183], v[204:207], v[100:103]
	v_mfma_f32_16x16x32_bf16 v[96:99], v[188:191], v[204:207], v[96:99]
	v_mfma_f32_16x16x32_bf16 v[84:87], v[180:183], v[216:219], v[84:87]
	v_mfma_f32_16x16x32_bf16 v[80:83], v[188:191], v[216:219], v[80:83]
	v_mfma_f32_16x16x32_bf16 v[68:71], v[180:183], v[224:227], v[68:71]
	v_mfma_f32_16x16x32_bf16 v[64:67], v[188:191], v[224:227], v[64:67]
	v_mfma_f32_16x16x32_bf16 v[116:119], v[184:187], v[200:203], v[116:119]
	v_mfma_f32_16x16x32_bf16 v[112:115], v[192:195], v[200:203], v[112:115]
	v_mfma_f32_16x16x32_bf16 v[100:103], v[184:187], v[208:211], v[100:103]
	v_mfma_f32_16x16x32_bf16 v[96:99], v[192:195], v[208:211], v[96:99]
	v_mfma_f32_16x16x32_bf16 v[84:87], v[184:187], v[220:223], v[84:87]
	v_mfma_f32_16x16x32_bf16 v[80:83], v[192:195], v[220:223], v[80:83]
	v_mfma_f32_16x16x32_bf16 v[68:71], v[184:187], v[228:231], v[68:71]
	v_mfma_f32_16x16x32_bf16 v[64:67], v[192:195], v[228:231], v[64:67]
	s_barrier
; #define PG8_STAGE(bufoff, gbase, voff) do { _Pragma("unroll") for (int _i = 0; _i < 2; ++_i) \
;         __builtin_amdgcn_global_load_lds((const unsigned*)((const char*)(gbase) + (voff)[_i]), (PG8_LAS unsigned*)(lds + (bufoff) + ldsw + _i * 8192), 16, 0, 0); } while (0)
; #define PG8_LDA(dst, b, h) do { _Pragma("unroll") for (int m = 0; m < 4; ++m) _Pragma("unroll") for (int k = 0; k < 2; ++k) dst[m][k] = *(const PG8_LAS bf16x8*)(lds + PG8_SA(b, h) + aoff + m * 2048 + k * 1024); } while (0)
; #define PG8_MMA(ai, bj, At, Bt) do { __builtin_amdgcn_s_setprio(1); _Pragma("unroll") for (int m = 0; m < 4; ++m) _Pragma("unroll") for (int n = 0; n < 2; ++n) _Pragma("unroll") for (int k = 0; k < 2; ++k) \
;         acc[ai][bj][m][n] = __builtin_amdgcn_mfma_f32_16x16x32_bf16(Bt[n][k], At[m][k], acc[ai][bj][m][n], 0, 0, 0); __builtin_amdgcn_s_setprio(0); } while (0)
; #define PG8_WAIT_V(n) asm volatile("s_waitcnt vmcnt(" #n ")" ::: "memory")
; #define PG8_WAIT_L(n) asm volatile("s_waitcnt lgkmcnt(" #n ")" ::: "memory")
; #define PG8_BAR __builtin_amdgcn_s_barrier()
; #define PG8_SCHED __builtin_amdgcn_sched_barrier(0)
; template <class Epi, class Sched, bool ALIGN_EPI = false, bool SP2 = false>
; __device__ __forceinline__ void gemm_phase(PG8_LAS unsigned char* lds, const Gemm g, const Sched& S, const Epi& E) {
;     ...
;         for (int t = 0; t < nt; t += 2) {
;     ...
;             PG8_LDA(At, 1, 1); PG8_STAGE(PG8_SB(1, 0), b3, voffB); PG8_STAGE(PG8_SB(1, 1), b3 + hstep, voffB); PG8_STAGE(PG8_SA(1, 0), a3, voffA);
;             PG8_WAIT_V(8); PG8_WAIT_L(0); PG8_BAR; PG8_MMA(1, 0, At, B0); PG8_MMA(1, 1, At, B1); PG8_BAR; PG8_SCHED;
	s_add_i32 m0, s59, 0xffffff80
	ds_read_b128 v[196:199], v163 offset:49152
	ds_read_b128 v[200:203], v163 offset:50176
	ds_read_b128 v[204:207], v163 offset:51200
	global_load_lds_dwordx4 v[232:233], off offset:128
	s_add_i32 m0, s60, 0xffffff80
	ds_read_b128 v[228:231], v163 offset:56320
	global_load_lds_dwordx4 v[234:235], off offset:128
	s_add_i32 m0, s61, 0xffffff80
	ds_read_b128 v[224:227], v163 offset:55296
	global_load_lds_dwordx4 v[236:237], off offset:128
	s_add_i32 m0, s62, 0xffffff80
	ds_read_b128 v[220:223], v163 offset:54272
	global_load_lds_dwordx4 v[214:215], off offset:128
	s_add_i32 m0, s46, 0xffffff80
	ds_read_b128 v[216:219], v163 offset:53248
	global_load_lds_dwordx4 v[238:239], off offset:128
	s_add_i32 m0, s47, 0xffffff80
	ds_read_b128 v[208:211], v163 offset:52224
	global_load_lds_dwordx4 v[240:241], off offset:128
	s_waitcnt vmcnt(8) lgkmcnt(0)
	s_barrier
	v_mfma_f32_16x16x32_bf16 v[60:63], v[164:167], v[196:199], v[60:63]
	v_mfma_f32_16x16x32_bf16 v[56:59], v[172:175], v[196:199], v[56:59]
	v_mfma_f32_16x16x32_bf16 v[44:47], v[164:167], v[204:207], v[44:47]
	v_mfma_f32_16x16x32_bf16 v[40:43], v[172:175], v[204:207], v[40:43]
	v_mfma_f32_16x16x32_bf16 v[28:31], v[164:167], v[216:219], v[28:31]
	v_mfma_f32_16x16x32_bf16 v[24:27], v[172:175], v[216:219], v[24:27]
	v_mfma_f32_16x16x32_bf16 v[12:15], v[164:167], v[224:227], v[12:15]
	v_mfma_f32_16x16x32_bf16 v[8:11], v[172:175], v[224:227], v[8:11]
	v_mfma_f32_16x16x32_bf16 v[60:63], v[168:171], v[200:203], v[60:63]
	v_mfma_f32_16x16x32_bf16 v[56:59], v[176:179], v[200:203], v[56:59]
	v_mfma_f32_16x16x32_bf16 v[44:47], v[168:171], v[208:211], v[44:47]
	v_mfma_f32_16x16x32_bf16 v[40:43], v[176:179], v[208:211], v[40:43]
	v_mfma_f32_16x16x32_bf16 v[28:31], v[168:171], v[220:223], v[28:31]
	v_mfma_f32_16x16x32_bf16 v[24:27], v[176:179], v[220:223], v[24:27]
	v_mfma_f32_16x16x32_bf16 v[12:15], v[168:171], v[228:231], v[12:15]
	v_mfma_f32_16x16x32_bf16 v[8:11], v[176:179], v[228:231], v[8:11]
	v_mfma_f32_16x16x32_bf16 v[52:55], v[180:183], v[196:199], v[52:55]
	v_mfma_f32_16x16x32_bf16 v[48:51], v[188:191], v[196:199], v[48:51]
	v_mfma_f32_16x16x32_bf16 v[36:39], v[180:183], v[204:207], v[36:39]
	v_mfma_f32_16x16x32_bf16 v[32:35], v[188:191], v[204:207], v[32:35]
	v_mfma_f32_16x16x32_bf16 v[20:23], v[180:183], v[216:219], v[20:23]
	v_mfma_f32_16x16x32_bf16 v[16:19], v[188:191], v[216:219], v[16:19]
	v_mfma_f32_16x16x32_bf16 v[4:7], v[180:183], v[224:227], v[4:7]
	v_mfma_f32_16x16x32_bf16 v[0:3], v[188:191], v[224:227], v[0:3]
	v_mfma_f32_16x16x32_bf16 v[52:55], v[184:187], v[200:203], v[52:55]
	v_mfma_f32_16x16x32_bf16 v[48:51], v[192:195], v[200:203], v[48:51]
	v_mfma_f32_16x16x32_bf16 v[36:39], v[184:187], v[208:211], v[36:39]
	v_mfma_f32_16x16x32_bf16 v[32:35], v[192:195], v[208:211], v[32:35]
	v_mfma_f32_16x16x32_bf16 v[20:23], v[184:187], v[220:223], v[20:23]
	v_mfma_f32_16x16x32_bf16 v[16:19], v[192:195], v[220:223], v[16:19]
	v_mfma_f32_16x16x32_bf16 v[4:7], v[184:187], v[228:231], v[4:7]
	v_mfma_f32_16x16x32_bf16 v[0:3], v[192:195], v[228:231], v[0:3]
	s_barrier
	v_lshl_add_u64 v[154:155], v[154:155], 0, s[28:29]
	s_cmp_ge_i32 s10, s48
	v_lshl_add_u64 v[158:159], v[158:159], 0, s[28:29]
	s_cbranch_scc0 .LBB0_1924

; #define PG8_STAGE(bufoff, gbase, voff) do { _Pragma("unroll") for (int _i = 0; _i < 2; ++_i) \
;         __builtin_amdgcn_global_load_lds((const unsigned*)((const char*)(gbase) + (voff)[_i]), (PG8_LAS unsigned*)(lds + (bufoff) + ldsw + _i * 8192), 16, 0, 0); } while (0)
; #define PG8_LDA(dst, b, h) do { _Pragma("unroll") for (int m = 0; m < 4; ++m) _Pragma("unroll") for (int k = 0; k < 2; ++k) dst[m][k] = *(const PG8_LAS bf16x8*)(lds + PG8_SA(b, h) + aoff + m * 2048 + k * 1024); } while (0)
; #define PG8_LDB(dst, b, h) do { _Pragma("unroll") for (int n = 0; n < 2; ++n) _Pragma("unroll") for (int k = 0; k < 2; ++k) dst[n][k] = *(const PG8_LAS bf16x8*)(lds + PG8_SB(b, h) + boff + n * 2048 + k * 1024); } while (0)
; #define PG8_MMA(ai, bj, At, Bt) do { __builtin_amdgcn_s_setprio(1); _Pragma("unroll") for (int m = 0; m < 4; ++m) _Pragma("unroll") for (int n = 0; n < 2; ++n) _Pragma("unroll") for (int k = 0; k < 2; ++k) \
;         acc[ai][bj][m][n] = __builtin_amdgcn_mfma_f32_16x16x32_bf16(Bt[n][k], At[m][k], acc[ai][bj][m][n], 0, 0, 0); __builtin_amdgcn_s_setprio(0); } while (0)
; #define PG8_WAIT_V(n) asm volatile("s_waitcnt vmcnt(" #n ")" ::: "memory")
; #define PG8_WAIT_L(n) asm volatile("s_waitcnt lgkmcnt(" #n ")" ::: "memory")
; #define PG8_BAR __builtin_amdgcn_s_barrier()
; template <class Epi, class Sched, bool ALIGN_EPI = false, bool SP2 = false>
; __device__ __forceinline__ void gemm_phase(PG8_LAS unsigned char* lds, const Gemm g, const Sched& S, const Epi& E) {
;     ...
;             const char* a1 = cA + (size_t)(t + 1) * kstep;
;             const char* a2 = last ? nA : cA + (size_t)(t + 2) * kstep; const char* b2 = last ? nB : cB + (size_t)(t + 2) * kstep;
;             const char* a3 = a2 + kstep; const char* b3 = b2 + kstep;
;             if (last && has_next) S.a_ready(nxt);
;             if constexpr (SP2) {
;             PG8_LDB(B0, 0, 0); PG8_LDB(B1, 0, 1); PG8_SCHED; PG8_LDA(At, 0, 0); PG8_STAGE(PG8_SA(1, 1), a1 + hstep, voffA);
;             PG8_WAIT_V(8); PG8_WAIT_L(0); PG8_BAR; PG8_MMA(0, 0, At, B0); PG8_MMA(0, 1, At, B1); PG8_BAR; PG8_SCHED;
;             PG8_LDA(At, 0, 1); PG8_STAGE(PG8_SB(0, 0), b2, voffB); PG8_STAGE(PG8_SB(0, 1), b2 + hstep, voffB); PG8_STAGE(PG8_SA(0, 0), a2, voffA);
;             PG8_WAIT_V(8); PG8_WAIT_L(0); PG8_BAR; PG8_MMA(1, 0, At, B0); PG8_MMA(1, 1, At, B1); PG8_BAR; PG8_SCHED;
.LBB0_1947:
	v_add_u32_e32 v255, s53, v216
	ds_read_b128 v[138:141], v255
	ds_read_b128 v[142:145], v255 offset:1024
	ds_read_b128 v[146:149], v255 offset:2048
	ds_read_b128 v[178:181], v255 offset:3072
	ds_read_b128 v[182:185], v255 offset:16384
	ds_read_b128 v[186:189], v255 offset:17408
	ds_read_b128 v[190:193], v255 offset:18432
	ds_read_b128 v[194:197], v255 offset:19456
	s_cmp_eq_u32 s47, s10
	v_lshl_add_u64 v[198:199], v[136:137], 0, s[20:21]
	s_cselect_b64 vcc, -1, 0
	s_add_i32 s10, s10, 2
	v_cndmask_b32_e32 v215, v199, v175, vcc
	v_cndmask_b32_e32 v214, v198, v174, vcc
	v_cndmask_b32_e32 v237, v135, v177, vcc
	v_cndmask_b32_e32 v236, v134, v176, vcc
	v_lshl_add_u64 v[238:239], v[136:137], 0, v[168:169]
	s_add_i32 m0, s34, 0xc000
	ds_read_b128 v[198:201], v218
	ds_read_b128 v[202:205], v218 offset:1024
	ds_read_b128 v[206:209], v218 offset:2048
	ds_read_b128 v[210:213], v218 offset:3072
	ds_read_b128 v[220:223], v218 offset:4096
	ds_read_b128 v[224:227], v218 offset:5120
	ds_read_b128 v[228:231], v218 offset:6144
	ds_read_b128 v[232:235], v218 offset:7168
	global_load_lds_dwordx4 v[238:239], off
	s_add_i32 m0, s34, 0xe000
	v_lshl_add_u64 v[238:239], v[136:137], 0, v[166:167]
	global_load_lds_dwordx4 v[238:239], off
	s_waitcnt vmcnt(8) lgkmcnt(0)
	s_barrier
	v_mfma_f32_16x16x32_bf16 v[130:133], v[138:141], v[198:201], v[130:133]
	v_mfma_f32_16x16x32_bf16 v[126:129], v[146:149], v[198:201], v[126:129]
	v_mfma_f32_16x16x32_bf16 v[114:117], v[138:141], v[206:209], v[114:117]
	v_mfma_f32_16x16x32_bf16 v[110:113], v[146:149], v[206:209], v[110:113]
	v_mfma_f32_16x16x32_bf16 v[98:101], v[138:141], v[220:223], v[98:101]
	v_mfma_f32_16x16x32_bf16 v[94:97], v[146:149], v[220:223], v[94:97]
	v_mfma_f32_16x16x32_bf16 v[82:85], v[138:141], v[228:231], v[82:85]
	v_mfma_f32_16x16x32_bf16 v[78:81], v[146:149], v[228:231], v[78:81]
	v_mfma_f32_16x16x32_bf16 v[130:133], v[142:145], v[202:205], v[130:133]
	v_mfma_f32_16x16x32_bf16 v[126:129], v[178:181], v[202:205], v[126:129]
	v_mfma_f32_16x16x32_bf16 v[114:117], v[142:145], v[210:213], v[114:117]
	v_mfma_f32_16x16x32_bf16 v[110:113], v[178:181], v[210:213], v[110:113]
	v_mfma_f32_16x16x32_bf16 v[98:101], v[142:145], v[224:227], v[98:101]
	v_mfma_f32_16x16x32_bf16 v[94:97], v[178:181], v[224:227], v[94:97]
	v_mfma_f32_16x16x32_bf16 v[82:85], v[142:145], v[232:235], v[82:85]
	v_mfma_f32_16x16x32_bf16 v[78:81], v[178:181], v[232:235], v[78:81]
	v_mfma_f32_16x16x32_bf16 v[122:125], v[182:185], v[198:201], v[122:125]
	v_mfma_f32_16x16x32_bf16 v[118:121], v[190:193], v[198:201], v[118:121]
	v_mfma_f32_16x16x32_bf16 v[106:109], v[182:185], v[206:209], v[106:109]
	v_mfma_f32_16x16x32_bf16 v[102:105], v[190:193], v[206:209], v[102:105]
	v_mfma_f32_16x16x32_bf16 v[90:93], v[182:185], v[220:223], v[90:93]
	v_mfma_f32_16x16x32_bf16 v[86:89], v[190:193], v[220:223], v[86:89]
	v_mfma_f32_16x16x32_bf16 v[74:77], v[182:185], v[228:231], v[74:77]
	v_mfma_f32_16x16x32_bf16 v[70:73], v[190:193], v[228:231], v[70:73]
	v_mfma_f32_16x16x32_bf16 v[122:125], v[186:189], v[202:205], v[122:125]
	v_mfma_f32_16x16x32_bf16 v[118:121], v[194:197], v[202:205], v[118:121]
	v_mfma_f32_16x16x32_bf16 v[106:109], v[186:189], v[210:213], v[106:109]
	v_mfma_f32_16x16x32_bf16 v[102:105], v[194:197], v[210:213], v[102:105]
	v_mfma_f32_16x16x32_bf16 v[90:93], v[186:189], v[224:227], v[90:93]
	v_mfma_f32_16x16x32_bf16 v[86:89], v[194:197], v[224:227], v[86:89]
	v_mfma_f32_16x16x32_bf16 v[74:77], v[186:189], v[232:235], v[74:77]
	v_mfma_f32_16x16x32_bf16 v[70:73], v[194:197], v[232:235], v[70:73]
	s_barrier
	s_add_i32 s11, s53, s29
	v_lshl_add_u64 v[238:239], v[236:237], 0, v[158:159]
	s_mov_b32 m0, s11
	ds_read_b128 v[198:201], v218 offset:16384
	ds_read_b128 v[202:205], v218 offset:17408
	ds_read_b128 v[206:209], v218 offset:18432
	ds_read_b128 v[210:213], v218 offset:19456
	ds_read_b128 v[220:223], v218 offset:20480
	ds_read_b128 v[224:227], v218 offset:21504
	ds_read_b128 v[228:231], v218 offset:22528
	ds_read_b128 v[232:235], v218 offset:23552
	global_load_lds_dwordx4 v[238:239], off
	v_lshl_add_u64 v[240:241], v[236:237], 0, v[162:163]
	s_add_i32 m0, s11, 0x2000
	v_lshl_add_u64 v[236:237], v[236:237], 0, s[12:13]
	s_add_i32 s11, s54, s29
	global_load_lds_dwordx4 v[240:241], off
	v_lshl_add_u64 v[242:243], v[236:237], 0, v[158:159]
	s_mov_b32 m0, s11
	v_lshl_add_u64 v[236:237], v[236:237], 0, v[162:163]
	global_load_lds_dwordx4 v[242:243], off
	s_add_i32 m0, s11, 0x2000
	v_lshl_add_u64 v[244:245], v[214:215], 0, v[154:155]
	global_load_lds_dwordx4 v[236:237], off
	s_mov_b32 m0, s34
	v_lshl_add_u64 v[246:247], v[214:215], 0, v[160:161]
	global_load_lds_dwordx4 v[244:245], off
	s_mov_b32 m0, s35
	s_nop 0
	global_load_lds_dwordx4 v[246:247], off
	s_waitcnt vmcnt(8) lgkmcnt(0)
	s_barrier
; #define PG8_STAGE(bufoff, gbase, voff) do { _Pragma("unroll") for (int _i = 0; _i < 2; ++_i) \
;         __builtin_amdgcn_global_load_lds((const unsigned*)((const char*)(gbase) + (voff)[_i]), (PG8_LAS unsigned*)(lds + (bufoff) + ldsw + _i * 8192), 16, 0, 0); } while (0)
; #define PG8_LDA(dst, b, h) do { _Pragma("unroll") for (int m = 0; m < 4; ++m) _Pragma("unroll") for (int k = 0; k < 2; ++k) dst[m][k] = *(const PG8_LAS bf16x8*)(lds + PG8_SA(b, h) + aoff + m * 2048 + k * 1024); } while (0)
; #define PG8_LDB(dst, b, h) do { _Pragma("unroll") for (int n = 0; n < 2; ++n) _Pragma("unroll") for (int k = 0; k < 2; ++k) dst[n][k] = *(const PG8_LAS bf16x8*)(lds + PG8_SB(b, h) + boff + n * 2048 + k * 1024); } while (0)
; #define PG8_MMA(ai, bj, At, Bt) do { __builtin_amdgcn_s_setprio(1); _Pragma("unroll") for (int m = 0; m < 4; ++m) _Pragma("unroll") for (int n = 0; n < 2; ++n) _Pragma("unroll") for (int k = 0; k < 2; ++k) \
;         acc[ai][bj][m][n] = __builtin_amdgcn_mfma_f32_16x16x32_bf16(Bt[n][k], At[m][k], acc[ai][bj][m][n], 0, 0, 0); __builtin_amdgcn_s_setprio(0); } while (0)
; #define PG8_WAIT_V(n) asm volatile("s_waitcnt vmcnt(" #n ")" ::: "memory")
; #define PG8_WAIT_L(n) asm volatile("s_waitcnt lgkmcnt(" #n ")" ::: "memory")
; #define PG8_BAR __builtin_amdgcn_s_barrier()
; #define PG8_SCHED __builtin_amdgcn_sched_barrier(0)
; template <class Epi, class Sched, bool ALIGN_EPI = false, bool SP2 = false>
; __device__ __forceinline__ void gemm_phase(PG8_LAS unsigned char* lds, const Gemm g, const Sched& S, const Epi& E) {
;     ...
;             PG8_WAIT_V(8); PG8_WAIT_L(0); PG8_BAR; PG8_MMA(1, 0, At, B0); PG8_MMA(1, 1, At, B1); PG8_BAR; PG8_SCHED;
;             PG8_LDB(B0, 1, 0); PG8_LDB(B1, 1, 1); PG8_SCHED; PG8_LDA(At, 1, 0); PG8_STAGE(PG8_SA(0, 1), a2 + hstep, voffA);
;             PG8_WAIT_V(8); PG8_WAIT_L(0); PG8_BAR; PG8_MMA(0, 0, At, B0); PG8_MMA(0, 1, At, B1); PG8_BAR; PG8_SCHED;
	v_mfma_f32_16x16x32_bf16 v[66:69], v[138:141], v[198:201], v[66:69]
	v_mfma_f32_16x16x32_bf16 v[62:65], v[146:149], v[198:201], v[62:65]
	v_mfma_f32_16x16x32_bf16 v[50:53], v[138:141], v[206:209], v[50:53]
	v_mfma_f32_16x16x32_bf16 v[46:49], v[146:149], v[206:209], v[46:49]
	v_mfma_f32_16x16x32_bf16 v[34:37], v[138:141], v[220:223], v[34:37]
	v_mfma_f32_16x16x32_bf16 v[30:33], v[146:149], v[220:223], v[30:33]
	v_mfma_f32_16x16x32_bf16 v[18:21], v[138:141], v[228:231], v[18:21]
	v_mfma_f32_16x16x32_bf16 v[14:17], v[146:149], v[228:231], v[14:17]
	v_mfma_f32_16x16x32_bf16 v[66:69], v[142:145], v[202:205], v[66:69]
	v_mfma_f32_16x16x32_bf16 v[62:65], v[178:181], v[202:205], v[62:65]
	v_mfma_f32_16x16x32_bf16 v[50:53], v[142:145], v[210:213], v[50:53]
	v_mfma_f32_16x16x32_bf16 v[46:49], v[178:181], v[210:213], v[46:49]
	v_mfma_f32_16x16x32_bf16 v[34:37], v[142:145], v[224:227], v[34:37]
	v_mfma_f32_16x16x32_bf16 v[30:33], v[178:181], v[224:227], v[30:33]
	v_mfma_f32_16x16x32_bf16 v[18:21], v[142:145], v[232:235], v[18:21]
	v_mfma_f32_16x16x32_bf16 v[14:17], v[178:181], v[232:235], v[14:17]
	v_mfma_f32_16x16x32_bf16 v[58:61], v[182:185], v[198:201], v[58:61]
	v_mfma_f32_16x16x32_bf16 v[54:57], v[190:193], v[198:201], v[54:57]
	v_mfma_f32_16x16x32_bf16 v[42:45], v[182:185], v[206:209], v[42:45]
	v_mfma_f32_16x16x32_bf16 v[38:41], v[190:193], v[206:209], v[38:41]
	v_mfma_f32_16x16x32_bf16 v[26:29], v[182:185], v[220:223], v[26:29]
	v_mfma_f32_16x16x32_bf16 v[22:25], v[190:193], v[220:223], v[22:25]
	v_mfma_f32_16x16x32_bf16 v[10:13], v[182:185], v[228:231], v[10:13]
	v_mfma_f32_16x16x32_bf16 v[6:9], v[190:193], v[228:231], v[6:9]
	v_mfma_f32_16x16x32_bf16 v[58:61], v[186:189], v[202:205], v[58:61]
	v_mfma_f32_16x16x32_bf16 v[54:57], v[194:197], v[202:205], v[54:57]
	v_mfma_f32_16x16x32_bf16 v[42:45], v[186:189], v[210:213], v[42:45]
	v_mfma_f32_16x16x32_bf16 v[38:41], v[194:197], v[210:213], v[38:41]
	v_mfma_f32_16x16x32_bf16 v[26:29], v[186:189], v[224:227], v[26:29]
	v_mfma_f32_16x16x32_bf16 v[22:25], v[194:197], v[224:227], v[22:25]
	v_mfma_f32_16x16x32_bf16 v[10:13], v[186:189], v[232:235], v[10:13]
	v_mfma_f32_16x16x32_bf16 v[6:9], v[194:197], v[232:235], v[6:9]
	s_barrier
	s_add_i32 s11, 0, 0x18000
	s_add_i32 s31, 0, 0x1c000
	ds_read_b128 v[138:141], v255 offset:32768
	ds_read_b128 v[142:145], v255 offset:33792
	ds_read_b128 v[146:149], v255 offset:34816
	ds_read_b128 v[178:181], v255 offset:35840
	ds_read_b128 v[182:185], v255 offset:49152
	ds_read_b128 v[186:189], v255 offset:50176
	ds_read_b128 v[190:193], v255 offset:51200
	ds_read_b128 v[194:197], v255 offset:52224
	v_lshl_add_u64 v[214:215], v[214:215], 0, s[12:13]
	s_mov_b32 m0, s36
	v_lshl_add_u64 v[248:249], v[214:215], 0, v[154:155]
	ds_read_b128 v[198:201], v218 offset:32768
	ds_read_b128 v[202:205], v218 offset:33792
	ds_read_b128 v[206:209], v218 offset:34816
	ds_read_b128 v[210:213], v218 offset:35840
	ds_read_b128 v[220:223], v218 offset:36864
	ds_read_b128 v[224:227], v218 offset:37888
	ds_read_b128 v[228:231], v218 offset:38912
	ds_read_b128 v[232:235], v218 offset:39936
	global_load_lds_dwordx4 v[248:249], off
	s_mov_b32 m0, s37
	v_lshl_add_u64 v[214:215], v[214:215], 0, v[160:161]
	global_load_lds_dwordx4 v[214:215], off
	s_waitcnt vmcnt(8) lgkmcnt(0)
	s_barrier
	v_mfma_f32_16x16x32_bf16 v[130:133], v[138:141], v[198:201], v[130:133]
	v_mfma_f32_16x16x32_bf16 v[126:129], v[146:149], v[198:201], v[126:129]
	v_mfma_f32_16x16x32_bf16 v[114:117], v[138:141], v[206:209], v[114:117]
	v_mfma_f32_16x16x32_bf16 v[110:113], v[146:149], v[206:209], v[110:113]
	v_mfma_f32_16x16x32_bf16 v[98:101], v[138:141], v[220:223], v[98:101]
	v_mfma_f32_16x16x32_bf16 v[94:97], v[146:149], v[220:223], v[94:97]
	v_mfma_f32_16x16x32_bf16 v[82:85], v[138:141], v[228:231], v[82:85]
	v_mfma_f32_16x16x32_bf16 v[78:81], v[146:149], v[228:231], v[78:81]
	v_mfma_f32_16x16x32_bf16 v[130:133], v[142:145], v[202:205], v[130:133]
	v_mfma_f32_16x16x32_bf16 v[126:129], v[178:181], v[202:205], v[126:129]
	v_mfma_f32_16x16x32_bf16 v[114:117], v[142:145], v[210:213], v[114:117]
	v_mfma_f32_16x16x32_bf16 v[110:113], v[178:181], v[210:213], v[110:113]
	v_mfma_f32_16x16x32_bf16 v[98:101], v[142:145], v[224:227], v[98:101]
	v_mfma_f32_16x16x32_bf16 v[94:97], v[178:181], v[224:227], v[94:97]
	v_mfma_f32_16x16x32_bf16 v[82:85], v[142:145], v[232:235], v[82:85]
	v_mfma_f32_16x16x32_bf16 v[78:81], v[178:181], v[232:235], v[78:81]
	v_mfma_f32_16x16x32_bf16 v[122:125], v[182:185], v[198:201], v[122:125]
	v_mfma_f32_16x16x32_bf16 v[118:121], v[190:193], v[198:201], v[118:121]
	v_mfma_f32_16x16x32_bf16 v[106:109], v[182:185], v[206:209], v[106:109]
	v_mfma_f32_16x16x32_bf16 v[102:105], v[190:193], v[206:209], v[102:105]
	v_mfma_f32_16x16x32_bf16 v[90:93], v[182:185], v[220:223], v[90:93]
	v_mfma_f32_16x16x32_bf16 v[86:89], v[190:193], v[220:223], v[86:89]
	v_mfma_f32_16x16x32_bf16 v[74:77], v[182:185], v[228:231], v[74:77]
	v_mfma_f32_16x16x32_bf16 v[70:73], v[190:193], v[228:231], v[70:73]
	v_mfma_f32_16x16x32_bf16 v[122:125], v[186:189], v[202:205], v[122:125]
	v_mfma_f32_16x16x32_bf16 v[118:121], v[194:197], v[202:205], v[118:121]
	v_mfma_f32_16x16x32_bf16 v[106:109], v[186:189], v[210:213], v[106:109]
	v_mfma_f32_16x16x32_bf16 v[102:105], v[194:197], v[210:213], v[102:105]
	v_mfma_f32_16x16x32_bf16 v[90:93], v[186:189], v[224:227], v[90:93]
	v_mfma_f32_16x16x32_bf16 v[86:89], v[194:197], v[224:227], v[86:89]
	v_mfma_f32_16x16x32_bf16 v[74:77], v[186:189], v[232:235], v[74:77]
	v_mfma_f32_16x16x32_bf16 v[70:73], v[194:197], v[232:235], v[70:73]
	s_barrier
; #define PG8_STAGE(bufoff, gbase, voff) do { _Pragma("unroll") for (int _i = 0; _i < 2; ++_i) \
;         __builtin_amdgcn_global_load_lds((const unsigned*)((const char*)(gbase) + (voff)[_i]), (PG8_LAS unsigned*)(lds + (bufoff) + ldsw + _i * 8192), 16, 0, 0); } while (0)
; #define PG8_LDA(dst, b, h) do { _Pragma("unroll") for (int m = 0; m < 4; ++m) _Pragma("unroll") for (int k = 0; k < 2; ++k) dst[m][k] = *(const PG8_LAS bf16x8*)(lds + PG8_SA(b, h) + aoff + m * 2048 + k * 1024); } while (0)
; #define PG8_MMA(ai, bj, At, Bt) do { __builtin_amdgcn_s_setprio(1); _Pragma("unroll") for (int m = 0; m < 4; ++m) _Pragma("unroll") for (int n = 0; n < 2; ++n) _Pragma("unroll") for (int k = 0; k < 2; ++k) \
;         acc[ai][bj][m][n] = __builtin_amdgcn_mfma_f32_16x16x32_bf16(Bt[n][k], At[m][k], acc[ai][bj][m][n], 0, 0, 0); __builtin_amdgcn_s_setprio(0); } while (0)
; #define PG8_WAIT_V(n) asm volatile("s_waitcnt vmcnt(" #n ")" ::: "memory")
; #define PG8_WAIT_L(n) asm volatile("s_waitcnt lgkmcnt(" #n ")" ::: "memory")
; #define PG8_BAR __builtin_amdgcn_s_barrier()
; #define PG8_SCHED __builtin_amdgcn_sched_barrier(0)
; template <class Epi, class Sched, bool ALIGN_EPI = false, bool SP2 = false>
; __device__ __forceinline__ void gemm_phase(PG8_LAS unsigned char* lds, const Gemm g, const Sched& S, const Epi& E) {
;     ...
;         for (int t = 0; t < nt; t += 2) {
;     ...
;             PG8_LDA(At, 1, 1); PG8_STAGE(PG8_SB(1, 0), b3, voffB); PG8_STAGE(PG8_SB(1, 1), b3 + hstep, voffB); PG8_STAGE(PG8_SA(1, 0), a3, voffA);
;             PG8_WAIT_V(8); PG8_WAIT_L(0); PG8_BAR; PG8_MMA(1, 0, At, B0); PG8_MMA(1, 1, At, B1); PG8_BAR; PG8_SCHED;
	s_add_i32 s11, s11, s29
	s_add_i32 m0, s11, 0xffffff80
	ds_read_b128 v[198:201], v218 offset:49152
	ds_read_b128 v[202:205], v218 offset:50176
	ds_read_b128 v[206:209], v218 offset:51200
	ds_read_b128 v[210:213], v218 offset:52224
	global_load_lds_dwordx4 v[238:239], off offset:128
	s_add_i32 m0, s11, 0x1f80
	s_add_i32 s11, s31, s29
	global_load_lds_dwordx4 v[240:241], off offset:128
	s_add_i32 m0, s11, 0xffffff80
	ds_read_b128 v[232:235], v218 offset:56320
	global_load_lds_dwordx4 v[242:243], off offset:128
	s_add_i32 m0, s11, 0x1f80
	ds_read_b128 v[228:231], v218 offset:55296
	global_load_lds_dwordx4 v[236:237], off offset:128
	s_add_i32 m0, s41, 0xffffff80
	ds_read_b128 v[224:227], v218 offset:54272
	global_load_lds_dwordx4 v[244:245], off offset:128
	s_add_i32 m0, s44, 0xffffff80
	ds_read_b128 v[220:223], v218 offset:53248
	global_load_lds_dwordx4 v[246:247], off offset:128
	s_waitcnt vmcnt(8) lgkmcnt(0)
	s_barrier
	v_mfma_f32_16x16x32_bf16 v[66:69], v[138:141], v[198:201], v[66:69]
	v_mfma_f32_16x16x32_bf16 v[62:65], v[146:149], v[198:201], v[62:65]
	v_mfma_f32_16x16x32_bf16 v[50:53], v[138:141], v[206:209], v[50:53]
	v_mfma_f32_16x16x32_bf16 v[46:49], v[146:149], v[206:209], v[46:49]
	v_mfma_f32_16x16x32_bf16 v[34:37], v[138:141], v[220:223], v[34:37]
	v_mfma_f32_16x16x32_bf16 v[30:33], v[146:149], v[220:223], v[30:33]
	v_mfma_f32_16x16x32_bf16 v[18:21], v[138:141], v[228:231], v[18:21]
	v_mfma_f32_16x16x32_bf16 v[14:17], v[146:149], v[228:231], v[14:17]
	v_mfma_f32_16x16x32_bf16 v[66:69], v[142:145], v[202:205], v[66:69]
	v_mfma_f32_16x16x32_bf16 v[62:65], v[178:181], v[202:205], v[62:65]
	v_mfma_f32_16x16x32_bf16 v[50:53], v[142:145], v[210:213], v[50:53]
	v_mfma_f32_16x16x32_bf16 v[46:49], v[178:181], v[210:213], v[46:49]
	v_mfma_f32_16x16x32_bf16 v[34:37], v[142:145], v[224:227], v[34:37]
	v_mfma_f32_16x16x32_bf16 v[30:33], v[178:181], v[224:227], v[30:33]
	v_mfma_f32_16x16x32_bf16 v[18:21], v[142:145], v[232:235], v[18:21]
	v_mfma_f32_16x16x32_bf16 v[14:17], v[178:181], v[232:235], v[14:17]
	v_mfma_f32_16x16x32_bf16 v[58:61], v[182:185], v[198:201], v[58:61]
	v_mfma_f32_16x16x32_bf16 v[54:57], v[190:193], v[198:201], v[54:57]
	v_mfma_f32_16x16x32_bf16 v[42:45], v[182:185], v[206:209], v[42:45]
	v_mfma_f32_16x16x32_bf16 v[38:41], v[190:193], v[206:209], v[38:41]
	v_mfma_f32_16x16x32_bf16 v[26:29], v[182:185], v[220:223], v[26:29]
	v_mfma_f32_16x16x32_bf16 v[22:25], v[190:193], v[220:223], v[22:25]
	v_mfma_f32_16x16x32_bf16 v[10:13], v[182:185], v[228:231], v[10:13]
	v_mfma_f32_16x16x32_bf16 v[6:9], v[190:193], v[228:231], v[6:9]
	v_mfma_f32_16x16x32_bf16 v[58:61], v[186:189], v[202:205], v[58:61]
	v_mfma_f32_16x16x32_bf16 v[54:57], v[194:197], v[202:205], v[54:57]
	v_mfma_f32_16x16x32_bf16 v[42:45], v[186:189], v[210:213], v[42:45]
	v_mfma_f32_16x16x32_bf16 v[38:41], v[194:197], v[210:213], v[38:41]
	v_mfma_f32_16x16x32_bf16 v[26:29], v[186:189], v[224:227], v[26:29]
	v_mfma_f32_16x16x32_bf16 v[22:25], v[194:197], v[224:227], v[22:25]
	v_mfma_f32_16x16x32_bf16 v[10:13], v[186:189], v[232:235], v[10:13]
	v_mfma_f32_16x16x32_bf16 v[6:9], v[194:197], v[232:235], v[6:9]
	s_barrier
	v_lshl_add_u64 v[134:135], v[134:135], 0, s[26:27]
	s_cmp_ge_i32 s10, s46
	v_lshl_add_u64 v[136:137], v[136:137], 0, s[26:27]
	s_cbranch_scc0 .LBB0_1947
